# v26 + K-loops: redundant s_waitcnt lgkmcnt(0) behind each pre-MFMA barrier removed (already drained before the barrier)
# baseline (speedup 1.0000x reference)
; #define PG8_STAGE(bufoff, gbase, voff) do { _Pragma("unroll") for (int _i = 0; _i < 2; ++_i) \
;         __builtin_amdgcn_global_load_lds((const unsigned*)((const char*)(gbase) + (voff)[_i]), (PG8_LAS unsigned*)(lds + (bufoff) + ldsw + _i * 8192), 16, 0, 0); } while (0)
; #define PG8_LDA(dst, b, h) do { _Pragma("unroll") for (int m = 0; m < 4; ++m) _Pragma("unroll") for (int k = 0; k < 2; ++k) dst[m][k] = *(const PG8_LAS bf16x8*)(lds + PG8_SA(b, h) + aoff + m * 2048 + k * 1024); } while (0)
; #define PG8_LDB(dst, b, h) do { _Pragma("unroll") for (int n = 0; n < 2; ++n) _Pragma("unroll") for (int k = 0; k < 2; ++k) dst[n][k] = *(const PG8_LAS bf16x8*)(lds + PG8_SB(b, h) + boff + n * 2048 + k * 1024); } while (0)
; #define PG8_WAIT_V(n) asm volatile("s_waitcnt vmcnt(" #n ")" ::: "memory")
; #define PG8_WAIT_L(n) asm volatile("s_waitcnt lgkmcnt(" #n ")" ::: "memory")
; #define PG8_BAR __builtin_amdgcn_s_barrier()
; #define PG8_SCHED __builtin_amdgcn_sched_barrier(0)
; template <class Epi, class Sched, bool ALIGN_EPI = false, bool SP2 = false>
; __device__ __forceinline__ void gemm_phase(PG8_LAS unsigned char* lds, const Gemm g, const Sched& S, const Epi& E, const int tid) {
;     ...
;         const bool has_next = S.next(ui + 1, nxt);
;         const char* nA = has_next ? S.aptr(nxt) : cA; const char* nB = has_next ? S.bptr(nxt) : cB;
;         for (int t = 0; t < nt; t += 2) {
;             const bool last = (t == nt - 2);
;             const char* a1 = cA + (size_t)(t + 1) * kstep;
;             const char* a2 = last ? nA : cA + (size_t)(t + 2) * kstep; const char* b2 = last ? nB : cB + (size_t)(t + 2) * kstep;
;             const char* a3 = a2 + kstep; const char* b3 = b2 + kstep;
;             if (last && has_next) S.a_ready(nxt);
;             if constexpr (SP2) {
;             PG8_LDB(B0, 0, 0); PG8_LDB(B1, 0, 1); PG8_SCHED; PG8_LDA(At, 0, 0); PG8_STAGE(PG8_SA(1, 1), a1 + hstep, voffA);
;             PG8_WAIT_V(8); PG8_WAIT_L(0); PG8_BAR; PG8_MMA(0, 0, At, B0); PG8_MMA(0, 1, At, B1); PG8_BAR; PG8_SCHED;
;             PG8_LDA(At, 0, 1); PG8_STAGE(PG8_SB(0, 0), b2, voffB); PG8_STAGE(PG8_SB(0, 1), b2 + hstep, voffB); PG8_STAGE(PG8_SA(0, 0), a2, voffA);
;             PG8_WAIT_V(8); PG8_WAIT_L(0); PG8_BAR; PG8_MMA(1, 0, At, B0); PG8_MMA(1, 1, At, B1); PG8_BAR; PG8_SCHED;
.LBB0_338:
	s_ashr_i32 s29, s28, 31
	s_lshl_b64 s[18:19], s[28:29], 19
	s_add_u32 s30, s46, s18
	s_addc_u32 s31, s47, s19
	s_and_b64 s[18:19], s[2:3], exec
	s_cselect_b32 s29, s31, s41
	s_cselect_b32 s62, s30, s40
	s_ashr_i32 s27, s26, 31
	s_lshl_b64 s[18:19], s[26:27], 19
	s_add_u32 s34, s48, s18
	s_addc_u32 s35, s49, s19
	s_and_b64 s[18:19], s[2:3], exec
	s_cselect_b32 s27, s35, s39
	s_cselect_b32 s63, s34, s38
	s_add_u32 s64, s38, 0x100
	s_addc_u32 s65, s39, 0
	s_add_u32 s38, s40, 0x40080
	s_addc_u32 s39, s41, 0
	s_mov_b32 s66, -2
	s_add_u32 s15, s38, 0xfffc0080
	s_addc_u32 s18, s39, -1
	s_cmp_eq_u32 s66, 12
	s_cselect_b32 s43, s29, s18
	s_cselect_b32 s42, s62, s15
	s_cselect_b32 s41, s27, s65
	s_cselect_b32 s40, s63, s64
	v_lshl_add_u64 v[154:155], s[38:39], 0, v[144:145]
	s_add_i32 m0, s51, 0xc000
	global_load_lds_dwordx4 v[154:155], off
	v_lshl_add_u64 v[154:155], s[38:39], 0, v[142:143]
	s_add_i32 m0, s51, 0xe000
	s_nop 0
	global_load_lds_dwordx4 v[154:155], off
	s_waitcnt vmcnt(16)
	s_waitcnt lgkmcnt(0)
	s_barrier
	s_setprio 1
	v_mfma_f32_16x16x32_bf16 v[126:129], v[150:153], v[204:207], 0
	v_mfma_f32_16x16x32_bf16 v[122:125], v[176:179], v[204:207], 0
	v_mfma_f32_16x16x32_bf16 v[110:113], v[150:153], v[212:215], 0
	v_mfma_f32_16x16x32_bf16 v[106:109], v[176:179], v[212:215], 0
	v_mfma_f32_16x16x32_bf16 v[94:97], v[150:153], v[220:223], 0
	v_mfma_f32_16x16x32_bf16 v[90:93], v[176:179], v[220:223], 0
	v_mfma_f32_16x16x32_bf16 v[78:81], v[150:153], v[228:231], 0
	v_mfma_f32_16x16x32_bf16 v[74:77], v[176:179], v[228:231], 0
	v_mfma_f32_16x16x32_bf16 v[126:129], v[172:175], v[208:211], v[126:129]
	v_mfma_f32_16x16x32_bf16 v[122:125], v[180:183], v[208:211], v[122:125]
	v_mfma_f32_16x16x32_bf16 v[110:113], v[172:175], v[216:219], v[110:113]
	v_mfma_f32_16x16x32_bf16 v[106:109], v[180:183], v[216:219], v[106:109]
	v_mfma_f32_16x16x32_bf16 v[94:97], v[172:175], v[224:227], v[94:97]
	v_mfma_f32_16x16x32_bf16 v[90:93], v[180:183], v[224:227], v[90:93]
	v_mfma_f32_16x16x32_bf16 v[78:81], v[172:175], v[232:235], v[78:81]
	v_mfma_f32_16x16x32_bf16 v[74:77], v[180:183], v[232:235], v[74:77]
	s_setprio 0
	s_setprio 1
	v_mfma_f32_16x16x32_bf16 v[118:121], v[184:187], v[204:207], 0
	v_mfma_f32_16x16x32_bf16 v[114:117], v[196:199], v[204:207], 0
	v_mfma_f32_16x16x32_bf16 v[102:105], v[184:187], v[212:215], 0
	v_mfma_f32_16x16x32_bf16 v[98:101], v[196:199], v[212:215], 0
	v_mfma_f32_16x16x32_bf16 v[86:89], v[184:187], v[220:223], 0
	v_mfma_f32_16x16x32_bf16 v[82:85], v[196:199], v[220:223], 0
	v_mfma_f32_16x16x32_bf16 v[70:73], v[184:187], v[228:231], 0
	v_mfma_f32_16x16x32_bf16 v[66:69], v[196:199], v[228:231], 0
	v_mfma_f32_16x16x32_bf16 v[118:121], v[192:195], v[208:211], v[118:121]
	v_mfma_f32_16x16x32_bf16 v[114:117], v[200:203], v[208:211], v[114:117]
	v_mfma_f32_16x16x32_bf16 v[102:105], v[192:195], v[216:219], v[102:105]
	v_mfma_f32_16x16x32_bf16 v[98:101], v[200:203], v[216:219], v[98:101]
	v_mfma_f32_16x16x32_bf16 v[86:89], v[192:195], v[224:227], v[86:89]
	v_mfma_f32_16x16x32_bf16 v[82:85], v[200:203], v[224:227], v[82:85]
	v_mfma_f32_16x16x32_bf16 v[70:73], v[192:195], v[232:235], v[70:73]
	v_mfma_f32_16x16x32_bf16 v[66:69], v[200:203], v[232:235], v[66:69]
	s_setprio 0
	s_barrier
	s_add_i32 s15, s58, s50
	v_lshl_add_u64 v[154:155], s[40:41], 0, v[132:133]
	s_mov_b32 m0, s15
	ds_read_b128 v[204:207], v167 offset:16384
	ds_read_b128 v[208:211], v167 offset:17408
	ds_read_b128 v[212:215], v167 offset:18432
	ds_read_b128 v[216:219], v167 offset:19456
	ds_read_b128 v[220:223], v167 offset:20480
	ds_read_b128 v[224:227], v167 offset:21504
	ds_read_b128 v[228:231], v167 offset:22528
	ds_read_b128 v[232:235], v167 offset:23552
	global_load_lds_dwordx4 v[154:155], off
	s_add_i32 m0, s15, 0x2000
	s_add_u32 s18, s40, 0x40000
	v_lshl_add_u64 v[158:159], s[40:41], 0, v[136:137]
	s_addc_u32 s19, s41, 0
	s_add_i32 s15, s59, s50
	global_load_lds_dwordx4 v[158:159], off
	v_lshl_add_u64 v[164:165], s[18:19], 0, v[132:133]
	s_mov_b32 m0, s15
	v_lshl_add_u64 v[168:169], s[42:43], 0, v[134:135]
	global_load_lds_dwordx4 v[164:165], off
	v_lshl_add_u64 v[164:165], s[18:19], 0, v[136:137]
	s_add_i32 m0, s15, 0x2000
	s_nop 0
	global_load_lds_dwordx4 v[164:165], off
	v_lshl_add_u64 v[164:165], s[42:43], 0, v[130:131]
	s_mov_b32 m0, s51
	s_nop 0
	global_load_lds_dwordx4 v[164:165], off
	s_mov_b32 m0, s52
	s_nop 0
	global_load_lds_dwordx4 v[168:169], off
	s_waitcnt vmcnt(8)
; #define PG8_STAGE(bufoff, gbase, voff) do { _Pragma("unroll") for (int _i = 0; _i < 2; ++_i) \
;         __builtin_amdgcn_global_load_lds((const unsigned*)((const char*)(gbase) + (voff)[_i]), (PG8_LAS unsigned*)(lds + (bufoff) + ldsw + _i * 8192), 16, 0, 0); } while (0)
; #define PG8_LDA(dst, b, h) do { _Pragma("unroll") for (int m = 0; m < 4; ++m) _Pragma("unroll") for (int k = 0; k < 2; ++k) dst[m][k] = *(const PG8_LAS bf16x8*)(lds + PG8_SA(b, h) + aoff + m * 2048 + k * 1024); } while (0)
; #define PG8_LDB(dst, b, h) do { _Pragma("unroll") for (int n = 0; n < 2; ++n) _Pragma("unroll") for (int k = 0; k < 2; ++k) dst[n][k] = *(const PG8_LAS bf16x8*)(lds + PG8_SB(b, h) + boff + n * 2048 + k * 1024); } while (0)
; #define PG8_WAIT_V(n) asm volatile("s_waitcnt vmcnt(" #n ")" ::: "memory")
; #define PG8_WAIT_L(n) asm volatile("s_waitcnt lgkmcnt(" #n ")" ::: "memory")
; #define PG8_BAR __builtin_amdgcn_s_barrier()
; #define PG8_SCHED __builtin_amdgcn_sched_barrier(0)
; template <class Epi, class Sched, bool ALIGN_EPI = false, bool SP2 = false>
; __device__ __forceinline__ void gemm_phase(PG8_LAS unsigned char* lds, const Gemm g, const Sched& S, const Epi& E, const int tid) {
;     ...
;             PG8_WAIT_V(8); PG8_WAIT_L(0); PG8_BAR; PG8_MMA(0, 0, At, B0); PG8_MMA(0, 1, At, B1); PG8_BAR; PG8_SCHED;
;             PG8_LDA(At, 0, 1); PG8_STAGE(PG8_SB(0, 0), b2, voffB); PG8_STAGE(PG8_SB(0, 1), b2 + hstep, voffB); PG8_STAGE(PG8_SA(0, 0), a2, voffA);
;             PG8_WAIT_V(8); PG8_WAIT_L(0); PG8_BAR; PG8_MMA(1, 0, At, B0); PG8_MMA(1, 1, At, B1); PG8_BAR; PG8_SCHED;
;             PG8_LDB(B0, 1, 0); PG8_LDB(B1, 1, 1); PG8_SCHED; PG8_LDA(At, 1, 0); PG8_STAGE(PG8_SA(0, 1), a2 + hstep, voffA);
;             PG8_WAIT_V(8); PG8_WAIT_L(0); PG8_BAR; PG8_MMA(0, 0, At, B0); PG8_MMA(0, 1, At, B1); PG8_BAR; PG8_SCHED;
; __device__ __forceinline__ void rstd8(const float* ssq, int row0, int fq, float (&rs)[8]) {
;     f32x4 pr[8];
; #pragma unroll
;     for (int i = 0; i < 8; ++i) pr[i] = *(const f32x4*)(ssq + (size_t)(row0 + (i >> 2) * 128 + (i & 3) * 16) * 16 + 4 * fq);
; #pragma unroll
;     for (int i = 0; i < 8; ++i) { float s = (pr[i][0] + pr[i][1]) + (pr[i][2] + pr[i][3]); s = xsum16(s); s = xsum32(s); rs[i] = __builtin_amdgcn_rsqf(s * (1.0f / DM) + NORM_EPS); }
; }
	v_add_f32_e32 v6, v6, v7
	v_add_f32_e32 v18, v18, v19
	v_add_f32_e32 v22, v22, v23
	v_add_f32_e32 v34, v34, v35
	v_add_f32_e32 v38, v38, v39
	v_add_f32_e32 v50, v50, v51
	v_add_f32_e32 v54, v54, v55
	v_add_f32_e32 v58, v58, v59
	v_add_f32_e32 v8, v8, v9
	v_add_f32_e32 v20, v20, v21
	v_add_f32_e32 v24, v24, v25
	v_add_f32_e32 v36, v36, v37
	v_add_f32_e32 v40, v40, v41
	v_add_f32_e32 v52, v52, v53
	v_add_f32_e32 v56, v56, v57
	v_add_f32_e32 v60, v60, v61
	v_add_f32_e32 v243, v6, v8
	v_add_f32_e32 v244, v18, v20
	v_add_f32_e32 v245, v22, v24
	v_add_f32_e32 v246, v34, v36
	v_add_f32_e32 v247, v38, v40
	v_add_f32_e32 v248, v50, v52
	v_add_f32_e32 v249, v54, v56
	v_add_f32_e32 v250, v58, v60
	v_mov_b32_e32 v6, v243
	v_mov_b32_e32 v18, v244
	v_mov_b32_e32 v22, v245
	v_mov_b32_e32 v34, v246
	v_mov_b32_e32 v38, v247
	v_mov_b32_e32 v50, v248
	v_mov_b32_e32 v54, v249
	v_mov_b32_e32 v58, v250
	v_permlane16_swap_b32_e32 v243, v6
	v_permlane16_swap_b32_e32 v244, v18
	v_permlane16_swap_b32_e32 v245, v22
	v_permlane16_swap_b32_e32 v246, v34
	v_permlane16_swap_b32_e32 v247, v38
	v_permlane16_swap_b32_e32 v248, v50
	v_permlane16_swap_b32_e32 v249, v54
	v_permlane16_swap_b32_e32 v250, v58
	v_add_f32_e32 v243, v243, v6
	v_add_f32_e32 v244, v244, v18
	v_add_f32_e32 v245, v245, v22
	v_add_f32_e32 v246, v246, v34
	v_add_f32_e32 v247, v247, v38
	v_add_f32_e32 v248, v248, v50
	v_add_f32_e32 v249, v249, v54
	v_add_f32_e32 v250, v250, v58
	v_mov_b32_e32 v6, v243
	v_mov_b32_e32 v18, v244
	v_mov_b32_e32 v22, v245
	v_mov_b32_e32 v34, v246
	v_mov_b32_e32 v38, v247
	v_mov_b32_e32 v50, v248
	v_mov_b32_e32 v54, v249
	v_mov_b32_e32 v58, v250
	v_permlane32_swap_b32_e32 v243, v6
	v_permlane32_swap_b32_e32 v244, v18
	v_permlane32_swap_b32_e32 v245, v22
	v_permlane32_swap_b32_e32 v246, v34
	v_permlane32_swap_b32_e32 v247, v38
	v_permlane32_swap_b32_e32 v248, v50
	v_permlane32_swap_b32_e32 v249, v54
	v_permlane32_swap_b32_e32 v250, v58
	v_add_f32_e32 v243, v243, v6
	v_add_f32_e32 v244, v244, v18
	v_add_f32_e32 v245, v245, v22
	v_add_f32_e32 v246, v246, v34
	v_add_f32_e32 v247, v247, v38
	v_add_f32_e32 v248, v248, v50
	v_add_f32_e32 v249, v249, v54
	v_add_f32_e32 v250, v250, v58
	v_fmamk_f32 v243, v243, 0x3a800000, v171
	v_fmamk_f32 v244, v244, 0x3a800000, v171
	v_fmamk_f32 v245, v245, 0x3a800000, v171
	v_fmamk_f32 v246, v246, 0x3a800000, v171
	v_fmamk_f32 v247, v247, 0x3a800000, v171
	v_fmamk_f32 v248, v248, 0x3a800000, v171
	v_fmamk_f32 v249, v249, 0x3a800000, v171
	v_fmamk_f32 v250, v250, 0x3a800000, v171
	v_rsq_f32_e32 v243, v243
	v_rsq_f32_e32 v244, v244
	v_rsq_f32_e32 v245, v245
	v_rsq_f32_e32 v246, v246
	v_rsq_f32_e32 v247, v247
	v_rsq_f32_e32 v248, v248
	v_rsq_f32_e32 v249, v249
	v_rsq_f32_e32 v250, v250
	s_waitcnt lgkmcnt(0)
	s_barrier
	s_setprio 1
	v_mfma_f32_16x16x32_bf16 v[62:65], v[150:153], v[204:207], 0
	v_mfma_f32_16x16x32_bf16 v[58:61], v[176:179], v[204:207], 0
	v_mfma_f32_16x16x32_bf16 v[46:49], v[150:153], v[212:215], 0
	v_mfma_f32_16x16x32_bf16 v[42:45], v[176:179], v[212:215], 0
	v_mfma_f32_16x16x32_bf16 v[30:33], v[150:153], v[220:223], 0
	v_mfma_f32_16x16x32_bf16 v[26:29], v[176:179], v[220:223], 0
	v_mfma_f32_16x16x32_bf16 v[14:17], v[150:153], v[228:231], 0
	v_mfma_f32_16x16x32_bf16 v[10:13], v[176:179], v[228:231], 0
	v_mfma_f32_16x16x32_bf16 v[62:65], v[172:175], v[208:211], v[62:65]
	v_mfma_f32_16x16x32_bf16 v[58:61], v[180:183], v[208:211], v[58:61]
	v_mfma_f32_16x16x32_bf16 v[46:49], v[172:175], v[216:219], v[46:49]
	v_mfma_f32_16x16x32_bf16 v[42:45], v[180:183], v[216:219], v[42:45]
	v_mfma_f32_16x16x32_bf16 v[30:33], v[172:175], v[224:227], v[30:33]
	v_mfma_f32_16x16x32_bf16 v[26:29], v[180:183], v[224:227], v[26:29]
	v_mfma_f32_16x16x32_bf16 v[14:17], v[172:175], v[232:235], v[14:17]
	v_mfma_f32_16x16x32_bf16 v[10:13], v[180:183], v[232:235], v[10:13]
	s_setprio 0
	s_setprio 1
	v_mfma_f32_16x16x32_bf16 v[54:57], v[184:187], v[204:207], 0
	v_mfma_f32_16x16x32_bf16 v[50:53], v[196:199], v[204:207], 0
	v_mfma_f32_16x16x32_bf16 v[38:41], v[184:187], v[212:215], 0
	v_mfma_f32_16x16x32_bf16 v[34:37], v[196:199], v[212:215], 0
	v_mfma_f32_16x16x32_bf16 v[22:25], v[184:187], v[220:223], 0
	v_mfma_f32_16x16x32_bf16 v[18:21], v[196:199], v[220:223], 0
	v_mfma_f32_16x16x32_bf16 v[6:9], v[184:187], v[228:231], 0
	v_mfma_f32_16x16x32_bf16 v[2:5], v[196:199], v[228:231], 0
	v_mfma_f32_16x16x32_bf16 v[54:57], v[192:195], v[208:211], v[54:57]
	v_mfma_f32_16x16x32_bf16 v[50:53], v[200:203], v[208:211], v[50:53]
	v_mfma_f32_16x16x32_bf16 v[38:41], v[192:195], v[216:219], v[38:41]
	v_mfma_f32_16x16x32_bf16 v[34:37], v[200:203], v[216:219], v[34:37]
	v_mfma_f32_16x16x32_bf16 v[22:25], v[192:195], v[224:227], v[22:25]
	v_mfma_f32_16x16x32_bf16 v[18:21], v[200:203], v[224:227], v[18:21]
	v_mfma_f32_16x16x32_bf16 v[6:9], v[192:195], v[232:235], v[6:9]
	v_mfma_f32_16x16x32_bf16 v[2:5], v[200:203], v[232:235], v[2:5]
	s_setprio 0
	s_barrier
	s_add_i32 s15, 0, 0x18000
	v_add_u32_e32 v156, s15, v157
	s_add_i32 s67, 0, 0x1c000
	ds_read_b128 v[150:153], v156
	ds_read_b128 v[172:175], v156 offset:1024
	ds_read_b128 v[176:179], v156 offset:2048
	ds_read_b128 v[180:183], v156 offset:3072
	v_add_u32_e32 v156, s67, v157
	ds_read_b128 v[184:187], v156
	ds_read_b128 v[192:195], v156 offset:1024
	ds_read_b128 v[196:199], v156 offset:2048
	ds_read_b128 v[200:203], v156 offset:3072
	s_add_u32 s18, s42, 0x40000
	s_addc_u32 s19, s43, 0
	s_mov_b32 m0, s53
	v_lshl_add_u64 v[188:189], s[18:19], 0, v[130:131]
	ds_read_b128 v[204:207], v167 offset:32768
	ds_read_b128 v[208:211], v167 offset:33792
	ds_read_b128 v[212:215], v167 offset:34816
	ds_read_b128 v[216:219], v167 offset:35840
	ds_read_b128 v[220:223], v167 offset:36864
	ds_read_b128 v[224:227], v167 offset:37888
	ds_read_b128 v[228:231], v167 offset:38912
	ds_read_b128 v[232:235], v167 offset:39936
	global_load_lds_dwordx4 v[188:189], off
	v_lshl_add_u64 v[188:189], s[18:19], 0, v[134:135]
	s_mov_b32 m0, s54
	s_nop 0
	global_load_lds_dwordx4 v[188:189], off
	s_waitcnt vmcnt(8)
	s_waitcnt lgkmcnt(0)
	s_barrier
; #define PG8_STAGE(bufoff, gbase, voff) do { _Pragma("unroll") for (int _i = 0; _i < 2; ++_i) \
;         __builtin_amdgcn_global_load_lds((const unsigned*)((const char*)(gbase) + (voff)[_i]), (PG8_LAS unsigned*)(lds + (bufoff) + ldsw + _i * 8192), 16, 0, 0); } while (0)
; #define PG8_LDA(dst, b, h) do { _Pragma("unroll") for (int m = 0; m < 4; ++m) _Pragma("unroll") for (int k = 0; k < 2; ++k) dst[m][k] = *(const PG8_LAS bf16x8*)(lds + PG8_SA(b, h) + aoff + m * 2048 + k * 1024); } while (0)
; #define PG8_MMA(ai, bj, At, Bt) do { __builtin_amdgcn_s_setprio(1); _Pragma("unroll") for (int m = 0; m < 4; ++m) _Pragma("unroll") for (int n = 0; n < 2; ++n) _Pragma("unroll") for (int k = 0; k < 2; ++k) \
;         acc[ai][bj][m][n] = __builtin_amdgcn_mfma_f32_16x16x32_bf16(Bt[n][k], At[m][k], acc[ai][bj][m][n], 0, 0, 0); __builtin_amdgcn_s_setprio(0); } while (0)
; #define PG8_WAIT_V(n) asm volatile("s_waitcnt vmcnt(" #n ")" ::: "memory")
; #define PG8_WAIT_L(n) asm volatile("s_waitcnt lgkmcnt(" #n ")" ::: "memory")
; #define PG8_BAR __builtin_amdgcn_s_barrier()
; #define PG8_SCHED __builtin_amdgcn_sched_barrier(0)
; template <class Epi, class Sched, bool ALIGN_EPI = false, bool SP2 = false>
; __device__ __forceinline__ void gemm_phase(PG8_LAS unsigned char* lds, const Gemm g, const Sched& S, const Epi& E, const int tid) {
;     ...
;             PG8_WAIT_V(8); PG8_WAIT_L(0); PG8_BAR; PG8_MMA(0, 0, At, B0); PG8_MMA(0, 1, At, B1); PG8_BAR; PG8_SCHED;
;             PG8_LDA(At, 1, 1); PG8_STAGE(PG8_SB(1, 0), b3, voffB); PG8_STAGE(PG8_SB(1, 1), b3 + hstep, voffB); PG8_STAGE(PG8_SA(1, 0), a3, voffA);
;             PG8_WAIT_V(8); PG8_WAIT_L(0); PG8_BAR; PG8_MMA(1, 0, At, B0); PG8_MMA(1, 1, At, B1); PG8_BAR; PG8_SCHED;
	s_setprio 1
	v_mfma_f32_16x16x32_bf16 v[126:129], v[150:153], v[204:207], v[126:129]
	v_mfma_f32_16x16x32_bf16 v[122:125], v[176:179], v[204:207], v[122:125]
	v_mfma_f32_16x16x32_bf16 v[110:113], v[150:153], v[212:215], v[110:113]
	v_mfma_f32_16x16x32_bf16 v[106:109], v[176:179], v[212:215], v[106:109]
	v_mfma_f32_16x16x32_bf16 v[94:97], v[150:153], v[220:223], v[94:97]
	v_mfma_f32_16x16x32_bf16 v[90:93], v[176:179], v[220:223], v[90:93]
	v_mfma_f32_16x16x32_bf16 v[78:81], v[150:153], v[228:231], v[78:81]
	v_mfma_f32_16x16x32_bf16 v[74:77], v[176:179], v[228:231], v[74:77]
	v_mfma_f32_16x16x32_bf16 v[126:129], v[172:175], v[208:211], v[126:129]
	v_mfma_f32_16x16x32_bf16 v[122:125], v[180:183], v[208:211], v[122:125]
	v_mfma_f32_16x16x32_bf16 v[110:113], v[172:175], v[216:219], v[110:113]
	v_mfma_f32_16x16x32_bf16 v[106:109], v[180:183], v[216:219], v[106:109]
	v_mfma_f32_16x16x32_bf16 v[94:97], v[172:175], v[224:227], v[94:97]
	v_mfma_f32_16x16x32_bf16 v[90:93], v[180:183], v[224:227], v[90:93]
	v_mfma_f32_16x16x32_bf16 v[78:81], v[172:175], v[232:235], v[78:81]
	v_mfma_f32_16x16x32_bf16 v[74:77], v[180:183], v[232:235], v[74:77]
	s_setprio 0
	s_setprio 1
	v_mfma_f32_16x16x32_bf16 v[118:121], v[184:187], v[204:207], v[118:121]
	v_mfma_f32_16x16x32_bf16 v[114:117], v[196:199], v[204:207], v[114:117]
	v_mfma_f32_16x16x32_bf16 v[102:105], v[184:187], v[212:215], v[102:105]
	v_mfma_f32_16x16x32_bf16 v[98:101], v[196:199], v[212:215], v[98:101]
	v_mfma_f32_16x16x32_bf16 v[86:89], v[184:187], v[220:223], v[86:89]
	v_mfma_f32_16x16x32_bf16 v[82:85], v[196:199], v[220:223], v[82:85]
	v_mfma_f32_16x16x32_bf16 v[70:73], v[184:187], v[228:231], v[70:73]
	v_mfma_f32_16x16x32_bf16 v[66:69], v[196:199], v[228:231], v[66:69]
	v_mfma_f32_16x16x32_bf16 v[118:121], v[192:195], v[208:211], v[118:121]
	v_mfma_f32_16x16x32_bf16 v[114:117], v[200:203], v[208:211], v[114:117]
	v_mfma_f32_16x16x32_bf16 v[102:105], v[192:195], v[216:219], v[102:105]
	v_mfma_f32_16x16x32_bf16 v[98:101], v[200:203], v[216:219], v[98:101]
	v_mfma_f32_16x16x32_bf16 v[86:89], v[192:195], v[224:227], v[86:89]
	v_mfma_f32_16x16x32_bf16 v[82:85], v[200:203], v[224:227], v[82:85]
	v_mfma_f32_16x16x32_bf16 v[70:73], v[192:195], v[232:235], v[70:73]
	v_mfma_f32_16x16x32_bf16 v[66:69], v[200:203], v[232:235], v[66:69]
	s_setprio 0
	s_barrier
	s_add_i32 s15, s15, s50
	v_lshl_add_u64 v[154:155], v[154:155], 0, s[8:9]
	s_mov_b32 m0, s15
	ds_read_b128 v[204:207], v167 offset:49152
	ds_read_b128 v[208:211], v167 offset:50176
	ds_read_b128 v[212:215], v167 offset:51200
	ds_read_b128 v[216:219], v167 offset:52224
	ds_read_b128 v[220:223], v167 offset:53248
	ds_read_b128 v[224:227], v167 offset:54272
	ds_read_b128 v[228:231], v167 offset:55296
	ds_read_b128 v[232:235], v167 offset:56320
	global_load_lds_dwordx4 v[154:155], off
	s_add_i32 m0, s15, 0x2000
	s_add_u32 s18, s40, 0x40080
	v_lshl_add_u64 v[154:155], v[158:159], 0, s[8:9]
	s_addc_u32 s19, s41, 0
	s_add_i32 s15, s67, s50
	global_load_lds_dwordx4 v[154:155], off
	v_lshl_add_u64 v[154:155], s[18:19], 0, v[132:133]
	s_mov_b32 m0, s15
	s_nop 0
	global_load_lds_dwordx4 v[154:155], off
	v_lshl_add_u64 v[154:155], s[18:19], 0, v[136:137]
	s_add_i32 m0, s15, 0x2000
	s_nop 0
	global_load_lds_dwordx4 v[154:155], off
	v_lshl_add_u64 v[154:155], v[164:165], 0, s[8:9]
	s_mov_b32 m0, s55
	s_nop 0
	global_load_lds_dwordx4 v[154:155], off
	v_lshl_add_u64 v[154:155], v[168:169], 0, s[8:9]
	s_mov_b32 m0, s56
	s_nop 0
	global_load_lds_dwordx4 v[154:155], off
	s_waitcnt vmcnt(8)
	s_waitcnt lgkmcnt(0)
	s_barrier
	s_setprio 1
	v_mfma_f32_16x16x32_bf16 v[62:65], v[150:153], v[204:207], v[62:65]
	v_mfma_f32_16x16x32_bf16 v[58:61], v[176:179], v[204:207], v[58:61]
	v_mfma_f32_16x16x32_bf16 v[46:49], v[150:153], v[212:215], v[46:49]
	v_mfma_f32_16x16x32_bf16 v[42:45], v[176:179], v[212:215], v[42:45]
	v_mfma_f32_16x16x32_bf16 v[30:33], v[150:153], v[220:223], v[30:33]
	v_mfma_f32_16x16x32_bf16 v[26:29], v[176:179], v[220:223], v[26:29]
	v_mfma_f32_16x16x32_bf16 v[14:17], v[150:153], v[228:231], v[14:17]
	v_mfma_f32_16x16x32_bf16 v[10:13], v[176:179], v[228:231], v[10:13]
	v_mfma_f32_16x16x32_bf16 v[62:65], v[172:175], v[208:211], v[62:65]
	v_mfma_f32_16x16x32_bf16 v[58:61], v[180:183], v[208:211], v[58:61]
	v_mfma_f32_16x16x32_bf16 v[46:49], v[172:175], v[216:219], v[46:49]
	v_mfma_f32_16x16x32_bf16 v[42:45], v[180:183], v[216:219], v[42:45]
	v_mfma_f32_16x16x32_bf16 v[30:33], v[172:175], v[224:227], v[30:33]
	v_mfma_f32_16x16x32_bf16 v[26:29], v[180:183], v[224:227], v[26:29]
	v_mfma_f32_16x16x32_bf16 v[14:17], v[172:175], v[232:235], v[14:17]
	v_mfma_f32_16x16x32_bf16 v[10:13], v[180:183], v[232:235], v[10:13]
	s_setprio 0
	s_setprio 1
	v_mfma_f32_16x16x32_bf16 v[54:57], v[184:187], v[204:207], v[54:57]
	v_mfma_f32_16x16x32_bf16 v[50:53], v[196:199], v[204:207], v[50:53]
	v_mfma_f32_16x16x32_bf16 v[38:41], v[184:187], v[212:215], v[38:41]
	v_mfma_f32_16x16x32_bf16 v[34:37], v[196:199], v[212:215], v[34:37]
	v_mfma_f32_16x16x32_bf16 v[22:25], v[184:187], v[220:223], v[22:25]
	v_mfma_f32_16x16x32_bf16 v[18:21], v[196:199], v[220:223], v[18:21]
	v_mfma_f32_16x16x32_bf16 v[6:9], v[184:187], v[228:231], v[6:9]
	v_mfma_f32_16x16x32_bf16 v[2:5], v[196:199], v[228:231], v[2:5]
	v_mfma_f32_16x16x32_bf16 v[54:57], v[192:195], v[208:211], v[54:57]
	v_mfma_f32_16x16x32_bf16 v[50:53], v[200:203], v[208:211], v[50:53]
	v_mfma_f32_16x16x32_bf16 v[38:41], v[192:195], v[216:219], v[38:41]
	v_mfma_f32_16x16x32_bf16 v[34:37], v[200:203], v[216:219], v[34:37]
	v_mfma_f32_16x16x32_bf16 v[22:25], v[192:195], v[224:227], v[22:25]
	v_mfma_f32_16x16x32_bf16 v[18:21], v[200:203], v[224:227], v[18:21]
	v_mfma_f32_16x16x32_bf16 v[6:9], v[192:195], v[232:235], v[6:9]
	v_mfma_f32_16x16x32_bf16 v[2:5], v[200:203], v[232:235], v[2:5]
	s_setprio 0
	s_barrier
	s_add_i32 s66, s66, 2
	s_add_u32 s64, s64, 0x100
	s_addc_u32 s65, s65, 0
	s_add_u32 s38, s38, 0x100
	s_addc_u32 s39, s39, 0
; #define PG8_STAGE(bufoff, gbase, voff) do { _Pragma("unroll") for (int _i = 0; _i < 2; ++_i) \
;         __builtin_amdgcn_global_load_lds((const unsigned*)((const char*)(gbase) + (voff)[_i]), (PG8_LAS unsigned*)(lds + (bufoff) + ldsw + _i * 8192), 16, 0, 0); } while (0)
; #define PG8_LDA(dst, b, h) do { _Pragma("unroll") for (int m = 0; m < 4; ++m) _Pragma("unroll") for (int k = 0; k < 2; ++k) dst[m][k] = *(const PG8_LAS bf16x8*)(lds + PG8_SA(b, h) + aoff + m * 2048 + k * 1024); } while (0)
; #define PG8_LDB(dst, b, h) do { _Pragma("unroll") for (int n = 0; n < 2; ++n) _Pragma("unroll") for (int k = 0; k < 2; ++k) dst[n][k] = *(const PG8_LAS bf16x8*)(lds + PG8_SB(b, h) + boff + n * 2048 + k * 1024); } while (0)
; #define PG8_MMA(ai, bj, At, Bt) do { __builtin_amdgcn_s_setprio(1); _Pragma("unroll") for (int m = 0; m < 4; ++m) _Pragma("unroll") for (int n = 0; n < 2; ++n) _Pragma("unroll") for (int k = 0; k < 2; ++k) \
;         acc[ai][bj][m][n] = __builtin_amdgcn_mfma_f32_16x16x32_bf16(Bt[n][k], At[m][k], acc[ai][bj][m][n], 0, 0, 0); __builtin_amdgcn_s_setprio(0); } while (0)
; #define PG8_WAIT_V(n) asm volatile("s_waitcnt vmcnt(" #n ")" ::: "memory")
; #define PG8_BAR __builtin_amdgcn_s_barrier()
; template <class Epi, class Sched, bool ALIGN_EPI = false, bool SP2 = false>
; __device__ __forceinline__ void gemm_phase(PG8_LAS unsigned char* lds, const Gemm g, const Sched& S, const Epi& E, const int tid) {
;     ...
;         for (int t = 0; t < nt; t += 2) {
;             const bool last = (t == nt - 2);
;             const char* a1 = cA + (size_t)(t + 1) * kstep;
;             const char* a2 = last ? nA : cA + (size_t)(t + 2) * kstep; const char* b2 = last ? nB : cB + (size_t)(t + 2) * kstep;
;             const char* a3 = a2 + kstep; const char* b3 = b2 + kstep;
;             if (last && has_next) S.a_ready(nxt);
;             if constexpr (SP2) {
;             PG8_LDB(B0, 0, 0); PG8_LDB(B1, 0, 1); PG8_SCHED; PG8_LDA(At, 0, 0); PG8_STAGE(PG8_SA(1, 1), a1 + hstep, voffA);
;             PG8_WAIT_V(8); PG8_WAIT_L(0); PG8_BAR; PG8_MMA(0, 0, At, B0); PG8_MMA(0, 1, At, B1); PG8_BAR; PG8_SCHED;
;             PG8_LDA(At, 0, 1); PG8_STAGE(PG8_SB(0, 0), b2, voffB); PG8_STAGE(PG8_SB(0, 1), b2 + hstep, voffB); PG8_STAGE(PG8_SA(0, 0), a2, voffA);
;             PG8_WAIT_V(8); PG8_WAIT_L(0); PG8_BAR; PG8_MMA(1, 0, At, B0); PG8_MMA(1, 1, At, B1); PG8_BAR; PG8_SCHED;
.LBB0_339:
	ds_read_b128 v[150:153], v161
	ds_read_b128 v[172:175], v161 offset:1024
	ds_read_b128 v[176:179], v161 offset:2048
	ds_read_b128 v[180:183], v161 offset:3072
	ds_read_b128 v[184:187], v163
	ds_read_b128 v[192:195], v163 offset:1024
	ds_read_b128 v[196:199], v163 offset:2048
	ds_read_b128 v[200:203], v163 offset:3072
	s_add_u32 s15, s38, 0xfffc0080
	s_addc_u32 s18, s39, -1
	s_cmp_eq_u32 s66, 12
	s_cselect_b32 s43, s29, s18
	s_cselect_b32 s42, s62, s15
	s_cselect_b32 s41, s27, s65
	s_cselect_b32 s40, s63, s64
	v_lshl_add_u64 v[154:155], s[38:39], 0, v[144:145]
	s_add_i32 m0, s51, 0xc000
	ds_read_b128 v[204:207], v167
	ds_read_b128 v[208:211], v167 offset:1024
	ds_read_b128 v[212:215], v167 offset:2048
	ds_read_b128 v[216:219], v167 offset:3072
	ds_read_b128 v[220:223], v167 offset:4096
	ds_read_b128 v[224:227], v167 offset:5120
	ds_read_b128 v[228:231], v167 offset:6144
	ds_read_b128 v[232:235], v167 offset:7168
	global_load_lds_dwordx4 v[154:155], off
	v_lshl_add_u64 v[154:155], s[38:39], 0, v[142:143]
	s_add_i32 m0, s51, 0xe000
	s_nop 0
	global_load_lds_dwordx4 v[154:155], off
	s_waitcnt vmcnt(8)
	s_waitcnt lgkmcnt(0)
	s_barrier
	s_setprio 1
	v_mfma_f32_16x16x32_bf16 v[126:129], v[150:153], v[204:207], v[126:129]
	v_mfma_f32_16x16x32_bf16 v[122:125], v[176:179], v[204:207], v[122:125]
	v_mfma_f32_16x16x32_bf16 v[110:113], v[150:153], v[212:215], v[110:113]
	v_mfma_f32_16x16x32_bf16 v[106:109], v[176:179], v[212:215], v[106:109]
	v_mfma_f32_16x16x32_bf16 v[94:97], v[150:153], v[220:223], v[94:97]
	v_mfma_f32_16x16x32_bf16 v[90:93], v[176:179], v[220:223], v[90:93]
	v_mfma_f32_16x16x32_bf16 v[78:81], v[150:153], v[228:231], v[78:81]
	v_mfma_f32_16x16x32_bf16 v[74:77], v[176:179], v[228:231], v[74:77]
	v_mfma_f32_16x16x32_bf16 v[126:129], v[172:175], v[208:211], v[126:129]
	v_mfma_f32_16x16x32_bf16 v[122:125], v[180:183], v[208:211], v[122:125]
	v_mfma_f32_16x16x32_bf16 v[110:113], v[172:175], v[216:219], v[110:113]
	v_mfma_f32_16x16x32_bf16 v[106:109], v[180:183], v[216:219], v[106:109]
	v_mfma_f32_16x16x32_bf16 v[94:97], v[172:175], v[224:227], v[94:97]
	v_mfma_f32_16x16x32_bf16 v[90:93], v[180:183], v[224:227], v[90:93]
	v_mfma_f32_16x16x32_bf16 v[78:81], v[172:175], v[232:235], v[78:81]
	v_mfma_f32_16x16x32_bf16 v[74:77], v[180:183], v[232:235], v[74:77]
	s_setprio 0
	s_setprio 1
	v_mfma_f32_16x16x32_bf16 v[118:121], v[184:187], v[204:207], v[118:121]
	v_mfma_f32_16x16x32_bf16 v[114:117], v[196:199], v[204:207], v[114:117]
	v_mfma_f32_16x16x32_bf16 v[102:105], v[184:187], v[212:215], v[102:105]
	v_mfma_f32_16x16x32_bf16 v[98:101], v[196:199], v[212:215], v[98:101]
	v_mfma_f32_16x16x32_bf16 v[86:89], v[184:187], v[220:223], v[86:89]
	v_mfma_f32_16x16x32_bf16 v[82:85], v[196:199], v[220:223], v[82:85]
	v_mfma_f32_16x16x32_bf16 v[70:73], v[184:187], v[228:231], v[70:73]
	v_mfma_f32_16x16x32_bf16 v[66:69], v[196:199], v[228:231], v[66:69]
	v_mfma_f32_16x16x32_bf16 v[118:121], v[192:195], v[208:211], v[118:121]
	v_mfma_f32_16x16x32_bf16 v[114:117], v[200:203], v[208:211], v[114:117]
	v_mfma_f32_16x16x32_bf16 v[102:105], v[192:195], v[216:219], v[102:105]
	v_mfma_f32_16x16x32_bf16 v[98:101], v[200:203], v[216:219], v[98:101]
	v_mfma_f32_16x16x32_bf16 v[86:89], v[192:195], v[224:227], v[86:89]
	v_mfma_f32_16x16x32_bf16 v[82:85], v[200:203], v[224:227], v[82:85]
	v_mfma_f32_16x16x32_bf16 v[70:73], v[192:195], v[232:235], v[70:73]
	v_mfma_f32_16x16x32_bf16 v[66:69], v[200:203], v[232:235], v[66:69]
	s_setprio 0
	s_barrier
	s_add_i32 s15, s58, s50
	v_lshl_add_u64 v[154:155], s[40:41], 0, v[132:133]
	s_mov_b32 m0, s15
	ds_read_b128 v[204:207], v167 offset:16384
	ds_read_b128 v[208:211], v167 offset:17408
	ds_read_b128 v[212:215], v167 offset:18432
	ds_read_b128 v[216:219], v167 offset:19456
	ds_read_b128 v[220:223], v167 offset:20480
	ds_read_b128 v[224:227], v167 offset:21504
	ds_read_b128 v[228:231], v167 offset:22528
	ds_read_b128 v[232:235], v167 offset:23552
	global_load_lds_dwordx4 v[154:155], off
	s_add_i32 m0, s15, 0x2000
	s_add_u32 s18, s40, 0x40000
	v_lshl_add_u64 v[158:159], s[40:41], 0, v[136:137]
	s_addc_u32 s19, s41, 0
	s_add_i32 s15, s59, s50
	global_load_lds_dwordx4 v[158:159], off
	v_lshl_add_u64 v[164:165], s[18:19], 0, v[132:133]
	s_mov_b32 m0, s15
	v_lshl_add_u64 v[168:169], s[42:43], 0, v[134:135]
	global_load_lds_dwordx4 v[164:165], off
	v_lshl_add_u64 v[164:165], s[18:19], 0, v[136:137]
	s_add_i32 m0, s15, 0x2000
	s_nop 0
	global_load_lds_dwordx4 v[164:165], off
	v_lshl_add_u64 v[164:165], s[42:43], 0, v[130:131]
	s_mov_b32 m0, s51
	s_nop 0
	global_load_lds_dwordx4 v[164:165], off
	s_mov_b32 m0, s52
	s_nop 0
	global_load_lds_dwordx4 v[168:169], off
	s_waitcnt vmcnt(8)
	s_waitcnt lgkmcnt(0)
	s_barrier
; #define PG8_STAGE(bufoff, gbase, voff) do { _Pragma("unroll") for (int _i = 0; _i < 2; ++_i) \
;         __builtin_amdgcn_global_load_lds((const unsigned*)((const char*)(gbase) + (voff)[_i]), (PG8_LAS unsigned*)(lds + (bufoff) + ldsw + _i * 8192), 16, 0, 0); } while (0)
; #define PG8_LDA(dst, b, h) do { _Pragma("unroll") for (int m = 0; m < 4; ++m) _Pragma("unroll") for (int k = 0; k < 2; ++k) dst[m][k] = *(const PG8_LAS bf16x8*)(lds + PG8_SA(b, h) + aoff + m * 2048 + k * 1024); } while (0)
; #define PG8_LDB(dst, b, h) do { _Pragma("unroll") for (int n = 0; n < 2; ++n) _Pragma("unroll") for (int k = 0; k < 2; ++k) dst[n][k] = *(const PG8_LAS bf16x8*)(lds + PG8_SB(b, h) + boff + n * 2048 + k * 1024); } while (0)
; #define PG8_MMA(ai, bj, At, Bt) do { __builtin_amdgcn_s_setprio(1); _Pragma("unroll") for (int m = 0; m < 4; ++m) _Pragma("unroll") for (int n = 0; n < 2; ++n) _Pragma("unroll") for (int k = 0; k < 2; ++k) \
;         acc[ai][bj][m][n] = __builtin_amdgcn_mfma_f32_16x16x32_bf16(Bt[n][k], At[m][k], acc[ai][bj][m][n], 0, 0, 0); __builtin_amdgcn_s_setprio(0); } while (0)
; #define PG8_WAIT_V(n) asm volatile("s_waitcnt vmcnt(" #n ")" ::: "memory")
; #define PG8_WAIT_L(n) asm volatile("s_waitcnt lgkmcnt(" #n ")" ::: "memory")
; #define PG8_BAR __builtin_amdgcn_s_barrier()
; #define PG8_SCHED __builtin_amdgcn_sched_barrier(0)
; template <class Epi, class Sched, bool ALIGN_EPI = false, bool SP2 = false>
; __device__ __forceinline__ void gemm_phase(PG8_LAS unsigned char* lds, const Gemm g, const Sched& S, const Epi& E, const int tid) {
;     ...
;             PG8_WAIT_V(8); PG8_WAIT_L(0); PG8_BAR; PG8_MMA(1, 0, At, B0); PG8_MMA(1, 1, At, B1); PG8_BAR; PG8_SCHED;
;             PG8_LDB(B0, 1, 0); PG8_LDB(B1, 1, 1); PG8_SCHED; PG8_LDA(At, 1, 0); PG8_STAGE(PG8_SA(0, 1), a2 + hstep, voffA);
;             PG8_WAIT_V(8); PG8_WAIT_L(0); PG8_BAR; PG8_MMA(0, 0, At, B0); PG8_MMA(0, 1, At, B1); PG8_BAR; PG8_SCHED;
	s_setprio 1
	v_mfma_f32_16x16x32_bf16 v[62:65], v[150:153], v[204:207], v[62:65]
	v_mfma_f32_16x16x32_bf16 v[58:61], v[176:179], v[204:207], v[58:61]
	v_mfma_f32_16x16x32_bf16 v[46:49], v[150:153], v[212:215], v[46:49]
	v_mfma_f32_16x16x32_bf16 v[42:45], v[176:179], v[212:215], v[42:45]
	v_mfma_f32_16x16x32_bf16 v[30:33], v[150:153], v[220:223], v[30:33]
	v_mfma_f32_16x16x32_bf16 v[26:29], v[176:179], v[220:223], v[26:29]
	v_mfma_f32_16x16x32_bf16 v[14:17], v[150:153], v[228:231], v[14:17]
	v_mfma_f32_16x16x32_bf16 v[10:13], v[176:179], v[228:231], v[10:13]
	v_mfma_f32_16x16x32_bf16 v[62:65], v[172:175], v[208:211], v[62:65]
	v_mfma_f32_16x16x32_bf16 v[58:61], v[180:183], v[208:211], v[58:61]
	v_mfma_f32_16x16x32_bf16 v[46:49], v[172:175], v[216:219], v[46:49]
	v_mfma_f32_16x16x32_bf16 v[42:45], v[180:183], v[216:219], v[42:45]
	v_mfma_f32_16x16x32_bf16 v[30:33], v[172:175], v[224:227], v[30:33]
	v_mfma_f32_16x16x32_bf16 v[26:29], v[180:183], v[224:227], v[26:29]
	v_mfma_f32_16x16x32_bf16 v[14:17], v[172:175], v[232:235], v[14:17]
	v_mfma_f32_16x16x32_bf16 v[10:13], v[180:183], v[232:235], v[10:13]
	s_setprio 0
	s_setprio 1
	v_mfma_f32_16x16x32_bf16 v[54:57], v[184:187], v[204:207], v[54:57]
	v_mfma_f32_16x16x32_bf16 v[50:53], v[196:199], v[204:207], v[50:53]
	v_mfma_f32_16x16x32_bf16 v[38:41], v[184:187], v[212:215], v[38:41]
	v_mfma_f32_16x16x32_bf16 v[34:37], v[196:199], v[212:215], v[34:37]
	v_mfma_f32_16x16x32_bf16 v[22:25], v[184:187], v[220:223], v[22:25]
	v_mfma_f32_16x16x32_bf16 v[18:21], v[196:199], v[220:223], v[18:21]
	v_mfma_f32_16x16x32_bf16 v[6:9], v[184:187], v[228:231], v[6:9]
	v_mfma_f32_16x16x32_bf16 v[2:5], v[196:199], v[228:231], v[2:5]
	v_mfma_f32_16x16x32_bf16 v[54:57], v[192:195], v[208:211], v[54:57]
	v_mfma_f32_16x16x32_bf16 v[50:53], v[200:203], v[208:211], v[50:53]
	v_mfma_f32_16x16x32_bf16 v[38:41], v[192:195], v[216:219], v[38:41]
	v_mfma_f32_16x16x32_bf16 v[34:37], v[200:203], v[216:219], v[34:37]
	v_mfma_f32_16x16x32_bf16 v[22:25], v[192:195], v[224:227], v[22:25]
	v_mfma_f32_16x16x32_bf16 v[18:21], v[200:203], v[224:227], v[18:21]
	v_mfma_f32_16x16x32_bf16 v[6:9], v[192:195], v[232:235], v[6:9]
	v_mfma_f32_16x16x32_bf16 v[2:5], v[200:203], v[232:235], v[2:5]
	s_setprio 0
	s_barrier
	s_add_i32 s15, 0, 0x18000
	v_add_u32_e32 v156, s15, v157
	s_add_i32 s67, 0, 0x1c000
	ds_read_b128 v[150:153], v156
	ds_read_b128 v[172:175], v156 offset:1024
	ds_read_b128 v[176:179], v156 offset:2048
	ds_read_b128 v[180:183], v156 offset:3072
	v_add_u32_e32 v156, s67, v157
	ds_read_b128 v[184:187], v156
	ds_read_b128 v[192:195], v156 offset:1024
	ds_read_b128 v[196:199], v156 offset:2048
	ds_read_b128 v[200:203], v156 offset:3072
	s_add_u32 s18, s42, 0x40000
	s_addc_u32 s19, s43, 0
	s_mov_b32 m0, s53
	v_lshl_add_u64 v[188:189], s[18:19], 0, v[130:131]
	ds_read_b128 v[204:207], v167 offset:32768
	ds_read_b128 v[208:211], v167 offset:33792
	ds_read_b128 v[212:215], v167 offset:34816
	ds_read_b128 v[216:219], v167 offset:35840
	ds_read_b128 v[220:223], v167 offset:36864
	ds_read_b128 v[224:227], v167 offset:37888
	ds_read_b128 v[228:231], v167 offset:38912
	ds_read_b128 v[232:235], v167 offset:39936
	global_load_lds_dwordx4 v[188:189], off
	v_lshl_add_u64 v[188:189], s[18:19], 0, v[134:135]
	s_mov_b32 m0, s54
	s_nop 0
	global_load_lds_dwordx4 v[188:189], off
	s_waitcnt vmcnt(8)
	s_waitcnt lgkmcnt(0)
	s_barrier
	s_setprio 1
	v_mfma_f32_16x16x32_bf16 v[126:129], v[150:153], v[204:207], v[126:129]
	v_mfma_f32_16x16x32_bf16 v[122:125], v[176:179], v[204:207], v[122:125]
	v_mfma_f32_16x16x32_bf16 v[110:113], v[150:153], v[212:215], v[110:113]
	v_mfma_f32_16x16x32_bf16 v[106:109], v[176:179], v[212:215], v[106:109]
	v_mfma_f32_16x16x32_bf16 v[94:97], v[150:153], v[220:223], v[94:97]
	v_mfma_f32_16x16x32_bf16 v[90:93], v[176:179], v[220:223], v[90:93]
	v_mfma_f32_16x16x32_bf16 v[78:81], v[150:153], v[228:231], v[78:81]
	v_mfma_f32_16x16x32_bf16 v[74:77], v[176:179], v[228:231], v[74:77]
	v_mfma_f32_16x16x32_bf16 v[126:129], v[172:175], v[208:211], v[126:129]
	v_mfma_f32_16x16x32_bf16 v[122:125], v[180:183], v[208:211], v[122:125]
	v_mfma_f32_16x16x32_bf16 v[110:113], v[172:175], v[216:219], v[110:113]
	v_mfma_f32_16x16x32_bf16 v[106:109], v[180:183], v[216:219], v[106:109]
	v_mfma_f32_16x16x32_bf16 v[94:97], v[172:175], v[224:227], v[94:97]
	v_mfma_f32_16x16x32_bf16 v[90:93], v[180:183], v[224:227], v[90:93]
	v_mfma_f32_16x16x32_bf16 v[78:81], v[172:175], v[232:235], v[78:81]
	v_mfma_f32_16x16x32_bf16 v[74:77], v[180:183], v[232:235], v[74:77]
	s_setprio 0
	s_setprio 1
	v_mfma_f32_16x16x32_bf16 v[118:121], v[184:187], v[204:207], v[118:121]
	v_mfma_f32_16x16x32_bf16 v[114:117], v[196:199], v[204:207], v[114:117]
	v_mfma_f32_16x16x32_bf16 v[102:105], v[184:187], v[212:215], v[102:105]
	v_mfma_f32_16x16x32_bf16 v[98:101], v[196:199], v[212:215], v[98:101]
	v_mfma_f32_16x16x32_bf16 v[86:89], v[184:187], v[220:223], v[86:89]
	v_mfma_f32_16x16x32_bf16 v[82:85], v[196:199], v[220:223], v[82:85]
	v_mfma_f32_16x16x32_bf16 v[70:73], v[184:187], v[228:231], v[70:73]
	v_mfma_f32_16x16x32_bf16 v[66:69], v[196:199], v[228:231], v[66:69]
	v_mfma_f32_16x16x32_bf16 v[118:121], v[192:195], v[208:211], v[118:121]
	v_mfma_f32_16x16x32_bf16 v[114:117], v[200:203], v[208:211], v[114:117]
	v_mfma_f32_16x16x32_bf16 v[102:105], v[192:195], v[216:219], v[102:105]
	v_mfma_f32_16x16x32_bf16 v[98:101], v[200:203], v[216:219], v[98:101]
	v_mfma_f32_16x16x32_bf16 v[86:89], v[192:195], v[224:227], v[86:89]
	v_mfma_f32_16x16x32_bf16 v[82:85], v[200:203], v[224:227], v[82:85]
	v_mfma_f32_16x16x32_bf16 v[70:73], v[192:195], v[232:235], v[70:73]
	v_mfma_f32_16x16x32_bf16 v[66:69], v[200:203], v[232:235], v[66:69]
	s_setprio 0
	s_barrier
; #define PG8_STAGE(bufoff, gbase, voff) do { _Pragma("unroll") for (int _i = 0; _i < 2; ++_i) \
;         __builtin_amdgcn_global_load_lds((const unsigned*)((const char*)(gbase) + (voff)[_i]), (PG8_LAS unsigned*)(lds + (bufoff) + ldsw + _i * 8192), 16, 0, 0); } while (0)
; #define PG8_LDA(dst, b, h) do { _Pragma("unroll") for (int m = 0; m < 4; ++m) _Pragma("unroll") for (int k = 0; k < 2; ++k) dst[m][k] = *(const PG8_LAS bf16x8*)(lds + PG8_SA(b, h) + aoff + m * 2048 + k * 1024); } while (0)
; #define PG8_BAR __builtin_amdgcn_s_barrier()
; template <class Epi, class Sched, bool ALIGN_EPI = false, bool SP2 = false>
; __device__ __forceinline__ void gemm_phase(PG8_LAS unsigned char* lds, const Gemm g, const Sched& S, const Epi& E, const int tid) {
;     ...
;             PG8_LDA(At, 1, 1); PG8_STAGE(PG8_SB(1, 0), b3, voffB); PG8_STAGE(PG8_SB(1, 1), b3 + hstep, voffB); PG8_STAGE(PG8_SA(1, 0), a3, voffA);
;             PG8_WAIT_V(8); PG8_WAIT_L(0); PG8_BAR; PG8_MMA(1, 0, At, B0); PG8_MMA(1, 1, At, B1); PG8_BAR; PG8_SCHED;
;             } else {
;             PG8_LDB(B0, 0, 0); PG8_SCHED; PG8_LDA(At, 0, 0); PG8_STAGE(PG8_SA(1, 1), a1 + hstep, voffA);
;             PG8_WAIT_L(8); PG8_BAR; PG8_WAIT_L(0); PG8_MMA(0, 0, At, B0); PG8_BAR; PG8_SCHED;
;             PG8_LDB(B1, 0, 1); PG8_STAGE(PG8_SB(0, 0), b2, voffB);
;             PG8_BAR; PG8_WAIT_L(0); PG8_MMA(0, 1, At, B1); PG8_BAR;
;             PG8_LDA(At, 0, 1); PG8_STAGE(PG8_SA(0, 0), a2, voffA);
;             PG8_BAR; PG8_WAIT_L(0); PG8_MMA(1, 0, At, B0); PG8_BAR; PG8_SCHED;
;             PG8_STAGE(PG8_SB(0, 1), b2 + hstep, voffB);
;             PG8_WAIT_V(6); PG8_BAR; PG8_MMA(1, 1, At, B1); PG8_BAR;
;             PG8_LDB(B0, 1, 0); PG8_SCHED; PG8_LDA(At, 1, 0); PG8_STAGE(PG8_SA(0, 1), a2 + hstep, voffA);
;             PG8_WAIT_L(8); PG8_BAR; PG8_WAIT_L(0); PG8_MMA(0, 0, At, B0); PG8_BAR; PG8_SCHED;
;             PG8_LDB(B1, 1, 1); PG8_STAGE(PG8_SB(1, 0), b3, voffB);
;             PG8_BAR; PG8_WAIT_L(0); PG8_MMA(0, 1, At, B1); PG8_BAR;
;             PG8_LDA(At, 1, 1); PG8_STAGE(PG8_SA(1, 0), a3, voffA);
;             PG8_BAR; PG8_WAIT_L(0); PG8_MMA(1, 0, At, B0); PG8_BAR; PG8_SCHED;
;             PG8_STAGE(PG8_SB(1, 1), b3 + hstep, voffB);
;             PG8_WAIT_V(6); PG8_BAR; PG8_MMA(1, 1, At, B1); PG8_BAR;
;             }
;         }
;         if constexpr (ALIGN_EPI) { if (wr == 0) PG8_BAR; }
	s_add_i32 s15, s15, s50
	v_lshl_add_u64 v[154:155], v[154:155], 0, s[8:9]
	s_mov_b32 m0, s15
	ds_read_b128 v[204:207], v167 offset:49152
	ds_read_b128 v[208:211], v167 offset:50176
	ds_read_b128 v[212:215], v167 offset:51200
	ds_read_b128 v[216:219], v167 offset:52224
	ds_read_b128 v[220:223], v167 offset:53248
	ds_read_b128 v[224:227], v167 offset:54272
	ds_read_b128 v[228:231], v167 offset:55296
	ds_read_b128 v[232:235], v167 offset:56320
	global_load_lds_dwordx4 v[154:155], off
	s_add_i32 m0, s15, 0x2000
	s_add_u32 s18, s40, 0x40080
	v_lshl_add_u64 v[154:155], v[158:159], 0, s[8:9]
	s_addc_u32 s19, s41, 0
	s_add_i32 s15, s67, s50
	global_load_lds_dwordx4 v[154:155], off
	v_lshl_add_u64 v[154:155], s[18:19], 0, v[132:133]
	s_mov_b32 m0, s15
	s_nop 0
	global_load_lds_dwordx4 v[154:155], off
	v_lshl_add_u64 v[154:155], s[18:19], 0, v[136:137]
	s_add_i32 m0, s15, 0x2000
	s_nop 0
	global_load_lds_dwordx4 v[154:155], off
	v_lshl_add_u64 v[154:155], v[164:165], 0, s[8:9]
	s_mov_b32 m0, s55
	s_nop 0
	global_load_lds_dwordx4 v[154:155], off
	v_lshl_add_u64 v[154:155], v[168:169], 0, s[8:9]
	s_mov_b32 m0, s56
	s_nop 0
	global_load_lds_dwordx4 v[154:155], off
	s_waitcnt vmcnt(8)
	s_waitcnt lgkmcnt(0)
	s_barrier
	s_setprio 1
	v_mfma_f32_16x16x32_bf16 v[62:65], v[150:153], v[204:207], v[62:65]
	v_mfma_f32_16x16x32_bf16 v[58:61], v[176:179], v[204:207], v[58:61]
	v_mfma_f32_16x16x32_bf16 v[46:49], v[150:153], v[212:215], v[46:49]
	v_mfma_f32_16x16x32_bf16 v[42:45], v[176:179], v[212:215], v[42:45]
	v_mfma_f32_16x16x32_bf16 v[30:33], v[150:153], v[220:223], v[30:33]
	v_mfma_f32_16x16x32_bf16 v[26:29], v[176:179], v[220:223], v[26:29]
	v_mfma_f32_16x16x32_bf16 v[14:17], v[150:153], v[228:231], v[14:17]
	v_mfma_f32_16x16x32_bf16 v[10:13], v[176:179], v[228:231], v[10:13]
	v_mfma_f32_16x16x32_bf16 v[62:65], v[172:175], v[208:211], v[62:65]
	v_mfma_f32_16x16x32_bf16 v[58:61], v[180:183], v[208:211], v[58:61]
	v_mfma_f32_16x16x32_bf16 v[46:49], v[172:175], v[216:219], v[46:49]
	v_mfma_f32_16x16x32_bf16 v[42:45], v[180:183], v[216:219], v[42:45]
	v_mfma_f32_16x16x32_bf16 v[30:33], v[172:175], v[224:227], v[30:33]
	v_mfma_f32_16x16x32_bf16 v[26:29], v[180:183], v[224:227], v[26:29]
	v_mfma_f32_16x16x32_bf16 v[14:17], v[172:175], v[232:235], v[14:17]
	v_mfma_f32_16x16x32_bf16 v[10:13], v[180:183], v[232:235], v[10:13]
	s_setprio 0
	s_setprio 1
	v_mfma_f32_16x16x32_bf16 v[54:57], v[184:187], v[204:207], v[54:57]
	v_mfma_f32_16x16x32_bf16 v[50:53], v[196:199], v[204:207], v[50:53]
	v_mfma_f32_16x16x32_bf16 v[38:41], v[184:187], v[212:215], v[38:41]
	v_mfma_f32_16x16x32_bf16 v[34:37], v[196:199], v[212:215], v[34:37]
	v_mfma_f32_16x16x32_bf16 v[22:25], v[184:187], v[220:223], v[22:25]
	v_mfma_f32_16x16x32_bf16 v[18:21], v[196:199], v[220:223], v[18:21]
	v_mfma_f32_16x16x32_bf16 v[6:9], v[184:187], v[228:231], v[6:9]
	v_mfma_f32_16x16x32_bf16 v[2:5], v[196:199], v[228:231], v[2:5]
	v_mfma_f32_16x16x32_bf16 v[54:57], v[192:195], v[208:211], v[54:57]
	v_mfma_f32_16x16x32_bf16 v[50:53], v[200:203], v[208:211], v[50:53]
	v_mfma_f32_16x16x32_bf16 v[38:41], v[192:195], v[216:219], v[38:41]
	v_mfma_f32_16x16x32_bf16 v[34:37], v[200:203], v[216:219], v[34:37]
	v_mfma_f32_16x16x32_bf16 v[22:25], v[192:195], v[224:227], v[22:25]
	v_mfma_f32_16x16x32_bf16 v[18:21], v[200:203], v[224:227], v[18:21]
	v_mfma_f32_16x16x32_bf16 v[6:9], v[192:195], v[232:235], v[6:9]
	v_mfma_f32_16x16x32_bf16 v[2:5], v[200:203], v[232:235], v[2:5]
	s_setprio 0
	s_barrier
	s_add_i32 s66, s66, 2
	s_add_u32 s64, s64, 0x100
	s_addc_u32 s65, s65, 0
	s_add_u32 s38, s38, 0x100
	s_addc_u32 s39, s39, 0
	s_cmp_gt_u32 s66, 13
	s_cbranch_scc0 .LBB0_339
	s_and_b64 vcc, exec, s[10:11]
	s_cbranch_vccz .LBB0_342
	s_barrier

; #define PG8_STAGE(bufoff, gbase, voff) do { _Pragma("unroll") for (int _i = 0; _i < 2; ++_i) \
;         __builtin_amdgcn_global_load_lds((const unsigned*)((const char*)(gbase) + (voff)[_i]), (PG8_LAS unsigned*)(lds + (bufoff) + ldsw + _i * 8192), 16, 0, 0); } while (0)
; #define PG8_LDA(dst, b, h) do { _Pragma("unroll") for (int m = 0; m < 4; ++m) _Pragma("unroll") for (int k = 0; k < 2; ++k) dst[m][k] = *(const PG8_LAS bf16x8*)(lds + PG8_SA(b, h) + aoff + m * 2048 + k * 1024); } while (0)
; #define PG8_LDB(dst, b, h) do { _Pragma("unroll") for (int n = 0; n < 2; ++n) _Pragma("unroll") for (int k = 0; k < 2; ++k) dst[n][k] = *(const PG8_LAS bf16x8*)(lds + PG8_SB(b, h) + boff + n * 2048 + k * 1024); } while (0)
; #define PG8_MMA(ai, bj, At, Bt) do { __builtin_amdgcn_s_setprio(1); _Pragma("unroll") for (int m = 0; m < 4; ++m) _Pragma("unroll") for (int n = 0; n < 2; ++n) _Pragma("unroll") for (int k = 0; k < 2; ++k) \
;         acc[ai][bj][m][n] = __builtin_amdgcn_mfma_f32_16x16x32_bf16(Bt[n][k], At[m][k], acc[ai][bj][m][n], 0, 0, 0); __builtin_amdgcn_s_setprio(0); } while (0)
; #define PG8_WAIT_V(n) asm volatile("s_waitcnt vmcnt(" #n ")" ::: "memory")
; #define PG8_BAR __builtin_amdgcn_s_barrier()
; template <class Epi, class Sched, bool ALIGN_EPI = false, bool SP2 = false>
; __device__ __forceinline__ void gemm_phase(PG8_LAS unsigned char* lds, const Gemm g, const Sched& S, const Epi& E, const int tid) {
;     ...
;         for (int t = 0; t < nt; t += 2) {
;             const bool last = (t == nt - 2);
;             const char* a1 = cA + (size_t)(t + 1) * kstep;
;             const char* a2 = last ? nA : cA + (size_t)(t + 2) * kstep; const char* b2 = last ? nB : cB + (size_t)(t + 2) * kstep;
;             const char* a3 = a2 + kstep; const char* b3 = b2 + kstep;
;             if (last && has_next) S.a_ready(nxt);
;             if constexpr (SP2) {
;             PG8_LDB(B0, 0, 0); PG8_LDB(B1, 0, 1); PG8_SCHED; PG8_LDA(At, 0, 0); PG8_STAGE(PG8_SA(1, 1), a1 + hstep, voffA);
;             PG8_WAIT_V(8); PG8_WAIT_L(0); PG8_BAR; PG8_MMA(0, 0, At, B0); PG8_MMA(0, 1, At, B1); PG8_BAR; PG8_SCHED;
;             PG8_LDA(At, 0, 1); PG8_STAGE(PG8_SB(0, 0), b2, voffB); PG8_STAGE(PG8_SB(0, 1), b2 + hstep, voffB); PG8_STAGE(PG8_SA(0, 0), a2, voffA);
;             PG8_WAIT_V(8); PG8_WAIT_L(0); PG8_BAR; PG8_MMA(1, 0, At, B0); PG8_MMA(1, 1, At, B1); PG8_BAR; PG8_SCHED;
.LBB0_422:
	s_add_u32 s45, s8, 0x100
	s_addc_u32 s47, s9, 0
	s_mov_b32 s77, -2
	s_add_u32 s8, s6, 0x100
	s_addc_u32 s9, s7, 0
	s_cmp_eq_u32 s77, 40
	s_cselect_b32 s43, s1, s9
	s_cselect_b32 s42, s0, s8
	s_cselect_b32 s11, s41, s47
	s_cselect_b32 s10, s40, s45
	v_lshl_add_u64 v[220:221], s[6:7], 0, v[176:177]
	s_add_i32 m0, s56, 0xc000
	global_load_lds_dwordx4 v[220:221], off
	v_lshl_add_u64 v[220:221], s[6:7], 0, v[174:175]
	s_add_i32 m0, s56, 0xe000
	s_nop 0
	global_load_lds_dwordx4 v[220:221], off
	s_waitcnt vmcnt(8)
	s_waitcnt lgkmcnt(0)
	s_barrier
	s_setprio 1
	v_mfma_f32_16x16x32_bf16 v[126:129], v[130:133], v[182:185], 0
	v_mfma_f32_16x16x32_bf16 v[122:125], v[138:141], v[182:185], 0
	v_mfma_f32_16x16x32_bf16 v[110:113], v[130:133], v[192:195], 0
	v_mfma_f32_16x16x32_bf16 v[106:109], v[138:141], v[192:195], 0
	v_mfma_f32_16x16x32_bf16 v[94:97], v[130:133], v[200:203], 0
	v_mfma_f32_16x16x32_bf16 v[90:93], v[138:141], v[200:203], 0
	v_mfma_f32_16x16x32_bf16 v[78:81], v[130:133], v[212:215], 0
	v_mfma_f32_16x16x32_bf16 v[74:77], v[138:141], v[212:215], 0
	v_mfma_f32_16x16x32_bf16 v[126:129], v[134:137], v[186:189], v[126:129]
	v_mfma_f32_16x16x32_bf16 v[122:125], v[142:145], v[186:189], v[122:125]
	v_mfma_f32_16x16x32_bf16 v[110:113], v[134:137], v[196:199], v[110:113]
	v_mfma_f32_16x16x32_bf16 v[106:109], v[142:145], v[196:199], v[106:109]
	v_mfma_f32_16x16x32_bf16 v[94:97], v[134:137], v[208:211], v[94:97]
	v_mfma_f32_16x16x32_bf16 v[90:93], v[142:145], v[208:211], v[90:93]
	v_mfma_f32_16x16x32_bf16 v[78:81], v[134:137], v[216:219], v[78:81]
	v_mfma_f32_16x16x32_bf16 v[74:77], v[142:145], v[216:219], v[74:77]
	s_setprio 0
	s_setprio 1
	v_mfma_f32_16x16x32_bf16 v[118:121], v[146:149], v[182:185], 0
	v_mfma_f32_16x16x32_bf16 v[114:117], v[154:157], v[182:185], 0
	v_mfma_f32_16x16x32_bf16 v[102:105], v[146:149], v[192:195], 0
	v_mfma_f32_16x16x32_bf16 v[98:101], v[154:157], v[192:195], 0
	v_mfma_f32_16x16x32_bf16 v[86:89], v[146:149], v[200:203], 0
	v_mfma_f32_16x16x32_bf16 v[82:85], v[154:157], v[200:203], 0
	v_mfma_f32_16x16x32_bf16 v[70:73], v[146:149], v[212:215], 0
	v_mfma_f32_16x16x32_bf16 v[66:69], v[154:157], v[212:215], 0
	v_mfma_f32_16x16x32_bf16 v[118:121], v[150:153], v[186:189], v[118:121]
	v_mfma_f32_16x16x32_bf16 v[114:117], v[158:161], v[186:189], v[114:117]
	v_mfma_f32_16x16x32_bf16 v[102:105], v[150:153], v[196:199], v[102:105]
	v_mfma_f32_16x16x32_bf16 v[98:101], v[158:161], v[196:199], v[98:101]
	v_mfma_f32_16x16x32_bf16 v[86:89], v[150:153], v[208:211], v[86:89]
	v_mfma_f32_16x16x32_bf16 v[82:85], v[158:161], v[208:211], v[82:85]
	v_mfma_f32_16x16x32_bf16 v[70:73], v[150:153], v[216:219], v[70:73]
	v_mfma_f32_16x16x32_bf16 v[66:69], v[158:161], v[216:219], v[66:69]
	s_setprio 0
	s_barrier
	s_add_i32 s6, s66, s55
	v_lshl_add_u64 v[220:221], s[10:11], 0, v[164:165]
	s_mov_b32 m0, s6
	ds_read_b128 v[182:185], v207 offset:16384
	ds_read_b128 v[186:189], v207 offset:17408
	ds_read_b128 v[192:195], v207 offset:18432
	ds_read_b128 v[196:199], v207 offset:19456
	ds_read_b128 v[200:203], v207 offset:20480
	ds_read_b128 v[208:211], v207 offset:21504
	ds_read_b128 v[212:215], v207 offset:22528
	ds_read_b128 v[216:219], v207 offset:23552
	global_load_lds_dwordx4 v[220:221], off
	s_add_i32 m0, s6, 0x2000
	s_add_u32 s6, s10, 0xb0000
	v_lshl_add_u64 v[222:223], s[10:11], 0, v[168:169]
	s_addc_u32 s7, s11, 0
	s_add_i32 s15, s67, s55
	global_load_lds_dwordx4 v[222:223], off
	v_lshl_add_u64 v[224:225], s[6:7], 0, v[164:165]
	s_mov_b32 m0, s15
	v_lshl_add_u64 v[226:227], s[42:43], 0, v[166:167]
	global_load_lds_dwordx4 v[224:225], off
	v_lshl_add_u64 v[224:225], s[6:7], 0, v[168:169]
	s_add_i32 m0, s15, 0x2000
	s_nop 0
	global_load_lds_dwordx4 v[224:225], off
	v_lshl_add_u64 v[224:225], s[42:43], 0, v[162:163]
	s_mov_b32 m0, s56
	s_nop 0
	global_load_lds_dwordx4 v[224:225], off
	s_mov_b32 m0, s57
	s_nop 0
	global_load_lds_dwordx4 v[226:227], off
	s_waitcnt vmcnt(8)
	s_waitcnt lgkmcnt(0)
	s_barrier
	s_setprio 1
	v_mfma_f32_16x16x32_bf16 v[62:65], v[130:133], v[182:185], 0
	v_mfma_f32_16x16x32_bf16 v[58:61], v[138:141], v[182:185], 0
	v_mfma_f32_16x16x32_bf16 v[46:49], v[130:133], v[192:195], 0
	v_mfma_f32_16x16x32_bf16 v[42:45], v[138:141], v[192:195], 0
	v_mfma_f32_16x16x32_bf16 v[30:33], v[130:133], v[200:203], 0
	v_mfma_f32_16x16x32_bf16 v[26:29], v[138:141], v[200:203], 0
	v_mfma_f32_16x16x32_bf16 v[14:17], v[130:133], v[212:215], 0
	v_mfma_f32_16x16x32_bf16 v[10:13], v[138:141], v[212:215], 0
	v_mfma_f32_16x16x32_bf16 v[62:65], v[134:137], v[186:189], v[62:65]
	v_mfma_f32_16x16x32_bf16 v[58:61], v[142:145], v[186:189], v[58:61]
	v_mfma_f32_16x16x32_bf16 v[46:49], v[134:137], v[196:199], v[46:49]
	v_mfma_f32_16x16x32_bf16 v[42:45], v[142:145], v[196:199], v[42:45]
	v_mfma_f32_16x16x32_bf16 v[30:33], v[134:137], v[208:211], v[30:33]
	v_mfma_f32_16x16x32_bf16 v[26:29], v[142:145], v[208:211], v[26:29]
	v_mfma_f32_16x16x32_bf16 v[14:17], v[134:137], v[216:219], v[14:17]
	v_mfma_f32_16x16x32_bf16 v[10:13], v[142:145], v[216:219], v[10:13]
	s_setprio 0
	s_setprio 1
	v_mfma_f32_16x16x32_bf16 v[54:57], v[146:149], v[182:185], 0
	v_mfma_f32_16x16x32_bf16 v[50:53], v[154:157], v[182:185], 0
	v_mfma_f32_16x16x32_bf16 v[38:41], v[146:149], v[192:195], 0
	v_mfma_f32_16x16x32_bf16 v[34:37], v[154:157], v[192:195], 0
	v_mfma_f32_16x16x32_bf16 v[22:25], v[146:149], v[200:203], 0
	v_mfma_f32_16x16x32_bf16 v[18:21], v[154:157], v[200:203], 0
	v_mfma_f32_16x16x32_bf16 v[6:9], v[146:149], v[212:215], 0
	v_mfma_f32_16x16x32_bf16 v[2:5], v[154:157], v[212:215], 0
	v_mfma_f32_16x16x32_bf16 v[54:57], v[150:153], v[186:189], v[54:57]
	v_mfma_f32_16x16x32_bf16 v[50:53], v[158:161], v[186:189], v[50:53]
	v_mfma_f32_16x16x32_bf16 v[38:41], v[150:153], v[196:199], v[38:41]
	v_mfma_f32_16x16x32_bf16 v[34:37], v[158:161], v[196:199], v[34:37]
	v_mfma_f32_16x16x32_bf16 v[22:25], v[150:153], v[208:211], v[22:25]
	v_mfma_f32_16x16x32_bf16 v[18:21], v[158:161], v[208:211], v[18:21]
	v_mfma_f32_16x16x32_bf16 v[6:9], v[150:153], v[216:219], v[6:9]
	v_mfma_f32_16x16x32_bf16 v[2:5], v[158:161], v[216:219], v[2:5]
	s_setprio 0
	s_barrier
; #define PG8_STAGE(bufoff, gbase, voff) do { _Pragma("unroll") for (int _i = 0; _i < 2; ++_i) \
;         __builtin_amdgcn_global_load_lds((const unsigned*)((const char*)(gbase) + (voff)[_i]), (PG8_LAS unsigned*)(lds + (bufoff) + ldsw + _i * 8192), 16, 0, 0); } while (0)
; #define PG8_LDA(dst, b, h) do { _Pragma("unroll") for (int m = 0; m < 4; ++m) _Pragma("unroll") for (int k = 0; k < 2; ++k) dst[m][k] = *(const PG8_LAS bf16x8*)(lds + PG8_SA(b, h) + aoff + m * 2048 + k * 1024); } while (0)
; #define PG8_LDB(dst, b, h) do { _Pragma("unroll") for (int n = 0; n < 2; ++n) _Pragma("unroll") for (int k = 0; k < 2; ++k) dst[n][k] = *(const PG8_LAS bf16x8*)(lds + PG8_SB(b, h) + boff + n * 2048 + k * 1024); } while (0)
; #define PG8_MMA(ai, bj, At, Bt) do { __builtin_amdgcn_s_setprio(1); _Pragma("unroll") for (int m = 0; m < 4; ++m) _Pragma("unroll") for (int n = 0; n < 2; ++n) _Pragma("unroll") for (int k = 0; k < 2; ++k) \
;         acc[ai][bj][m][n] = __builtin_amdgcn_mfma_f32_16x16x32_bf16(Bt[n][k], At[m][k], acc[ai][bj][m][n], 0, 0, 0); __builtin_amdgcn_s_setprio(0); } while (0)
; #define PG8_WAIT_V(n) asm volatile("s_waitcnt vmcnt(" #n ")" ::: "memory")
; #define PG8_WAIT_L(n) asm volatile("s_waitcnt lgkmcnt(" #n ")" ::: "memory")
; #define PG8_BAR __builtin_amdgcn_s_barrier()
; #define PG8_SCHED __builtin_amdgcn_sched_barrier(0)
; template <class Epi, class Sched, bool ALIGN_EPI = false, bool SP2 = false>
; __device__ __forceinline__ void gemm_phase(PG8_LAS unsigned char* lds, const Gemm g, const Sched& S, const Epi& E, const int tid) {
;     ...
;             PG8_LDB(B0, 1, 0); PG8_LDB(B1, 1, 1); PG8_SCHED; PG8_LDA(At, 1, 0); PG8_STAGE(PG8_SA(0, 1), a2 + hstep, voffA);
;             PG8_WAIT_V(8); PG8_WAIT_L(0); PG8_BAR; PG8_MMA(0, 0, At, B0); PG8_MMA(0, 1, At, B1); PG8_BAR; PG8_SCHED;
;             PG8_LDA(At, 1, 1); PG8_STAGE(PG8_SB(1, 0), b3, voffB); PG8_STAGE(PG8_SB(1, 1), b3 + hstep, voffB); PG8_STAGE(PG8_SA(1, 0), a3, voffA);
;             PG8_WAIT_V(8); PG8_WAIT_L(0); PG8_BAR; PG8_MMA(1, 0, At, B0); PG8_MMA(1, 1, At, B1); PG8_BAR; PG8_SCHED;
	s_add_i32 s15, 0, 0x18000
	s_add_i32 s18, 0, 0x1c000
	v_add_u32_e32 v142, s15, v204
	v_add_u32_e32 v158, s18, v204
	ds_read_b128 v[130:133], v142
	ds_read_b128 v[134:137], v142 offset:1024
	ds_read_b128 v[138:141], v142 offset:2048
	ds_read_b128 v[142:145], v142 offset:3072
	ds_read_b128 v[146:149], v158
	ds_read_b128 v[150:153], v158 offset:1024
	ds_read_b128 v[154:157], v158 offset:2048
	ds_read_b128 v[158:161], v158 offset:3072
	s_add_u32 s6, s42, 0xb0000
	s_addc_u32 s7, s43, 0
	s_mov_b32 m0, s58
	v_lshl_add_u64 v[228:229], s[6:7], 0, v[162:163]
	ds_read_b128 v[182:185], v207 offset:32768
	ds_read_b128 v[186:189], v207 offset:33792
	ds_read_b128 v[192:195], v207 offset:34816
	ds_read_b128 v[196:199], v207 offset:35840
	ds_read_b128 v[200:203], v207 offset:36864
	ds_read_b128 v[208:211], v207 offset:37888
	ds_read_b128 v[212:215], v207 offset:38912
	ds_read_b128 v[216:219], v207 offset:39936
	global_load_lds_dwordx4 v[228:229], off
	v_lshl_add_u64 v[228:229], s[6:7], 0, v[166:167]
	s_mov_b32 m0, s59
	s_nop 0
	global_load_lds_dwordx4 v[228:229], off
	s_waitcnt vmcnt(8)
	s_waitcnt lgkmcnt(0)
	s_barrier
	s_setprio 1
	v_mfma_f32_16x16x32_bf16 v[126:129], v[130:133], v[182:185], v[126:129]
	v_mfma_f32_16x16x32_bf16 v[122:125], v[138:141], v[182:185], v[122:125]
	v_mfma_f32_16x16x32_bf16 v[110:113], v[130:133], v[192:195], v[110:113]
	v_mfma_f32_16x16x32_bf16 v[106:109], v[138:141], v[192:195], v[106:109]
	v_mfma_f32_16x16x32_bf16 v[94:97], v[130:133], v[200:203], v[94:97]
	v_mfma_f32_16x16x32_bf16 v[90:93], v[138:141], v[200:203], v[90:93]
	v_mfma_f32_16x16x32_bf16 v[78:81], v[130:133], v[212:215], v[78:81]
	v_mfma_f32_16x16x32_bf16 v[74:77], v[138:141], v[212:215], v[74:77]
	v_mfma_f32_16x16x32_bf16 v[126:129], v[134:137], v[186:189], v[126:129]
	v_mfma_f32_16x16x32_bf16 v[122:125], v[142:145], v[186:189], v[122:125]
	v_mfma_f32_16x16x32_bf16 v[110:113], v[134:137], v[196:199], v[110:113]
	v_mfma_f32_16x16x32_bf16 v[106:109], v[142:145], v[196:199], v[106:109]
	v_mfma_f32_16x16x32_bf16 v[94:97], v[134:137], v[208:211], v[94:97]
	v_mfma_f32_16x16x32_bf16 v[90:93], v[142:145], v[208:211], v[90:93]
	v_mfma_f32_16x16x32_bf16 v[78:81], v[134:137], v[216:219], v[78:81]
	v_mfma_f32_16x16x32_bf16 v[74:77], v[142:145], v[216:219], v[74:77]
	s_setprio 0
	s_setprio 1
	v_mfma_f32_16x16x32_bf16 v[118:121], v[146:149], v[182:185], v[118:121]
	v_mfma_f32_16x16x32_bf16 v[114:117], v[154:157], v[182:185], v[114:117]
	v_mfma_f32_16x16x32_bf16 v[102:105], v[146:149], v[192:195], v[102:105]
	v_mfma_f32_16x16x32_bf16 v[98:101], v[154:157], v[192:195], v[98:101]
	v_mfma_f32_16x16x32_bf16 v[86:89], v[146:149], v[200:203], v[86:89]
	v_mfma_f32_16x16x32_bf16 v[82:85], v[154:157], v[200:203], v[82:85]
	v_mfma_f32_16x16x32_bf16 v[70:73], v[146:149], v[212:215], v[70:73]
	v_mfma_f32_16x16x32_bf16 v[66:69], v[154:157], v[212:215], v[66:69]
	v_mfma_f32_16x16x32_bf16 v[118:121], v[150:153], v[186:189], v[118:121]
	v_mfma_f32_16x16x32_bf16 v[114:117], v[158:161], v[186:189], v[114:117]
	v_mfma_f32_16x16x32_bf16 v[102:105], v[150:153], v[196:199], v[102:105]
	v_mfma_f32_16x16x32_bf16 v[98:101], v[158:161], v[196:199], v[98:101]
	v_mfma_f32_16x16x32_bf16 v[86:89], v[150:153], v[208:211], v[86:89]
	v_mfma_f32_16x16x32_bf16 v[82:85], v[158:161], v[208:211], v[82:85]
	v_mfma_f32_16x16x32_bf16 v[70:73], v[150:153], v[216:219], v[70:73]
	v_mfma_f32_16x16x32_bf16 v[66:69], v[158:161], v[216:219], v[66:69]
	s_setprio 0
	s_barrier
	s_add_i32 s6, s15, s55
	v_lshl_add_u64 v[220:221], v[220:221], 0, s[36:37]
	s_mov_b32 m0, s6
	ds_read_b128 v[182:185], v207 offset:49152
	ds_read_b128 v[186:189], v207 offset:50176
	ds_read_b128 v[192:195], v207 offset:51200
	ds_read_b128 v[196:199], v207 offset:52224
	ds_read_b128 v[200:203], v207 offset:53248
	ds_read_b128 v[208:211], v207 offset:54272
	ds_read_b128 v[212:215], v207 offset:55296
	ds_read_b128 v[216:219], v207 offset:56320
	global_load_lds_dwordx4 v[220:221], off
	s_add_i32 m0, s6, 0x2000
	s_add_u32 s6, s10, 0xb0080
	v_lshl_add_u64 v[220:221], v[222:223], 0, s[36:37]
	s_addc_u32 s7, s11, 0
	s_add_i32 s10, s18, s55
	global_load_lds_dwordx4 v[220:221], off
	v_lshl_add_u64 v[220:221], s[6:7], 0, v[164:165]
	s_mov_b32 m0, s10
	s_nop 0
	global_load_lds_dwordx4 v[220:221], off
	v_lshl_add_u64 v[220:221], s[6:7], 0, v[168:169]
	s_add_i32 m0, s10, 0x2000
	s_nop 0
	global_load_lds_dwordx4 v[220:221], off
	v_lshl_add_u64 v[220:221], v[224:225], 0, s[36:37]
	s_mov_b32 m0, s61
	s_nop 0
	global_load_lds_dwordx4 v[220:221], off
	v_lshl_add_u64 v[220:221], v[226:227], 0, s[36:37]
	s_mov_b32 m0, s62
	s_nop 0
	global_load_lds_dwordx4 v[220:221], off
	s_waitcnt vmcnt(8)
	s_waitcnt lgkmcnt(0)
	s_barrier
	s_setprio 1
	v_mfma_f32_16x16x32_bf16 v[62:65], v[130:133], v[182:185], v[62:65]
	v_mfma_f32_16x16x32_bf16 v[58:61], v[138:141], v[182:185], v[58:61]
	v_mfma_f32_16x16x32_bf16 v[46:49], v[130:133], v[192:195], v[46:49]
	v_mfma_f32_16x16x32_bf16 v[42:45], v[138:141], v[192:195], v[42:45]
	v_mfma_f32_16x16x32_bf16 v[30:33], v[130:133], v[200:203], v[30:33]
	v_mfma_f32_16x16x32_bf16 v[26:29], v[138:141], v[200:203], v[26:29]
	v_mfma_f32_16x16x32_bf16 v[14:17], v[130:133], v[212:215], v[14:17]
	v_mfma_f32_16x16x32_bf16 v[10:13], v[138:141], v[212:215], v[10:13]
	v_mfma_f32_16x16x32_bf16 v[62:65], v[134:137], v[186:189], v[62:65]
	v_mfma_f32_16x16x32_bf16 v[58:61], v[142:145], v[186:189], v[58:61]
	v_mfma_f32_16x16x32_bf16 v[46:49], v[134:137], v[196:199], v[46:49]
	v_mfma_f32_16x16x32_bf16 v[42:45], v[142:145], v[196:199], v[42:45]
	v_mfma_f32_16x16x32_bf16 v[30:33], v[134:137], v[208:211], v[30:33]
	v_mfma_f32_16x16x32_bf16 v[26:29], v[142:145], v[208:211], v[26:29]
	v_mfma_f32_16x16x32_bf16 v[14:17], v[134:137], v[216:219], v[14:17]
	v_mfma_f32_16x16x32_bf16 v[10:13], v[142:145], v[216:219], v[10:13]
	s_setprio 0
	s_setprio 1
	v_mfma_f32_16x16x32_bf16 v[54:57], v[146:149], v[182:185], v[54:57]
	v_mfma_f32_16x16x32_bf16 v[50:53], v[154:157], v[182:185], v[50:53]
	v_mfma_f32_16x16x32_bf16 v[38:41], v[146:149], v[192:195], v[38:41]
	v_mfma_f32_16x16x32_bf16 v[34:37], v[154:157], v[192:195], v[34:37]
	v_mfma_f32_16x16x32_bf16 v[22:25], v[146:149], v[200:203], v[22:25]
	v_mfma_f32_16x16x32_bf16 v[18:21], v[154:157], v[200:203], v[18:21]
	v_mfma_f32_16x16x32_bf16 v[6:9], v[146:149], v[212:215], v[6:9]
	v_mfma_f32_16x16x32_bf16 v[2:5], v[154:157], v[212:215], v[2:5]
	v_mfma_f32_16x16x32_bf16 v[54:57], v[150:153], v[186:189], v[54:57]
	v_mfma_f32_16x16x32_bf16 v[50:53], v[158:161], v[186:189], v[50:53]
	v_mfma_f32_16x16x32_bf16 v[38:41], v[150:153], v[196:199], v[38:41]
	v_mfma_f32_16x16x32_bf16 v[34:37], v[158:161], v[196:199], v[34:37]
	v_mfma_f32_16x16x32_bf16 v[22:25], v[150:153], v[208:211], v[22:25]
	v_mfma_f32_16x16x32_bf16 v[18:21], v[158:161], v[208:211], v[18:21]
	v_mfma_f32_16x16x32_bf16 v[6:9], v[150:153], v[216:219], v[6:9]
	v_mfma_f32_16x16x32_bf16 v[2:5], v[158:161], v[216:219], v[2:5]
	s_setprio 0
	s_barrier
	s_add_i32 s77, s77, 2
	s_add_u32 s45, s45, 0x100
	s_addc_u32 s47, s47, 0
	s_mov_b64 s[6:7], s[8:9]
; #define PG8_STAGE(bufoff, gbase, voff) do { _Pragma("unroll") for (int _i = 0; _i < 2; ++_i) \
;         __builtin_amdgcn_global_load_lds((const unsigned*)((const char*)(gbase) + (voff)[_i]), (PG8_LAS unsigned*)(lds + (bufoff) + ldsw + _i * 8192), 16, 0, 0); } while (0)
; #define PG8_LDA(dst, b, h) do { _Pragma("unroll") for (int m = 0; m < 4; ++m) _Pragma("unroll") for (int k = 0; k < 2; ++k) dst[m][k] = *(const PG8_LAS bf16x8*)(lds + PG8_SA(b, h) + aoff + m * 2048 + k * 1024); } while (0)
; #define PG8_LDB(dst, b, h) do { _Pragma("unroll") for (int n = 0; n < 2; ++n) _Pragma("unroll") for (int k = 0; k < 2; ++k) dst[n][k] = *(const PG8_LAS bf16x8*)(lds + PG8_SB(b, h) + boff + n * 2048 + k * 1024); } while (0)
; #define PG8_MMA(ai, bj, At, Bt) do { __builtin_amdgcn_s_setprio(1); _Pragma("unroll") for (int m = 0; m < 4; ++m) _Pragma("unroll") for (int n = 0; n < 2; ++n) _Pragma("unroll") for (int k = 0; k < 2; ++k) \
;         acc[ai][bj][m][n] = __builtin_amdgcn_mfma_f32_16x16x32_bf16(Bt[n][k], At[m][k], acc[ai][bj][m][n], 0, 0, 0); __builtin_amdgcn_s_setprio(0); } while (0)
; #define PG8_WAIT_V(n) asm volatile("s_waitcnt vmcnt(" #n ")" ::: "memory")
; #define PG8_BAR __builtin_amdgcn_s_barrier()
; template <class Epi, class Sched, bool ALIGN_EPI = false, bool SP2 = false>
; __device__ __forceinline__ void gemm_phase(PG8_LAS unsigned char* lds, const Gemm g, const Sched& S, const Epi& E, const int tid) {
;     ...
;         for (int t = 0; t < nt; t += 2) {
;             const bool last = (t == nt - 2);
;             const char* a1 = cA + (size_t)(t + 1) * kstep;
;             const char* a2 = last ? nA : cA + (size_t)(t + 2) * kstep; const char* b2 = last ? nB : cB + (size_t)(t + 2) * kstep;
;             const char* a3 = a2 + kstep; const char* b3 = b2 + kstep;
;             if (last && has_next) S.a_ready(nxt);
;             if constexpr (SP2) {
;             PG8_LDB(B0, 0, 0); PG8_LDB(B1, 0, 1); PG8_SCHED; PG8_LDA(At, 0, 0); PG8_STAGE(PG8_SA(1, 1), a1 + hstep, voffA);
;             PG8_WAIT_V(8); PG8_WAIT_L(0); PG8_BAR; PG8_MMA(0, 0, At, B0); PG8_MMA(0, 1, At, B1); PG8_BAR; PG8_SCHED;
;             PG8_LDA(At, 0, 1); PG8_STAGE(PG8_SB(0, 0), b2, voffB); PG8_STAGE(PG8_SB(0, 1), b2 + hstep, voffB); PG8_STAGE(PG8_SA(0, 0), a2, voffA);
;             PG8_WAIT_V(8); PG8_WAIT_L(0); PG8_BAR; PG8_MMA(1, 0, At, B0); PG8_MMA(1, 1, At, B1); PG8_BAR; PG8_SCHED;
.LBB0_423:
	ds_read_b128 v[130:133], v205
	ds_read_b128 v[134:137], v205 offset:1024
	ds_read_b128 v[138:141], v205 offset:2048
	ds_read_b128 v[142:145], v205 offset:3072
	ds_read_b128 v[146:149], v206
	ds_read_b128 v[150:153], v206 offset:1024
	ds_read_b128 v[154:157], v206 offset:2048
	ds_read_b128 v[158:161], v206 offset:3072
	s_add_u32 s8, s6, 0x100
	s_addc_u32 s9, s7, 0
	s_cmp_eq_u32 s77, 40
	s_cselect_b32 s43, s1, s9
	s_cselect_b32 s42, s0, s8
	s_cselect_b32 s11, s41, s47
	s_cselect_b32 s10, s40, s45
	v_lshl_add_u64 v[220:221], s[6:7], 0, v[176:177]
	s_add_i32 m0, s56, 0xc000
	ds_read_b128 v[182:185], v207
	ds_read_b128 v[186:189], v207 offset:1024
	ds_read_b128 v[192:195], v207 offset:2048
	ds_read_b128 v[196:199], v207 offset:3072
	ds_read_b128 v[200:203], v207 offset:4096
	ds_read_b128 v[208:211], v207 offset:5120
	ds_read_b128 v[212:215], v207 offset:6144
	ds_read_b128 v[216:219], v207 offset:7168
	global_load_lds_dwordx4 v[220:221], off
	v_lshl_add_u64 v[220:221], s[6:7], 0, v[174:175]
	s_add_i32 m0, s56, 0xe000
	s_nop 0
	global_load_lds_dwordx4 v[220:221], off
	s_waitcnt vmcnt(8)
	s_waitcnt lgkmcnt(0)
	s_barrier
	s_setprio 1
	v_mfma_f32_16x16x32_bf16 v[126:129], v[130:133], v[182:185], v[126:129]
	v_mfma_f32_16x16x32_bf16 v[122:125], v[138:141], v[182:185], v[122:125]
	v_mfma_f32_16x16x32_bf16 v[110:113], v[130:133], v[192:195], v[110:113]
	v_mfma_f32_16x16x32_bf16 v[106:109], v[138:141], v[192:195], v[106:109]
	v_mfma_f32_16x16x32_bf16 v[94:97], v[130:133], v[200:203], v[94:97]
	v_mfma_f32_16x16x32_bf16 v[90:93], v[138:141], v[200:203], v[90:93]
	v_mfma_f32_16x16x32_bf16 v[78:81], v[130:133], v[212:215], v[78:81]
	v_mfma_f32_16x16x32_bf16 v[74:77], v[138:141], v[212:215], v[74:77]
	v_mfma_f32_16x16x32_bf16 v[126:129], v[134:137], v[186:189], v[126:129]
	v_mfma_f32_16x16x32_bf16 v[122:125], v[142:145], v[186:189], v[122:125]
	v_mfma_f32_16x16x32_bf16 v[110:113], v[134:137], v[196:199], v[110:113]
	v_mfma_f32_16x16x32_bf16 v[106:109], v[142:145], v[196:199], v[106:109]
	v_mfma_f32_16x16x32_bf16 v[94:97], v[134:137], v[208:211], v[94:97]
	v_mfma_f32_16x16x32_bf16 v[90:93], v[142:145], v[208:211], v[90:93]
	v_mfma_f32_16x16x32_bf16 v[78:81], v[134:137], v[216:219], v[78:81]
	v_mfma_f32_16x16x32_bf16 v[74:77], v[142:145], v[216:219], v[74:77]
	s_setprio 0
	s_setprio 1
	v_mfma_f32_16x16x32_bf16 v[118:121], v[146:149], v[182:185], v[118:121]
	v_mfma_f32_16x16x32_bf16 v[114:117], v[154:157], v[182:185], v[114:117]
	v_mfma_f32_16x16x32_bf16 v[102:105], v[146:149], v[192:195], v[102:105]
	v_mfma_f32_16x16x32_bf16 v[98:101], v[154:157], v[192:195], v[98:101]
	v_mfma_f32_16x16x32_bf16 v[86:89], v[146:149], v[200:203], v[86:89]
	v_mfma_f32_16x16x32_bf16 v[82:85], v[154:157], v[200:203], v[82:85]
	v_mfma_f32_16x16x32_bf16 v[70:73], v[146:149], v[212:215], v[70:73]
	v_mfma_f32_16x16x32_bf16 v[66:69], v[154:157], v[212:215], v[66:69]
	v_mfma_f32_16x16x32_bf16 v[118:121], v[150:153], v[186:189], v[118:121]
	v_mfma_f32_16x16x32_bf16 v[114:117], v[158:161], v[186:189], v[114:117]
	v_mfma_f32_16x16x32_bf16 v[102:105], v[150:153], v[196:199], v[102:105]
	v_mfma_f32_16x16x32_bf16 v[98:101], v[158:161], v[196:199], v[98:101]
	v_mfma_f32_16x16x32_bf16 v[86:89], v[150:153], v[208:211], v[86:89]
	v_mfma_f32_16x16x32_bf16 v[82:85], v[158:161], v[208:211], v[82:85]
	v_mfma_f32_16x16x32_bf16 v[70:73], v[150:153], v[216:219], v[70:73]
	v_mfma_f32_16x16x32_bf16 v[66:69], v[158:161], v[216:219], v[66:69]
	s_setprio 0
	s_barrier
	s_add_i32 s6, s66, s55
	v_lshl_add_u64 v[220:221], s[10:11], 0, v[164:165]
	s_mov_b32 m0, s6
	ds_read_b128 v[182:185], v207 offset:16384
	ds_read_b128 v[186:189], v207 offset:17408
	ds_read_b128 v[192:195], v207 offset:18432
	ds_read_b128 v[196:199], v207 offset:19456
	ds_read_b128 v[200:203], v207 offset:20480
	ds_read_b128 v[208:211], v207 offset:21504
	ds_read_b128 v[212:215], v207 offset:22528
	ds_read_b128 v[216:219], v207 offset:23552
	global_load_lds_dwordx4 v[220:221], off
	s_add_i32 m0, s6, 0x2000
	s_add_u32 s6, s10, 0xb0000
	v_lshl_add_u64 v[222:223], s[10:11], 0, v[168:169]
	s_addc_u32 s7, s11, 0
	s_add_i32 s15, s67, s55
	global_load_lds_dwordx4 v[222:223], off
	v_lshl_add_u64 v[224:225], s[6:7], 0, v[164:165]
	s_mov_b32 m0, s15
	v_lshl_add_u64 v[226:227], s[42:43], 0, v[166:167]
	global_load_lds_dwordx4 v[224:225], off
	v_lshl_add_u64 v[224:225], s[6:7], 0, v[168:169]
	s_add_i32 m0, s15, 0x2000
	s_nop 0
	global_load_lds_dwordx4 v[224:225], off
	v_lshl_add_u64 v[224:225], s[42:43], 0, v[162:163]
	s_mov_b32 m0, s56
	s_nop 0
	global_load_lds_dwordx4 v[224:225], off
	s_mov_b32 m0, s57
	s_nop 0
	global_load_lds_dwordx4 v[226:227], off
	s_waitcnt vmcnt(8)
	s_waitcnt lgkmcnt(0)
	s_barrier
; #define PG8_STAGE(bufoff, gbase, voff) do { _Pragma("unroll") for (int _i = 0; _i < 2; ++_i) \
;         __builtin_amdgcn_global_load_lds((const unsigned*)((const char*)(gbase) + (voff)[_i]), (PG8_LAS unsigned*)(lds + (bufoff) + ldsw + _i * 8192), 16, 0, 0); } while (0)
; #define PG8_LDA(dst, b, h) do { _Pragma("unroll") for (int m = 0; m < 4; ++m) _Pragma("unroll") for (int k = 0; k < 2; ++k) dst[m][k] = *(const PG8_LAS bf16x8*)(lds + PG8_SA(b, h) + aoff + m * 2048 + k * 1024); } while (0)
; #define PG8_LDB(dst, b, h) do { _Pragma("unroll") for (int n = 0; n < 2; ++n) _Pragma("unroll") for (int k = 0; k < 2; ++k) dst[n][k] = *(const PG8_LAS bf16x8*)(lds + PG8_SB(b, h) + boff + n * 2048 + k * 1024); } while (0)
; #define PG8_MMA(ai, bj, At, Bt) do { __builtin_amdgcn_s_setprio(1); _Pragma("unroll") for (int m = 0; m < 4; ++m) _Pragma("unroll") for (int n = 0; n < 2; ++n) _Pragma("unroll") for (int k = 0; k < 2; ++k) \
;         acc[ai][bj][m][n] = __builtin_amdgcn_mfma_f32_16x16x32_bf16(Bt[n][k], At[m][k], acc[ai][bj][m][n], 0, 0, 0); __builtin_amdgcn_s_setprio(0); } while (0)
; #define PG8_WAIT_V(n) asm volatile("s_waitcnt vmcnt(" #n ")" ::: "memory")
; #define PG8_WAIT_L(n) asm volatile("s_waitcnt lgkmcnt(" #n ")" ::: "memory")
; #define PG8_BAR __builtin_amdgcn_s_barrier()
; #define PG8_SCHED __builtin_amdgcn_sched_barrier(0)
; template <class Epi, class Sched, bool ALIGN_EPI = false, bool SP2 = false>
; __device__ __forceinline__ void gemm_phase(PG8_LAS unsigned char* lds, const Gemm g, const Sched& S, const Epi& E, const int tid) {
;     ...
;             PG8_WAIT_V(8); PG8_WAIT_L(0); PG8_BAR; PG8_MMA(1, 0, At, B0); PG8_MMA(1, 1, At, B1); PG8_BAR; PG8_SCHED;
;             PG8_LDB(B0, 1, 0); PG8_LDB(B1, 1, 1); PG8_SCHED; PG8_LDA(At, 1, 0); PG8_STAGE(PG8_SA(0, 1), a2 + hstep, voffA);
;             PG8_WAIT_V(8); PG8_WAIT_L(0); PG8_BAR; PG8_MMA(0, 0, At, B0); PG8_MMA(0, 1, At, B1); PG8_BAR; PG8_SCHED;
	s_setprio 1
	v_mfma_f32_16x16x32_bf16 v[62:65], v[130:133], v[182:185], v[62:65]
	v_mfma_f32_16x16x32_bf16 v[58:61], v[138:141], v[182:185], v[58:61]
	v_mfma_f32_16x16x32_bf16 v[46:49], v[130:133], v[192:195], v[46:49]
	v_mfma_f32_16x16x32_bf16 v[42:45], v[138:141], v[192:195], v[42:45]
	v_mfma_f32_16x16x32_bf16 v[30:33], v[130:133], v[200:203], v[30:33]
	v_mfma_f32_16x16x32_bf16 v[26:29], v[138:141], v[200:203], v[26:29]
	v_mfma_f32_16x16x32_bf16 v[14:17], v[130:133], v[212:215], v[14:17]
	v_mfma_f32_16x16x32_bf16 v[10:13], v[138:141], v[212:215], v[10:13]
	v_mfma_f32_16x16x32_bf16 v[62:65], v[134:137], v[186:189], v[62:65]
	v_mfma_f32_16x16x32_bf16 v[58:61], v[142:145], v[186:189], v[58:61]
	v_mfma_f32_16x16x32_bf16 v[46:49], v[134:137], v[196:199], v[46:49]
	v_mfma_f32_16x16x32_bf16 v[42:45], v[142:145], v[196:199], v[42:45]
	v_mfma_f32_16x16x32_bf16 v[30:33], v[134:137], v[208:211], v[30:33]
	v_mfma_f32_16x16x32_bf16 v[26:29], v[142:145], v[208:211], v[26:29]
	v_mfma_f32_16x16x32_bf16 v[14:17], v[134:137], v[216:219], v[14:17]
	v_mfma_f32_16x16x32_bf16 v[10:13], v[142:145], v[216:219], v[10:13]
	s_setprio 0
	s_setprio 1
	v_mfma_f32_16x16x32_bf16 v[54:57], v[146:149], v[182:185], v[54:57]
	v_mfma_f32_16x16x32_bf16 v[50:53], v[154:157], v[182:185], v[50:53]
	v_mfma_f32_16x16x32_bf16 v[38:41], v[146:149], v[192:195], v[38:41]
	v_mfma_f32_16x16x32_bf16 v[34:37], v[154:157], v[192:195], v[34:37]
	v_mfma_f32_16x16x32_bf16 v[22:25], v[146:149], v[200:203], v[22:25]
	v_mfma_f32_16x16x32_bf16 v[18:21], v[154:157], v[200:203], v[18:21]
	v_mfma_f32_16x16x32_bf16 v[6:9], v[146:149], v[212:215], v[6:9]
	v_mfma_f32_16x16x32_bf16 v[2:5], v[154:157], v[212:215], v[2:5]
	v_mfma_f32_16x16x32_bf16 v[54:57], v[150:153], v[186:189], v[54:57]
	v_mfma_f32_16x16x32_bf16 v[50:53], v[158:161], v[186:189], v[50:53]
	v_mfma_f32_16x16x32_bf16 v[38:41], v[150:153], v[196:199], v[38:41]
	v_mfma_f32_16x16x32_bf16 v[34:37], v[158:161], v[196:199], v[34:37]
	v_mfma_f32_16x16x32_bf16 v[22:25], v[150:153], v[208:211], v[22:25]
	v_mfma_f32_16x16x32_bf16 v[18:21], v[158:161], v[208:211], v[18:21]
	v_mfma_f32_16x16x32_bf16 v[6:9], v[150:153], v[216:219], v[6:9]
	v_mfma_f32_16x16x32_bf16 v[2:5], v[158:161], v[216:219], v[2:5]
	s_setprio 0
	s_barrier
	s_add_i32 s15, 0, 0x18000
	s_add_i32 s18, 0, 0x1c000
	v_add_u32_e32 v142, s15, v204
	v_add_u32_e32 v158, s18, v204
	ds_read_b128 v[130:133], v142
	ds_read_b128 v[134:137], v142 offset:1024
	ds_read_b128 v[138:141], v142 offset:2048
	ds_read_b128 v[142:145], v142 offset:3072
	ds_read_b128 v[146:149], v158
	ds_read_b128 v[150:153], v158 offset:1024
	ds_read_b128 v[154:157], v158 offset:2048
	ds_read_b128 v[158:161], v158 offset:3072
	s_add_u32 s6, s42, 0xb0000
	s_addc_u32 s7, s43, 0
	s_mov_b32 m0, s58
	v_lshl_add_u64 v[228:229], s[6:7], 0, v[162:163]
	ds_read_b128 v[182:185], v207 offset:32768
	ds_read_b128 v[186:189], v207 offset:33792
	ds_read_b128 v[192:195], v207 offset:34816
	ds_read_b128 v[196:199], v207 offset:35840
	ds_read_b128 v[200:203], v207 offset:36864
	ds_read_b128 v[208:211], v207 offset:37888
	ds_read_b128 v[212:215], v207 offset:38912
	ds_read_b128 v[216:219], v207 offset:39936
	global_load_lds_dwordx4 v[228:229], off
	v_lshl_add_u64 v[228:229], s[6:7], 0, v[166:167]
	s_mov_b32 m0, s59
	s_nop 0
	global_load_lds_dwordx4 v[228:229], off
	s_waitcnt vmcnt(8)
	s_waitcnt lgkmcnt(0)
	s_barrier
	s_setprio 1
	v_mfma_f32_16x16x32_bf16 v[126:129], v[130:133], v[182:185], v[126:129]
	v_mfma_f32_16x16x32_bf16 v[122:125], v[138:141], v[182:185], v[122:125]
	v_mfma_f32_16x16x32_bf16 v[110:113], v[130:133], v[192:195], v[110:113]
	v_mfma_f32_16x16x32_bf16 v[106:109], v[138:141], v[192:195], v[106:109]
	v_mfma_f32_16x16x32_bf16 v[94:97], v[130:133], v[200:203], v[94:97]
	v_mfma_f32_16x16x32_bf16 v[90:93], v[138:141], v[200:203], v[90:93]
	v_mfma_f32_16x16x32_bf16 v[78:81], v[130:133], v[212:215], v[78:81]
	v_mfma_f32_16x16x32_bf16 v[74:77], v[138:141], v[212:215], v[74:77]
	v_mfma_f32_16x16x32_bf16 v[126:129], v[134:137], v[186:189], v[126:129]
	v_mfma_f32_16x16x32_bf16 v[122:125], v[142:145], v[186:189], v[122:125]
	v_mfma_f32_16x16x32_bf16 v[110:113], v[134:137], v[196:199], v[110:113]
	v_mfma_f32_16x16x32_bf16 v[106:109], v[142:145], v[196:199], v[106:109]
	v_mfma_f32_16x16x32_bf16 v[94:97], v[134:137], v[208:211], v[94:97]
	v_mfma_f32_16x16x32_bf16 v[90:93], v[142:145], v[208:211], v[90:93]
	v_mfma_f32_16x16x32_bf16 v[78:81], v[134:137], v[216:219], v[78:81]
	v_mfma_f32_16x16x32_bf16 v[74:77], v[142:145], v[216:219], v[74:77]
	s_setprio 0
	s_setprio 1
	v_mfma_f32_16x16x32_bf16 v[118:121], v[146:149], v[182:185], v[118:121]
	v_mfma_f32_16x16x32_bf16 v[114:117], v[154:157], v[182:185], v[114:117]
	v_mfma_f32_16x16x32_bf16 v[102:105], v[146:149], v[192:195], v[102:105]
	v_mfma_f32_16x16x32_bf16 v[98:101], v[154:157], v[192:195], v[98:101]
	v_mfma_f32_16x16x32_bf16 v[86:89], v[146:149], v[200:203], v[86:89]
	v_mfma_f32_16x16x32_bf16 v[82:85], v[154:157], v[200:203], v[82:85]
	v_mfma_f32_16x16x32_bf16 v[70:73], v[146:149], v[212:215], v[70:73]
	v_mfma_f32_16x16x32_bf16 v[66:69], v[154:157], v[212:215], v[66:69]
	v_mfma_f32_16x16x32_bf16 v[118:121], v[150:153], v[186:189], v[118:121]
	v_mfma_f32_16x16x32_bf16 v[114:117], v[158:161], v[186:189], v[114:117]
	v_mfma_f32_16x16x32_bf16 v[102:105], v[150:153], v[196:199], v[102:105]
	v_mfma_f32_16x16x32_bf16 v[98:101], v[158:161], v[196:199], v[98:101]
	v_mfma_f32_16x16x32_bf16 v[86:89], v[150:153], v[208:211], v[86:89]
	v_mfma_f32_16x16x32_bf16 v[82:85], v[158:161], v[208:211], v[82:85]
	v_mfma_f32_16x16x32_bf16 v[70:73], v[150:153], v[216:219], v[70:73]
	v_mfma_f32_16x16x32_bf16 v[66:69], v[158:161], v[216:219], v[66:69]
	s_setprio 0
	s_barrier
; #define PG8_STAGE(bufoff, gbase, voff) do { _Pragma("unroll") for (int _i = 0; _i < 2; ++_i) \
;         __builtin_amdgcn_global_load_lds((const unsigned*)((const char*)(gbase) + (voff)[_i]), (PG8_LAS unsigned*)(lds + (bufoff) + ldsw + _i * 8192), 16, 0, 0); } while (0)
; #define PG8_LDA(dst, b, h) do { _Pragma("unroll") for (int m = 0; m < 4; ++m) _Pragma("unroll") for (int k = 0; k < 2; ++k) dst[m][k] = *(const PG8_LAS bf16x8*)(lds + PG8_SA(b, h) + aoff + m * 2048 + k * 1024); } while (0)
; #define PG8_BAR __builtin_amdgcn_s_barrier()
; template <class Epi, class Sched, bool ALIGN_EPI = false, bool SP2 = false>
; __device__ __forceinline__ void gemm_phase(PG8_LAS unsigned char* lds, const Gemm g, const Sched& S, const Epi& E, const int tid) {
;     ...
;             PG8_LDA(At, 1, 1); PG8_STAGE(PG8_SB(1, 0), b3, voffB); PG8_STAGE(PG8_SB(1, 1), b3 + hstep, voffB); PG8_STAGE(PG8_SA(1, 0), a3, voffA);
;             PG8_WAIT_V(8); PG8_WAIT_L(0); PG8_BAR; PG8_MMA(1, 0, At, B0); PG8_MMA(1, 1, At, B1); PG8_BAR; PG8_SCHED;
;             } else {
;             PG8_LDB(B0, 0, 0); PG8_SCHED; PG8_LDA(At, 0, 0); PG8_STAGE(PG8_SA(1, 1), a1 + hstep, voffA);
;             PG8_WAIT_L(8); PG8_BAR; PG8_WAIT_L(0); PG8_MMA(0, 0, At, B0); PG8_BAR; PG8_SCHED;
;             PG8_LDB(B1, 0, 1); PG8_STAGE(PG8_SB(0, 0), b2, voffB);
;             PG8_BAR; PG8_WAIT_L(0); PG8_MMA(0, 1, At, B1); PG8_BAR;
;             PG8_LDA(At, 0, 1); PG8_STAGE(PG8_SA(0, 0), a2, voffA);
;             PG8_BAR; PG8_WAIT_L(0); PG8_MMA(1, 0, At, B0); PG8_BAR; PG8_SCHED;
;             PG8_STAGE(PG8_SB(0, 1), b2 + hstep, voffB);
;             PG8_WAIT_V(6); PG8_BAR; PG8_MMA(1, 1, At, B1); PG8_BAR;
;             PG8_LDB(B0, 1, 0); PG8_SCHED; PG8_LDA(At, 1, 0); PG8_STAGE(PG8_SA(0, 1), a2 + hstep, voffA);
;             PG8_WAIT_L(8); PG8_BAR; PG8_WAIT_L(0); PG8_MMA(0, 0, At, B0); PG8_BAR; PG8_SCHED;
;             PG8_LDB(B1, 1, 1); PG8_STAGE(PG8_SB(1, 0), b3, voffB);
;             PG8_BAR; PG8_WAIT_L(0); PG8_MMA(0, 1, At, B1); PG8_BAR;
;             PG8_LDA(At, 1, 1); PG8_STAGE(PG8_SA(1, 0), a3, voffA);
;             PG8_BAR; PG8_WAIT_L(0); PG8_MMA(1, 0, At, B0); PG8_BAR; PG8_SCHED;
;             PG8_STAGE(PG8_SB(1, 1), b3 + hstep, voffB);
;             PG8_WAIT_V(6); PG8_BAR; PG8_MMA(1, 1, At, B1); PG8_BAR;
;             }
;         }
;         if constexpr (ALIGN_EPI) { if (wr == 0) PG8_BAR; }
	s_add_i32 s6, s15, s55
	v_lshl_add_u64 v[220:221], v[220:221], 0, s[36:37]
	s_mov_b32 m0, s6
	ds_read_b128 v[182:185], v207 offset:49152
	ds_read_b128 v[186:189], v207 offset:50176
	ds_read_b128 v[192:195], v207 offset:51200
	ds_read_b128 v[196:199], v207 offset:52224
	ds_read_b128 v[200:203], v207 offset:53248
	ds_read_b128 v[208:211], v207 offset:54272
	ds_read_b128 v[212:215], v207 offset:55296
	ds_read_b128 v[216:219], v207 offset:56320
	global_load_lds_dwordx4 v[220:221], off
	s_add_i32 m0, s6, 0x2000
	s_add_u32 s6, s10, 0xb0080
	v_lshl_add_u64 v[220:221], v[222:223], 0, s[36:37]
	s_addc_u32 s7, s11, 0
	s_add_i32 s10, s18, s55
	global_load_lds_dwordx4 v[220:221], off
	v_lshl_add_u64 v[220:221], s[6:7], 0, v[164:165]
	s_mov_b32 m0, s10
	s_nop 0
	global_load_lds_dwordx4 v[220:221], off
	v_lshl_add_u64 v[220:221], s[6:7], 0, v[168:169]
	s_add_i32 m0, s10, 0x2000
	s_nop 0
	global_load_lds_dwordx4 v[220:221], off
	v_lshl_add_u64 v[220:221], v[224:225], 0, s[36:37]
	s_mov_b32 m0, s61
	s_nop 0
	global_load_lds_dwordx4 v[220:221], off
	v_lshl_add_u64 v[220:221], v[226:227], 0, s[36:37]
	s_mov_b32 m0, s62
	s_nop 0
	global_load_lds_dwordx4 v[220:221], off
	s_waitcnt vmcnt(8)
	s_waitcnt lgkmcnt(0)
	s_barrier
	s_setprio 1
	v_mfma_f32_16x16x32_bf16 v[62:65], v[130:133], v[182:185], v[62:65]
	v_mfma_f32_16x16x32_bf16 v[58:61], v[138:141], v[182:185], v[58:61]
	v_mfma_f32_16x16x32_bf16 v[46:49], v[130:133], v[192:195], v[46:49]
	v_mfma_f32_16x16x32_bf16 v[42:45], v[138:141], v[192:195], v[42:45]
	v_mfma_f32_16x16x32_bf16 v[30:33], v[130:133], v[200:203], v[30:33]
	v_mfma_f32_16x16x32_bf16 v[26:29], v[138:141], v[200:203], v[26:29]
	v_mfma_f32_16x16x32_bf16 v[14:17], v[130:133], v[212:215], v[14:17]
	v_mfma_f32_16x16x32_bf16 v[10:13], v[138:141], v[212:215], v[10:13]
	v_mfma_f32_16x16x32_bf16 v[62:65], v[134:137], v[186:189], v[62:65]
	v_mfma_f32_16x16x32_bf16 v[58:61], v[142:145], v[186:189], v[58:61]
	v_mfma_f32_16x16x32_bf16 v[46:49], v[134:137], v[196:199], v[46:49]
	v_mfma_f32_16x16x32_bf16 v[42:45], v[142:145], v[196:199], v[42:45]
	v_mfma_f32_16x16x32_bf16 v[30:33], v[134:137], v[208:211], v[30:33]
	v_mfma_f32_16x16x32_bf16 v[26:29], v[142:145], v[208:211], v[26:29]
	v_mfma_f32_16x16x32_bf16 v[14:17], v[134:137], v[216:219], v[14:17]
	v_mfma_f32_16x16x32_bf16 v[10:13], v[142:145], v[216:219], v[10:13]
	s_setprio 0
	s_setprio 1
	v_mfma_f32_16x16x32_bf16 v[54:57], v[146:149], v[182:185], v[54:57]
	v_mfma_f32_16x16x32_bf16 v[50:53], v[154:157], v[182:185], v[50:53]
	v_mfma_f32_16x16x32_bf16 v[38:41], v[146:149], v[192:195], v[38:41]
	v_mfma_f32_16x16x32_bf16 v[34:37], v[154:157], v[192:195], v[34:37]
	v_mfma_f32_16x16x32_bf16 v[22:25], v[146:149], v[200:203], v[22:25]
	v_mfma_f32_16x16x32_bf16 v[18:21], v[154:157], v[200:203], v[18:21]
	v_mfma_f32_16x16x32_bf16 v[6:9], v[146:149], v[212:215], v[6:9]
	v_mfma_f32_16x16x32_bf16 v[2:5], v[154:157], v[212:215], v[2:5]
	v_mfma_f32_16x16x32_bf16 v[54:57], v[150:153], v[186:189], v[54:57]
	v_mfma_f32_16x16x32_bf16 v[50:53], v[158:161], v[186:189], v[50:53]
	v_mfma_f32_16x16x32_bf16 v[38:41], v[150:153], v[196:199], v[38:41]
	v_mfma_f32_16x16x32_bf16 v[34:37], v[158:161], v[196:199], v[34:37]
	v_mfma_f32_16x16x32_bf16 v[22:25], v[150:153], v[208:211], v[22:25]
	v_mfma_f32_16x16x32_bf16 v[18:21], v[158:161], v[208:211], v[18:21]
	v_mfma_f32_16x16x32_bf16 v[6:9], v[150:153], v[216:219], v[6:9]
	v_mfma_f32_16x16x32_bf16 v[2:5], v[158:161], v[216:219], v[2:5]
	s_setprio 0
	s_barrier
	s_add_i32 s77, s77, 2
	s_add_u32 s45, s45, 0x100
	s_addc_u32 s47, s47, 0
	s_cmp_gt_u32 s77, 41
	s_mov_b64 s[6:7], s[8:9]
	s_cbranch_scc0 .LBB0_423
	s_and_b64 vcc, exec, s[38:39]
	s_cbranch_vccz .LBB0_426
	s_barrier

; #define PG8_STAGE(bufoff, gbase, voff) do { _Pragma("unroll") for (int _i = 0; _i < 2; ++_i) \
;         __builtin_amdgcn_global_load_lds((const unsigned*)((const char*)(gbase) + (voff)[_i]), (PG8_LAS unsigned*)(lds + (bufoff) + ldsw + _i * 8192), 16, 0, 0); } while (0)
; #define PG8_LDA(dst, b, h) do { _Pragma("unroll") for (int m = 0; m < 4; ++m) _Pragma("unroll") for (int k = 0; k < 2; ++k) dst[m][k] = *(const PG8_LAS bf16x8*)(lds + PG8_SA(b, h) + aoff + m * 2048 + k * 1024); } while (0)
; #define PG8_LDB(dst, b, h) do { _Pragma("unroll") for (int n = 0; n < 2; ++n) _Pragma("unroll") for (int k = 0; k < 2; ++k) dst[n][k] = *(const PG8_LAS bf16x8*)(lds + PG8_SB(b, h) + boff + n * 2048 + k * 1024); } while (0)
; #define PG8_WAIT_V(n) asm volatile("s_waitcnt vmcnt(" #n ")" ::: "memory")
; #define PG8_WAIT_L(n) asm volatile("s_waitcnt lgkmcnt(" #n ")" ::: "memory")
; #define PG8_BAR __builtin_amdgcn_s_barrier()
; #define PG8_SCHED __builtin_amdgcn_sched_barrier(0)
; template <class Epi, class Sched, bool ALIGN_EPI = false, bool SP2 = false>
; __device__ __forceinline__ void gemm_phase(PG8_LAS unsigned char* lds, const Gemm g, const Sched& S, const Epi& E, const int tid) {
;     ...
;         const bool has_next = S.next(ui + 1, nxt);
;         const char* nA = has_next ? S.aptr(nxt) : cA; const char* nB = has_next ? S.bptr(nxt) : cB;
;         for (int t = 0; t < nt; t += 2) {
;             const bool last = (t == nt - 2);
;             const char* a1 = cA + (size_t)(t + 1) * kstep;
;             const char* a2 = last ? nA : cA + (size_t)(t + 2) * kstep; const char* b2 = last ? nB : cB + (size_t)(t + 2) * kstep;
;             const char* a3 = a2 + kstep; const char* b3 = b2 + kstep;
;             if (last && has_next) S.a_ready(nxt);
;             if constexpr (SP2) {
;             PG8_LDB(B0, 0, 0); PG8_LDB(B1, 0, 1); PG8_SCHED; PG8_LDA(At, 0, 0); PG8_STAGE(PG8_SA(1, 1), a1 + hstep, voffA);
;             PG8_WAIT_V(8); PG8_WAIT_L(0); PG8_BAR; PG8_MMA(0, 0, At, B0); PG8_MMA(0, 1, At, B1); PG8_BAR; PG8_SCHED;
;             PG8_LDA(At, 0, 1); PG8_STAGE(PG8_SB(0, 0), b2, voffB); PG8_STAGE(PG8_SB(0, 1), b2 + hstep, voffB); PG8_STAGE(PG8_SA(0, 0), a2, voffA);
;             PG8_WAIT_V(8); PG8_WAIT_L(0); PG8_BAR; PG8_MMA(1, 0, At, B0); PG8_MMA(1, 1, At, B1); PG8_BAR; PG8_SCHED;
.LBB0_732:
	s_ashr_i32 s29, s28, 31
	s_lshl_b64 s[18:19], s[28:29], 19
	s_add_u32 s30, s50, s18
	s_addc_u32 s31, s51, s19
	s_and_b64 s[18:19], s[2:3], exec
	s_cselect_b32 s29, s31, s41
	s_cselect_b32 s37, s30, s40
	s_ashr_i32 s27, s26, 31
	s_lshl_b64 s[18:19], s[26:27], 19
	s_add_u32 s34, s52, s18
	s_addc_u32 s35, s53, s19
	s_and_b64 s[18:19], s[2:3], exec
	s_cselect_b32 s27, s35, s39
	s_cselect_b32 s79, s34, s38
	s_add_u32 s80, s38, 0x100
	s_addc_u32 s81, s39, 0
	s_add_u32 s38, s40, 0x40080
	s_addc_u32 s39, s41, 0
	s_mov_b32 s82, -2
	s_add_u32 s15, s38, 0xfffc0080
	s_addc_u32 s18, s39, -1
	s_cmp_eq_u32 s82, 12
	s_cselect_b32 s43, s29, s18
	s_cselect_b32 s42, s37, s15
	s_cselect_b32 s41, s27, s81
	s_cselect_b32 s40, s79, s80
	v_lshl_add_u64 v[194:195], s[38:39], 0, v[180:181]
	s_add_i32 m0, s55, 0xc000
	global_load_lds_dwordx4 v[194:195], off
	v_lshl_add_u64 v[194:195], s[38:39], 0, v[178:179]
	s_add_i32 m0, s55, 0xe000
	s_nop 0
	global_load_lds_dwordx4 v[194:195], off
	s_waitcnt vmcnt(8)
	s_waitcnt lgkmcnt(0)
	s_barrier
	s_setprio 1
	v_mfma_f32_16x16x32_bf16 v[126:129], v[130:133], v[186:189], 0
	v_mfma_f32_16x16x32_bf16 v[122:125], v[138:141], v[186:189], 0
	v_mfma_f32_16x16x32_bf16 v[110:113], v[130:133], v[206:209], 0
	v_mfma_f32_16x16x32_bf16 v[106:109], v[138:141], v[206:209], 0
	v_mfma_f32_16x16x32_bf16 v[94:97], v[130:133], v[216:219], 0
	v_mfma_f32_16x16x32_bf16 v[90:93], v[138:141], v[216:219], 0
	v_mfma_f32_16x16x32_bf16 v[78:81], v[130:133], v[224:227], 0
	v_mfma_f32_16x16x32_bf16 v[74:77], v[138:141], v[224:227], 0
	v_mfma_f32_16x16x32_bf16 v[126:129], v[134:137], v[198:201], v[126:129]
	v_mfma_f32_16x16x32_bf16 v[122:125], v[142:145], v[198:201], v[122:125]
	v_mfma_f32_16x16x32_bf16 v[110:113], v[134:137], v[212:215], v[110:113]
	v_mfma_f32_16x16x32_bf16 v[106:109], v[142:145], v[212:215], v[106:109]
	v_mfma_f32_16x16x32_bf16 v[94:97], v[134:137], v[220:223], v[94:97]
	v_mfma_f32_16x16x32_bf16 v[90:93], v[142:145], v[220:223], v[90:93]
	v_mfma_f32_16x16x32_bf16 v[78:81], v[134:137], v[228:231], v[78:81]
	v_mfma_f32_16x16x32_bf16 v[74:77], v[142:145], v[228:231], v[74:77]
	s_setprio 0
	s_setprio 1
	v_mfma_f32_16x16x32_bf16 v[118:121], v[146:149], v[186:189], 0
	v_mfma_f32_16x16x32_bf16 v[114:117], v[154:157], v[186:189], 0
	v_mfma_f32_16x16x32_bf16 v[102:105], v[146:149], v[206:209], 0
	v_mfma_f32_16x16x32_bf16 v[98:101], v[154:157], v[206:209], 0
	v_mfma_f32_16x16x32_bf16 v[86:89], v[146:149], v[216:219], 0
	v_mfma_f32_16x16x32_bf16 v[82:85], v[154:157], v[216:219], 0
	v_mfma_f32_16x16x32_bf16 v[70:73], v[146:149], v[224:227], 0
	v_mfma_f32_16x16x32_bf16 v[66:69], v[154:157], v[224:227], 0
	v_mfma_f32_16x16x32_bf16 v[118:121], v[150:153], v[198:201], v[118:121]
	v_mfma_f32_16x16x32_bf16 v[114:117], v[158:161], v[198:201], v[114:117]
	v_mfma_f32_16x16x32_bf16 v[102:105], v[150:153], v[212:215], v[102:105]
	v_mfma_f32_16x16x32_bf16 v[98:101], v[158:161], v[212:215], v[98:101]
	v_mfma_f32_16x16x32_bf16 v[86:89], v[150:153], v[220:223], v[86:89]
	v_mfma_f32_16x16x32_bf16 v[82:85], v[158:161], v[220:223], v[82:85]
	v_mfma_f32_16x16x32_bf16 v[70:73], v[150:153], v[228:231], v[70:73]
	v_mfma_f32_16x16x32_bf16 v[66:69], v[158:161], v[228:231], v[66:69]
	s_setprio 0
	s_barrier
	s_add_i32 s15, s66, s54
	v_lshl_add_u64 v[194:195], s[40:41], 0, v[164:165]
	s_mov_b32 m0, s15
	ds_read_b128 v[186:189], v197 offset:16384
	ds_read_b128 v[198:201], v197 offset:17408
	ds_read_b128 v[206:209], v197 offset:18432
	ds_read_b128 v[212:215], v197 offset:19456
	ds_read_b128 v[216:219], v197 offset:20480
	ds_read_b128 v[220:223], v197 offset:21504
	ds_read_b128 v[224:227], v197 offset:22528
	ds_read_b128 v[228:231], v197 offset:23552
	global_load_lds_dwordx4 v[194:195], off
	s_add_i32 m0, s15, 0x2000
	s_add_u32 s18, s40, 0x40000
	v_lshl_add_u64 v[232:233], s[40:41], 0, v[168:169]
	s_addc_u32 s19, s41, 0
	s_add_i32 s15, s67, s54
	global_load_lds_dwordx4 v[232:233], off
	v_lshl_add_u64 v[234:235], s[18:19], 0, v[164:165]
	s_mov_b32 m0, s15
	v_lshl_add_u64 v[236:237], s[42:43], 0, v[166:167]
	global_load_lds_dwordx4 v[234:235], off
	v_lshl_add_u64 v[234:235], s[18:19], 0, v[168:169]
	s_add_i32 m0, s15, 0x2000
	s_nop 0
	global_load_lds_dwordx4 v[234:235], off
	v_lshl_add_u64 v[234:235], s[42:43], 0, v[162:163]
	s_mov_b32 m0, s55
	s_nop 0
	global_load_lds_dwordx4 v[234:235], off
	s_mov_b32 m0, s56
	s_nop 0
	global_load_lds_dwordx4 v[236:237], off
	s_waitcnt vmcnt(8)
	s_waitcnt lgkmcnt(0)
	s_barrier
	s_setprio 1
	v_mfma_f32_16x16x32_bf16 v[62:65], v[130:133], v[186:189], 0
	v_mfma_f32_16x16x32_bf16 v[58:61], v[138:141], v[186:189], 0
	v_mfma_f32_16x16x32_bf16 v[46:49], v[130:133], v[206:209], 0
	v_mfma_f32_16x16x32_bf16 v[42:45], v[138:141], v[206:209], 0
	v_mfma_f32_16x16x32_bf16 v[30:33], v[130:133], v[216:219], 0
	v_mfma_f32_16x16x32_bf16 v[26:29], v[138:141], v[216:219], 0
	v_mfma_f32_16x16x32_bf16 v[14:17], v[130:133], v[224:227], 0
	v_mfma_f32_16x16x32_bf16 v[10:13], v[138:141], v[224:227], 0
	v_mfma_f32_16x16x32_bf16 v[62:65], v[134:137], v[198:201], v[62:65]
	v_mfma_f32_16x16x32_bf16 v[58:61], v[142:145], v[198:201], v[58:61]
	v_mfma_f32_16x16x32_bf16 v[46:49], v[134:137], v[212:215], v[46:49]
	v_mfma_f32_16x16x32_bf16 v[42:45], v[142:145], v[212:215], v[42:45]
	v_mfma_f32_16x16x32_bf16 v[30:33], v[134:137], v[220:223], v[30:33]
	v_mfma_f32_16x16x32_bf16 v[26:29], v[142:145], v[220:223], v[26:29]
	v_mfma_f32_16x16x32_bf16 v[14:17], v[134:137], v[228:231], v[14:17]
	v_mfma_f32_16x16x32_bf16 v[10:13], v[142:145], v[228:231], v[10:13]
	s_setprio 0
	s_setprio 1
	v_mfma_f32_16x16x32_bf16 v[54:57], v[146:149], v[186:189], 0
	v_mfma_f32_16x16x32_bf16 v[50:53], v[154:157], v[186:189], 0
	v_mfma_f32_16x16x32_bf16 v[38:41], v[146:149], v[206:209], 0
	v_mfma_f32_16x16x32_bf16 v[34:37], v[154:157], v[206:209], 0
	v_mfma_f32_16x16x32_bf16 v[22:25], v[146:149], v[216:219], 0
	v_mfma_f32_16x16x32_bf16 v[18:21], v[154:157], v[216:219], 0
	v_mfma_f32_16x16x32_bf16 v[6:9], v[146:149], v[224:227], 0
	v_mfma_f32_16x16x32_bf16 v[2:5], v[154:157], v[224:227], 0
	v_mfma_f32_16x16x32_bf16 v[54:57], v[150:153], v[198:201], v[54:57]
	v_mfma_f32_16x16x32_bf16 v[50:53], v[158:161], v[198:201], v[50:53]
	v_mfma_f32_16x16x32_bf16 v[38:41], v[150:153], v[212:215], v[38:41]
	v_mfma_f32_16x16x32_bf16 v[34:37], v[158:161], v[212:215], v[34:37]
	v_mfma_f32_16x16x32_bf16 v[22:25], v[150:153], v[220:223], v[22:25]
	v_mfma_f32_16x16x32_bf16 v[18:21], v[158:161], v[220:223], v[18:21]
	v_mfma_f32_16x16x32_bf16 v[6:9], v[150:153], v[228:231], v[6:9]
	v_mfma_f32_16x16x32_bf16 v[2:5], v[158:161], v[228:231], v[2:5]
	s_setprio 0
	s_barrier
; #define PG8_STAGE(bufoff, gbase, voff) do { _Pragma("unroll") for (int _i = 0; _i < 2; ++_i) \
;         __builtin_amdgcn_global_load_lds((const unsigned*)((const char*)(gbase) + (voff)[_i]), (PG8_LAS unsigned*)(lds + (bufoff) + ldsw + _i * 8192), 16, 0, 0); } while (0)
; #define PG8_LDA(dst, b, h) do { _Pragma("unroll") for (int m = 0; m < 4; ++m) _Pragma("unroll") for (int k = 0; k < 2; ++k) dst[m][k] = *(const PG8_LAS bf16x8*)(lds + PG8_SA(b, h) + aoff + m * 2048 + k * 1024); } while (0)
; #define PG8_LDB(dst, b, h) do { _Pragma("unroll") for (int n = 0; n < 2; ++n) _Pragma("unroll") for (int k = 0; k < 2; ++k) dst[n][k] = *(const PG8_LAS bf16x8*)(lds + PG8_SB(b, h) + boff + n * 2048 + k * 1024); } while (0)
; #define PG8_MMA(ai, bj, At, Bt) do { __builtin_amdgcn_s_setprio(1); _Pragma("unroll") for (int m = 0; m < 4; ++m) _Pragma("unroll") for (int n = 0; n < 2; ++n) _Pragma("unroll") for (int k = 0; k < 2; ++k) \
;         acc[ai][bj][m][n] = __builtin_amdgcn_mfma_f32_16x16x32_bf16(Bt[n][k], At[m][k], acc[ai][bj][m][n], 0, 0, 0); __builtin_amdgcn_s_setprio(0); } while (0)
; #define PG8_WAIT_V(n) asm volatile("s_waitcnt vmcnt(" #n ")" ::: "memory")
; #define PG8_WAIT_L(n) asm volatile("s_waitcnt lgkmcnt(" #n ")" ::: "memory")
; #define PG8_BAR __builtin_amdgcn_s_barrier()
; #define PG8_SCHED __builtin_amdgcn_sched_barrier(0)
; template <class Epi, class Sched, bool ALIGN_EPI = false, bool SP2 = false>
; __device__ __forceinline__ void gemm_phase(PG8_LAS unsigned char* lds, const Gemm g, const Sched& S, const Epi& E, const int tid) {
;     ...
;             PG8_LDB(B0, 1, 0); PG8_LDB(B1, 1, 1); PG8_SCHED; PG8_LDA(At, 1, 0); PG8_STAGE(PG8_SA(0, 1), a2 + hstep, voffA);
;             PG8_WAIT_V(8); PG8_WAIT_L(0); PG8_BAR; PG8_MMA(0, 0, At, B0); PG8_MMA(0, 1, At, B1); PG8_BAR; PG8_SCHED;
;             PG8_LDA(At, 1, 1); PG8_STAGE(PG8_SB(1, 0), b3, voffB); PG8_STAGE(PG8_SB(1, 1), b3 + hstep, voffB); PG8_STAGE(PG8_SA(1, 0), a3, voffA);
	s_add_i32 s15, 0, 0x18000
	s_add_i32 s83, 0, 0x1c000
	v_add_u32_e32 v142, s15, v173
	v_add_u32_e32 v158, s83, v173
	ds_read_b128 v[130:133], v142
	ds_read_b128 v[134:137], v142 offset:1024
	ds_read_b128 v[138:141], v142 offset:2048
	ds_read_b128 v[142:145], v142 offset:3072
	ds_read_b128 v[146:149], v158
	ds_read_b128 v[150:153], v158 offset:1024
	ds_read_b128 v[154:157], v158 offset:2048
	ds_read_b128 v[158:161], v158 offset:3072
	s_add_u32 s18, s42, 0x40000
	s_addc_u32 s19, s43, 0
	s_mov_b32 m0, s57
	v_lshl_add_u64 v[238:239], s[18:19], 0, v[162:163]
	ds_read_b128 v[186:189], v197 offset:32768
	ds_read_b128 v[198:201], v197 offset:33792
	ds_read_b128 v[206:209], v197 offset:34816
	ds_read_b128 v[212:215], v197 offset:35840
	ds_read_b128 v[216:219], v197 offset:36864
	ds_read_b128 v[220:223], v197 offset:37888
	ds_read_b128 v[224:227], v197 offset:38912
	ds_read_b128 v[228:231], v197 offset:39936
	global_load_lds_dwordx4 v[238:239], off
	v_lshl_add_u64 v[238:239], s[18:19], 0, v[166:167]
	s_mov_b32 m0, s58
	s_nop 0
	global_load_lds_dwordx4 v[238:239], off
	s_waitcnt vmcnt(8)
	s_waitcnt lgkmcnt(0)
	s_barrier
	s_setprio 1
	v_mfma_f32_16x16x32_bf16 v[126:129], v[130:133], v[186:189], v[126:129]
	v_mfma_f32_16x16x32_bf16 v[122:125], v[138:141], v[186:189], v[122:125]
	v_mfma_f32_16x16x32_bf16 v[110:113], v[130:133], v[206:209], v[110:113]
	v_mfma_f32_16x16x32_bf16 v[106:109], v[138:141], v[206:209], v[106:109]
	v_mfma_f32_16x16x32_bf16 v[94:97], v[130:133], v[216:219], v[94:97]
	v_mfma_f32_16x16x32_bf16 v[90:93], v[138:141], v[216:219], v[90:93]
	v_mfma_f32_16x16x32_bf16 v[78:81], v[130:133], v[224:227], v[78:81]
	v_mfma_f32_16x16x32_bf16 v[74:77], v[138:141], v[224:227], v[74:77]
	v_mfma_f32_16x16x32_bf16 v[126:129], v[134:137], v[198:201], v[126:129]
	v_mfma_f32_16x16x32_bf16 v[122:125], v[142:145], v[198:201], v[122:125]
	v_mfma_f32_16x16x32_bf16 v[110:113], v[134:137], v[212:215], v[110:113]
	v_mfma_f32_16x16x32_bf16 v[106:109], v[142:145], v[212:215], v[106:109]
	v_mfma_f32_16x16x32_bf16 v[94:97], v[134:137], v[220:223], v[94:97]
	v_mfma_f32_16x16x32_bf16 v[90:93], v[142:145], v[220:223], v[90:93]
	v_mfma_f32_16x16x32_bf16 v[78:81], v[134:137], v[228:231], v[78:81]
	v_mfma_f32_16x16x32_bf16 v[74:77], v[142:145], v[228:231], v[74:77]
	s_setprio 0
	s_setprio 1
	v_mfma_f32_16x16x32_bf16 v[118:121], v[146:149], v[186:189], v[118:121]
	v_mfma_f32_16x16x32_bf16 v[114:117], v[154:157], v[186:189], v[114:117]
	v_mfma_f32_16x16x32_bf16 v[102:105], v[146:149], v[206:209], v[102:105]
	v_mfma_f32_16x16x32_bf16 v[98:101], v[154:157], v[206:209], v[98:101]
	v_mfma_f32_16x16x32_bf16 v[86:89], v[146:149], v[216:219], v[86:89]
	v_mfma_f32_16x16x32_bf16 v[82:85], v[154:157], v[216:219], v[82:85]
	v_mfma_f32_16x16x32_bf16 v[70:73], v[146:149], v[224:227], v[70:73]
	v_mfma_f32_16x16x32_bf16 v[66:69], v[154:157], v[224:227], v[66:69]
	v_mfma_f32_16x16x32_bf16 v[118:121], v[150:153], v[198:201], v[118:121]
	v_mfma_f32_16x16x32_bf16 v[114:117], v[158:161], v[198:201], v[114:117]
	v_mfma_f32_16x16x32_bf16 v[102:105], v[150:153], v[212:215], v[102:105]
	v_mfma_f32_16x16x32_bf16 v[98:101], v[158:161], v[212:215], v[98:101]
	v_mfma_f32_16x16x32_bf16 v[86:89], v[150:153], v[220:223], v[86:89]
	v_mfma_f32_16x16x32_bf16 v[82:85], v[158:161], v[220:223], v[82:85]
	v_mfma_f32_16x16x32_bf16 v[70:73], v[150:153], v[228:231], v[70:73]
	v_mfma_f32_16x16x32_bf16 v[66:69], v[158:161], v[228:231], v[66:69]
	s_setprio 0
	s_barrier
	s_add_i32 s15, s15, s54
	v_lshl_add_u64 v[194:195], v[194:195], 0, s[10:11]
	s_mov_b32 m0, s15
	ds_read_b128 v[186:189], v197 offset:49152
	ds_read_b128 v[198:201], v197 offset:50176
	ds_read_b128 v[206:209], v197 offset:51200
	ds_read_b128 v[212:215], v197 offset:52224
	ds_read_b128 v[216:219], v197 offset:53248
	ds_read_b128 v[220:223], v197 offset:54272
	ds_read_b128 v[224:227], v197 offset:55296
	ds_read_b128 v[228:231], v197 offset:56320
	global_load_lds_dwordx4 v[194:195], off
	s_add_i32 m0, s15, 0x2000
	s_add_u32 s18, s40, 0x40080
	v_lshl_add_u64 v[194:195], v[232:233], 0, s[10:11]
	s_addc_u32 s19, s41, 0
	s_add_i32 s15, s83, s54
	global_load_lds_dwordx4 v[194:195], off
	v_lshl_add_u64 v[194:195], s[18:19], 0, v[164:165]
	s_mov_b32 m0, s15
	s_nop 0
	global_load_lds_dwordx4 v[194:195], off
	v_lshl_add_u64 v[194:195], s[18:19], 0, v[168:169]
	s_add_i32 m0, s15, 0x2000
	s_nop 0
	global_load_lds_dwordx4 v[194:195], off
	v_lshl_add_u64 v[194:195], v[234:235], 0, s[10:11]
	s_mov_b32 m0, s61
	s_nop 0
	global_load_lds_dwordx4 v[194:195], off
	v_lshl_add_u64 v[194:195], v[236:237], 0, s[10:11]
	s_mov_b32 m0, s62
	s_nop 0
	global_load_lds_dwordx4 v[194:195], off
	s_waitcnt vmcnt(8)
	s_waitcnt lgkmcnt(0)
	s_barrier
; #define PG8_STAGE(bufoff, gbase, voff) do { _Pragma("unroll") for (int _i = 0; _i < 2; ++_i) \
;         __builtin_amdgcn_global_load_lds((const unsigned*)((const char*)(gbase) + (voff)[_i]), (PG8_LAS unsigned*)(lds + (bufoff) + ldsw + _i * 8192), 16, 0, 0); } while (0)
; #define PG8_LDA(dst, b, h) do { _Pragma("unroll") for (int m = 0; m < 4; ++m) _Pragma("unroll") for (int k = 0; k < 2; ++k) dst[m][k] = *(const PG8_LAS bf16x8*)(lds + PG8_SA(b, h) + aoff + m * 2048 + k * 1024); } while (0)
; #define PG8_LDB(dst, b, h) do { _Pragma("unroll") for (int n = 0; n < 2; ++n) _Pragma("unroll") for (int k = 0; k < 2; ++k) dst[n][k] = *(const PG8_LAS bf16x8*)(lds + PG8_SB(b, h) + boff + n * 2048 + k * 1024); } while (0)
; #define PG8_MMA(ai, bj, At, Bt) do { __builtin_amdgcn_s_setprio(1); _Pragma("unroll") for (int m = 0; m < 4; ++m) _Pragma("unroll") for (int n = 0; n < 2; ++n) _Pragma("unroll") for (int k = 0; k < 2; ++k) \
;         acc[ai][bj][m][n] = __builtin_amdgcn_mfma_f32_16x16x32_bf16(Bt[n][k], At[m][k], acc[ai][bj][m][n], 0, 0, 0); __builtin_amdgcn_s_setprio(0); } while (0)
; #define PG8_BAR __builtin_amdgcn_s_barrier()
; template <class Epi, class Sched, bool ALIGN_EPI = false, bool SP2 = false>
; __device__ __forceinline__ void gemm_phase(PG8_LAS unsigned char* lds, const Gemm g, const Sched& S, const Epi& E, const int tid) {
;     ...
;             PG8_LDB(B0, 0, 0); PG8_LDB(B1, 0, 1); PG8_SCHED; PG8_LDA(At, 0, 0); PG8_STAGE(PG8_SA(1, 1), a1 + hstep, voffA);
;             PG8_WAIT_V(8); PG8_WAIT_L(0); PG8_BAR; PG8_MMA(0, 0, At, B0); PG8_MMA(0, 1, At, B1); PG8_BAR; PG8_SCHED;
;             PG8_LDA(At, 0, 1); PG8_STAGE(PG8_SB(0, 0), b2, voffB); PG8_STAGE(PG8_SB(0, 1), b2 + hstep, voffB); PG8_STAGE(PG8_SA(0, 0), a2, voffA);
;             PG8_WAIT_V(8); PG8_WAIT_L(0); PG8_BAR; PG8_MMA(1, 0, At, B0); PG8_MMA(1, 1, At, B1); PG8_BAR; PG8_SCHED;
;             PG8_LDB(B0, 1, 0); PG8_LDB(B1, 1, 1); PG8_SCHED; PG8_LDA(At, 1, 0); PG8_STAGE(PG8_SA(0, 1), a2 + hstep, voffA);
;             PG8_WAIT_V(8); PG8_WAIT_L(0); PG8_BAR; PG8_MMA(0, 0, At, B0); PG8_MMA(0, 1, At, B1); PG8_BAR; PG8_SCHED;
;             PG8_LDA(At, 1, 1); PG8_STAGE(PG8_SB(1, 0), b3, voffB); PG8_STAGE(PG8_SB(1, 1), b3 + hstep, voffB); PG8_STAGE(PG8_SA(1, 0), a3, voffA);
;             PG8_WAIT_V(8); PG8_WAIT_L(0); PG8_BAR; PG8_MMA(1, 0, At, B0); PG8_MMA(1, 1, At, B1); PG8_BAR; PG8_SCHED;
	s_setprio 1
	v_mfma_f32_16x16x32_bf16 v[62:65], v[130:133], v[186:189], v[62:65]
	v_mfma_f32_16x16x32_bf16 v[58:61], v[138:141], v[186:189], v[58:61]
	v_mfma_f32_16x16x32_bf16 v[46:49], v[130:133], v[206:209], v[46:49]
	v_mfma_f32_16x16x32_bf16 v[42:45], v[138:141], v[206:209], v[42:45]
	v_mfma_f32_16x16x32_bf16 v[30:33], v[130:133], v[216:219], v[30:33]
	v_mfma_f32_16x16x32_bf16 v[26:29], v[138:141], v[216:219], v[26:29]
	v_mfma_f32_16x16x32_bf16 v[14:17], v[130:133], v[224:227], v[14:17]
	v_mfma_f32_16x16x32_bf16 v[10:13], v[138:141], v[224:227], v[10:13]
	v_mfma_f32_16x16x32_bf16 v[62:65], v[134:137], v[198:201], v[62:65]
	v_mfma_f32_16x16x32_bf16 v[58:61], v[142:145], v[198:201], v[58:61]
	v_mfma_f32_16x16x32_bf16 v[46:49], v[134:137], v[212:215], v[46:49]
	v_mfma_f32_16x16x32_bf16 v[42:45], v[142:145], v[212:215], v[42:45]
	v_mfma_f32_16x16x32_bf16 v[30:33], v[134:137], v[220:223], v[30:33]
	v_mfma_f32_16x16x32_bf16 v[26:29], v[142:145], v[220:223], v[26:29]
	v_mfma_f32_16x16x32_bf16 v[14:17], v[134:137], v[228:231], v[14:17]
	v_mfma_f32_16x16x32_bf16 v[10:13], v[142:145], v[228:231], v[10:13]
	s_setprio 0
	s_setprio 1
	v_mfma_f32_16x16x32_bf16 v[54:57], v[146:149], v[186:189], v[54:57]
	v_mfma_f32_16x16x32_bf16 v[50:53], v[154:157], v[186:189], v[50:53]
	v_mfma_f32_16x16x32_bf16 v[38:41], v[146:149], v[206:209], v[38:41]
	v_mfma_f32_16x16x32_bf16 v[34:37], v[154:157], v[206:209], v[34:37]
	v_mfma_f32_16x16x32_bf16 v[22:25], v[146:149], v[216:219], v[22:25]
	v_mfma_f32_16x16x32_bf16 v[18:21], v[154:157], v[216:219], v[18:21]
	v_mfma_f32_16x16x32_bf16 v[6:9], v[146:149], v[224:227], v[6:9]
	v_mfma_f32_16x16x32_bf16 v[2:5], v[154:157], v[224:227], v[2:5]
	v_mfma_f32_16x16x32_bf16 v[54:57], v[150:153], v[198:201], v[54:57]
	v_mfma_f32_16x16x32_bf16 v[50:53], v[158:161], v[198:201], v[50:53]
	v_mfma_f32_16x16x32_bf16 v[38:41], v[150:153], v[212:215], v[38:41]
	v_mfma_f32_16x16x32_bf16 v[34:37], v[158:161], v[212:215], v[34:37]
	v_mfma_f32_16x16x32_bf16 v[22:25], v[150:153], v[220:223], v[22:25]
	v_mfma_f32_16x16x32_bf16 v[18:21], v[158:161], v[220:223], v[18:21]
	v_mfma_f32_16x16x32_bf16 v[6:9], v[150:153], v[228:231], v[6:9]
	v_mfma_f32_16x16x32_bf16 v[2:5], v[158:161], v[228:231], v[2:5]
	s_setprio 0
	s_barrier
	s_add_i32 s82, s82, 2
	s_add_u32 s80, s80, 0x100
	s_addc_u32 s81, s81, 0
	s_add_u32 s38, s38, 0x100
	s_addc_u32 s39, s39, 0
.LBB0_733:
	ds_read_b128 v[130:133], v191
	ds_read_b128 v[134:137], v191 offset:1024
	ds_read_b128 v[138:141], v191 offset:2048
	ds_read_b128 v[142:145], v191 offset:3072
	ds_read_b128 v[146:149], v193
	ds_read_b128 v[150:153], v193 offset:1024
	ds_read_b128 v[154:157], v193 offset:2048
	ds_read_b128 v[158:161], v193 offset:3072
	s_add_u32 s15, s38, 0xfffc0080
	s_addc_u32 s18, s39, -1
	s_cmp_eq_u32 s82, 12
	s_cselect_b32 s43, s29, s18
	s_cselect_b32 s42, s37, s15
	s_cselect_b32 s41, s27, s81
	s_cselect_b32 s40, s79, s80
	v_lshl_add_u64 v[194:195], s[38:39], 0, v[180:181]
	s_add_i32 m0, s55, 0xc000
	ds_read_b128 v[186:189], v197
	ds_read_b128 v[198:201], v197 offset:1024
	ds_read_b128 v[206:209], v197 offset:2048
	ds_read_b128 v[212:215], v197 offset:3072
	ds_read_b128 v[216:219], v197 offset:4096
	ds_read_b128 v[220:223], v197 offset:5120
	ds_read_b128 v[224:227], v197 offset:6144
	ds_read_b128 v[228:231], v197 offset:7168
	global_load_lds_dwordx4 v[194:195], off
	v_lshl_add_u64 v[194:195], s[38:39], 0, v[178:179]
	s_add_i32 m0, s55, 0xe000
	s_nop 0
	global_load_lds_dwordx4 v[194:195], off
	s_waitcnt vmcnt(8)
	s_waitcnt lgkmcnt(0)
	s_barrier
	s_setprio 1
	v_mfma_f32_16x16x32_bf16 v[126:129], v[130:133], v[186:189], v[126:129]
	v_mfma_f32_16x16x32_bf16 v[122:125], v[138:141], v[186:189], v[122:125]
	v_mfma_f32_16x16x32_bf16 v[110:113], v[130:133], v[206:209], v[110:113]
	v_mfma_f32_16x16x32_bf16 v[106:109], v[138:141], v[206:209], v[106:109]
	v_mfma_f32_16x16x32_bf16 v[94:97], v[130:133], v[216:219], v[94:97]
	v_mfma_f32_16x16x32_bf16 v[90:93], v[138:141], v[216:219], v[90:93]
	v_mfma_f32_16x16x32_bf16 v[78:81], v[130:133], v[224:227], v[78:81]
	v_mfma_f32_16x16x32_bf16 v[74:77], v[138:141], v[224:227], v[74:77]
	v_mfma_f32_16x16x32_bf16 v[126:129], v[134:137], v[198:201], v[126:129]
	v_mfma_f32_16x16x32_bf16 v[122:125], v[142:145], v[198:201], v[122:125]
	v_mfma_f32_16x16x32_bf16 v[110:113], v[134:137], v[212:215], v[110:113]
	v_mfma_f32_16x16x32_bf16 v[106:109], v[142:145], v[212:215], v[106:109]
	v_mfma_f32_16x16x32_bf16 v[94:97], v[134:137], v[220:223], v[94:97]
	v_mfma_f32_16x16x32_bf16 v[90:93], v[142:145], v[220:223], v[90:93]
	v_mfma_f32_16x16x32_bf16 v[78:81], v[134:137], v[228:231], v[78:81]
	v_mfma_f32_16x16x32_bf16 v[74:77], v[142:145], v[228:231], v[74:77]
	s_setprio 0
	s_setprio 1
	v_mfma_f32_16x16x32_bf16 v[118:121], v[146:149], v[186:189], v[118:121]
	v_mfma_f32_16x16x32_bf16 v[114:117], v[154:157], v[186:189], v[114:117]
	v_mfma_f32_16x16x32_bf16 v[102:105], v[146:149], v[206:209], v[102:105]
	v_mfma_f32_16x16x32_bf16 v[98:101], v[154:157], v[206:209], v[98:101]
	v_mfma_f32_16x16x32_bf16 v[86:89], v[146:149], v[216:219], v[86:89]
	v_mfma_f32_16x16x32_bf16 v[82:85], v[154:157], v[216:219], v[82:85]
	v_mfma_f32_16x16x32_bf16 v[70:73], v[146:149], v[224:227], v[70:73]
	v_mfma_f32_16x16x32_bf16 v[66:69], v[154:157], v[224:227], v[66:69]
	v_mfma_f32_16x16x32_bf16 v[118:121], v[150:153], v[198:201], v[118:121]
	v_mfma_f32_16x16x32_bf16 v[114:117], v[158:161], v[198:201], v[114:117]
	v_mfma_f32_16x16x32_bf16 v[102:105], v[150:153], v[212:215], v[102:105]
	v_mfma_f32_16x16x32_bf16 v[98:101], v[158:161], v[212:215], v[98:101]
	v_mfma_f32_16x16x32_bf16 v[86:89], v[150:153], v[220:223], v[86:89]
	v_mfma_f32_16x16x32_bf16 v[82:85], v[158:161], v[220:223], v[82:85]
	v_mfma_f32_16x16x32_bf16 v[70:73], v[150:153], v[228:231], v[70:73]
	v_mfma_f32_16x16x32_bf16 v[66:69], v[158:161], v[228:231], v[66:69]
	s_setprio 0
	s_barrier
; #define PG8_STAGE(bufoff, gbase, voff) do { _Pragma("unroll") for (int _i = 0; _i < 2; ++_i) \
;         __builtin_amdgcn_global_load_lds((const unsigned*)((const char*)(gbase) + (voff)[_i]), (PG8_LAS unsigned*)(lds + (bufoff) + ldsw + _i * 8192), 16, 0, 0); } while (0)
; #define PG8_LDA(dst, b, h) do { _Pragma("unroll") for (int m = 0; m < 4; ++m) _Pragma("unroll") for (int k = 0; k < 2; ++k) dst[m][k] = *(const PG8_LAS bf16x8*)(lds + PG8_SA(b, h) + aoff + m * 2048 + k * 1024); } while (0)
; #define PG8_LDB(dst, b, h) do { _Pragma("unroll") for (int n = 0; n < 2; ++n) _Pragma("unroll") for (int k = 0; k < 2; ++k) dst[n][k] = *(const PG8_LAS bf16x8*)(lds + PG8_SB(b, h) + boff + n * 2048 + k * 1024); } while (0)
; #define PG8_MMA(ai, bj, At, Bt) do { __builtin_amdgcn_s_setprio(1); _Pragma("unroll") for (int m = 0; m < 4; ++m) _Pragma("unroll") for (int n = 0; n < 2; ++n) _Pragma("unroll") for (int k = 0; k < 2; ++k) \
;         acc[ai][bj][m][n] = __builtin_amdgcn_mfma_f32_16x16x32_bf16(Bt[n][k], At[m][k], acc[ai][bj][m][n], 0, 0, 0); __builtin_amdgcn_s_setprio(0); } while (0)
; #define PG8_WAIT_V(n) asm volatile("s_waitcnt vmcnt(" #n ")" ::: "memory")
; #define PG8_WAIT_L(n) asm volatile("s_waitcnt lgkmcnt(" #n ")" ::: "memory")
; #define PG8_BAR __builtin_amdgcn_s_barrier()
; #define PG8_SCHED __builtin_amdgcn_sched_barrier(0)
; template <class Epi, class Sched, bool ALIGN_EPI = false, bool SP2 = false>
; __device__ __forceinline__ void gemm_phase(PG8_LAS unsigned char* lds, const Gemm g, const Sched& S, const Epi& E, const int tid) {
;     ...
;             PG8_LDA(At, 0, 1); PG8_STAGE(PG8_SB(0, 0), b2, voffB); PG8_STAGE(PG8_SB(0, 1), b2 + hstep, voffB); PG8_STAGE(PG8_SA(0, 0), a2, voffA);
;             PG8_WAIT_V(8); PG8_WAIT_L(0); PG8_BAR; PG8_MMA(1, 0, At, B0); PG8_MMA(1, 1, At, B1); PG8_BAR; PG8_SCHED;
;             PG8_LDB(B0, 1, 0); PG8_LDB(B1, 1, 1); PG8_SCHED; PG8_LDA(At, 1, 0); PG8_STAGE(PG8_SA(0, 1), a2 + hstep, voffA);
	s_add_i32 s15, s66, s54
	v_lshl_add_u64 v[194:195], s[40:41], 0, v[164:165]
	s_mov_b32 m0, s15
	ds_read_b128 v[186:189], v197 offset:16384
	ds_read_b128 v[198:201], v197 offset:17408
	ds_read_b128 v[206:209], v197 offset:18432
	ds_read_b128 v[212:215], v197 offset:19456
	ds_read_b128 v[216:219], v197 offset:20480
	ds_read_b128 v[220:223], v197 offset:21504
	ds_read_b128 v[224:227], v197 offset:22528
	ds_read_b128 v[228:231], v197 offset:23552
	global_load_lds_dwordx4 v[194:195], off
	s_add_i32 m0, s15, 0x2000
	s_add_u32 s18, s40, 0x40000
	v_lshl_add_u64 v[232:233], s[40:41], 0, v[168:169]
	s_addc_u32 s19, s41, 0
	s_add_i32 s15, s67, s54
	global_load_lds_dwordx4 v[232:233], off
	v_lshl_add_u64 v[234:235], s[18:19], 0, v[164:165]
	s_mov_b32 m0, s15
	v_lshl_add_u64 v[236:237], s[42:43], 0, v[166:167]
	global_load_lds_dwordx4 v[234:235], off
	v_lshl_add_u64 v[234:235], s[18:19], 0, v[168:169]
	s_add_i32 m0, s15, 0x2000
	s_nop 0
	global_load_lds_dwordx4 v[234:235], off
	v_lshl_add_u64 v[234:235], s[42:43], 0, v[162:163]
	s_mov_b32 m0, s55
	s_nop 0
	global_load_lds_dwordx4 v[234:235], off
	s_mov_b32 m0, s56
	s_nop 0
	global_load_lds_dwordx4 v[236:237], off
	s_waitcnt vmcnt(8)
	s_waitcnt lgkmcnt(0)
	s_barrier
	s_setprio 1
	v_mfma_f32_16x16x32_bf16 v[62:65], v[130:133], v[186:189], v[62:65]
	v_mfma_f32_16x16x32_bf16 v[58:61], v[138:141], v[186:189], v[58:61]
	v_mfma_f32_16x16x32_bf16 v[46:49], v[130:133], v[206:209], v[46:49]
	v_mfma_f32_16x16x32_bf16 v[42:45], v[138:141], v[206:209], v[42:45]
	v_mfma_f32_16x16x32_bf16 v[30:33], v[130:133], v[216:219], v[30:33]
	v_mfma_f32_16x16x32_bf16 v[26:29], v[138:141], v[216:219], v[26:29]
	v_mfma_f32_16x16x32_bf16 v[14:17], v[130:133], v[224:227], v[14:17]
	v_mfma_f32_16x16x32_bf16 v[10:13], v[138:141], v[224:227], v[10:13]
	v_mfma_f32_16x16x32_bf16 v[62:65], v[134:137], v[198:201], v[62:65]
	v_mfma_f32_16x16x32_bf16 v[58:61], v[142:145], v[198:201], v[58:61]
	v_mfma_f32_16x16x32_bf16 v[46:49], v[134:137], v[212:215], v[46:49]
	v_mfma_f32_16x16x32_bf16 v[42:45], v[142:145], v[212:215], v[42:45]
	v_mfma_f32_16x16x32_bf16 v[30:33], v[134:137], v[220:223], v[30:33]
	v_mfma_f32_16x16x32_bf16 v[26:29], v[142:145], v[220:223], v[26:29]
	v_mfma_f32_16x16x32_bf16 v[14:17], v[134:137], v[228:231], v[14:17]
	v_mfma_f32_16x16x32_bf16 v[10:13], v[142:145], v[228:231], v[10:13]
	s_setprio 0
	s_setprio 1
	v_mfma_f32_16x16x32_bf16 v[54:57], v[146:149], v[186:189], v[54:57]
	v_mfma_f32_16x16x32_bf16 v[50:53], v[154:157], v[186:189], v[50:53]
	v_mfma_f32_16x16x32_bf16 v[38:41], v[146:149], v[206:209], v[38:41]
	v_mfma_f32_16x16x32_bf16 v[34:37], v[154:157], v[206:209], v[34:37]
	v_mfma_f32_16x16x32_bf16 v[22:25], v[146:149], v[216:219], v[22:25]
	v_mfma_f32_16x16x32_bf16 v[18:21], v[154:157], v[216:219], v[18:21]
	v_mfma_f32_16x16x32_bf16 v[6:9], v[146:149], v[224:227], v[6:9]
	v_mfma_f32_16x16x32_bf16 v[2:5], v[154:157], v[224:227], v[2:5]
	v_mfma_f32_16x16x32_bf16 v[54:57], v[150:153], v[198:201], v[54:57]
	v_mfma_f32_16x16x32_bf16 v[50:53], v[158:161], v[198:201], v[50:53]
	v_mfma_f32_16x16x32_bf16 v[38:41], v[150:153], v[212:215], v[38:41]
	v_mfma_f32_16x16x32_bf16 v[34:37], v[158:161], v[212:215], v[34:37]
	v_mfma_f32_16x16x32_bf16 v[22:25], v[150:153], v[220:223], v[22:25]
	v_mfma_f32_16x16x32_bf16 v[18:21], v[158:161], v[220:223], v[18:21]
	v_mfma_f32_16x16x32_bf16 v[6:9], v[150:153], v[228:231], v[6:9]
	v_mfma_f32_16x16x32_bf16 v[2:5], v[158:161], v[228:231], v[2:5]
	s_setprio 0
	s_barrier
	s_add_i32 s15, 0, 0x18000
	s_add_i32 s83, 0, 0x1c000
	v_add_u32_e32 v142, s15, v173
	v_add_u32_e32 v158, s83, v173
	ds_read_b128 v[130:133], v142
	ds_read_b128 v[134:137], v142 offset:1024
	ds_read_b128 v[138:141], v142 offset:2048
	ds_read_b128 v[142:145], v142 offset:3072
	ds_read_b128 v[146:149], v158
	ds_read_b128 v[150:153], v158 offset:1024
	ds_read_b128 v[154:157], v158 offset:2048
	ds_read_b128 v[158:161], v158 offset:3072
	s_add_u32 s18, s42, 0x40000
	s_addc_u32 s19, s43, 0
	s_mov_b32 m0, s57
	v_lshl_add_u64 v[238:239], s[18:19], 0, v[162:163]
	ds_read_b128 v[186:189], v197 offset:32768
	ds_read_b128 v[198:201], v197 offset:33792
	ds_read_b128 v[206:209], v197 offset:34816
	ds_read_b128 v[212:215], v197 offset:35840
	ds_read_b128 v[216:219], v197 offset:36864
	ds_read_b128 v[220:223], v197 offset:37888
	ds_read_b128 v[224:227], v197 offset:38912
	ds_read_b128 v[228:231], v197 offset:39936
	global_load_lds_dwordx4 v[238:239], off
	v_lshl_add_u64 v[238:239], s[18:19], 0, v[166:167]
	s_mov_b32 m0, s58
	s_nop 0
	global_load_lds_dwordx4 v[238:239], off
	s_waitcnt vmcnt(8)
	s_waitcnt lgkmcnt(0)
	s_barrier
; #define PG8_STAGE(bufoff, gbase, voff) do { _Pragma("unroll") for (int _i = 0; _i < 2; ++_i) \
;         __builtin_amdgcn_global_load_lds((const unsigned*)((const char*)(gbase) + (voff)[_i]), (PG8_LAS unsigned*)(lds + (bufoff) + ldsw + _i * 8192), 16, 0, 0); } while (0)
; #define PG8_WAIT_V(n) asm volatile("s_waitcnt vmcnt(" #n ")" ::: "memory")
; #define PG8_WAIT_L(n) asm volatile("s_waitcnt lgkmcnt(" #n ")" ::: "memory")
; template <class Epi, class Sched, bool ALIGN_EPI = false, bool SP2 = false>
; __device__ __forceinline__ void gemm_phase(PG8_LAS unsigned char* lds, const Gemm g, const Sched& S, const Epi& E, const int tid) {
;     ...
;             PG8_WAIT_V(8); PG8_WAIT_L(0); PG8_BAR; PG8_MMA(0, 0, At, B0); PG8_MMA(0, 1, At, B1); PG8_BAR; PG8_SCHED;
;             PG8_LDA(At, 1, 1); PG8_STAGE(PG8_SB(1, 0), b3, voffB); PG8_STAGE(PG8_SB(1, 1), b3 + hstep, voffB); PG8_STAGE(PG8_SA(1, 0), a3, voffA);
;             PG8_WAIT_V(8); PG8_WAIT_L(0); PG8_BAR; PG8_MMA(1, 0, At, B0); PG8_MMA(1, 1, At, B1); PG8_BAR; PG8_SCHED;
;             } else {
;             PG8_LDB(B0, 0, 0); PG8_SCHED; PG8_LDA(At, 0, 0); PG8_STAGE(PG8_SA(1, 1), a1 + hstep, voffA);
;             PG8_WAIT_L(8); PG8_BAR; PG8_WAIT_L(0); PG8_MMA(0, 0, At, B0); PG8_BAR; PG8_SCHED;
;             PG8_LDB(B1, 0, 1); PG8_STAGE(PG8_SB(0, 0), b2, voffB);
;             PG8_BAR; PG8_WAIT_L(0); PG8_MMA(0, 1, At, B1); PG8_BAR;
;             PG8_LDA(At, 0, 1); PG8_STAGE(PG8_SA(0, 0), a2, voffA);
;             PG8_BAR; PG8_WAIT_L(0); PG8_MMA(1, 0, At, B0); PG8_BAR; PG8_SCHED;
;             PG8_STAGE(PG8_SB(0, 1), b2 + hstep, voffB);
;             PG8_WAIT_V(6); PG8_BAR; PG8_MMA(1, 1, At, B1); PG8_BAR;
;             PG8_LDB(B0, 1, 0); PG8_SCHED; PG8_LDA(At, 1, 0); PG8_STAGE(PG8_SA(0, 1), a2 + hstep, voffA);
;             PG8_WAIT_L(8); PG8_BAR; PG8_WAIT_L(0); PG8_MMA(0, 0, At, B0); PG8_BAR; PG8_SCHED;
;             PG8_LDB(B1, 1, 1); PG8_STAGE(PG8_SB(1, 0), b3, voffB);
;             PG8_BAR; PG8_WAIT_L(0); PG8_MMA(0, 1, At, B1); PG8_BAR;
;             PG8_LDA(At, 1, 1); PG8_STAGE(PG8_SA(1, 0), a3, voffA);
;             PG8_BAR; PG8_WAIT_L(0); PG8_MMA(1, 0, At, B0); PG8_BAR; PG8_SCHED;
;             PG8_STAGE(PG8_SB(1, 1), b3 + hstep, voffB);
;             PG8_WAIT_V(6); PG8_BAR; PG8_MMA(1, 1, At, B1); PG8_BAR;
;             }
;         }
;         if constexpr (ALIGN_EPI) { if (wr == 0) PG8_BAR; }
	s_setprio 1
	v_mfma_f32_16x16x32_bf16 v[126:129], v[130:133], v[186:189], v[126:129]
	v_mfma_f32_16x16x32_bf16 v[122:125], v[138:141], v[186:189], v[122:125]
	v_mfma_f32_16x16x32_bf16 v[110:113], v[130:133], v[206:209], v[110:113]
	v_mfma_f32_16x16x32_bf16 v[106:109], v[138:141], v[206:209], v[106:109]
	v_mfma_f32_16x16x32_bf16 v[94:97], v[130:133], v[216:219], v[94:97]
	v_mfma_f32_16x16x32_bf16 v[90:93], v[138:141], v[216:219], v[90:93]
	v_mfma_f32_16x16x32_bf16 v[78:81], v[130:133], v[224:227], v[78:81]
	v_mfma_f32_16x16x32_bf16 v[74:77], v[138:141], v[224:227], v[74:77]
	v_mfma_f32_16x16x32_bf16 v[126:129], v[134:137], v[198:201], v[126:129]
	v_mfma_f32_16x16x32_bf16 v[122:125], v[142:145], v[198:201], v[122:125]
	v_mfma_f32_16x16x32_bf16 v[110:113], v[134:137], v[212:215], v[110:113]
	v_mfma_f32_16x16x32_bf16 v[106:109], v[142:145], v[212:215], v[106:109]
	v_mfma_f32_16x16x32_bf16 v[94:97], v[134:137], v[220:223], v[94:97]
	v_mfma_f32_16x16x32_bf16 v[90:93], v[142:145], v[220:223], v[90:93]
	v_mfma_f32_16x16x32_bf16 v[78:81], v[134:137], v[228:231], v[78:81]
	v_mfma_f32_16x16x32_bf16 v[74:77], v[142:145], v[228:231], v[74:77]
	s_setprio 0
	s_setprio 1
	v_mfma_f32_16x16x32_bf16 v[118:121], v[146:149], v[186:189], v[118:121]
	v_mfma_f32_16x16x32_bf16 v[114:117], v[154:157], v[186:189], v[114:117]
	v_mfma_f32_16x16x32_bf16 v[102:105], v[146:149], v[206:209], v[102:105]
	v_mfma_f32_16x16x32_bf16 v[98:101], v[154:157], v[206:209], v[98:101]
	v_mfma_f32_16x16x32_bf16 v[86:89], v[146:149], v[216:219], v[86:89]
	v_mfma_f32_16x16x32_bf16 v[82:85], v[154:157], v[216:219], v[82:85]
	v_mfma_f32_16x16x32_bf16 v[70:73], v[146:149], v[224:227], v[70:73]
	v_mfma_f32_16x16x32_bf16 v[66:69], v[154:157], v[224:227], v[66:69]
	v_mfma_f32_16x16x32_bf16 v[118:121], v[150:153], v[198:201], v[118:121]
	v_mfma_f32_16x16x32_bf16 v[114:117], v[158:161], v[198:201], v[114:117]
	v_mfma_f32_16x16x32_bf16 v[102:105], v[150:153], v[212:215], v[102:105]
	v_mfma_f32_16x16x32_bf16 v[98:101], v[158:161], v[212:215], v[98:101]
	v_mfma_f32_16x16x32_bf16 v[86:89], v[150:153], v[220:223], v[86:89]
	v_mfma_f32_16x16x32_bf16 v[82:85], v[158:161], v[220:223], v[82:85]
	v_mfma_f32_16x16x32_bf16 v[70:73], v[150:153], v[228:231], v[70:73]
	v_mfma_f32_16x16x32_bf16 v[66:69], v[158:161], v[228:231], v[66:69]
	s_setprio 0
	s_barrier
	s_add_i32 s15, s15, s54
	v_lshl_add_u64 v[194:195], v[194:195], 0, s[10:11]
	s_mov_b32 m0, s15
	ds_read_b128 v[186:189], v197 offset:49152
	ds_read_b128 v[198:201], v197 offset:50176
	ds_read_b128 v[206:209], v197 offset:51200
	ds_read_b128 v[212:215], v197 offset:52224
	ds_read_b128 v[216:219], v197 offset:53248
	ds_read_b128 v[220:223], v197 offset:54272
	ds_read_b128 v[224:227], v197 offset:55296
	ds_read_b128 v[228:231], v197 offset:56320
	global_load_lds_dwordx4 v[194:195], off
	s_add_i32 m0, s15, 0x2000
	s_add_u32 s18, s40, 0x40080
	v_lshl_add_u64 v[194:195], v[232:233], 0, s[10:11]
	s_addc_u32 s19, s41, 0
	s_add_i32 s15, s83, s54
	global_load_lds_dwordx4 v[194:195], off
	v_lshl_add_u64 v[194:195], s[18:19], 0, v[164:165]
	s_mov_b32 m0, s15
	s_nop 0
	global_load_lds_dwordx4 v[194:195], off
	v_lshl_add_u64 v[194:195], s[18:19], 0, v[168:169]
	s_add_i32 m0, s15, 0x2000
	s_nop 0
	global_load_lds_dwordx4 v[194:195], off
	v_lshl_add_u64 v[194:195], v[234:235], 0, s[10:11]
	s_mov_b32 m0, s61
	s_nop 0
	global_load_lds_dwordx4 v[194:195], off
	v_lshl_add_u64 v[194:195], v[236:237], 0, s[10:11]
	s_mov_b32 m0, s62
	s_nop 0
	global_load_lds_dwordx4 v[194:195], off
	s_waitcnt vmcnt(8)
	s_waitcnt lgkmcnt(0)
	s_barrier
	s_setprio 1
	v_mfma_f32_16x16x32_bf16 v[62:65], v[130:133], v[186:189], v[62:65]
	v_mfma_f32_16x16x32_bf16 v[58:61], v[138:141], v[186:189], v[58:61]
	v_mfma_f32_16x16x32_bf16 v[46:49], v[130:133], v[206:209], v[46:49]
	v_mfma_f32_16x16x32_bf16 v[42:45], v[138:141], v[206:209], v[42:45]
	v_mfma_f32_16x16x32_bf16 v[30:33], v[130:133], v[216:219], v[30:33]
	v_mfma_f32_16x16x32_bf16 v[26:29], v[138:141], v[216:219], v[26:29]
	v_mfma_f32_16x16x32_bf16 v[14:17], v[130:133], v[224:227], v[14:17]
	v_mfma_f32_16x16x32_bf16 v[10:13], v[138:141], v[224:227], v[10:13]
	v_mfma_f32_16x16x32_bf16 v[62:65], v[134:137], v[198:201], v[62:65]
	v_mfma_f32_16x16x32_bf16 v[58:61], v[142:145], v[198:201], v[58:61]
	v_mfma_f32_16x16x32_bf16 v[46:49], v[134:137], v[212:215], v[46:49]
	v_mfma_f32_16x16x32_bf16 v[42:45], v[142:145], v[212:215], v[42:45]
	v_mfma_f32_16x16x32_bf16 v[30:33], v[134:137], v[220:223], v[30:33]
	v_mfma_f32_16x16x32_bf16 v[26:29], v[142:145], v[220:223], v[26:29]
	v_mfma_f32_16x16x32_bf16 v[14:17], v[134:137], v[228:231], v[14:17]
	v_mfma_f32_16x16x32_bf16 v[10:13], v[142:145], v[228:231], v[10:13]
	s_setprio 0
	s_setprio 1
	v_mfma_f32_16x16x32_bf16 v[54:57], v[146:149], v[186:189], v[54:57]
	v_mfma_f32_16x16x32_bf16 v[50:53], v[154:157], v[186:189], v[50:53]
	v_mfma_f32_16x16x32_bf16 v[38:41], v[146:149], v[206:209], v[38:41]
	v_mfma_f32_16x16x32_bf16 v[34:37], v[154:157], v[206:209], v[34:37]
	v_mfma_f32_16x16x32_bf16 v[22:25], v[146:149], v[216:219], v[22:25]
	v_mfma_f32_16x16x32_bf16 v[18:21], v[154:157], v[216:219], v[18:21]
	v_mfma_f32_16x16x32_bf16 v[6:9], v[146:149], v[224:227], v[6:9]
	v_mfma_f32_16x16x32_bf16 v[2:5], v[154:157], v[224:227], v[2:5]
	v_mfma_f32_16x16x32_bf16 v[54:57], v[150:153], v[198:201], v[54:57]
	v_mfma_f32_16x16x32_bf16 v[50:53], v[158:161], v[198:201], v[50:53]
	v_mfma_f32_16x16x32_bf16 v[38:41], v[150:153], v[212:215], v[38:41]
	v_mfma_f32_16x16x32_bf16 v[34:37], v[158:161], v[212:215], v[34:37]
	v_mfma_f32_16x16x32_bf16 v[22:25], v[150:153], v[220:223], v[22:25]
	v_mfma_f32_16x16x32_bf16 v[18:21], v[158:161], v[220:223], v[18:21]
	v_mfma_f32_16x16x32_bf16 v[6:9], v[150:153], v[228:231], v[6:9]
	v_mfma_f32_16x16x32_bf16 v[2:5], v[158:161], v[228:231], v[2:5]
	s_setprio 0
	s_barrier
	s_add_i32 s82, s82, 2
	s_add_u32 s80, s80, 0x100
	s_addc_u32 s81, s81, 0
	s_add_u32 s38, s38, 0x100
	s_addc_u32 s39, s39, 0
	s_cmp_gt_u32 s82, 13
	s_cbranch_scc0 .LBB0_733
	s_and_b64 vcc, exec, s[24:25]
	s_cbranch_vccz .LBB0_736
	s_barrier

; #define PG8_STAGE(bufoff, gbase, voff) do { _Pragma("unroll") for (int _i = 0; _i < 2; ++_i) \
;         __builtin_amdgcn_global_load_lds((const unsigned*)((const char*)(gbase) + (voff)[_i]), (PG8_LAS unsigned*)(lds + (bufoff) + ldsw + _i * 8192), 16, 0, 0); } while (0)
; #define PG8_LDA(dst, b, h) do { _Pragma("unroll") for (int m = 0; m < 4; ++m) _Pragma("unroll") for (int k = 0; k < 2; ++k) dst[m][k] = *(const PG8_LAS bf16x8*)(lds + PG8_SA(b, h) + aoff + m * 2048 + k * 1024); } while (0)
; #define PG8_LDB(dst, b, h) do { _Pragma("unroll") for (int n = 0; n < 2; ++n) _Pragma("unroll") for (int k = 0; k < 2; ++k) dst[n][k] = *(const PG8_LAS bf16x8*)(lds + PG8_SB(b, h) + boff + n * 2048 + k * 1024); } while (0)
; #define PG8_MMA(ai, bj, At, Bt) do { __builtin_amdgcn_s_setprio(1); _Pragma("unroll") for (int m = 0; m < 4; ++m) _Pragma("unroll") for (int n = 0; n < 2; ++n) _Pragma("unroll") for (int k = 0; k < 2; ++k) \
;         acc[ai][bj][m][n] = __builtin_amdgcn_mfma_f32_16x16x32_bf16(Bt[n][k], At[m][k], acc[ai][bj][m][n], 0, 0, 0); __builtin_amdgcn_s_setprio(0); } while (0)
; #define PG8_WAIT_V(n) asm volatile("s_waitcnt vmcnt(" #n ")" ::: "memory")
; #define PG8_BAR __builtin_amdgcn_s_barrier()
; template <class Epi, class Sched, bool ALIGN_EPI = false, bool SP2 = false>
; __device__ __forceinline__ void gemm_phase(PG8_LAS unsigned char* lds, const Gemm g, const Sched& S, const Epi& E, const int tid) {
;     ...
;         for (int t = 0; t < nt; t += 2) {
;             const bool last = (t == nt - 2);
;             const char* a1 = cA + (size_t)(t + 1) * kstep;
;             const char* a2 = last ? nA : cA + (size_t)(t + 2) * kstep; const char* b2 = last ? nB : cB + (size_t)(t + 2) * kstep;
;             const char* a3 = a2 + kstep; const char* b3 = b2 + kstep;
;             if (last && has_next) S.a_ready(nxt);
;             if constexpr (SP2) {
;             PG8_LDB(B0, 0, 0); PG8_LDB(B1, 0, 1); PG8_SCHED; PG8_LDA(At, 0, 0); PG8_STAGE(PG8_SA(1, 1), a1 + hstep, voffA);
;             PG8_WAIT_V(8); PG8_WAIT_L(0); PG8_BAR; PG8_MMA(0, 0, At, B0); PG8_MMA(0, 1, At, B1); PG8_BAR; PG8_SCHED;
;             PG8_LDA(At, 0, 1); PG8_STAGE(PG8_SB(0, 0), b2, voffB); PG8_STAGE(PG8_SB(0, 1), b2 + hstep, voffB); PG8_STAGE(PG8_SA(0, 0), a2, voffA);
;             PG8_WAIT_V(8); PG8_WAIT_L(0); PG8_BAR; PG8_MMA(1, 0, At, B0); PG8_MMA(1, 1, At, B1); PG8_BAR; PG8_SCHED;
.LBB0_1121:
	s_add_u32 s5, s56, 0x100
	s_addc_u32 s49, s57, 0
	s_add_u32 s56, s58, 0x40080
	s_addc_u32 s57, s59, 0
	s_mov_b32 s51, -2
	s_add_u32 s15, s56, 0xfffc0080
	s_addc_u32 s18, s57, -1
	s_cmp_eq_u32 s51, 12
	s_cselect_b32 s61, s1, s18
	s_cselect_b32 s60, s0, s15
	s_cselect_b32 s59, s53, s49
	s_cselect_b32 s58, s52, s5
	v_lshl_add_u64 v[170:171], s[56:57], 0, v[156:157]
	s_add_i32 m0, s67, 0xc000
	global_load_lds_dwordx4 v[170:171], off
	v_lshl_add_u64 v[170:171], s[56:57], 0, v[154:155]
	s_add_i32 m0, s67, 0xe000
	s_nop 0
	global_load_lds_dwordx4 v[170:171], off
	s_waitcnt vmcnt(8)
	s_waitcnt lgkmcnt(0)
	s_barrier
	s_setprio 1
	v_mfma_f32_16x16x32_bf16 v[126:129], v[130:133], v[196:199], 0
	v_mfma_f32_16x16x32_bf16 v[122:125], v[162:165], v[196:199], 0
	v_mfma_f32_16x16x32_bf16 v[110:113], v[130:133], v[204:207], 0
	v_mfma_f32_16x16x32_bf16 v[106:109], v[162:165], v[204:207], 0
	v_mfma_f32_16x16x32_bf16 v[94:97], v[130:133], v[212:215], 0
	v_mfma_f32_16x16x32_bf16 v[90:93], v[162:165], v[212:215], 0
	v_mfma_f32_16x16x32_bf16 v[78:81], v[130:133], v[220:223], 0
	v_mfma_f32_16x16x32_bf16 v[74:77], v[162:165], v[220:223], 0
	v_mfma_f32_16x16x32_bf16 v[126:129], v[134:137], v[200:203], v[126:129]
	v_mfma_f32_16x16x32_bf16 v[122:125], v[166:169], v[200:203], v[122:125]
	v_mfma_f32_16x16x32_bf16 v[110:113], v[134:137], v[208:211], v[110:113]
	v_mfma_f32_16x16x32_bf16 v[106:109], v[166:169], v[208:211], v[106:109]
	v_mfma_f32_16x16x32_bf16 v[94:97], v[134:137], v[216:219], v[94:97]
	v_mfma_f32_16x16x32_bf16 v[90:93], v[166:169], v[216:219], v[90:93]
	v_mfma_f32_16x16x32_bf16 v[78:81], v[134:137], v[224:227], v[78:81]
	v_mfma_f32_16x16x32_bf16 v[74:77], v[166:169], v[224:227], v[74:77]
	s_setprio 0
	s_setprio 1
	v_mfma_f32_16x16x32_bf16 v[118:121], v[176:179], v[196:199], 0
	v_mfma_f32_16x16x32_bf16 v[114:117], v[184:187], v[196:199], 0
	v_mfma_f32_16x16x32_bf16 v[102:105], v[176:179], v[204:207], 0
	v_mfma_f32_16x16x32_bf16 v[98:101], v[184:187], v[204:207], 0
	v_mfma_f32_16x16x32_bf16 v[86:89], v[176:179], v[212:215], 0
	v_mfma_f32_16x16x32_bf16 v[82:85], v[184:187], v[212:215], 0
	v_mfma_f32_16x16x32_bf16 v[70:73], v[176:179], v[220:223], 0
	v_mfma_f32_16x16x32_bf16 v[66:69], v[184:187], v[220:223], 0
	v_mfma_f32_16x16x32_bf16 v[118:121], v[180:183], v[200:203], v[118:121]
	v_mfma_f32_16x16x32_bf16 v[114:117], v[192:195], v[200:203], v[114:117]
	v_mfma_f32_16x16x32_bf16 v[102:105], v[180:183], v[208:211], v[102:105]
	v_mfma_f32_16x16x32_bf16 v[98:101], v[192:195], v[208:211], v[98:101]
	v_mfma_f32_16x16x32_bf16 v[86:89], v[180:183], v[216:219], v[86:89]
	v_mfma_f32_16x16x32_bf16 v[82:85], v[192:195], v[216:219], v[82:85]
	v_mfma_f32_16x16x32_bf16 v[70:73], v[180:183], v[224:227], v[70:73]
	v_mfma_f32_16x16x32_bf16 v[66:69], v[192:195], v[224:227], v[66:69]
	s_setprio 0
	s_barrier
	s_add_i32 s15, s86, s66
	v_lshl_add_u64 v[170:171], s[58:59], 0, v[142:143]
	s_mov_b32 m0, s15
	ds_read_b128 v[196:199], v174 offset:16384
	ds_read_b128 v[200:203], v174 offset:17408
	ds_read_b128 v[204:207], v174 offset:18432
	ds_read_b128 v[208:211], v174 offset:19456
	ds_read_b128 v[212:215], v174 offset:20480
	ds_read_b128 v[216:219], v174 offset:21504
	ds_read_b128 v[220:223], v174 offset:22528
	ds_read_b128 v[224:227], v174 offset:23552
	global_load_lds_dwordx4 v[170:171], off
	s_add_i32 m0, s15, 0x2000
	s_add_u32 s18, s58, 0x40000
	v_lshl_add_u64 v[188:189], s[58:59], 0, v[146:147]
	s_addc_u32 s19, s59, 0
	s_add_i32 s15, s87, s66
	global_load_lds_dwordx4 v[188:189], off
	v_lshl_add_u64 v[228:229], s[18:19], 0, v[142:143]
	s_mov_b32 m0, s15
	v_lshl_add_u64 v[230:231], s[60:61], 0, v[144:145]
	global_load_lds_dwordx4 v[228:229], off
	v_lshl_add_u64 v[228:229], s[18:19], 0, v[146:147]
	s_add_i32 m0, s15, 0x2000
	s_nop 0
	global_load_lds_dwordx4 v[228:229], off
	v_lshl_add_u64 v[228:229], s[60:61], 0, v[140:141]
	s_mov_b32 m0, s67
	s_nop 0
	global_load_lds_dwordx4 v[228:229], off
	s_mov_b32 m0, s68
	s_nop 0
	global_load_lds_dwordx4 v[230:231], off
	s_waitcnt vmcnt(8)
	s_waitcnt lgkmcnt(0)
	s_barrier
	s_setprio 1
	v_mfma_f32_16x16x32_bf16 v[62:65], v[130:133], v[196:199], 0
	v_mfma_f32_16x16x32_bf16 v[58:61], v[162:165], v[196:199], 0
	v_mfma_f32_16x16x32_bf16 v[46:49], v[130:133], v[204:207], 0
	v_mfma_f32_16x16x32_bf16 v[42:45], v[162:165], v[204:207], 0
	v_mfma_f32_16x16x32_bf16 v[30:33], v[130:133], v[212:215], 0
	v_mfma_f32_16x16x32_bf16 v[26:29], v[162:165], v[212:215], 0
	v_mfma_f32_16x16x32_bf16 v[14:17], v[130:133], v[220:223], 0
	v_mfma_f32_16x16x32_bf16 v[10:13], v[162:165], v[220:223], 0
	v_mfma_f32_16x16x32_bf16 v[62:65], v[134:137], v[200:203], v[62:65]
	v_mfma_f32_16x16x32_bf16 v[58:61], v[166:169], v[200:203], v[58:61]
	v_mfma_f32_16x16x32_bf16 v[46:49], v[134:137], v[208:211], v[46:49]
	v_mfma_f32_16x16x32_bf16 v[42:45], v[166:169], v[208:211], v[42:45]
	v_mfma_f32_16x16x32_bf16 v[30:33], v[134:137], v[216:219], v[30:33]
	v_mfma_f32_16x16x32_bf16 v[26:29], v[166:169], v[216:219], v[26:29]
	v_mfma_f32_16x16x32_bf16 v[14:17], v[134:137], v[224:227], v[14:17]
	v_mfma_f32_16x16x32_bf16 v[10:13], v[166:169], v[224:227], v[10:13]
	s_setprio 0
	s_setprio 1
	v_mfma_f32_16x16x32_bf16 v[54:57], v[176:179], v[196:199], 0
	v_mfma_f32_16x16x32_bf16 v[50:53], v[184:187], v[196:199], 0
	v_mfma_f32_16x16x32_bf16 v[38:41], v[176:179], v[204:207], 0
	v_mfma_f32_16x16x32_bf16 v[34:37], v[184:187], v[204:207], 0
	v_mfma_f32_16x16x32_bf16 v[22:25], v[176:179], v[212:215], 0
	v_mfma_f32_16x16x32_bf16 v[18:21], v[184:187], v[212:215], 0
	v_mfma_f32_16x16x32_bf16 v[6:9], v[176:179], v[220:223], 0
	v_mfma_f32_16x16x32_bf16 v[2:5], v[184:187], v[220:223], 0
	v_mfma_f32_16x16x32_bf16 v[54:57], v[180:183], v[200:203], v[54:57]
	v_mfma_f32_16x16x32_bf16 v[50:53], v[192:195], v[200:203], v[50:53]
	v_mfma_f32_16x16x32_bf16 v[38:41], v[180:183], v[208:211], v[38:41]
	v_mfma_f32_16x16x32_bf16 v[34:37], v[192:195], v[208:211], v[34:37]
	v_mfma_f32_16x16x32_bf16 v[22:25], v[180:183], v[216:219], v[22:25]
	v_mfma_f32_16x16x32_bf16 v[18:21], v[192:195], v[216:219], v[18:21]
	v_mfma_f32_16x16x32_bf16 v[6:9], v[180:183], v[224:227], v[6:9]
	v_mfma_f32_16x16x32_bf16 v[2:5], v[192:195], v[224:227], v[2:5]
	s_setprio 0
	s_barrier
; #define PG8_STAGE(bufoff, gbase, voff) do { _Pragma("unroll") for (int _i = 0; _i < 2; ++_i) \
;         __builtin_amdgcn_global_load_lds((const unsigned*)((const char*)(gbase) + (voff)[_i]), (PG8_LAS unsigned*)(lds + (bufoff) + ldsw + _i * 8192), 16, 0, 0); } while (0)
; #define PG8_LDA(dst, b, h) do { _Pragma("unroll") for (int m = 0; m < 4; ++m) _Pragma("unroll") for (int k = 0; k < 2; ++k) dst[m][k] = *(const PG8_LAS bf16x8*)(lds + PG8_SA(b, h) + aoff + m * 2048 + k * 1024); } while (0)
; #define PG8_LDB(dst, b, h) do { _Pragma("unroll") for (int n = 0; n < 2; ++n) _Pragma("unroll") for (int k = 0; k < 2; ++k) dst[n][k] = *(const PG8_LAS bf16x8*)(lds + PG8_SB(b, h) + boff + n * 2048 + k * 1024); } while (0)
; #define PG8_MMA(ai, bj, At, Bt) do { __builtin_amdgcn_s_setprio(1); _Pragma("unroll") for (int m = 0; m < 4; ++m) _Pragma("unroll") for (int n = 0; n < 2; ++n) _Pragma("unroll") for (int k = 0; k < 2; ++k) \
;         acc[ai][bj][m][n] = __builtin_amdgcn_mfma_f32_16x16x32_bf16(Bt[n][k], At[m][k], acc[ai][bj][m][n], 0, 0, 0); __builtin_amdgcn_s_setprio(0); } while (0)
; #define PG8_WAIT_V(n) asm volatile("s_waitcnt vmcnt(" #n ")" ::: "memory")
; #define PG8_WAIT_L(n) asm volatile("s_waitcnt lgkmcnt(" #n ")" ::: "memory")
; #define PG8_BAR __builtin_amdgcn_s_barrier()
; #define PG8_SCHED __builtin_amdgcn_sched_barrier(0)
; template <class Epi, class Sched, bool ALIGN_EPI = false, bool SP2 = false>
; __device__ __forceinline__ void gemm_phase(PG8_LAS unsigned char* lds, const Gemm g, const Sched& S, const Epi& E, const int tid) {
;     ...
;             PG8_LDB(B0, 1, 0); PG8_LDB(B1, 1, 1); PG8_SCHED; PG8_LDA(At, 1, 0); PG8_STAGE(PG8_SA(0, 1), a2 + hstep, voffA);
;             PG8_WAIT_V(8); PG8_WAIT_L(0); PG8_BAR; PG8_MMA(0, 0, At, B0); PG8_MMA(0, 1, At, B1); PG8_BAR; PG8_SCHED;
;             PG8_LDA(At, 1, 1); PG8_STAGE(PG8_SB(1, 0), b3, voffB); PG8_STAGE(PG8_SB(1, 1), b3 + hstep, voffB); PG8_STAGE(PG8_SA(1, 0), a3, voffA);
	s_add_i32 s15, 0, 0x18000
	s_add_i32 s62, 0, 0x1c000
	v_add_u32_e32 v166, s15, v172
	v_add_u32_e32 v191, s62, v172
	ds_read_b128 v[130:133], v166
	ds_read_b128 v[134:137], v166 offset:1024
	ds_read_b128 v[162:165], v166 offset:2048
	ds_read_b128 v[166:169], v166 offset:3072
	ds_read_b128 v[176:179], v191
	ds_read_b128 v[180:183], v191 offset:1024
	ds_read_b128 v[184:187], v191 offset:2048
	ds_read_b128 v[192:195], v191 offset:3072
	s_add_u32 s18, s60, 0x40000
	s_addc_u32 s19, s61, 0
	s_mov_b32 m0, s69
	v_lshl_add_u64 v[232:233], s[18:19], 0, v[140:141]
	ds_read_b128 v[196:199], v174 offset:32768
	ds_read_b128 v[200:203], v174 offset:33792
	ds_read_b128 v[204:207], v174 offset:34816
	ds_read_b128 v[208:211], v174 offset:35840
	ds_read_b128 v[212:215], v174 offset:36864
	ds_read_b128 v[216:219], v174 offset:37888
	ds_read_b128 v[220:223], v174 offset:38912
	ds_read_b128 v[224:227], v174 offset:39936
	global_load_lds_dwordx4 v[232:233], off
	v_lshl_add_u64 v[232:233], s[18:19], 0, v[144:145]
	s_mov_b32 m0, s71
	s_nop 0
	global_load_lds_dwordx4 v[232:233], off
	s_waitcnt vmcnt(8)
	s_waitcnt lgkmcnt(0)
	s_barrier
	s_setprio 1
	v_mfma_f32_16x16x32_bf16 v[126:129], v[130:133], v[196:199], v[126:129]
	v_mfma_f32_16x16x32_bf16 v[122:125], v[162:165], v[196:199], v[122:125]
	v_mfma_f32_16x16x32_bf16 v[110:113], v[130:133], v[204:207], v[110:113]
	v_mfma_f32_16x16x32_bf16 v[106:109], v[162:165], v[204:207], v[106:109]
	v_mfma_f32_16x16x32_bf16 v[94:97], v[130:133], v[212:215], v[94:97]
	v_mfma_f32_16x16x32_bf16 v[90:93], v[162:165], v[212:215], v[90:93]
	v_mfma_f32_16x16x32_bf16 v[78:81], v[130:133], v[220:223], v[78:81]
	v_mfma_f32_16x16x32_bf16 v[74:77], v[162:165], v[220:223], v[74:77]
	v_mfma_f32_16x16x32_bf16 v[126:129], v[134:137], v[200:203], v[126:129]
	v_mfma_f32_16x16x32_bf16 v[122:125], v[166:169], v[200:203], v[122:125]
	v_mfma_f32_16x16x32_bf16 v[110:113], v[134:137], v[208:211], v[110:113]
	v_mfma_f32_16x16x32_bf16 v[106:109], v[166:169], v[208:211], v[106:109]
	v_mfma_f32_16x16x32_bf16 v[94:97], v[134:137], v[216:219], v[94:97]
	v_mfma_f32_16x16x32_bf16 v[90:93], v[166:169], v[216:219], v[90:93]
	v_mfma_f32_16x16x32_bf16 v[78:81], v[134:137], v[224:227], v[78:81]
	v_mfma_f32_16x16x32_bf16 v[74:77], v[166:169], v[224:227], v[74:77]
	s_setprio 0
	s_setprio 1
	v_mfma_f32_16x16x32_bf16 v[118:121], v[176:179], v[196:199], v[118:121]
	v_mfma_f32_16x16x32_bf16 v[114:117], v[184:187], v[196:199], v[114:117]
	v_mfma_f32_16x16x32_bf16 v[102:105], v[176:179], v[204:207], v[102:105]
	v_mfma_f32_16x16x32_bf16 v[98:101], v[184:187], v[204:207], v[98:101]
	v_mfma_f32_16x16x32_bf16 v[86:89], v[176:179], v[212:215], v[86:89]
	v_mfma_f32_16x16x32_bf16 v[82:85], v[184:187], v[212:215], v[82:85]
	v_mfma_f32_16x16x32_bf16 v[70:73], v[176:179], v[220:223], v[70:73]
	v_mfma_f32_16x16x32_bf16 v[66:69], v[184:187], v[220:223], v[66:69]
	v_mfma_f32_16x16x32_bf16 v[118:121], v[180:183], v[200:203], v[118:121]
	v_mfma_f32_16x16x32_bf16 v[114:117], v[192:195], v[200:203], v[114:117]
	v_mfma_f32_16x16x32_bf16 v[102:105], v[180:183], v[208:211], v[102:105]
	v_mfma_f32_16x16x32_bf16 v[98:101], v[192:195], v[208:211], v[98:101]
	v_mfma_f32_16x16x32_bf16 v[86:89], v[180:183], v[216:219], v[86:89]
	v_mfma_f32_16x16x32_bf16 v[82:85], v[192:195], v[216:219], v[82:85]
	v_mfma_f32_16x16x32_bf16 v[70:73], v[180:183], v[224:227], v[70:73]
	v_mfma_f32_16x16x32_bf16 v[66:69], v[192:195], v[224:227], v[66:69]
	s_setprio 0
	s_barrier
	s_add_i32 s15, s15, s66
	v_lshl_add_u64 v[170:171], v[170:171], 0, s[44:45]
	s_mov_b32 m0, s15
	ds_read_b128 v[196:199], v174 offset:49152
	ds_read_b128 v[200:203], v174 offset:50176
	ds_read_b128 v[204:207], v174 offset:51200
	ds_read_b128 v[208:211], v174 offset:52224
	ds_read_b128 v[212:215], v174 offset:53248
	ds_read_b128 v[216:219], v174 offset:54272
	ds_read_b128 v[220:223], v174 offset:55296
	ds_read_b128 v[224:227], v174 offset:56320
	global_load_lds_dwordx4 v[170:171], off
	s_add_i32 m0, s15, 0x2000
	s_add_u32 s18, s58, 0x40080
	v_lshl_add_u64 v[170:171], v[188:189], 0, s[44:45]
	s_addc_u32 s19, s59, 0
	s_add_i32 s15, s62, s66
	global_load_lds_dwordx4 v[170:171], off
	v_lshl_add_u64 v[170:171], s[18:19], 0, v[142:143]
	s_mov_b32 m0, s15
	s_nop 0
	global_load_lds_dwordx4 v[170:171], off
	v_lshl_add_u64 v[170:171], s[18:19], 0, v[146:147]
	s_add_i32 m0, s15, 0x2000
	s_nop 0
	global_load_lds_dwordx4 v[170:171], off
	v_lshl_add_u64 v[170:171], v[228:229], 0, s[44:45]
	s_mov_b32 m0, s77
	s_nop 0
	global_load_lds_dwordx4 v[170:171], off
	v_lshl_add_u64 v[170:171], v[230:231], 0, s[44:45]
	s_mov_b32 m0, s78
	s_nop 0
	global_load_lds_dwordx4 v[170:171], off
	s_waitcnt vmcnt(8)
	s_waitcnt lgkmcnt(0)
	s_barrier
; #define PG8_STAGE(bufoff, gbase, voff) do { _Pragma("unroll") for (int _i = 0; _i < 2; ++_i) \
;         __builtin_amdgcn_global_load_lds((const unsigned*)((const char*)(gbase) + (voff)[_i]), (PG8_LAS unsigned*)(lds + (bufoff) + ldsw + _i * 8192), 16, 0, 0); } while (0)
; #define PG8_LDA(dst, b, h) do { _Pragma("unroll") for (int m = 0; m < 4; ++m) _Pragma("unroll") for (int k = 0; k < 2; ++k) dst[m][k] = *(const PG8_LAS bf16x8*)(lds + PG8_SA(b, h) + aoff + m * 2048 + k * 1024); } while (0)
; #define PG8_LDB(dst, b, h) do { _Pragma("unroll") for (int n = 0; n < 2; ++n) _Pragma("unroll") for (int k = 0; k < 2; ++k) dst[n][k] = *(const PG8_LAS bf16x8*)(lds + PG8_SB(b, h) + boff + n * 2048 + k * 1024); } while (0)
; #define PG8_MMA(ai, bj, At, Bt) do { __builtin_amdgcn_s_setprio(1); _Pragma("unroll") for (int m = 0; m < 4; ++m) _Pragma("unroll") for (int n = 0; n < 2; ++n) _Pragma("unroll") for (int k = 0; k < 2; ++k) \
;         acc[ai][bj][m][n] = __builtin_amdgcn_mfma_f32_16x16x32_bf16(Bt[n][k], At[m][k], acc[ai][bj][m][n], 0, 0, 0); __builtin_amdgcn_s_setprio(0); } while (0)
; #define PG8_BAR __builtin_amdgcn_s_barrier()
; template <class Epi, class Sched, bool ALIGN_EPI = false, bool SP2 = false>
; __device__ __forceinline__ void gemm_phase(PG8_LAS unsigned char* lds, const Gemm g, const Sched& S, const Epi& E, const int tid) {
;     ...
;             PG8_LDB(B0, 0, 0); PG8_LDB(B1, 0, 1); PG8_SCHED; PG8_LDA(At, 0, 0); PG8_STAGE(PG8_SA(1, 1), a1 + hstep, voffA);
;             PG8_WAIT_V(8); PG8_WAIT_L(0); PG8_BAR; PG8_MMA(0, 0, At, B0); PG8_MMA(0, 1, At, B1); PG8_BAR; PG8_SCHED;
;             PG8_LDA(At, 0, 1); PG8_STAGE(PG8_SB(0, 0), b2, voffB); PG8_STAGE(PG8_SB(0, 1), b2 + hstep, voffB); PG8_STAGE(PG8_SA(0, 0), a2, voffA);
;             PG8_WAIT_V(8); PG8_WAIT_L(0); PG8_BAR; PG8_MMA(1, 0, At, B0); PG8_MMA(1, 1, At, B1); PG8_BAR; PG8_SCHED;
;             PG8_LDB(B0, 1, 0); PG8_LDB(B1, 1, 1); PG8_SCHED; PG8_LDA(At, 1, 0); PG8_STAGE(PG8_SA(0, 1), a2 + hstep, voffA);
;             PG8_WAIT_V(8); PG8_WAIT_L(0); PG8_BAR; PG8_MMA(0, 0, At, B0); PG8_MMA(0, 1, At, B1); PG8_BAR; PG8_SCHED;
;             PG8_LDA(At, 1, 1); PG8_STAGE(PG8_SB(1, 0), b3, voffB); PG8_STAGE(PG8_SB(1, 1), b3 + hstep, voffB); PG8_STAGE(PG8_SA(1, 0), a3, voffA);
;             PG8_WAIT_V(8); PG8_WAIT_L(0); PG8_BAR; PG8_MMA(1, 0, At, B0); PG8_MMA(1, 1, At, B1); PG8_BAR; PG8_SCHED;
	s_setprio 1
	v_mfma_f32_16x16x32_bf16 v[62:65], v[130:133], v[196:199], v[62:65]
	v_mfma_f32_16x16x32_bf16 v[58:61], v[162:165], v[196:199], v[58:61]
	v_mfma_f32_16x16x32_bf16 v[46:49], v[130:133], v[204:207], v[46:49]
	v_mfma_f32_16x16x32_bf16 v[42:45], v[162:165], v[204:207], v[42:45]
	v_mfma_f32_16x16x32_bf16 v[30:33], v[130:133], v[212:215], v[30:33]
	v_mfma_f32_16x16x32_bf16 v[26:29], v[162:165], v[212:215], v[26:29]
	v_mfma_f32_16x16x32_bf16 v[14:17], v[130:133], v[220:223], v[14:17]
	v_mfma_f32_16x16x32_bf16 v[10:13], v[162:165], v[220:223], v[10:13]
	v_mfma_f32_16x16x32_bf16 v[62:65], v[134:137], v[200:203], v[62:65]
	v_mfma_f32_16x16x32_bf16 v[58:61], v[166:169], v[200:203], v[58:61]
	v_mfma_f32_16x16x32_bf16 v[46:49], v[134:137], v[208:211], v[46:49]
	v_mfma_f32_16x16x32_bf16 v[42:45], v[166:169], v[208:211], v[42:45]
	v_mfma_f32_16x16x32_bf16 v[30:33], v[134:137], v[216:219], v[30:33]
	v_mfma_f32_16x16x32_bf16 v[26:29], v[166:169], v[216:219], v[26:29]
	v_mfma_f32_16x16x32_bf16 v[14:17], v[134:137], v[224:227], v[14:17]
	v_mfma_f32_16x16x32_bf16 v[10:13], v[166:169], v[224:227], v[10:13]
	s_setprio 0
	s_setprio 1
	v_mfma_f32_16x16x32_bf16 v[54:57], v[176:179], v[196:199], v[54:57]
	v_mfma_f32_16x16x32_bf16 v[50:53], v[184:187], v[196:199], v[50:53]
	v_mfma_f32_16x16x32_bf16 v[38:41], v[176:179], v[204:207], v[38:41]
	v_mfma_f32_16x16x32_bf16 v[34:37], v[184:187], v[204:207], v[34:37]
	v_mfma_f32_16x16x32_bf16 v[22:25], v[176:179], v[212:215], v[22:25]
	v_mfma_f32_16x16x32_bf16 v[18:21], v[184:187], v[212:215], v[18:21]
	v_mfma_f32_16x16x32_bf16 v[6:9], v[176:179], v[220:223], v[6:9]
	v_mfma_f32_16x16x32_bf16 v[2:5], v[184:187], v[220:223], v[2:5]
	v_mfma_f32_16x16x32_bf16 v[54:57], v[180:183], v[200:203], v[54:57]
	v_mfma_f32_16x16x32_bf16 v[50:53], v[192:195], v[200:203], v[50:53]
	v_mfma_f32_16x16x32_bf16 v[38:41], v[180:183], v[208:211], v[38:41]
	v_mfma_f32_16x16x32_bf16 v[34:37], v[192:195], v[208:211], v[34:37]
	v_mfma_f32_16x16x32_bf16 v[22:25], v[180:183], v[216:219], v[22:25]
	v_mfma_f32_16x16x32_bf16 v[18:21], v[192:195], v[216:219], v[18:21]
	v_mfma_f32_16x16x32_bf16 v[6:9], v[180:183], v[224:227], v[6:9]
	v_mfma_f32_16x16x32_bf16 v[2:5], v[192:195], v[224:227], v[2:5]
	s_setprio 0
	s_barrier
	s_add_i32 s51, s51, 2
	s_add_u32 s5, s5, 0x100
	s_addc_u32 s49, s49, 0
	s_add_u32 s56, s56, 0x100
	s_addc_u32 s57, s57, 0
.LBB0_1122:
	ds_read_b128 v[130:133], v139
	ds_read_b128 v[134:137], v139 offset:1024
	ds_read_b128 v[162:165], v139 offset:2048
	ds_read_b128 v[166:169], v139 offset:3072
	ds_read_b128 v[176:179], v173
	ds_read_b128 v[180:183], v173 offset:1024
	ds_read_b128 v[184:187], v173 offset:2048
	ds_read_b128 v[192:195], v173 offset:3072
	s_add_u32 s15, s56, 0xfffc0080
	s_addc_u32 s18, s57, -1
	s_cmp_eq_u32 s51, 12
	s_cselect_b32 s61, s1, s18
	s_cselect_b32 s60, s0, s15
	s_cselect_b32 s59, s53, s49
	s_cselect_b32 s58, s52, s5
	v_lshl_add_u64 v[170:171], s[56:57], 0, v[156:157]
	s_add_i32 m0, s67, 0xc000
	ds_read_b128 v[196:199], v174
	ds_read_b128 v[200:203], v174 offset:1024
	ds_read_b128 v[204:207], v174 offset:2048
	ds_read_b128 v[208:211], v174 offset:3072
	ds_read_b128 v[212:215], v174 offset:4096
	ds_read_b128 v[216:219], v174 offset:5120
	ds_read_b128 v[220:223], v174 offset:6144
	ds_read_b128 v[224:227], v174 offset:7168
	global_load_lds_dwordx4 v[170:171], off
	v_lshl_add_u64 v[170:171], s[56:57], 0, v[154:155]
	s_add_i32 m0, s67, 0xe000
	s_nop 0
	global_load_lds_dwordx4 v[170:171], off
	s_waitcnt vmcnt(8)
	s_waitcnt lgkmcnt(0)
	s_barrier
	s_setprio 1
	v_mfma_f32_16x16x32_bf16 v[126:129], v[130:133], v[196:199], v[126:129]
	v_mfma_f32_16x16x32_bf16 v[122:125], v[162:165], v[196:199], v[122:125]
	v_mfma_f32_16x16x32_bf16 v[110:113], v[130:133], v[204:207], v[110:113]
	v_mfma_f32_16x16x32_bf16 v[106:109], v[162:165], v[204:207], v[106:109]
	v_mfma_f32_16x16x32_bf16 v[94:97], v[130:133], v[212:215], v[94:97]
	v_mfma_f32_16x16x32_bf16 v[90:93], v[162:165], v[212:215], v[90:93]
	v_mfma_f32_16x16x32_bf16 v[78:81], v[130:133], v[220:223], v[78:81]
	v_mfma_f32_16x16x32_bf16 v[74:77], v[162:165], v[220:223], v[74:77]
	v_mfma_f32_16x16x32_bf16 v[126:129], v[134:137], v[200:203], v[126:129]
	v_mfma_f32_16x16x32_bf16 v[122:125], v[166:169], v[200:203], v[122:125]
	v_mfma_f32_16x16x32_bf16 v[110:113], v[134:137], v[208:211], v[110:113]
	v_mfma_f32_16x16x32_bf16 v[106:109], v[166:169], v[208:211], v[106:109]
	v_mfma_f32_16x16x32_bf16 v[94:97], v[134:137], v[216:219], v[94:97]
	v_mfma_f32_16x16x32_bf16 v[90:93], v[166:169], v[216:219], v[90:93]
	v_mfma_f32_16x16x32_bf16 v[78:81], v[134:137], v[224:227], v[78:81]
	v_mfma_f32_16x16x32_bf16 v[74:77], v[166:169], v[224:227], v[74:77]
	s_setprio 0
	s_setprio 1
	v_mfma_f32_16x16x32_bf16 v[118:121], v[176:179], v[196:199], v[118:121]
	v_mfma_f32_16x16x32_bf16 v[114:117], v[184:187], v[196:199], v[114:117]
	v_mfma_f32_16x16x32_bf16 v[102:105], v[176:179], v[204:207], v[102:105]
	v_mfma_f32_16x16x32_bf16 v[98:101], v[184:187], v[204:207], v[98:101]
	v_mfma_f32_16x16x32_bf16 v[86:89], v[176:179], v[212:215], v[86:89]
	v_mfma_f32_16x16x32_bf16 v[82:85], v[184:187], v[212:215], v[82:85]
	v_mfma_f32_16x16x32_bf16 v[70:73], v[176:179], v[220:223], v[70:73]
	v_mfma_f32_16x16x32_bf16 v[66:69], v[184:187], v[220:223], v[66:69]
	v_mfma_f32_16x16x32_bf16 v[118:121], v[180:183], v[200:203], v[118:121]
	v_mfma_f32_16x16x32_bf16 v[114:117], v[192:195], v[200:203], v[114:117]
	v_mfma_f32_16x16x32_bf16 v[102:105], v[180:183], v[208:211], v[102:105]
	v_mfma_f32_16x16x32_bf16 v[98:101], v[192:195], v[208:211], v[98:101]
	v_mfma_f32_16x16x32_bf16 v[86:89], v[180:183], v[216:219], v[86:89]
	v_mfma_f32_16x16x32_bf16 v[82:85], v[192:195], v[216:219], v[82:85]
	v_mfma_f32_16x16x32_bf16 v[70:73], v[180:183], v[224:227], v[70:73]
	v_mfma_f32_16x16x32_bf16 v[66:69], v[192:195], v[224:227], v[66:69]
	s_setprio 0
	s_barrier
; #define PG8_STAGE(bufoff, gbase, voff) do { _Pragma("unroll") for (int _i = 0; _i < 2; ++_i) \
;         __builtin_amdgcn_global_load_lds((const unsigned*)((const char*)(gbase) + (voff)[_i]), (PG8_LAS unsigned*)(lds + (bufoff) + ldsw + _i * 8192), 16, 0, 0); } while (0)
; #define PG8_LDA(dst, b, h) do { _Pragma("unroll") for (int m = 0; m < 4; ++m) _Pragma("unroll") for (int k = 0; k < 2; ++k) dst[m][k] = *(const PG8_LAS bf16x8*)(lds + PG8_SA(b, h) + aoff + m * 2048 + k * 1024); } while (0)
; #define PG8_LDB(dst, b, h) do { _Pragma("unroll") for (int n = 0; n < 2; ++n) _Pragma("unroll") for (int k = 0; k < 2; ++k) dst[n][k] = *(const PG8_LAS bf16x8*)(lds + PG8_SB(b, h) + boff + n * 2048 + k * 1024); } while (0)
; #define PG8_MMA(ai, bj, At, Bt) do { __builtin_amdgcn_s_setprio(1); _Pragma("unroll") for (int m = 0; m < 4; ++m) _Pragma("unroll") for (int n = 0; n < 2; ++n) _Pragma("unroll") for (int k = 0; k < 2; ++k) \
;         acc[ai][bj][m][n] = __builtin_amdgcn_mfma_f32_16x16x32_bf16(Bt[n][k], At[m][k], acc[ai][bj][m][n], 0, 0, 0); __builtin_amdgcn_s_setprio(0); } while (0)
; #define PG8_WAIT_V(n) asm volatile("s_waitcnt vmcnt(" #n ")" ::: "memory")
; #define PG8_WAIT_L(n) asm volatile("s_waitcnt lgkmcnt(" #n ")" ::: "memory")
; #define PG8_BAR __builtin_amdgcn_s_barrier()
; #define PG8_SCHED __builtin_amdgcn_sched_barrier(0)
; template <class Epi, class Sched, bool ALIGN_EPI = false, bool SP2 = false>
; __device__ __forceinline__ void gemm_phase(PG8_LAS unsigned char* lds, const Gemm g, const Sched& S, const Epi& E, const int tid) {
;     ...
;             PG8_LDA(At, 0, 1); PG8_STAGE(PG8_SB(0, 0), b2, voffB); PG8_STAGE(PG8_SB(0, 1), b2 + hstep, voffB); PG8_STAGE(PG8_SA(0, 0), a2, voffA);
;             PG8_WAIT_V(8); PG8_WAIT_L(0); PG8_BAR; PG8_MMA(1, 0, At, B0); PG8_MMA(1, 1, At, B1); PG8_BAR; PG8_SCHED;
;             PG8_LDB(B0, 1, 0); PG8_LDB(B1, 1, 1); PG8_SCHED; PG8_LDA(At, 1, 0); PG8_STAGE(PG8_SA(0, 1), a2 + hstep, voffA);
;             PG8_WAIT_V(8); PG8_WAIT_L(0); PG8_BAR; PG8_MMA(0, 0, At, B0); PG8_MMA(0, 1, At, B1); PG8_BAR; PG8_SCHED;
	s_add_i32 s15, s86, s66
	v_lshl_add_u64 v[170:171], s[58:59], 0, v[142:143]
	s_mov_b32 m0, s15
	ds_read_b128 v[196:199], v174 offset:16384
	ds_read_b128 v[200:203], v174 offset:17408
	ds_read_b128 v[204:207], v174 offset:18432
	ds_read_b128 v[208:211], v174 offset:19456
	ds_read_b128 v[212:215], v174 offset:20480
	ds_read_b128 v[216:219], v174 offset:21504
	ds_read_b128 v[220:223], v174 offset:22528
	ds_read_b128 v[224:227], v174 offset:23552
	global_load_lds_dwordx4 v[170:171], off
	s_add_i32 m0, s15, 0x2000
	s_add_u32 s18, s58, 0x40000
	v_lshl_add_u64 v[188:189], s[58:59], 0, v[146:147]
	s_addc_u32 s19, s59, 0
	s_add_i32 s15, s87, s66
	global_load_lds_dwordx4 v[188:189], off
	v_lshl_add_u64 v[228:229], s[18:19], 0, v[142:143]
	s_mov_b32 m0, s15
	v_lshl_add_u64 v[230:231], s[60:61], 0, v[144:145]
	global_load_lds_dwordx4 v[228:229], off
	v_lshl_add_u64 v[228:229], s[18:19], 0, v[146:147]
	s_add_i32 m0, s15, 0x2000
	s_nop 0
	global_load_lds_dwordx4 v[228:229], off
	v_lshl_add_u64 v[228:229], s[60:61], 0, v[140:141]
	s_mov_b32 m0, s67
	s_nop 0
	global_load_lds_dwordx4 v[228:229], off
	s_mov_b32 m0, s68
	s_nop 0
	global_load_lds_dwordx4 v[230:231], off
	s_waitcnt vmcnt(8)
	s_waitcnt lgkmcnt(0)
	s_barrier
	s_setprio 1
	v_mfma_f32_16x16x32_bf16 v[62:65], v[130:133], v[196:199], v[62:65]
	v_mfma_f32_16x16x32_bf16 v[58:61], v[162:165], v[196:199], v[58:61]
	v_mfma_f32_16x16x32_bf16 v[46:49], v[130:133], v[204:207], v[46:49]
	v_mfma_f32_16x16x32_bf16 v[42:45], v[162:165], v[204:207], v[42:45]
	v_mfma_f32_16x16x32_bf16 v[30:33], v[130:133], v[212:215], v[30:33]
	v_mfma_f32_16x16x32_bf16 v[26:29], v[162:165], v[212:215], v[26:29]
	v_mfma_f32_16x16x32_bf16 v[14:17], v[130:133], v[220:223], v[14:17]
	v_mfma_f32_16x16x32_bf16 v[10:13], v[162:165], v[220:223], v[10:13]
	v_mfma_f32_16x16x32_bf16 v[62:65], v[134:137], v[200:203], v[62:65]
	v_mfma_f32_16x16x32_bf16 v[58:61], v[166:169], v[200:203], v[58:61]
	v_mfma_f32_16x16x32_bf16 v[46:49], v[134:137], v[208:211], v[46:49]
	v_mfma_f32_16x16x32_bf16 v[42:45], v[166:169], v[208:211], v[42:45]
	v_mfma_f32_16x16x32_bf16 v[30:33], v[134:137], v[216:219], v[30:33]
	v_mfma_f32_16x16x32_bf16 v[26:29], v[166:169], v[216:219], v[26:29]
	v_mfma_f32_16x16x32_bf16 v[14:17], v[134:137], v[224:227], v[14:17]
	v_mfma_f32_16x16x32_bf16 v[10:13], v[166:169], v[224:227], v[10:13]
	s_setprio 0
	s_setprio 1
	v_mfma_f32_16x16x32_bf16 v[54:57], v[176:179], v[196:199], v[54:57]
	v_mfma_f32_16x16x32_bf16 v[50:53], v[184:187], v[196:199], v[50:53]
	v_mfma_f32_16x16x32_bf16 v[38:41], v[176:179], v[204:207], v[38:41]
	v_mfma_f32_16x16x32_bf16 v[34:37], v[184:187], v[204:207], v[34:37]
	v_mfma_f32_16x16x32_bf16 v[22:25], v[176:179], v[212:215], v[22:25]
	v_mfma_f32_16x16x32_bf16 v[18:21], v[184:187], v[212:215], v[18:21]
	v_mfma_f32_16x16x32_bf16 v[6:9], v[176:179], v[220:223], v[6:9]
	v_mfma_f32_16x16x32_bf16 v[2:5], v[184:187], v[220:223], v[2:5]
	v_mfma_f32_16x16x32_bf16 v[54:57], v[180:183], v[200:203], v[54:57]
	v_mfma_f32_16x16x32_bf16 v[50:53], v[192:195], v[200:203], v[50:53]
	v_mfma_f32_16x16x32_bf16 v[38:41], v[180:183], v[208:211], v[38:41]
	v_mfma_f32_16x16x32_bf16 v[34:37], v[192:195], v[208:211], v[34:37]
	v_mfma_f32_16x16x32_bf16 v[22:25], v[180:183], v[216:219], v[22:25]
	v_mfma_f32_16x16x32_bf16 v[18:21], v[192:195], v[216:219], v[18:21]
	v_mfma_f32_16x16x32_bf16 v[6:9], v[180:183], v[224:227], v[6:9]
	v_mfma_f32_16x16x32_bf16 v[2:5], v[192:195], v[224:227], v[2:5]
	s_setprio 0
	s_barrier
	s_add_i32 s15, 0, 0x18000
	s_add_i32 s62, 0, 0x1c000
	v_add_u32_e32 v166, s15, v172
	v_add_u32_e32 v191, s62, v172
	ds_read_b128 v[130:133], v166
	ds_read_b128 v[134:137], v166 offset:1024
	ds_read_b128 v[162:165], v166 offset:2048
	ds_read_b128 v[166:169], v166 offset:3072
	ds_read_b128 v[176:179], v191
	ds_read_b128 v[180:183], v191 offset:1024
	ds_read_b128 v[184:187], v191 offset:2048
	ds_read_b128 v[192:195], v191 offset:3072
	s_add_u32 s18, s60, 0x40000
	s_addc_u32 s19, s61, 0
	s_mov_b32 m0, s69
	v_lshl_add_u64 v[232:233], s[18:19], 0, v[140:141]
	ds_read_b128 v[196:199], v174 offset:32768
	ds_read_b128 v[200:203], v174 offset:33792
	ds_read_b128 v[204:207], v174 offset:34816
	ds_read_b128 v[208:211], v174 offset:35840
	ds_read_b128 v[212:215], v174 offset:36864
	ds_read_b128 v[216:219], v174 offset:37888
	ds_read_b128 v[220:223], v174 offset:38912
	ds_read_b128 v[224:227], v174 offset:39936
	global_load_lds_dwordx4 v[232:233], off
	v_lshl_add_u64 v[232:233], s[18:19], 0, v[144:145]
	s_mov_b32 m0, s71
	s_nop 0
	global_load_lds_dwordx4 v[232:233], off
	s_waitcnt vmcnt(8)
	s_waitcnt lgkmcnt(0)
	s_barrier
; #define PG8_STAGE(bufoff, gbase, voff) do { _Pragma("unroll") for (int _i = 0; _i < 2; ++_i) \
;         __builtin_amdgcn_global_load_lds((const unsigned*)((const char*)(gbase) + (voff)[_i]), (PG8_LAS unsigned*)(lds + (bufoff) + ldsw + _i * 8192), 16, 0, 0); } while (0)
; #define PG8_LDA(dst, b, h) do { _Pragma("unroll") for (int m = 0; m < 4; ++m) _Pragma("unroll") for (int k = 0; k < 2; ++k) dst[m][k] = *(const PG8_LAS bf16x8*)(lds + PG8_SA(b, h) + aoff + m * 2048 + k * 1024); } while (0)
; #define PG8_MMA(ai, bj, At, Bt) do { __builtin_amdgcn_s_setprio(1); _Pragma("unroll") for (int m = 0; m < 4; ++m) _Pragma("unroll") for (int n = 0; n < 2; ++n) _Pragma("unroll") for (int k = 0; k < 2; ++k) \
;         acc[ai][bj][m][n] = __builtin_amdgcn_mfma_f32_16x16x32_bf16(Bt[n][k], At[m][k], acc[ai][bj][m][n], 0, 0, 0); __builtin_amdgcn_s_setprio(0); } while (0)
; #define PG8_WAIT_V(n) asm volatile("s_waitcnt vmcnt(" #n ")" ::: "memory")
; #define PG8_WAIT_L(n) asm volatile("s_waitcnt lgkmcnt(" #n ")" ::: "memory")
; #define PG8_BAR __builtin_amdgcn_s_barrier()
; #define PG8_SCHED __builtin_amdgcn_sched_barrier(0)
; template <class Epi, class Sched, bool ALIGN_EPI = false, bool SP2 = false>
; __device__ __forceinline__ void gemm_phase(PG8_LAS unsigned char* lds, const Gemm g, const Sched& S, const Epi& E, const int tid) {
;     ...
;             PG8_WAIT_V(8); PG8_WAIT_L(0); PG8_BAR; PG8_MMA(0, 0, At, B0); PG8_MMA(0, 1, At, B1); PG8_BAR; PG8_SCHED;
;             PG8_LDA(At, 1, 1); PG8_STAGE(PG8_SB(1, 0), b3, voffB); PG8_STAGE(PG8_SB(1, 1), b3 + hstep, voffB); PG8_STAGE(PG8_SA(1, 0), a3, voffA);
;             PG8_WAIT_V(8); PG8_WAIT_L(0); PG8_BAR; PG8_MMA(1, 0, At, B0); PG8_MMA(1, 1, At, B1); PG8_BAR; PG8_SCHED;
;     ...
;         if constexpr (ALIGN_EPI) { if (wr == 0) PG8_BAR; }
	s_setprio 1
	v_mfma_f32_16x16x32_bf16 v[126:129], v[130:133], v[196:199], v[126:129]
	v_mfma_f32_16x16x32_bf16 v[122:125], v[162:165], v[196:199], v[122:125]
	v_mfma_f32_16x16x32_bf16 v[110:113], v[130:133], v[204:207], v[110:113]
	v_mfma_f32_16x16x32_bf16 v[106:109], v[162:165], v[204:207], v[106:109]
	v_mfma_f32_16x16x32_bf16 v[94:97], v[130:133], v[212:215], v[94:97]
	v_mfma_f32_16x16x32_bf16 v[90:93], v[162:165], v[212:215], v[90:93]
	v_mfma_f32_16x16x32_bf16 v[78:81], v[130:133], v[220:223], v[78:81]
	v_mfma_f32_16x16x32_bf16 v[74:77], v[162:165], v[220:223], v[74:77]
	v_mfma_f32_16x16x32_bf16 v[126:129], v[134:137], v[200:203], v[126:129]
	v_mfma_f32_16x16x32_bf16 v[122:125], v[166:169], v[200:203], v[122:125]
	v_mfma_f32_16x16x32_bf16 v[110:113], v[134:137], v[208:211], v[110:113]
	v_mfma_f32_16x16x32_bf16 v[106:109], v[166:169], v[208:211], v[106:109]
	v_mfma_f32_16x16x32_bf16 v[94:97], v[134:137], v[216:219], v[94:97]
	v_mfma_f32_16x16x32_bf16 v[90:93], v[166:169], v[216:219], v[90:93]
	v_mfma_f32_16x16x32_bf16 v[78:81], v[134:137], v[224:227], v[78:81]
	v_mfma_f32_16x16x32_bf16 v[74:77], v[166:169], v[224:227], v[74:77]
	s_setprio 0
	s_setprio 1
	v_mfma_f32_16x16x32_bf16 v[118:121], v[176:179], v[196:199], v[118:121]
	v_mfma_f32_16x16x32_bf16 v[114:117], v[184:187], v[196:199], v[114:117]
	v_mfma_f32_16x16x32_bf16 v[102:105], v[176:179], v[204:207], v[102:105]
	v_mfma_f32_16x16x32_bf16 v[98:101], v[184:187], v[204:207], v[98:101]
	v_mfma_f32_16x16x32_bf16 v[86:89], v[176:179], v[212:215], v[86:89]
	v_mfma_f32_16x16x32_bf16 v[82:85], v[184:187], v[212:215], v[82:85]
	v_mfma_f32_16x16x32_bf16 v[70:73], v[176:179], v[220:223], v[70:73]
	v_mfma_f32_16x16x32_bf16 v[66:69], v[184:187], v[220:223], v[66:69]
	v_mfma_f32_16x16x32_bf16 v[118:121], v[180:183], v[200:203], v[118:121]
	v_mfma_f32_16x16x32_bf16 v[114:117], v[192:195], v[200:203], v[114:117]
	v_mfma_f32_16x16x32_bf16 v[102:105], v[180:183], v[208:211], v[102:105]
	v_mfma_f32_16x16x32_bf16 v[98:101], v[192:195], v[208:211], v[98:101]
	v_mfma_f32_16x16x32_bf16 v[86:89], v[180:183], v[216:219], v[86:89]
	v_mfma_f32_16x16x32_bf16 v[82:85], v[192:195], v[216:219], v[82:85]
	v_mfma_f32_16x16x32_bf16 v[70:73], v[180:183], v[224:227], v[70:73]
	v_mfma_f32_16x16x32_bf16 v[66:69], v[192:195], v[224:227], v[66:69]
	s_setprio 0
	s_barrier
	s_add_i32 s15, s15, s66
	v_lshl_add_u64 v[170:171], v[170:171], 0, s[44:45]
	s_mov_b32 m0, s15
	ds_read_b128 v[196:199], v174 offset:49152
	ds_read_b128 v[200:203], v174 offset:50176
	ds_read_b128 v[204:207], v174 offset:51200
	ds_read_b128 v[208:211], v174 offset:52224
	ds_read_b128 v[212:215], v174 offset:53248
	ds_read_b128 v[216:219], v174 offset:54272
	ds_read_b128 v[220:223], v174 offset:55296
	ds_read_b128 v[224:227], v174 offset:56320
	global_load_lds_dwordx4 v[170:171], off
	s_add_i32 m0, s15, 0x2000
	s_add_u32 s18, s58, 0x40080
	v_lshl_add_u64 v[170:171], v[188:189], 0, s[44:45]
	s_addc_u32 s19, s59, 0
	s_add_i32 s15, s62, s66
	global_load_lds_dwordx4 v[170:171], off
	v_lshl_add_u64 v[170:171], s[18:19], 0, v[142:143]
	s_mov_b32 m0, s15
	s_nop 0
	global_load_lds_dwordx4 v[170:171], off
	v_lshl_add_u64 v[170:171], s[18:19], 0, v[146:147]
	s_add_i32 m0, s15, 0x2000
	s_nop 0
	global_load_lds_dwordx4 v[170:171], off
	v_lshl_add_u64 v[170:171], v[228:229], 0, s[44:45]
	s_mov_b32 m0, s77
	s_nop 0
	global_load_lds_dwordx4 v[170:171], off
	v_lshl_add_u64 v[170:171], v[230:231], 0, s[44:45]
	s_mov_b32 m0, s78
	s_nop 0
	global_load_lds_dwordx4 v[170:171], off
	s_waitcnt vmcnt(8)
	s_waitcnt lgkmcnt(0)
	s_barrier
	s_setprio 1
	v_mfma_f32_16x16x32_bf16 v[62:65], v[130:133], v[196:199], v[62:65]
	v_mfma_f32_16x16x32_bf16 v[58:61], v[162:165], v[196:199], v[58:61]
	v_mfma_f32_16x16x32_bf16 v[46:49], v[130:133], v[204:207], v[46:49]
	v_mfma_f32_16x16x32_bf16 v[42:45], v[162:165], v[204:207], v[42:45]
	v_mfma_f32_16x16x32_bf16 v[30:33], v[130:133], v[212:215], v[30:33]
	v_mfma_f32_16x16x32_bf16 v[26:29], v[162:165], v[212:215], v[26:29]
	v_mfma_f32_16x16x32_bf16 v[14:17], v[130:133], v[220:223], v[14:17]
	v_mfma_f32_16x16x32_bf16 v[10:13], v[162:165], v[220:223], v[10:13]
	v_mfma_f32_16x16x32_bf16 v[62:65], v[134:137], v[200:203], v[62:65]
	v_mfma_f32_16x16x32_bf16 v[58:61], v[166:169], v[200:203], v[58:61]
	v_mfma_f32_16x16x32_bf16 v[46:49], v[134:137], v[208:211], v[46:49]
	v_mfma_f32_16x16x32_bf16 v[42:45], v[166:169], v[208:211], v[42:45]
	v_mfma_f32_16x16x32_bf16 v[30:33], v[134:137], v[216:219], v[30:33]
	v_mfma_f32_16x16x32_bf16 v[26:29], v[166:169], v[216:219], v[26:29]
	v_mfma_f32_16x16x32_bf16 v[14:17], v[134:137], v[224:227], v[14:17]
	v_mfma_f32_16x16x32_bf16 v[10:13], v[166:169], v[224:227], v[10:13]
	s_setprio 0
	s_setprio 1
	v_mfma_f32_16x16x32_bf16 v[54:57], v[176:179], v[196:199], v[54:57]
	v_mfma_f32_16x16x32_bf16 v[50:53], v[184:187], v[196:199], v[50:53]
	v_mfma_f32_16x16x32_bf16 v[38:41], v[176:179], v[204:207], v[38:41]
	v_mfma_f32_16x16x32_bf16 v[34:37], v[184:187], v[204:207], v[34:37]
	v_mfma_f32_16x16x32_bf16 v[22:25], v[176:179], v[212:215], v[22:25]
	v_mfma_f32_16x16x32_bf16 v[18:21], v[184:187], v[212:215], v[18:21]
	v_mfma_f32_16x16x32_bf16 v[6:9], v[176:179], v[220:223], v[6:9]
	v_mfma_f32_16x16x32_bf16 v[2:5], v[184:187], v[220:223], v[2:5]
	v_mfma_f32_16x16x32_bf16 v[54:57], v[180:183], v[200:203], v[54:57]
	v_mfma_f32_16x16x32_bf16 v[50:53], v[192:195], v[200:203], v[50:53]
	v_mfma_f32_16x16x32_bf16 v[38:41], v[180:183], v[208:211], v[38:41]
	v_mfma_f32_16x16x32_bf16 v[34:37], v[192:195], v[208:211], v[34:37]
	v_mfma_f32_16x16x32_bf16 v[22:25], v[180:183], v[216:219], v[22:25]
	v_mfma_f32_16x16x32_bf16 v[18:21], v[192:195], v[216:219], v[18:21]
	v_mfma_f32_16x16x32_bf16 v[6:9], v[180:183], v[224:227], v[6:9]
	v_mfma_f32_16x16x32_bf16 v[2:5], v[192:195], v[224:227], v[2:5]
	s_setprio 0
	s_barrier
	s_add_i32 s51, s51, 2
	s_add_u32 s5, s5, 0x100
	s_addc_u32 s49, s49, 0
	s_add_u32 s56, s56, 0x100
	s_addc_u32 s57, s57, 0
	s_cmp_gt_u32 s51, 13
	s_cbranch_scc0 .LBB0_1122
	s_and_b64 vcc, exec, s[46:47]
	s_cbranch_vccz .LBB0_1125
	s_barrier

; #define PG8_STAGE(bufoff, gbase, voff) do { _Pragma("unroll") for (int _i = 0; _i < 2; ++_i) \
;         __builtin_amdgcn_global_load_lds((const unsigned*)((const char*)(gbase) + (voff)[_i]), (PG8_LAS unsigned*)(lds + (bufoff) + ldsw + _i * 8192), 16, 0, 0); } while (0)
; #define PG8_LDA(dst, b, h) do { _Pragma("unroll") for (int m = 0; m < 4; ++m) _Pragma("unroll") for (int k = 0; k < 2; ++k) dst[m][k] = *(const PG8_LAS bf16x8*)(lds + PG8_SA(b, h) + aoff + m * 2048 + k * 1024); } while (0)
; #define PG8_LDB(dst, b, h) do { _Pragma("unroll") for (int n = 0; n < 2; ++n) _Pragma("unroll") for (int k = 0; k < 2; ++k) dst[n][k] = *(const PG8_LAS bf16x8*)(lds + PG8_SB(b, h) + boff + n * 2048 + k * 1024); } while (0)
; #define PG8_WAIT_V(n) asm volatile("s_waitcnt vmcnt(" #n ")" ::: "memory")
; #define PG8_WAIT_L(n) asm volatile("s_waitcnt lgkmcnt(" #n ")" ::: "memory")
; #define PG8_BAR __builtin_amdgcn_s_barrier()
; #define PG8_SCHED __builtin_amdgcn_sched_barrier(0)
; template <class Epi, class Sched, bool ALIGN_EPI = false, bool SP2 = false>
; __device__ __forceinline__ void gemm_phase(PG8_LAS unsigned char* lds, const Gemm g, const Sched& S, const Epi& E, const int tid) {
;     ...
;         const bool has_next = S.next(ui + 1, nxt);
;         const char* nA = has_next ? S.aptr(nxt) : cA; const char* nB = has_next ? S.bptr(nxt) : cB;
;         for (int t = 0; t < nt; t += 2) {
;             const bool last = (t == nt - 2);
;             const char* a1 = cA + (size_t)(t + 1) * kstep;
;             const char* a2 = last ? nA : cA + (size_t)(t + 2) * kstep; const char* b2 = last ? nB : cB + (size_t)(t + 2) * kstep;
;             const char* a3 = a2 + kstep; const char* b3 = b2 + kstep;
;             if (last && has_next) S.a_ready(nxt);
;             if constexpr (SP2) {
;             PG8_LDB(B0, 0, 0); PG8_LDB(B1, 0, 1); PG8_SCHED; PG8_LDA(At, 0, 0); PG8_STAGE(PG8_SA(1, 1), a1 + hstep, voffA);
;             PG8_WAIT_V(8); PG8_WAIT_L(0); PG8_BAR; PG8_MMA(0, 0, At, B0); PG8_MMA(0, 1, At, B1); PG8_BAR; PG8_SCHED;
;             PG8_LDA(At, 0, 1); PG8_STAGE(PG8_SB(0, 0), b2, voffB); PG8_STAGE(PG8_SB(0, 1), b2 + hstep, voffB); PG8_STAGE(PG8_SA(0, 0), a2, voffA);
;             PG8_WAIT_V(8); PG8_WAIT_L(0); PG8_BAR; PG8_MMA(1, 0, At, B0); PG8_MMA(1, 1, At, B1); PG8_BAR; PG8_SCHED;
.LBB0_1373:
	s_ashr_i32 s39, s38, 31
	s_lshl_b64 s[18:19], s[38:39], 19
	s_add_u32 s40, s52, s18
	s_addc_u32 s41, s53, s19
	s_and_b64 s[18:19], s[4:5], exec
	s_cselect_b32 s7, s41, s11
	s_cselect_b32 s39, s40, s10
	s_ashr_i32 s37, s36, 31
	s_lshl_b64 s[18:19], s[36:37], 19
	s_add_u32 s42, s54, s18
	s_addc_u32 s43, s55, s19
	s_and_b64 s[18:19], s[4:5], exec
	s_cselect_b32 s37, s43, s9
	s_cselect_b32 s45, s42, s8
	s_add_u32 s48, s8, 0x100
	s_addc_u32 s49, s9, 0
	s_add_u32 s8, s10, 0x40080
	s_addc_u32 s9, s11, 0
	s_mov_b32 s76, -2
	s_add_u32 s10, s8, 0xfffc0080
	s_addc_u32 s11, s9, -1
	s_cmp_eq_u32 s76, 12
	s_cselect_b32 s47, s7, s11
	s_cselect_b32 s46, s39, s10
	s_cselect_b32 s11, s37, s49
	s_cselect_b32 s10, s45, s48
	v_lshl_add_u64 v[220:221], s[8:9], 0, v[176:177]
	s_add_i32 m0, s57, 0xc000
	global_load_lds_dwordx4 v[220:221], off
	v_lshl_add_u64 v[220:221], s[8:9], 0, v[174:175]
	s_add_i32 m0, s57, 0xe000
	s_nop 0
	global_load_lds_dwordx4 v[220:221], off
	s_waitcnt vmcnt(8)
	s_waitcnt lgkmcnt(0)
	s_barrier
	s_setprio 1
	v_mfma_f32_16x16x32_bf16 v[126:129], v[130:133], v[182:185], 0
	v_mfma_f32_16x16x32_bf16 v[122:125], v[138:141], v[182:185], 0
	v_mfma_f32_16x16x32_bf16 v[110:113], v[130:133], v[192:195], 0
	v_mfma_f32_16x16x32_bf16 v[106:109], v[138:141], v[192:195], 0
	v_mfma_f32_16x16x32_bf16 v[94:97], v[130:133], v[200:203], 0
	v_mfma_f32_16x16x32_bf16 v[90:93], v[138:141], v[200:203], 0
	v_mfma_f32_16x16x32_bf16 v[78:81], v[130:133], v[212:215], 0
	v_mfma_f32_16x16x32_bf16 v[74:77], v[138:141], v[212:215], 0
	v_mfma_f32_16x16x32_bf16 v[126:129], v[134:137], v[186:189], v[126:129]
	v_mfma_f32_16x16x32_bf16 v[122:125], v[142:145], v[186:189], v[122:125]
	v_mfma_f32_16x16x32_bf16 v[110:113], v[134:137], v[196:199], v[110:113]
	v_mfma_f32_16x16x32_bf16 v[106:109], v[142:145], v[196:199], v[106:109]
	v_mfma_f32_16x16x32_bf16 v[94:97], v[134:137], v[208:211], v[94:97]
	v_mfma_f32_16x16x32_bf16 v[90:93], v[142:145], v[208:211], v[90:93]
	v_mfma_f32_16x16x32_bf16 v[78:81], v[134:137], v[216:219], v[78:81]
	v_mfma_f32_16x16x32_bf16 v[74:77], v[142:145], v[216:219], v[74:77]
	s_setprio 0
	s_setprio 1
	v_mfma_f32_16x16x32_bf16 v[118:121], v[146:149], v[182:185], 0
	v_mfma_f32_16x16x32_bf16 v[114:117], v[154:157], v[182:185], 0
	v_mfma_f32_16x16x32_bf16 v[102:105], v[146:149], v[192:195], 0
	v_mfma_f32_16x16x32_bf16 v[98:101], v[154:157], v[192:195], 0
	v_mfma_f32_16x16x32_bf16 v[86:89], v[146:149], v[200:203], 0
	v_mfma_f32_16x16x32_bf16 v[82:85], v[154:157], v[200:203], 0
	v_mfma_f32_16x16x32_bf16 v[70:73], v[146:149], v[212:215], 0
	v_mfma_f32_16x16x32_bf16 v[66:69], v[154:157], v[212:215], 0
	v_mfma_f32_16x16x32_bf16 v[118:121], v[150:153], v[186:189], v[118:121]
	v_mfma_f32_16x16x32_bf16 v[114:117], v[158:161], v[186:189], v[114:117]
	v_mfma_f32_16x16x32_bf16 v[102:105], v[150:153], v[196:199], v[102:105]
	v_mfma_f32_16x16x32_bf16 v[98:101], v[158:161], v[196:199], v[98:101]
	v_mfma_f32_16x16x32_bf16 v[86:89], v[150:153], v[208:211], v[86:89]
	v_mfma_f32_16x16x32_bf16 v[82:85], v[158:161], v[208:211], v[82:85]
	v_mfma_f32_16x16x32_bf16 v[70:73], v[150:153], v[216:219], v[70:73]
	v_mfma_f32_16x16x32_bf16 v[66:69], v[158:161], v[216:219], v[66:69]
	s_setprio 0
	s_barrier
	s_add_i32 s15, s67, s56
	v_lshl_add_u64 v[220:221], s[10:11], 0, v[164:165]
	s_mov_b32 m0, s15
	ds_read_b128 v[182:185], v206 offset:16384
	ds_read_b128 v[186:189], v206 offset:17408
	ds_read_b128 v[192:195], v206 offset:18432
	ds_read_b128 v[196:199], v206 offset:19456
	ds_read_b128 v[200:203], v206 offset:20480
	ds_read_b128 v[208:211], v206 offset:21504
	ds_read_b128 v[212:215], v206 offset:22528
	ds_read_b128 v[216:219], v206 offset:23552
	global_load_lds_dwordx4 v[220:221], off
	s_add_i32 m0, s15, 0x2000
	s_add_u32 s18, s10, 0x40000
	v_lshl_add_u64 v[222:223], s[10:11], 0, v[168:169]
	s_addc_u32 s19, s11, 0
	s_add_i32 s15, s68, s56
	global_load_lds_dwordx4 v[222:223], off
	v_lshl_add_u64 v[224:225], s[18:19], 0, v[164:165]
	s_mov_b32 m0, s15
	v_lshl_add_u64 v[226:227], s[46:47], 0, v[166:167]
	global_load_lds_dwordx4 v[224:225], off
	v_lshl_add_u64 v[224:225], s[18:19], 0, v[168:169]
	s_add_i32 m0, s15, 0x2000
	s_nop 0
	global_load_lds_dwordx4 v[224:225], off
	v_lshl_add_u64 v[224:225], s[46:47], 0, v[162:163]
	s_mov_b32 m0, s57
	s_nop 0
	global_load_lds_dwordx4 v[224:225], off
	s_mov_b32 m0, s58
	s_nop 0
	global_load_lds_dwordx4 v[226:227], off
	s_waitcnt vmcnt(8)
	s_waitcnt lgkmcnt(0)
	s_barrier
	s_setprio 1
	v_mfma_f32_16x16x32_bf16 v[62:65], v[130:133], v[182:185], 0
	v_mfma_f32_16x16x32_bf16 v[58:61], v[138:141], v[182:185], 0
	v_mfma_f32_16x16x32_bf16 v[46:49], v[130:133], v[192:195], 0
	v_mfma_f32_16x16x32_bf16 v[42:45], v[138:141], v[192:195], 0
	v_mfma_f32_16x16x32_bf16 v[30:33], v[130:133], v[200:203], 0
	v_mfma_f32_16x16x32_bf16 v[26:29], v[138:141], v[200:203], 0
	v_mfma_f32_16x16x32_bf16 v[14:17], v[130:133], v[212:215], 0
	v_mfma_f32_16x16x32_bf16 v[10:13], v[138:141], v[212:215], 0
	v_mfma_f32_16x16x32_bf16 v[62:65], v[134:137], v[186:189], v[62:65]
	v_mfma_f32_16x16x32_bf16 v[58:61], v[142:145], v[186:189], v[58:61]
	v_mfma_f32_16x16x32_bf16 v[46:49], v[134:137], v[196:199], v[46:49]
	v_mfma_f32_16x16x32_bf16 v[42:45], v[142:145], v[196:199], v[42:45]
	v_mfma_f32_16x16x32_bf16 v[30:33], v[134:137], v[208:211], v[30:33]
	v_mfma_f32_16x16x32_bf16 v[26:29], v[142:145], v[208:211], v[26:29]
	v_mfma_f32_16x16x32_bf16 v[14:17], v[134:137], v[216:219], v[14:17]
	v_mfma_f32_16x16x32_bf16 v[10:13], v[142:145], v[216:219], v[10:13]
	s_setprio 0
	s_setprio 1
	v_mfma_f32_16x16x32_bf16 v[54:57], v[146:149], v[182:185], 0
	v_mfma_f32_16x16x32_bf16 v[50:53], v[154:157], v[182:185], 0
	v_mfma_f32_16x16x32_bf16 v[38:41], v[146:149], v[192:195], 0
	v_mfma_f32_16x16x32_bf16 v[34:37], v[154:157], v[192:195], 0
	v_mfma_f32_16x16x32_bf16 v[22:25], v[146:149], v[200:203], 0
	v_mfma_f32_16x16x32_bf16 v[18:21], v[154:157], v[200:203], 0
	v_mfma_f32_16x16x32_bf16 v[6:9], v[146:149], v[212:215], 0
	v_mfma_f32_16x16x32_bf16 v[2:5], v[154:157], v[212:215], 0
	v_mfma_f32_16x16x32_bf16 v[54:57], v[150:153], v[186:189], v[54:57]
	v_mfma_f32_16x16x32_bf16 v[50:53], v[158:161], v[186:189], v[50:53]
	v_mfma_f32_16x16x32_bf16 v[38:41], v[150:153], v[196:199], v[38:41]
	v_mfma_f32_16x16x32_bf16 v[34:37], v[158:161], v[196:199], v[34:37]
	v_mfma_f32_16x16x32_bf16 v[22:25], v[150:153], v[208:211], v[22:25]
	v_mfma_f32_16x16x32_bf16 v[18:21], v[158:161], v[208:211], v[18:21]
	v_mfma_f32_16x16x32_bf16 v[6:9], v[150:153], v[216:219], v[6:9]
	v_mfma_f32_16x16x32_bf16 v[2:5], v[158:161], v[216:219], v[2:5]
	s_setprio 0
	s_barrier
; #define PG8_STAGE(bufoff, gbase, voff) do { _Pragma("unroll") for (int _i = 0; _i < 2; ++_i) \
;         __builtin_amdgcn_global_load_lds((const unsigned*)((const char*)(gbase) + (voff)[_i]), (PG8_LAS unsigned*)(lds + (bufoff) + ldsw + _i * 8192), 16, 0, 0); } while (0)
; #define PG8_LDA(dst, b, h) do { _Pragma("unroll") for (int m = 0; m < 4; ++m) _Pragma("unroll") for (int k = 0; k < 2; ++k) dst[m][k] = *(const PG8_LAS bf16x8*)(lds + PG8_SA(b, h) + aoff + m * 2048 + k * 1024); } while (0)
; #define PG8_LDB(dst, b, h) do { _Pragma("unroll") for (int n = 0; n < 2; ++n) _Pragma("unroll") for (int k = 0; k < 2; ++k) dst[n][k] = *(const PG8_LAS bf16x8*)(lds + PG8_SB(b, h) + boff + n * 2048 + k * 1024); } while (0)
; #define PG8_MMA(ai, bj, At, Bt) do { __builtin_amdgcn_s_setprio(1); _Pragma("unroll") for (int m = 0; m < 4; ++m) _Pragma("unroll") for (int n = 0; n < 2; ++n) _Pragma("unroll") for (int k = 0; k < 2; ++k) \
;         acc[ai][bj][m][n] = __builtin_amdgcn_mfma_f32_16x16x32_bf16(Bt[n][k], At[m][k], acc[ai][bj][m][n], 0, 0, 0); __builtin_amdgcn_s_setprio(0); } while (0)
; #define PG8_WAIT_V(n) asm volatile("s_waitcnt vmcnt(" #n ")" ::: "memory")
; #define PG8_WAIT_L(n) asm volatile("s_waitcnt lgkmcnt(" #n ")" ::: "memory")
; #define PG8_BAR __builtin_amdgcn_s_barrier()
; #define PG8_SCHED __builtin_amdgcn_sched_barrier(0)
; template <class Epi, class Sched, bool ALIGN_EPI = false, bool SP2 = false>
; __device__ __forceinline__ void gemm_phase(PG8_LAS unsigned char* lds, const Gemm g, const Sched& S, const Epi& E, const int tid) {
;     ...
;             PG8_LDB(B0, 1, 0); PG8_LDB(B1, 1, 1); PG8_SCHED; PG8_LDA(At, 1, 0); PG8_STAGE(PG8_SA(0, 1), a2 + hstep, voffA);
;             PG8_WAIT_V(8); PG8_WAIT_L(0); PG8_BAR; PG8_MMA(0, 0, At, B0); PG8_MMA(0, 1, At, B1); PG8_BAR; PG8_SCHED;
;             PG8_LDA(At, 1, 1); PG8_STAGE(PG8_SB(1, 0), b3, voffB); PG8_STAGE(PG8_SB(1, 1), b3 + hstep, voffB); PG8_STAGE(PG8_SA(1, 0), a3, voffA);
	s_add_i32 s15, 0, 0x18000
	s_add_i32 s77, 0, 0x1c000
	v_add_u32_e32 v142, s15, v191
	v_add_u32_e32 v158, s77, v191
	ds_read_b128 v[130:133], v142
	ds_read_b128 v[134:137], v142 offset:1024
	ds_read_b128 v[138:141], v142 offset:2048
	ds_read_b128 v[142:145], v142 offset:3072
	ds_read_b128 v[146:149], v158
	ds_read_b128 v[150:153], v158 offset:1024
	ds_read_b128 v[154:157], v158 offset:2048
	ds_read_b128 v[158:161], v158 offset:3072
	s_add_u32 s18, s46, 0x40000
	s_addc_u32 s19, s47, 0
	s_mov_b32 m0, s59
	v_lshl_add_u64 v[228:229], s[18:19], 0, v[162:163]
	ds_read_b128 v[182:185], v206 offset:32768
	ds_read_b128 v[186:189], v206 offset:33792
	ds_read_b128 v[192:195], v206 offset:34816
	ds_read_b128 v[196:199], v206 offset:35840
	ds_read_b128 v[200:203], v206 offset:36864
	ds_read_b128 v[208:211], v206 offset:37888
	ds_read_b128 v[212:215], v206 offset:38912
	ds_read_b128 v[216:219], v206 offset:39936
	global_load_lds_dwordx4 v[228:229], off
	v_lshl_add_u64 v[228:229], s[18:19], 0, v[166:167]
	s_mov_b32 m0, s60
	s_nop 0
	global_load_lds_dwordx4 v[228:229], off
	s_waitcnt vmcnt(8)
	s_waitcnt lgkmcnt(0)
	s_barrier
	s_setprio 1
	v_mfma_f32_16x16x32_bf16 v[126:129], v[130:133], v[182:185], v[126:129]
	v_mfma_f32_16x16x32_bf16 v[122:125], v[138:141], v[182:185], v[122:125]
	v_mfma_f32_16x16x32_bf16 v[110:113], v[130:133], v[192:195], v[110:113]
	v_mfma_f32_16x16x32_bf16 v[106:109], v[138:141], v[192:195], v[106:109]
	v_mfma_f32_16x16x32_bf16 v[94:97], v[130:133], v[200:203], v[94:97]
	v_mfma_f32_16x16x32_bf16 v[90:93], v[138:141], v[200:203], v[90:93]
	v_mfma_f32_16x16x32_bf16 v[78:81], v[130:133], v[212:215], v[78:81]
	v_mfma_f32_16x16x32_bf16 v[74:77], v[138:141], v[212:215], v[74:77]
	v_mfma_f32_16x16x32_bf16 v[126:129], v[134:137], v[186:189], v[126:129]
	v_mfma_f32_16x16x32_bf16 v[122:125], v[142:145], v[186:189], v[122:125]
	v_mfma_f32_16x16x32_bf16 v[110:113], v[134:137], v[196:199], v[110:113]
	v_mfma_f32_16x16x32_bf16 v[106:109], v[142:145], v[196:199], v[106:109]
	v_mfma_f32_16x16x32_bf16 v[94:97], v[134:137], v[208:211], v[94:97]
	v_mfma_f32_16x16x32_bf16 v[90:93], v[142:145], v[208:211], v[90:93]
	v_mfma_f32_16x16x32_bf16 v[78:81], v[134:137], v[216:219], v[78:81]
	v_mfma_f32_16x16x32_bf16 v[74:77], v[142:145], v[216:219], v[74:77]
	s_setprio 0
	s_setprio 1
	v_mfma_f32_16x16x32_bf16 v[118:121], v[146:149], v[182:185], v[118:121]
	v_mfma_f32_16x16x32_bf16 v[114:117], v[154:157], v[182:185], v[114:117]
	v_mfma_f32_16x16x32_bf16 v[102:105], v[146:149], v[192:195], v[102:105]
	v_mfma_f32_16x16x32_bf16 v[98:101], v[154:157], v[192:195], v[98:101]
	v_mfma_f32_16x16x32_bf16 v[86:89], v[146:149], v[200:203], v[86:89]
	v_mfma_f32_16x16x32_bf16 v[82:85], v[154:157], v[200:203], v[82:85]
	v_mfma_f32_16x16x32_bf16 v[70:73], v[146:149], v[212:215], v[70:73]
	v_mfma_f32_16x16x32_bf16 v[66:69], v[154:157], v[212:215], v[66:69]
	v_mfma_f32_16x16x32_bf16 v[118:121], v[150:153], v[186:189], v[118:121]
	v_mfma_f32_16x16x32_bf16 v[114:117], v[158:161], v[186:189], v[114:117]
	v_mfma_f32_16x16x32_bf16 v[102:105], v[150:153], v[196:199], v[102:105]
	v_mfma_f32_16x16x32_bf16 v[98:101], v[158:161], v[196:199], v[98:101]
	v_mfma_f32_16x16x32_bf16 v[86:89], v[150:153], v[208:211], v[86:89]
	v_mfma_f32_16x16x32_bf16 v[82:85], v[158:161], v[208:211], v[82:85]
	v_mfma_f32_16x16x32_bf16 v[70:73], v[150:153], v[216:219], v[70:73]
	v_mfma_f32_16x16x32_bf16 v[66:69], v[158:161], v[216:219], v[66:69]
	s_setprio 0
	s_barrier
	s_add_i32 s15, s15, s56
	v_lshl_add_u64 v[220:221], v[220:221], 0, s[30:31]
	s_mov_b32 m0, s15
	ds_read_b128 v[182:185], v206 offset:49152
	ds_read_b128 v[186:189], v206 offset:50176
	ds_read_b128 v[192:195], v206 offset:51200
	ds_read_b128 v[196:199], v206 offset:52224
	ds_read_b128 v[200:203], v206 offset:53248
	ds_read_b128 v[208:211], v206 offset:54272
	ds_read_b128 v[212:215], v206 offset:55296
	ds_read_b128 v[216:219], v206 offset:56320
	global_load_lds_dwordx4 v[220:221], off
	s_add_i32 m0, s15, 0x2000
	s_add_u32 s10, s10, 0x40080
	v_lshl_add_u64 v[220:221], v[222:223], 0, s[30:31]
	s_addc_u32 s11, s11, 0
	s_add_i32 s15, s77, s56
	global_load_lds_dwordx4 v[220:221], off
	v_lshl_add_u64 v[220:221], s[10:11], 0, v[164:165]
	s_mov_b32 m0, s15
	s_nop 0
	global_load_lds_dwordx4 v[220:221], off
	v_lshl_add_u64 v[220:221], s[10:11], 0, v[168:169]
	s_add_i32 m0, s15, 0x2000
	s_nop 0
	global_load_lds_dwordx4 v[220:221], off
	v_lshl_add_u64 v[220:221], v[224:225], 0, s[30:31]
	s_mov_b32 m0, s62
	s_nop 0
	global_load_lds_dwordx4 v[220:221], off
	v_lshl_add_u64 v[220:221], v[226:227], 0, s[30:31]
	s_mov_b32 m0, s63
	s_nop 0
	global_load_lds_dwordx4 v[220:221], off
	s_waitcnt vmcnt(8)
	s_waitcnt lgkmcnt(0)
	s_barrier
; #define PG8_STAGE(bufoff, gbase, voff) do { _Pragma("unroll") for (int _i = 0; _i < 2; ++_i) \
;         __builtin_amdgcn_global_load_lds((const unsigned*)((const char*)(gbase) + (voff)[_i]), (PG8_LAS unsigned*)(lds + (bufoff) + ldsw + _i * 8192), 16, 0, 0); } while (0)
; #define PG8_LDA(dst, b, h) do { _Pragma("unroll") for (int m = 0; m < 4; ++m) _Pragma("unroll") for (int k = 0; k < 2; ++k) dst[m][k] = *(const PG8_LAS bf16x8*)(lds + PG8_SA(b, h) + aoff + m * 2048 + k * 1024); } while (0)
; #define PG8_WAIT_V(n) asm volatile("s_waitcnt vmcnt(" #n ")" ::: "memory")
; #define PG8_WAIT_L(n) asm volatile("s_waitcnt lgkmcnt(" #n ")" ::: "memory")
; #define PG8_BAR __builtin_amdgcn_s_barrier()
; template <class Epi, class Sched, bool ALIGN_EPI = false, bool SP2 = false>
; __device__ __forceinline__ void gemm_phase(PG8_LAS unsigned char* lds, const Gemm g, const Sched& S, const Epi& E, const int tid) {
;     ...
;         for (int t = 0; t < nt; t += 2) {
;             const bool last = (t == nt - 2);
;             const char* a1 = cA + (size_t)(t + 1) * kstep;
;             const char* a2 = last ? nA : cA + (size_t)(t + 2) * kstep; const char* b2 = last ? nB : cB + (size_t)(t + 2) * kstep;
;             const char* a3 = a2 + kstep; const char* b3 = b2 + kstep;
;             if (last && has_next) S.a_ready(nxt);
;             if constexpr (SP2) {
;             PG8_LDB(B0, 0, 0); PG8_LDB(B1, 0, 1); PG8_SCHED; PG8_LDA(At, 0, 0); PG8_STAGE(PG8_SA(1, 1), a1 + hstep, voffA);
;             PG8_WAIT_V(8); PG8_WAIT_L(0); PG8_BAR; PG8_MMA(0, 0, At, B0); PG8_MMA(0, 1, At, B1); PG8_BAR; PG8_SCHED;
;             PG8_LDA(At, 0, 1); PG8_STAGE(PG8_SB(0, 0), b2, voffB); PG8_STAGE(PG8_SB(0, 1), b2 + hstep, voffB); PG8_STAGE(PG8_SA(0, 0), a2, voffA);
;             PG8_WAIT_V(8); PG8_WAIT_L(0); PG8_BAR; PG8_MMA(1, 0, At, B0); PG8_MMA(1, 1, At, B1); PG8_BAR; PG8_SCHED;
;             PG8_LDB(B0, 1, 0); PG8_LDB(B1, 1, 1); PG8_SCHED; PG8_LDA(At, 1, 0); PG8_STAGE(PG8_SA(0, 1), a2 + hstep, voffA);
;             PG8_WAIT_V(8); PG8_WAIT_L(0); PG8_BAR; PG8_MMA(0, 0, At, B0); PG8_MMA(0, 1, At, B1); PG8_BAR; PG8_SCHED;
;             PG8_LDA(At, 1, 1); PG8_STAGE(PG8_SB(1, 0), b3, voffB); PG8_STAGE(PG8_SB(1, 1), b3 + hstep, voffB); PG8_STAGE(PG8_SA(1, 0), a3, voffA);
;             PG8_WAIT_V(8); PG8_WAIT_L(0); PG8_BAR; PG8_MMA(1, 0, At, B0); PG8_MMA(1, 1, At, B1); PG8_BAR; PG8_SCHED;
	s_setprio 1
	v_mfma_f32_16x16x32_bf16 v[62:65], v[130:133], v[182:185], v[62:65]
	v_mfma_f32_16x16x32_bf16 v[58:61], v[138:141], v[182:185], v[58:61]
	v_mfma_f32_16x16x32_bf16 v[46:49], v[130:133], v[192:195], v[46:49]
	v_mfma_f32_16x16x32_bf16 v[42:45], v[138:141], v[192:195], v[42:45]
	v_mfma_f32_16x16x32_bf16 v[30:33], v[130:133], v[200:203], v[30:33]
	v_mfma_f32_16x16x32_bf16 v[26:29], v[138:141], v[200:203], v[26:29]
	v_mfma_f32_16x16x32_bf16 v[14:17], v[130:133], v[212:215], v[14:17]
	v_mfma_f32_16x16x32_bf16 v[10:13], v[138:141], v[212:215], v[10:13]
	v_mfma_f32_16x16x32_bf16 v[62:65], v[134:137], v[186:189], v[62:65]
	v_mfma_f32_16x16x32_bf16 v[58:61], v[142:145], v[186:189], v[58:61]
	v_mfma_f32_16x16x32_bf16 v[46:49], v[134:137], v[196:199], v[46:49]
	v_mfma_f32_16x16x32_bf16 v[42:45], v[142:145], v[196:199], v[42:45]
	v_mfma_f32_16x16x32_bf16 v[30:33], v[134:137], v[208:211], v[30:33]
	v_mfma_f32_16x16x32_bf16 v[26:29], v[142:145], v[208:211], v[26:29]
	v_mfma_f32_16x16x32_bf16 v[14:17], v[134:137], v[216:219], v[14:17]
	v_mfma_f32_16x16x32_bf16 v[10:13], v[142:145], v[216:219], v[10:13]
	s_setprio 0
	s_setprio 1
	v_mfma_f32_16x16x32_bf16 v[54:57], v[146:149], v[182:185], v[54:57]
	v_mfma_f32_16x16x32_bf16 v[50:53], v[154:157], v[182:185], v[50:53]
	v_mfma_f32_16x16x32_bf16 v[38:41], v[146:149], v[192:195], v[38:41]
	v_mfma_f32_16x16x32_bf16 v[34:37], v[154:157], v[192:195], v[34:37]
	v_mfma_f32_16x16x32_bf16 v[22:25], v[146:149], v[200:203], v[22:25]
	v_mfma_f32_16x16x32_bf16 v[18:21], v[154:157], v[200:203], v[18:21]
	v_mfma_f32_16x16x32_bf16 v[6:9], v[146:149], v[212:215], v[6:9]
	v_mfma_f32_16x16x32_bf16 v[2:5], v[154:157], v[212:215], v[2:5]
	v_mfma_f32_16x16x32_bf16 v[54:57], v[150:153], v[186:189], v[54:57]
	v_mfma_f32_16x16x32_bf16 v[50:53], v[158:161], v[186:189], v[50:53]
	v_mfma_f32_16x16x32_bf16 v[38:41], v[150:153], v[196:199], v[38:41]
	v_mfma_f32_16x16x32_bf16 v[34:37], v[158:161], v[196:199], v[34:37]
	v_mfma_f32_16x16x32_bf16 v[22:25], v[150:153], v[208:211], v[22:25]
	v_mfma_f32_16x16x32_bf16 v[18:21], v[158:161], v[208:211], v[18:21]
	v_mfma_f32_16x16x32_bf16 v[6:9], v[150:153], v[216:219], v[6:9]
	v_mfma_f32_16x16x32_bf16 v[2:5], v[158:161], v[216:219], v[2:5]
	s_setprio 0
	s_barrier
	s_add_i32 s76, s76, 2
	s_add_u32 s48, s48, 0x100
	s_addc_u32 s49, s49, 0
	s_add_u32 s8, s8, 0x100
	s_addc_u32 s9, s9, 0
.LBB0_1374:
	ds_read_b128 v[130:133], v204
	ds_read_b128 v[134:137], v204 offset:1024
	ds_read_b128 v[138:141], v204 offset:2048
	ds_read_b128 v[142:145], v204 offset:3072
	ds_read_b128 v[146:149], v205
	ds_read_b128 v[150:153], v205 offset:1024
	ds_read_b128 v[154:157], v205 offset:2048
	ds_read_b128 v[158:161], v205 offset:3072
	s_add_u32 s10, s8, 0xfffc0080
	s_addc_u32 s11, s9, -1
	s_cmp_eq_u32 s76, 12
	s_cselect_b32 s47, s7, s11
	s_cselect_b32 s46, s39, s10
	s_cselect_b32 s11, s37, s49
	s_cselect_b32 s10, s45, s48
	v_lshl_add_u64 v[220:221], s[8:9], 0, v[176:177]
	s_add_i32 m0, s57, 0xc000
	ds_read_b128 v[182:185], v206
	ds_read_b128 v[186:189], v206 offset:1024
	ds_read_b128 v[192:195], v206 offset:2048
	ds_read_b128 v[196:199], v206 offset:3072
	ds_read_b128 v[200:203], v206 offset:4096
	ds_read_b128 v[208:211], v206 offset:5120
	ds_read_b128 v[212:215], v206 offset:6144
	ds_read_b128 v[216:219], v206 offset:7168
	global_load_lds_dwordx4 v[220:221], off
	v_lshl_add_u64 v[220:221], s[8:9], 0, v[174:175]
	s_add_i32 m0, s57, 0xe000
	s_nop 0
	global_load_lds_dwordx4 v[220:221], off
	s_waitcnt vmcnt(8)
	s_waitcnt lgkmcnt(0)
	s_barrier
	s_setprio 1
	v_mfma_f32_16x16x32_bf16 v[126:129], v[130:133], v[182:185], v[126:129]
	v_mfma_f32_16x16x32_bf16 v[122:125], v[138:141], v[182:185], v[122:125]
	v_mfma_f32_16x16x32_bf16 v[110:113], v[130:133], v[192:195], v[110:113]
	v_mfma_f32_16x16x32_bf16 v[106:109], v[138:141], v[192:195], v[106:109]
	v_mfma_f32_16x16x32_bf16 v[94:97], v[130:133], v[200:203], v[94:97]
	v_mfma_f32_16x16x32_bf16 v[90:93], v[138:141], v[200:203], v[90:93]
	v_mfma_f32_16x16x32_bf16 v[78:81], v[130:133], v[212:215], v[78:81]
	v_mfma_f32_16x16x32_bf16 v[74:77], v[138:141], v[212:215], v[74:77]
	v_mfma_f32_16x16x32_bf16 v[126:129], v[134:137], v[186:189], v[126:129]
	v_mfma_f32_16x16x32_bf16 v[122:125], v[142:145], v[186:189], v[122:125]
	v_mfma_f32_16x16x32_bf16 v[110:113], v[134:137], v[196:199], v[110:113]
	v_mfma_f32_16x16x32_bf16 v[106:109], v[142:145], v[196:199], v[106:109]
	v_mfma_f32_16x16x32_bf16 v[94:97], v[134:137], v[208:211], v[94:97]
	v_mfma_f32_16x16x32_bf16 v[90:93], v[142:145], v[208:211], v[90:93]
	v_mfma_f32_16x16x32_bf16 v[78:81], v[134:137], v[216:219], v[78:81]
	v_mfma_f32_16x16x32_bf16 v[74:77], v[142:145], v[216:219], v[74:77]
	s_setprio 0
	s_setprio 1
	v_mfma_f32_16x16x32_bf16 v[118:121], v[146:149], v[182:185], v[118:121]
	v_mfma_f32_16x16x32_bf16 v[114:117], v[154:157], v[182:185], v[114:117]
	v_mfma_f32_16x16x32_bf16 v[102:105], v[146:149], v[192:195], v[102:105]
	v_mfma_f32_16x16x32_bf16 v[98:101], v[154:157], v[192:195], v[98:101]
	v_mfma_f32_16x16x32_bf16 v[86:89], v[146:149], v[200:203], v[86:89]
	v_mfma_f32_16x16x32_bf16 v[82:85], v[154:157], v[200:203], v[82:85]
	v_mfma_f32_16x16x32_bf16 v[70:73], v[146:149], v[212:215], v[70:73]
	v_mfma_f32_16x16x32_bf16 v[66:69], v[154:157], v[212:215], v[66:69]
	v_mfma_f32_16x16x32_bf16 v[118:121], v[150:153], v[186:189], v[118:121]
	v_mfma_f32_16x16x32_bf16 v[114:117], v[158:161], v[186:189], v[114:117]
	v_mfma_f32_16x16x32_bf16 v[102:105], v[150:153], v[196:199], v[102:105]
	v_mfma_f32_16x16x32_bf16 v[98:101], v[158:161], v[196:199], v[98:101]
	v_mfma_f32_16x16x32_bf16 v[86:89], v[150:153], v[208:211], v[86:89]
	v_mfma_f32_16x16x32_bf16 v[82:85], v[158:161], v[208:211], v[82:85]
	v_mfma_f32_16x16x32_bf16 v[70:73], v[150:153], v[216:219], v[70:73]
	v_mfma_f32_16x16x32_bf16 v[66:69], v[158:161], v[216:219], v[66:69]
	s_setprio 0
	s_barrier
; #define PG8_STAGE(bufoff, gbase, voff) do { _Pragma("unroll") for (int _i = 0; _i < 2; ++_i) \
;         __builtin_amdgcn_global_load_lds((const unsigned*)((const char*)(gbase) + (voff)[_i]), (PG8_LAS unsigned*)(lds + (bufoff) + ldsw + _i * 8192), 16, 0, 0); } while (0)
; #define PG8_LDA(dst, b, h) do { _Pragma("unroll") for (int m = 0; m < 4; ++m) _Pragma("unroll") for (int k = 0; k < 2; ++k) dst[m][k] = *(const PG8_LAS bf16x8*)(lds + PG8_SA(b, h) + aoff + m * 2048 + k * 1024); } while (0)
; #define PG8_LDB(dst, b, h) do { _Pragma("unroll") for (int n = 0; n < 2; ++n) _Pragma("unroll") for (int k = 0; k < 2; ++k) dst[n][k] = *(const PG8_LAS bf16x8*)(lds + PG8_SB(b, h) + boff + n * 2048 + k * 1024); } while (0)
; #define PG8_MMA(ai, bj, At, Bt) do { __builtin_amdgcn_s_setprio(1); _Pragma("unroll") for (int m = 0; m < 4; ++m) _Pragma("unroll") for (int n = 0; n < 2; ++n) _Pragma("unroll") for (int k = 0; k < 2; ++k) \
;         acc[ai][bj][m][n] = __builtin_amdgcn_mfma_f32_16x16x32_bf16(Bt[n][k], At[m][k], acc[ai][bj][m][n], 0, 0, 0); __builtin_amdgcn_s_setprio(0); } while (0)
; #define PG8_WAIT_V(n) asm volatile("s_waitcnt vmcnt(" #n ")" ::: "memory")
; #define PG8_WAIT_L(n) asm volatile("s_waitcnt lgkmcnt(" #n ")" ::: "memory")
; #define PG8_BAR __builtin_amdgcn_s_barrier()
; #define PG8_SCHED __builtin_amdgcn_sched_barrier(0)
; template <class Epi, class Sched, bool ALIGN_EPI = false, bool SP2 = false>
; __device__ __forceinline__ void gemm_phase(PG8_LAS unsigned char* lds, const Gemm g, const Sched& S, const Epi& E, const int tid) {
;     ...
;             PG8_LDA(At, 0, 1); PG8_STAGE(PG8_SB(0, 0), b2, voffB); PG8_STAGE(PG8_SB(0, 1), b2 + hstep, voffB); PG8_STAGE(PG8_SA(0, 0), a2, voffA);
;             PG8_WAIT_V(8); PG8_WAIT_L(0); PG8_BAR; PG8_MMA(1, 0, At, B0); PG8_MMA(1, 1, At, B1); PG8_BAR; PG8_SCHED;
;             PG8_LDB(B0, 1, 0); PG8_LDB(B1, 1, 1); PG8_SCHED; PG8_LDA(At, 1, 0); PG8_STAGE(PG8_SA(0, 1), a2 + hstep, voffA);
	s_add_i32 s15, s67, s56
	v_lshl_add_u64 v[220:221], s[10:11], 0, v[164:165]
	s_mov_b32 m0, s15
	ds_read_b128 v[182:185], v206 offset:16384
	ds_read_b128 v[186:189], v206 offset:17408
	ds_read_b128 v[192:195], v206 offset:18432
	ds_read_b128 v[196:199], v206 offset:19456
	ds_read_b128 v[200:203], v206 offset:20480
	ds_read_b128 v[208:211], v206 offset:21504
	ds_read_b128 v[212:215], v206 offset:22528
	ds_read_b128 v[216:219], v206 offset:23552
	global_load_lds_dwordx4 v[220:221], off
	s_add_i32 m0, s15, 0x2000
	s_add_u32 s18, s10, 0x40000
	v_lshl_add_u64 v[222:223], s[10:11], 0, v[168:169]
	s_addc_u32 s19, s11, 0
	s_add_i32 s15, s68, s56
	global_load_lds_dwordx4 v[222:223], off
	v_lshl_add_u64 v[224:225], s[18:19], 0, v[164:165]
	s_mov_b32 m0, s15
	v_lshl_add_u64 v[226:227], s[46:47], 0, v[166:167]
	global_load_lds_dwordx4 v[224:225], off
	v_lshl_add_u64 v[224:225], s[18:19], 0, v[168:169]
	s_add_i32 m0, s15, 0x2000
	s_nop 0
	global_load_lds_dwordx4 v[224:225], off
	v_lshl_add_u64 v[224:225], s[46:47], 0, v[162:163]
	s_mov_b32 m0, s57
	s_nop 0
	global_load_lds_dwordx4 v[224:225], off
	s_mov_b32 m0, s58
	s_nop 0
	global_load_lds_dwordx4 v[226:227], off
	s_waitcnt vmcnt(8)
	s_waitcnt lgkmcnt(0)
	s_barrier
	s_setprio 1
	v_mfma_f32_16x16x32_bf16 v[62:65], v[130:133], v[182:185], v[62:65]
	v_mfma_f32_16x16x32_bf16 v[58:61], v[138:141], v[182:185], v[58:61]
	v_mfma_f32_16x16x32_bf16 v[46:49], v[130:133], v[192:195], v[46:49]
	v_mfma_f32_16x16x32_bf16 v[42:45], v[138:141], v[192:195], v[42:45]
	v_mfma_f32_16x16x32_bf16 v[30:33], v[130:133], v[200:203], v[30:33]
	v_mfma_f32_16x16x32_bf16 v[26:29], v[138:141], v[200:203], v[26:29]
	v_mfma_f32_16x16x32_bf16 v[14:17], v[130:133], v[212:215], v[14:17]
	v_mfma_f32_16x16x32_bf16 v[10:13], v[138:141], v[212:215], v[10:13]
	v_mfma_f32_16x16x32_bf16 v[62:65], v[134:137], v[186:189], v[62:65]
	v_mfma_f32_16x16x32_bf16 v[58:61], v[142:145], v[186:189], v[58:61]
	v_mfma_f32_16x16x32_bf16 v[46:49], v[134:137], v[196:199], v[46:49]
	v_mfma_f32_16x16x32_bf16 v[42:45], v[142:145], v[196:199], v[42:45]
	v_mfma_f32_16x16x32_bf16 v[30:33], v[134:137], v[208:211], v[30:33]
	v_mfma_f32_16x16x32_bf16 v[26:29], v[142:145], v[208:211], v[26:29]
	v_mfma_f32_16x16x32_bf16 v[14:17], v[134:137], v[216:219], v[14:17]
	v_mfma_f32_16x16x32_bf16 v[10:13], v[142:145], v[216:219], v[10:13]
	s_setprio 0
	s_setprio 1
	v_mfma_f32_16x16x32_bf16 v[54:57], v[146:149], v[182:185], v[54:57]
	v_mfma_f32_16x16x32_bf16 v[50:53], v[154:157], v[182:185], v[50:53]
	v_mfma_f32_16x16x32_bf16 v[38:41], v[146:149], v[192:195], v[38:41]
	v_mfma_f32_16x16x32_bf16 v[34:37], v[154:157], v[192:195], v[34:37]
	v_mfma_f32_16x16x32_bf16 v[22:25], v[146:149], v[200:203], v[22:25]
	v_mfma_f32_16x16x32_bf16 v[18:21], v[154:157], v[200:203], v[18:21]
	v_mfma_f32_16x16x32_bf16 v[6:9], v[146:149], v[212:215], v[6:9]
	v_mfma_f32_16x16x32_bf16 v[2:5], v[154:157], v[212:215], v[2:5]
	v_mfma_f32_16x16x32_bf16 v[54:57], v[150:153], v[186:189], v[54:57]
	v_mfma_f32_16x16x32_bf16 v[50:53], v[158:161], v[186:189], v[50:53]
	v_mfma_f32_16x16x32_bf16 v[38:41], v[150:153], v[196:199], v[38:41]
	v_mfma_f32_16x16x32_bf16 v[34:37], v[158:161], v[196:199], v[34:37]
	v_mfma_f32_16x16x32_bf16 v[22:25], v[150:153], v[208:211], v[22:25]
	v_mfma_f32_16x16x32_bf16 v[18:21], v[158:161], v[208:211], v[18:21]
	v_mfma_f32_16x16x32_bf16 v[6:9], v[150:153], v[216:219], v[6:9]
	v_mfma_f32_16x16x32_bf16 v[2:5], v[158:161], v[216:219], v[2:5]
	s_setprio 0
	s_barrier
	s_add_i32 s15, 0, 0x18000
	s_add_i32 s77, 0, 0x1c000
	v_add_u32_e32 v142, s15, v191
	v_add_u32_e32 v158, s77, v191
	ds_read_b128 v[130:133], v142
	ds_read_b128 v[134:137], v142 offset:1024
	ds_read_b128 v[138:141], v142 offset:2048
	ds_read_b128 v[142:145], v142 offset:3072
	ds_read_b128 v[146:149], v158
	ds_read_b128 v[150:153], v158 offset:1024
	ds_read_b128 v[154:157], v158 offset:2048
	ds_read_b128 v[158:161], v158 offset:3072
	s_add_u32 s18, s46, 0x40000
	s_addc_u32 s19, s47, 0
	s_mov_b32 m0, s59
	v_lshl_add_u64 v[228:229], s[18:19], 0, v[162:163]
	ds_read_b128 v[182:185], v206 offset:32768
	ds_read_b128 v[186:189], v206 offset:33792
	ds_read_b128 v[192:195], v206 offset:34816
	ds_read_b128 v[196:199], v206 offset:35840
	ds_read_b128 v[200:203], v206 offset:36864
	ds_read_b128 v[208:211], v206 offset:37888
	ds_read_b128 v[212:215], v206 offset:38912
	ds_read_b128 v[216:219], v206 offset:39936
	global_load_lds_dwordx4 v[228:229], off
	v_lshl_add_u64 v[228:229], s[18:19], 0, v[166:167]
	s_mov_b32 m0, s60
	s_nop 0
	global_load_lds_dwordx4 v[228:229], off
	s_waitcnt vmcnt(8)
	s_waitcnt lgkmcnt(0)
	s_barrier
; #define PG8_STAGE(bufoff, gbase, voff) do { _Pragma("unroll") for (int _i = 0; _i < 2; ++_i) \
;         __builtin_amdgcn_global_load_lds((const unsigned*)((const char*)(gbase) + (voff)[_i]), (PG8_LAS unsigned*)(lds + (bufoff) + ldsw + _i * 8192), 16, 0, 0); } while (0)
; #define PG8_LDA(dst, b, h) do { _Pragma("unroll") for (int m = 0; m < 4; ++m) _Pragma("unroll") for (int k = 0; k < 2; ++k) dst[m][k] = *(const PG8_LAS bf16x8*)(lds + PG8_SA(b, h) + aoff + m * 2048 + k * 1024); } while (0)
; #define PG8_MMA(ai, bj, At, Bt) do { __builtin_amdgcn_s_setprio(1); _Pragma("unroll") for (int m = 0; m < 4; ++m) _Pragma("unroll") for (int n = 0; n < 2; ++n) _Pragma("unroll") for (int k = 0; k < 2; ++k) \
;         acc[ai][bj][m][n] = __builtin_amdgcn_mfma_f32_16x16x32_bf16(Bt[n][k], At[m][k], acc[ai][bj][m][n], 0, 0, 0); __builtin_amdgcn_s_setprio(0); } while (0)
; #define PG8_WAIT_V(n) asm volatile("s_waitcnt vmcnt(" #n ")" ::: "memory")
; #define PG8_WAIT_L(n) asm volatile("s_waitcnt lgkmcnt(" #n ")" ::: "memory")
; #define PG8_BAR __builtin_amdgcn_s_barrier()
; #define PG8_SCHED __builtin_amdgcn_sched_barrier(0)
; template <class Epi, class Sched, bool ALIGN_EPI = false, bool SP2 = false>
; __device__ __forceinline__ void gemm_phase(PG8_LAS unsigned char* lds, const Gemm g, const Sched& S, const Epi& E, const int tid) {
;     ...
;             PG8_WAIT_V(8); PG8_WAIT_L(0); PG8_BAR; PG8_MMA(0, 0, At, B0); PG8_MMA(0, 1, At, B1); PG8_BAR; PG8_SCHED;
;             PG8_LDA(At, 1, 1); PG8_STAGE(PG8_SB(1, 0), b3, voffB); PG8_STAGE(PG8_SB(1, 1), b3 + hstep, voffB); PG8_STAGE(PG8_SA(1, 0), a3, voffA);
;             PG8_WAIT_V(8); PG8_WAIT_L(0); PG8_BAR; PG8_MMA(1, 0, At, B0); PG8_MMA(1, 1, At, B1); PG8_BAR; PG8_SCHED;
;     ...
;         if constexpr (ALIGN_EPI) { if (wr == 0) PG8_BAR; }
	s_setprio 1
	v_mfma_f32_16x16x32_bf16 v[126:129], v[130:133], v[182:185], v[126:129]
	v_mfma_f32_16x16x32_bf16 v[122:125], v[138:141], v[182:185], v[122:125]
	v_mfma_f32_16x16x32_bf16 v[110:113], v[130:133], v[192:195], v[110:113]
	v_mfma_f32_16x16x32_bf16 v[106:109], v[138:141], v[192:195], v[106:109]
	v_mfma_f32_16x16x32_bf16 v[94:97], v[130:133], v[200:203], v[94:97]
	v_mfma_f32_16x16x32_bf16 v[90:93], v[138:141], v[200:203], v[90:93]
	v_mfma_f32_16x16x32_bf16 v[78:81], v[130:133], v[212:215], v[78:81]
	v_mfma_f32_16x16x32_bf16 v[74:77], v[138:141], v[212:215], v[74:77]
	v_mfma_f32_16x16x32_bf16 v[126:129], v[134:137], v[186:189], v[126:129]
	v_mfma_f32_16x16x32_bf16 v[122:125], v[142:145], v[186:189], v[122:125]
	v_mfma_f32_16x16x32_bf16 v[110:113], v[134:137], v[196:199], v[110:113]
	v_mfma_f32_16x16x32_bf16 v[106:109], v[142:145], v[196:199], v[106:109]
	v_mfma_f32_16x16x32_bf16 v[94:97], v[134:137], v[208:211], v[94:97]
	v_mfma_f32_16x16x32_bf16 v[90:93], v[142:145], v[208:211], v[90:93]
	v_mfma_f32_16x16x32_bf16 v[78:81], v[134:137], v[216:219], v[78:81]
	v_mfma_f32_16x16x32_bf16 v[74:77], v[142:145], v[216:219], v[74:77]
	s_setprio 0
	s_setprio 1
	v_mfma_f32_16x16x32_bf16 v[118:121], v[146:149], v[182:185], v[118:121]
	v_mfma_f32_16x16x32_bf16 v[114:117], v[154:157], v[182:185], v[114:117]
	v_mfma_f32_16x16x32_bf16 v[102:105], v[146:149], v[192:195], v[102:105]
	v_mfma_f32_16x16x32_bf16 v[98:101], v[154:157], v[192:195], v[98:101]
	v_mfma_f32_16x16x32_bf16 v[86:89], v[146:149], v[200:203], v[86:89]
	v_mfma_f32_16x16x32_bf16 v[82:85], v[154:157], v[200:203], v[82:85]
	v_mfma_f32_16x16x32_bf16 v[70:73], v[146:149], v[212:215], v[70:73]
	v_mfma_f32_16x16x32_bf16 v[66:69], v[154:157], v[212:215], v[66:69]
	v_mfma_f32_16x16x32_bf16 v[118:121], v[150:153], v[186:189], v[118:121]
	v_mfma_f32_16x16x32_bf16 v[114:117], v[158:161], v[186:189], v[114:117]
	v_mfma_f32_16x16x32_bf16 v[102:105], v[150:153], v[196:199], v[102:105]
	v_mfma_f32_16x16x32_bf16 v[98:101], v[158:161], v[196:199], v[98:101]
	v_mfma_f32_16x16x32_bf16 v[86:89], v[150:153], v[208:211], v[86:89]
	v_mfma_f32_16x16x32_bf16 v[82:85], v[158:161], v[208:211], v[82:85]
	v_mfma_f32_16x16x32_bf16 v[70:73], v[150:153], v[216:219], v[70:73]
	v_mfma_f32_16x16x32_bf16 v[66:69], v[158:161], v[216:219], v[66:69]
	s_setprio 0
	s_barrier
	s_add_i32 s15, s15, s56
	v_lshl_add_u64 v[220:221], v[220:221], 0, s[30:31]
	s_mov_b32 m0, s15
	ds_read_b128 v[182:185], v206 offset:49152
	ds_read_b128 v[186:189], v206 offset:50176
	ds_read_b128 v[192:195], v206 offset:51200
	ds_read_b128 v[196:199], v206 offset:52224
	ds_read_b128 v[200:203], v206 offset:53248
	ds_read_b128 v[208:211], v206 offset:54272
	ds_read_b128 v[212:215], v206 offset:55296
	ds_read_b128 v[216:219], v206 offset:56320
	global_load_lds_dwordx4 v[220:221], off
	s_add_i32 m0, s15, 0x2000
	s_add_u32 s10, s10, 0x40080
	v_lshl_add_u64 v[220:221], v[222:223], 0, s[30:31]
	s_addc_u32 s11, s11, 0
	s_add_i32 s15, s77, s56
	global_load_lds_dwordx4 v[220:221], off
	v_lshl_add_u64 v[220:221], s[10:11], 0, v[164:165]
	s_mov_b32 m0, s15
	s_nop 0
	global_load_lds_dwordx4 v[220:221], off
	v_lshl_add_u64 v[220:221], s[10:11], 0, v[168:169]
	s_add_i32 m0, s15, 0x2000
	s_nop 0
	global_load_lds_dwordx4 v[220:221], off
	v_lshl_add_u64 v[220:221], v[224:225], 0, s[30:31]
	s_mov_b32 m0, s62
	s_nop 0
	global_load_lds_dwordx4 v[220:221], off
	v_lshl_add_u64 v[220:221], v[226:227], 0, s[30:31]
	s_mov_b32 m0, s63
	s_nop 0
	global_load_lds_dwordx4 v[220:221], off
	s_waitcnt vmcnt(8)
	s_waitcnt lgkmcnt(0)
	s_barrier
	s_setprio 1
	v_mfma_f32_16x16x32_bf16 v[62:65], v[130:133], v[182:185], v[62:65]
	v_mfma_f32_16x16x32_bf16 v[58:61], v[138:141], v[182:185], v[58:61]
	v_mfma_f32_16x16x32_bf16 v[46:49], v[130:133], v[192:195], v[46:49]
	v_mfma_f32_16x16x32_bf16 v[42:45], v[138:141], v[192:195], v[42:45]
	v_mfma_f32_16x16x32_bf16 v[30:33], v[130:133], v[200:203], v[30:33]
	v_mfma_f32_16x16x32_bf16 v[26:29], v[138:141], v[200:203], v[26:29]
	v_mfma_f32_16x16x32_bf16 v[14:17], v[130:133], v[212:215], v[14:17]
	v_mfma_f32_16x16x32_bf16 v[10:13], v[138:141], v[212:215], v[10:13]
	v_mfma_f32_16x16x32_bf16 v[62:65], v[134:137], v[186:189], v[62:65]
	v_mfma_f32_16x16x32_bf16 v[58:61], v[142:145], v[186:189], v[58:61]
	v_mfma_f32_16x16x32_bf16 v[46:49], v[134:137], v[196:199], v[46:49]
	v_mfma_f32_16x16x32_bf16 v[42:45], v[142:145], v[196:199], v[42:45]
	v_mfma_f32_16x16x32_bf16 v[30:33], v[134:137], v[208:211], v[30:33]
	v_mfma_f32_16x16x32_bf16 v[26:29], v[142:145], v[208:211], v[26:29]
	v_mfma_f32_16x16x32_bf16 v[14:17], v[134:137], v[216:219], v[14:17]
	v_mfma_f32_16x16x32_bf16 v[10:13], v[142:145], v[216:219], v[10:13]
	s_setprio 0
	s_setprio 1
	v_mfma_f32_16x16x32_bf16 v[54:57], v[146:149], v[182:185], v[54:57]
	v_mfma_f32_16x16x32_bf16 v[50:53], v[154:157], v[182:185], v[50:53]
	v_mfma_f32_16x16x32_bf16 v[38:41], v[146:149], v[192:195], v[38:41]
	v_mfma_f32_16x16x32_bf16 v[34:37], v[154:157], v[192:195], v[34:37]
	v_mfma_f32_16x16x32_bf16 v[22:25], v[146:149], v[200:203], v[22:25]
	v_mfma_f32_16x16x32_bf16 v[18:21], v[154:157], v[200:203], v[18:21]
	v_mfma_f32_16x16x32_bf16 v[6:9], v[146:149], v[212:215], v[6:9]
	v_mfma_f32_16x16x32_bf16 v[2:5], v[154:157], v[212:215], v[2:5]
	v_mfma_f32_16x16x32_bf16 v[54:57], v[150:153], v[186:189], v[54:57]
	v_mfma_f32_16x16x32_bf16 v[50:53], v[158:161], v[186:189], v[50:53]
	v_mfma_f32_16x16x32_bf16 v[38:41], v[150:153], v[196:199], v[38:41]
	v_mfma_f32_16x16x32_bf16 v[34:37], v[158:161], v[196:199], v[34:37]
	v_mfma_f32_16x16x32_bf16 v[22:25], v[150:153], v[208:211], v[22:25]
	v_mfma_f32_16x16x32_bf16 v[18:21], v[158:161], v[208:211], v[18:21]
	v_mfma_f32_16x16x32_bf16 v[6:9], v[150:153], v[216:219], v[6:9]
	v_mfma_f32_16x16x32_bf16 v[2:5], v[158:161], v[216:219], v[2:5]
	s_setprio 0
	s_barrier
	s_add_i32 s76, s76, 2
	s_add_u32 s48, s48, 0x100
	s_addc_u32 s49, s49, 0
	s_add_u32 s8, s8, 0x100
	s_addc_u32 s9, s9, 0
	s_cmp_gt_u32 s76, 13
	s_cbranch_scc0 .LBB0_1374
	s_and_b64 vcc, exec, s[34:35]
	s_cbranch_vccz .LBB0_1377
	s_barrier

; #define PG8_STAGE(bufoff, gbase, voff) do { _Pragma("unroll") for (int _i = 0; _i < 2; ++_i) \
;         __builtin_amdgcn_global_load_lds((const unsigned*)((const char*)(gbase) + (voff)[_i]), (PG8_LAS unsigned*)(lds + (bufoff) + ldsw + _i * 8192), 16, 0, 0); } while (0)
; #define PG8_LDA(dst, b, h) do { _Pragma("unroll") for (int m = 0; m < 4; ++m) _Pragma("unroll") for (int k = 0; k < 2; ++k) dst[m][k] = *(const PG8_LAS bf16x8*)(lds + PG8_SA(b, h) + aoff + m * 2048 + k * 1024); } while (0)
; #define PG8_LDB(dst, b, h) do { _Pragma("unroll") for (int n = 0; n < 2; ++n) _Pragma("unroll") for (int k = 0; k < 2; ++k) dst[n][k] = *(const PG8_LAS bf16x8*)(lds + PG8_SB(b, h) + boff + n * 2048 + k * 1024); } while (0)
; #define PG8_MMA(ai, bj, At, Bt) do { __builtin_amdgcn_s_setprio(1); _Pragma("unroll") for (int m = 0; m < 4; ++m) _Pragma("unroll") for (int n = 0; n < 2; ++n) _Pragma("unroll") for (int k = 0; k < 2; ++k) \
;         acc[ai][bj][m][n] = __builtin_amdgcn_mfma_f32_16x16x32_bf16(Bt[n][k], At[m][k], acc[ai][bj][m][n], 0, 0, 0); __builtin_amdgcn_s_setprio(0); } while (0)
; #define PG8_WAIT_V(n) asm volatile("s_waitcnt vmcnt(" #n ")" ::: "memory")
; #define PG8_BAR __builtin_amdgcn_s_barrier()
; template <class Epi, class Sched, bool ALIGN_EPI = false, bool SP2 = false>
; __device__ __forceinline__ void gemm_phase(PG8_LAS unsigned char* lds, const Gemm g, const Sched& S, const Epi& E, const int tid) {
;     ...
;         for (int t = 0; t < nt; t += 2) {
;             const bool last = (t == nt - 2);
;             const char* a1 = cA + (size_t)(t + 1) * kstep;
;             const char* a2 = last ? nA : cA + (size_t)(t + 2) * kstep; const char* b2 = last ? nB : cB + (size_t)(t + 2) * kstep;
;             const char* a3 = a2 + kstep; const char* b3 = b2 + kstep;
;             if (last && has_next) S.a_ready(nxt);
;             if constexpr (SP2) {
;             PG8_LDB(B0, 0, 0); PG8_LDB(B1, 0, 1); PG8_SCHED; PG8_LDA(At, 0, 0); PG8_STAGE(PG8_SA(1, 1), a1 + hstep, voffA);
;             PG8_WAIT_V(8); PG8_WAIT_L(0); PG8_BAR; PG8_MMA(0, 0, At, B0); PG8_MMA(0, 1, At, B1); PG8_BAR; PG8_SCHED;
;             PG8_LDA(At, 0, 1); PG8_STAGE(PG8_SB(0, 0), b2, voffB); PG8_STAGE(PG8_SB(0, 1), b2 + hstep, voffB); PG8_STAGE(PG8_SA(0, 0), a2, voffA);
;             PG8_WAIT_V(8); PG8_WAIT_L(0); PG8_BAR; PG8_MMA(1, 0, At, B0); PG8_MMA(1, 1, At, B1); PG8_BAR; PG8_SCHED;
.LBB0_5219:
	s_add_u32 s43, s8, 0x100
	s_addc_u32 s45, s9, 0
	s_mov_b32 s74, -2
	s_add_u32 s8, s6, 0x100
	s_addc_u32 s9, s7, 0
	s_cmp_eq_u32 s74, 40
	s_cselect_b32 s41, s1, s9
	s_cselect_b32 s40, s0, s8
	s_cselect_b32 s11, s39, s45
	s_cselect_b32 s10, s38, s43
	v_lshl_add_u64 v[220:221], s[6:7], 0, v[176:177]
	s_add_i32 m0, s53, 0xc000
	global_load_lds_dwordx4 v[220:221], off
	v_lshl_add_u64 v[220:221], s[6:7], 0, v[174:175]
	s_add_i32 m0, s53, 0xe000
	s_nop 0
	global_load_lds_dwordx4 v[220:221], off
	s_waitcnt vmcnt(8)
	s_waitcnt lgkmcnt(0)
	s_barrier
	s_setprio 1
	v_mfma_f32_16x16x32_bf16 v[126:129], v[130:133], v[182:185], 0
	v_mfma_f32_16x16x32_bf16 v[122:125], v[138:141], v[182:185], 0
	v_mfma_f32_16x16x32_bf16 v[110:113], v[130:133], v[192:195], 0
	v_mfma_f32_16x16x32_bf16 v[106:109], v[138:141], v[192:195], 0
	v_mfma_f32_16x16x32_bf16 v[94:97], v[130:133], v[200:203], 0
	v_mfma_f32_16x16x32_bf16 v[90:93], v[138:141], v[200:203], 0
	v_mfma_f32_16x16x32_bf16 v[78:81], v[130:133], v[212:215], 0
	v_mfma_f32_16x16x32_bf16 v[74:77], v[138:141], v[212:215], 0
	v_mfma_f32_16x16x32_bf16 v[126:129], v[134:137], v[186:189], v[126:129]
	v_mfma_f32_16x16x32_bf16 v[122:125], v[142:145], v[186:189], v[122:125]
	v_mfma_f32_16x16x32_bf16 v[110:113], v[134:137], v[196:199], v[110:113]
	v_mfma_f32_16x16x32_bf16 v[106:109], v[142:145], v[196:199], v[106:109]
	v_mfma_f32_16x16x32_bf16 v[94:97], v[134:137], v[208:211], v[94:97]
	v_mfma_f32_16x16x32_bf16 v[90:93], v[142:145], v[208:211], v[90:93]
	v_mfma_f32_16x16x32_bf16 v[78:81], v[134:137], v[216:219], v[78:81]
	v_mfma_f32_16x16x32_bf16 v[74:77], v[142:145], v[216:219], v[74:77]
	s_setprio 0
	s_setprio 1
	v_mfma_f32_16x16x32_bf16 v[118:121], v[146:149], v[182:185], 0
	v_mfma_f32_16x16x32_bf16 v[114:117], v[154:157], v[182:185], 0
	v_mfma_f32_16x16x32_bf16 v[102:105], v[146:149], v[192:195], 0
	v_mfma_f32_16x16x32_bf16 v[98:101], v[154:157], v[192:195], 0
	v_mfma_f32_16x16x32_bf16 v[86:89], v[146:149], v[200:203], 0
	v_mfma_f32_16x16x32_bf16 v[82:85], v[154:157], v[200:203], 0
	v_mfma_f32_16x16x32_bf16 v[70:73], v[146:149], v[212:215], 0
	v_mfma_f32_16x16x32_bf16 v[66:69], v[154:157], v[212:215], 0
	v_mfma_f32_16x16x32_bf16 v[118:121], v[150:153], v[186:189], v[118:121]
	v_mfma_f32_16x16x32_bf16 v[114:117], v[158:161], v[186:189], v[114:117]
	v_mfma_f32_16x16x32_bf16 v[102:105], v[150:153], v[196:199], v[102:105]
	v_mfma_f32_16x16x32_bf16 v[98:101], v[158:161], v[196:199], v[98:101]
	v_mfma_f32_16x16x32_bf16 v[86:89], v[150:153], v[208:211], v[86:89]
	v_mfma_f32_16x16x32_bf16 v[82:85], v[158:161], v[208:211], v[82:85]
	v_mfma_f32_16x16x32_bf16 v[70:73], v[150:153], v[216:219], v[70:73]
	v_mfma_f32_16x16x32_bf16 v[66:69], v[158:161], v[216:219], v[66:69]
	s_setprio 0
	s_barrier
	s_add_i32 s6, s63, s52
	v_lshl_add_u64 v[220:221], s[10:11], 0, v[164:165]
	s_mov_b32 m0, s6
	ds_read_b128 v[182:185], v206 offset:16384
	ds_read_b128 v[186:189], v206 offset:17408
	ds_read_b128 v[192:195], v206 offset:18432
	ds_read_b128 v[196:199], v206 offset:19456
	ds_read_b128 v[200:203], v206 offset:20480
	ds_read_b128 v[208:211], v206 offset:21504
	ds_read_b128 v[212:215], v206 offset:22528
	ds_read_b128 v[216:219], v206 offset:23552
	global_load_lds_dwordx4 v[220:221], off
	s_add_i32 m0, s6, 0x2000
	s_add_u32 s6, s10, 0xb0000
	v_lshl_add_u64 v[222:223], s[10:11], 0, v[168:169]
	s_addc_u32 s7, s11, 0
	s_add_i32 s15, s64, s52
	global_load_lds_dwordx4 v[222:223], off
	v_lshl_add_u64 v[224:225], s[6:7], 0, v[164:165]
	s_mov_b32 m0, s15
	v_lshl_add_u64 v[226:227], s[40:41], 0, v[166:167]
	global_load_lds_dwordx4 v[224:225], off
	v_lshl_add_u64 v[224:225], s[6:7], 0, v[168:169]
	s_add_i32 m0, s15, 0x2000
	s_nop 0
	global_load_lds_dwordx4 v[224:225], off
	v_lshl_add_u64 v[224:225], s[40:41], 0, v[162:163]
	s_mov_b32 m0, s53
	s_nop 0
	global_load_lds_dwordx4 v[224:225], off
	s_mov_b32 m0, s54
	s_nop 0
	global_load_lds_dwordx4 v[226:227], off
	s_waitcnt vmcnt(8)
	s_waitcnt lgkmcnt(0)
	s_barrier
	s_setprio 1
	v_mfma_f32_16x16x32_bf16 v[62:65], v[130:133], v[182:185], 0
	v_mfma_f32_16x16x32_bf16 v[58:61], v[138:141], v[182:185], 0
	v_mfma_f32_16x16x32_bf16 v[46:49], v[130:133], v[192:195], 0
	v_mfma_f32_16x16x32_bf16 v[42:45], v[138:141], v[192:195], 0
	v_mfma_f32_16x16x32_bf16 v[30:33], v[130:133], v[200:203], 0
	v_mfma_f32_16x16x32_bf16 v[26:29], v[138:141], v[200:203], 0
	v_mfma_f32_16x16x32_bf16 v[14:17], v[130:133], v[212:215], 0
	v_mfma_f32_16x16x32_bf16 v[10:13], v[138:141], v[212:215], 0
	v_mfma_f32_16x16x32_bf16 v[62:65], v[134:137], v[186:189], v[62:65]
	v_mfma_f32_16x16x32_bf16 v[58:61], v[142:145], v[186:189], v[58:61]
	v_mfma_f32_16x16x32_bf16 v[46:49], v[134:137], v[196:199], v[46:49]
	v_mfma_f32_16x16x32_bf16 v[42:45], v[142:145], v[196:199], v[42:45]
	v_mfma_f32_16x16x32_bf16 v[30:33], v[134:137], v[208:211], v[30:33]
	v_mfma_f32_16x16x32_bf16 v[26:29], v[142:145], v[208:211], v[26:29]
	v_mfma_f32_16x16x32_bf16 v[14:17], v[134:137], v[216:219], v[14:17]
	v_mfma_f32_16x16x32_bf16 v[10:13], v[142:145], v[216:219], v[10:13]
	s_setprio 0
	s_setprio 1
	v_mfma_f32_16x16x32_bf16 v[54:57], v[146:149], v[182:185], 0
	v_mfma_f32_16x16x32_bf16 v[50:53], v[154:157], v[182:185], 0
	v_mfma_f32_16x16x32_bf16 v[38:41], v[146:149], v[192:195], 0
	v_mfma_f32_16x16x32_bf16 v[34:37], v[154:157], v[192:195], 0
	v_mfma_f32_16x16x32_bf16 v[22:25], v[146:149], v[200:203], 0
	v_mfma_f32_16x16x32_bf16 v[18:21], v[154:157], v[200:203], 0
	v_mfma_f32_16x16x32_bf16 v[6:9], v[146:149], v[212:215], 0
	v_mfma_f32_16x16x32_bf16 v[2:5], v[154:157], v[212:215], 0
	v_mfma_f32_16x16x32_bf16 v[54:57], v[150:153], v[186:189], v[54:57]
	v_mfma_f32_16x16x32_bf16 v[50:53], v[158:161], v[186:189], v[50:53]
	v_mfma_f32_16x16x32_bf16 v[38:41], v[150:153], v[196:199], v[38:41]
	v_mfma_f32_16x16x32_bf16 v[34:37], v[158:161], v[196:199], v[34:37]
	v_mfma_f32_16x16x32_bf16 v[22:25], v[150:153], v[208:211], v[22:25]
	v_mfma_f32_16x16x32_bf16 v[18:21], v[158:161], v[208:211], v[18:21]
	v_mfma_f32_16x16x32_bf16 v[6:9], v[150:153], v[216:219], v[6:9]
	v_mfma_f32_16x16x32_bf16 v[2:5], v[158:161], v[216:219], v[2:5]
	s_setprio 0
	s_barrier
; #define PG8_STAGE(bufoff, gbase, voff) do { _Pragma("unroll") for (int _i = 0; _i < 2; ++_i) \
;         __builtin_amdgcn_global_load_lds((const unsigned*)((const char*)(gbase) + (voff)[_i]), (PG8_LAS unsigned*)(lds + (bufoff) + ldsw + _i * 8192), 16, 0, 0); } while (0)
; #define PG8_LDA(dst, b, h) do { _Pragma("unroll") for (int m = 0; m < 4; ++m) _Pragma("unroll") for (int k = 0; k < 2; ++k) dst[m][k] = *(const PG8_LAS bf16x8*)(lds + PG8_SA(b, h) + aoff + m * 2048 + k * 1024); } while (0)
; #define PG8_LDB(dst, b, h) do { _Pragma("unroll") for (int n = 0; n < 2; ++n) _Pragma("unroll") for (int k = 0; k < 2; ++k) dst[n][k] = *(const PG8_LAS bf16x8*)(lds + PG8_SB(b, h) + boff + n * 2048 + k * 1024); } while (0)
; #define PG8_MMA(ai, bj, At, Bt) do { __builtin_amdgcn_s_setprio(1); _Pragma("unroll") for (int m = 0; m < 4; ++m) _Pragma("unroll") for (int n = 0; n < 2; ++n) _Pragma("unroll") for (int k = 0; k < 2; ++k) \
;         acc[ai][bj][m][n] = __builtin_amdgcn_mfma_f32_16x16x32_bf16(Bt[n][k], At[m][k], acc[ai][bj][m][n], 0, 0, 0); __builtin_amdgcn_s_setprio(0); } while (0)
; #define PG8_WAIT_V(n) asm volatile("s_waitcnt vmcnt(" #n ")" ::: "memory")
; #define PG8_WAIT_L(n) asm volatile("s_waitcnt lgkmcnt(" #n ")" ::: "memory")
; #define PG8_BAR __builtin_amdgcn_s_barrier()
; #define PG8_SCHED __builtin_amdgcn_sched_barrier(0)
; template <class Epi, class Sched, bool ALIGN_EPI = false, bool SP2 = false>
; __device__ __forceinline__ void gemm_phase(PG8_LAS unsigned char* lds, const Gemm g, const Sched& S, const Epi& E, const int tid) {
;     ...
;         for (int t = 0; t < nt; t += 2) {
;     ...
;             PG8_LDB(B0, 1, 0); PG8_LDB(B1, 1, 1); PG8_SCHED; PG8_LDA(At, 1, 0); PG8_STAGE(PG8_SA(0, 1), a2 + hstep, voffA);
;             PG8_WAIT_V(8); PG8_WAIT_L(0); PG8_BAR; PG8_MMA(0, 0, At, B0); PG8_MMA(0, 1, At, B1); PG8_BAR; PG8_SCHED;
;             PG8_LDA(At, 1, 1); PG8_STAGE(PG8_SB(1, 0), b3, voffB); PG8_STAGE(PG8_SB(1, 1), b3 + hstep, voffB); PG8_STAGE(PG8_SA(1, 0), a3, voffA);
;             PG8_WAIT_V(8); PG8_WAIT_L(0); PG8_BAR; PG8_MMA(1, 0, At, B0); PG8_MMA(1, 1, At, B1); PG8_BAR; PG8_SCHED;
	s_add_i32 s15, 0, 0x18000
	s_add_i32 s18, 0, 0x1c000
	v_add_u32_e32 v142, s15, v191
	v_add_u32_e32 v158, s18, v191
	ds_read_b128 v[130:133], v142
	ds_read_b128 v[134:137], v142 offset:1024
	ds_read_b128 v[138:141], v142 offset:2048
	ds_read_b128 v[142:145], v142 offset:3072
	ds_read_b128 v[146:149], v158
	ds_read_b128 v[150:153], v158 offset:1024
	ds_read_b128 v[154:157], v158 offset:2048
	ds_read_b128 v[158:161], v158 offset:3072
	s_add_u32 s6, s40, 0xb0000
	s_addc_u32 s7, s41, 0
	s_mov_b32 m0, s55
	v_lshl_add_u64 v[228:229], s[6:7], 0, v[162:163]
	ds_read_b128 v[182:185], v206 offset:32768
	ds_read_b128 v[186:189], v206 offset:33792
	ds_read_b128 v[192:195], v206 offset:34816
	ds_read_b128 v[196:199], v206 offset:35840
	ds_read_b128 v[200:203], v206 offset:36864
	ds_read_b128 v[208:211], v206 offset:37888
	ds_read_b128 v[212:215], v206 offset:38912
	ds_read_b128 v[216:219], v206 offset:39936
	global_load_lds_dwordx4 v[228:229], off
	v_lshl_add_u64 v[228:229], s[6:7], 0, v[166:167]
	s_mov_b32 m0, s56
	s_nop 0
	global_load_lds_dwordx4 v[228:229], off
	s_waitcnt vmcnt(8)
	s_waitcnt lgkmcnt(0)
	s_barrier
	s_setprio 1
	v_mfma_f32_16x16x32_bf16 v[126:129], v[130:133], v[182:185], v[126:129]
	v_mfma_f32_16x16x32_bf16 v[122:125], v[138:141], v[182:185], v[122:125]
	v_mfma_f32_16x16x32_bf16 v[110:113], v[130:133], v[192:195], v[110:113]
	v_mfma_f32_16x16x32_bf16 v[106:109], v[138:141], v[192:195], v[106:109]
	v_mfma_f32_16x16x32_bf16 v[94:97], v[130:133], v[200:203], v[94:97]
	v_mfma_f32_16x16x32_bf16 v[90:93], v[138:141], v[200:203], v[90:93]
	v_mfma_f32_16x16x32_bf16 v[78:81], v[130:133], v[212:215], v[78:81]
	v_mfma_f32_16x16x32_bf16 v[74:77], v[138:141], v[212:215], v[74:77]
	v_mfma_f32_16x16x32_bf16 v[126:129], v[134:137], v[186:189], v[126:129]
	v_mfma_f32_16x16x32_bf16 v[122:125], v[142:145], v[186:189], v[122:125]
	v_mfma_f32_16x16x32_bf16 v[110:113], v[134:137], v[196:199], v[110:113]
	v_mfma_f32_16x16x32_bf16 v[106:109], v[142:145], v[196:199], v[106:109]
	v_mfma_f32_16x16x32_bf16 v[94:97], v[134:137], v[208:211], v[94:97]
	v_mfma_f32_16x16x32_bf16 v[90:93], v[142:145], v[208:211], v[90:93]
	v_mfma_f32_16x16x32_bf16 v[78:81], v[134:137], v[216:219], v[78:81]
	v_mfma_f32_16x16x32_bf16 v[74:77], v[142:145], v[216:219], v[74:77]
	s_setprio 0
	s_setprio 1
	v_mfma_f32_16x16x32_bf16 v[118:121], v[146:149], v[182:185], v[118:121]
	v_mfma_f32_16x16x32_bf16 v[114:117], v[154:157], v[182:185], v[114:117]
	v_mfma_f32_16x16x32_bf16 v[102:105], v[146:149], v[192:195], v[102:105]
	v_mfma_f32_16x16x32_bf16 v[98:101], v[154:157], v[192:195], v[98:101]
	v_mfma_f32_16x16x32_bf16 v[86:89], v[146:149], v[200:203], v[86:89]
	v_mfma_f32_16x16x32_bf16 v[82:85], v[154:157], v[200:203], v[82:85]
	v_mfma_f32_16x16x32_bf16 v[70:73], v[146:149], v[212:215], v[70:73]
	v_mfma_f32_16x16x32_bf16 v[66:69], v[154:157], v[212:215], v[66:69]
	v_mfma_f32_16x16x32_bf16 v[118:121], v[150:153], v[186:189], v[118:121]
	v_mfma_f32_16x16x32_bf16 v[114:117], v[158:161], v[186:189], v[114:117]
	v_mfma_f32_16x16x32_bf16 v[102:105], v[150:153], v[196:199], v[102:105]
	v_mfma_f32_16x16x32_bf16 v[98:101], v[158:161], v[196:199], v[98:101]
	v_mfma_f32_16x16x32_bf16 v[86:89], v[150:153], v[208:211], v[86:89]
	v_mfma_f32_16x16x32_bf16 v[82:85], v[158:161], v[208:211], v[82:85]
	v_mfma_f32_16x16x32_bf16 v[70:73], v[150:153], v[216:219], v[70:73]
	v_mfma_f32_16x16x32_bf16 v[66:69], v[158:161], v[216:219], v[66:69]
	s_setprio 0
	s_barrier
	s_add_i32 s6, s15, s52
	v_lshl_add_u64 v[220:221], v[220:221], 0, s[34:35]
	s_mov_b32 m0, s6
	ds_read_b128 v[182:185], v206 offset:49152
	ds_read_b128 v[186:189], v206 offset:50176
	ds_read_b128 v[192:195], v206 offset:51200
	ds_read_b128 v[196:199], v206 offset:52224
	ds_read_b128 v[200:203], v206 offset:53248
	ds_read_b128 v[208:211], v206 offset:54272
	ds_read_b128 v[212:215], v206 offset:55296
	ds_read_b128 v[216:219], v206 offset:56320
	global_load_lds_dwordx4 v[220:221], off
	s_add_i32 m0, s6, 0x2000
	s_add_u32 s6, s10, 0xb0080
	v_lshl_add_u64 v[220:221], v[222:223], 0, s[34:35]
	s_addc_u32 s7, s11, 0
	s_add_i32 s10, s18, s52
	global_load_lds_dwordx4 v[220:221], off
	v_lshl_add_u64 v[220:221], s[6:7], 0, v[164:165]
	s_mov_b32 m0, s10
	s_nop 0
	global_load_lds_dwordx4 v[220:221], off
	v_lshl_add_u64 v[220:221], s[6:7], 0, v[168:169]
	s_add_i32 m0, s10, 0x2000
	s_nop 0
	global_load_lds_dwordx4 v[220:221], off
	v_lshl_add_u64 v[220:221], v[224:225], 0, s[34:35]
	s_mov_b32 m0, s58
	s_nop 0
	global_load_lds_dwordx4 v[220:221], off
	v_lshl_add_u64 v[220:221], v[226:227], 0, s[34:35]
	s_mov_b32 m0, s59
	s_nop 0
	global_load_lds_dwordx4 v[220:221], off
	s_waitcnt vmcnt(8)
	s_waitcnt lgkmcnt(0)
	s_barrier
	s_setprio 1
	v_mfma_f32_16x16x32_bf16 v[62:65], v[130:133], v[182:185], v[62:65]
	v_mfma_f32_16x16x32_bf16 v[58:61], v[138:141], v[182:185], v[58:61]
	v_mfma_f32_16x16x32_bf16 v[46:49], v[130:133], v[192:195], v[46:49]
	v_mfma_f32_16x16x32_bf16 v[42:45], v[138:141], v[192:195], v[42:45]
	v_mfma_f32_16x16x32_bf16 v[30:33], v[130:133], v[200:203], v[30:33]
	v_mfma_f32_16x16x32_bf16 v[26:29], v[138:141], v[200:203], v[26:29]
	v_mfma_f32_16x16x32_bf16 v[14:17], v[130:133], v[212:215], v[14:17]
	v_mfma_f32_16x16x32_bf16 v[10:13], v[138:141], v[212:215], v[10:13]
	v_mfma_f32_16x16x32_bf16 v[62:65], v[134:137], v[186:189], v[62:65]
	v_mfma_f32_16x16x32_bf16 v[58:61], v[142:145], v[186:189], v[58:61]
	v_mfma_f32_16x16x32_bf16 v[46:49], v[134:137], v[196:199], v[46:49]
	v_mfma_f32_16x16x32_bf16 v[42:45], v[142:145], v[196:199], v[42:45]
	v_mfma_f32_16x16x32_bf16 v[30:33], v[134:137], v[208:211], v[30:33]
	v_mfma_f32_16x16x32_bf16 v[26:29], v[142:145], v[208:211], v[26:29]
	v_mfma_f32_16x16x32_bf16 v[14:17], v[134:137], v[216:219], v[14:17]
	v_mfma_f32_16x16x32_bf16 v[10:13], v[142:145], v[216:219], v[10:13]
	s_setprio 0
	s_setprio 1
	v_mfma_f32_16x16x32_bf16 v[54:57], v[146:149], v[182:185], v[54:57]
	v_mfma_f32_16x16x32_bf16 v[50:53], v[154:157], v[182:185], v[50:53]
	v_mfma_f32_16x16x32_bf16 v[38:41], v[146:149], v[192:195], v[38:41]
	v_mfma_f32_16x16x32_bf16 v[34:37], v[154:157], v[192:195], v[34:37]
	v_mfma_f32_16x16x32_bf16 v[22:25], v[146:149], v[200:203], v[22:25]
	v_mfma_f32_16x16x32_bf16 v[18:21], v[154:157], v[200:203], v[18:21]
	v_mfma_f32_16x16x32_bf16 v[6:9], v[146:149], v[212:215], v[6:9]
	v_mfma_f32_16x16x32_bf16 v[2:5], v[154:157], v[212:215], v[2:5]
	v_mfma_f32_16x16x32_bf16 v[54:57], v[150:153], v[186:189], v[54:57]
	v_mfma_f32_16x16x32_bf16 v[50:53], v[158:161], v[186:189], v[50:53]
	v_mfma_f32_16x16x32_bf16 v[38:41], v[150:153], v[196:199], v[38:41]
	v_mfma_f32_16x16x32_bf16 v[34:37], v[158:161], v[196:199], v[34:37]
	v_mfma_f32_16x16x32_bf16 v[22:25], v[150:153], v[208:211], v[22:25]
	v_mfma_f32_16x16x32_bf16 v[18:21], v[158:161], v[208:211], v[18:21]
	v_mfma_f32_16x16x32_bf16 v[6:9], v[150:153], v[216:219], v[6:9]
	v_mfma_f32_16x16x32_bf16 v[2:5], v[158:161], v[216:219], v[2:5]
	s_setprio 0
	s_barrier
	s_add_i32 s74, s74, 2
	s_add_u32 s43, s43, 0x100
	s_addc_u32 s45, s45, 0
	s_mov_b64 s[6:7], s[8:9]
; #define PG8_STAGE(bufoff, gbase, voff) do { _Pragma("unroll") for (int _i = 0; _i < 2; ++_i) \
;         __builtin_amdgcn_global_load_lds((const unsigned*)((const char*)(gbase) + (voff)[_i]), (PG8_LAS unsigned*)(lds + (bufoff) + ldsw + _i * 8192), 16, 0, 0); } while (0)
; #define PG8_LDA(dst, b, h) do { _Pragma("unroll") for (int m = 0; m < 4; ++m) _Pragma("unroll") for (int k = 0; k < 2; ++k) dst[m][k] = *(const PG8_LAS bf16x8*)(lds + PG8_SA(b, h) + aoff + m * 2048 + k * 1024); } while (0)
; #define PG8_LDB(dst, b, h) do { _Pragma("unroll") for (int n = 0; n < 2; ++n) _Pragma("unroll") for (int k = 0; k < 2; ++k) dst[n][k] = *(const PG8_LAS bf16x8*)(lds + PG8_SB(b, h) + boff + n * 2048 + k * 1024); } while (0)
; #define PG8_MMA(ai, bj, At, Bt) do { __builtin_amdgcn_s_setprio(1); _Pragma("unroll") for (int m = 0; m < 4; ++m) _Pragma("unroll") for (int n = 0; n < 2; ++n) _Pragma("unroll") for (int k = 0; k < 2; ++k) \
;         acc[ai][bj][m][n] = __builtin_amdgcn_mfma_f32_16x16x32_bf16(Bt[n][k], At[m][k], acc[ai][bj][m][n], 0, 0, 0); __builtin_amdgcn_s_setprio(0); } while (0)
; #define PG8_WAIT_V(n) asm volatile("s_waitcnt vmcnt(" #n ")" ::: "memory")
; #define PG8_BAR __builtin_amdgcn_s_barrier()
; template <class Epi, class Sched, bool ALIGN_EPI = false, bool SP2 = false>
; __device__ __forceinline__ void gemm_phase(PG8_LAS unsigned char* lds, const Gemm g, const Sched& S, const Epi& E, const int tid) {
;     ...
;         for (int t = 0; t < nt; t += 2) {
;             const bool last = (t == nt - 2);
;             const char* a1 = cA + (size_t)(t + 1) * kstep;
;             const char* a2 = last ? nA : cA + (size_t)(t + 2) * kstep; const char* b2 = last ? nB : cB + (size_t)(t + 2) * kstep;
;             const char* a3 = a2 + kstep; const char* b3 = b2 + kstep;
;             if (last && has_next) S.a_ready(nxt);
;             if constexpr (SP2) {
;             PG8_LDB(B0, 0, 0); PG8_LDB(B1, 0, 1); PG8_SCHED; PG8_LDA(At, 0, 0); PG8_STAGE(PG8_SA(1, 1), a1 + hstep, voffA);
;             PG8_WAIT_V(8); PG8_WAIT_L(0); PG8_BAR; PG8_MMA(0, 0, At, B0); PG8_MMA(0, 1, At, B1); PG8_BAR; PG8_SCHED;
;             PG8_LDA(At, 0, 1); PG8_STAGE(PG8_SB(0, 0), b2, voffB); PG8_STAGE(PG8_SB(0, 1), b2 + hstep, voffB); PG8_STAGE(PG8_SA(0, 0), a2, voffA);
;             PG8_WAIT_V(8); PG8_WAIT_L(0); PG8_BAR; PG8_MMA(1, 0, At, B0); PG8_MMA(1, 1, At, B1); PG8_BAR; PG8_SCHED;
.LBB0_5220:
	ds_read_b128 v[130:133], v204
	ds_read_b128 v[134:137], v204 offset:1024
	ds_read_b128 v[138:141], v204 offset:2048
	ds_read_b128 v[142:145], v204 offset:3072
	ds_read_b128 v[146:149], v205
	ds_read_b128 v[150:153], v205 offset:1024
	ds_read_b128 v[154:157], v205 offset:2048
	ds_read_b128 v[158:161], v205 offset:3072
	s_add_u32 s8, s6, 0x100
	s_addc_u32 s9, s7, 0
	s_cmp_eq_u32 s74, 40
	s_cselect_b32 s41, s1, s9
	s_cselect_b32 s40, s0, s8
	s_cselect_b32 s11, s39, s45
	s_cselect_b32 s10, s38, s43
	v_lshl_add_u64 v[220:221], s[6:7], 0, v[176:177]
	s_add_i32 m0, s53, 0xc000
	ds_read_b128 v[182:185], v206
	ds_read_b128 v[186:189], v206 offset:1024
	ds_read_b128 v[192:195], v206 offset:2048
	ds_read_b128 v[196:199], v206 offset:3072
	ds_read_b128 v[200:203], v206 offset:4096
	ds_read_b128 v[208:211], v206 offset:5120
	ds_read_b128 v[212:215], v206 offset:6144
	ds_read_b128 v[216:219], v206 offset:7168
	global_load_lds_dwordx4 v[220:221], off
	v_lshl_add_u64 v[220:221], s[6:7], 0, v[174:175]
	s_add_i32 m0, s53, 0xe000
	s_nop 0
	global_load_lds_dwordx4 v[220:221], off
	s_waitcnt vmcnt(8)
	s_waitcnt lgkmcnt(0)
	s_barrier
	s_setprio 1
	v_mfma_f32_16x16x32_bf16 v[126:129], v[130:133], v[182:185], v[126:129]
	v_mfma_f32_16x16x32_bf16 v[122:125], v[138:141], v[182:185], v[122:125]
	v_mfma_f32_16x16x32_bf16 v[110:113], v[130:133], v[192:195], v[110:113]
	v_mfma_f32_16x16x32_bf16 v[106:109], v[138:141], v[192:195], v[106:109]
	v_mfma_f32_16x16x32_bf16 v[94:97], v[130:133], v[200:203], v[94:97]
	v_mfma_f32_16x16x32_bf16 v[90:93], v[138:141], v[200:203], v[90:93]
	v_mfma_f32_16x16x32_bf16 v[78:81], v[130:133], v[212:215], v[78:81]
	v_mfma_f32_16x16x32_bf16 v[74:77], v[138:141], v[212:215], v[74:77]
	v_mfma_f32_16x16x32_bf16 v[126:129], v[134:137], v[186:189], v[126:129]
	v_mfma_f32_16x16x32_bf16 v[122:125], v[142:145], v[186:189], v[122:125]
	v_mfma_f32_16x16x32_bf16 v[110:113], v[134:137], v[196:199], v[110:113]
	v_mfma_f32_16x16x32_bf16 v[106:109], v[142:145], v[196:199], v[106:109]
	v_mfma_f32_16x16x32_bf16 v[94:97], v[134:137], v[208:211], v[94:97]
	v_mfma_f32_16x16x32_bf16 v[90:93], v[142:145], v[208:211], v[90:93]
	v_mfma_f32_16x16x32_bf16 v[78:81], v[134:137], v[216:219], v[78:81]
	v_mfma_f32_16x16x32_bf16 v[74:77], v[142:145], v[216:219], v[74:77]
	s_setprio 0
	s_setprio 1
	v_mfma_f32_16x16x32_bf16 v[118:121], v[146:149], v[182:185], v[118:121]
	v_mfma_f32_16x16x32_bf16 v[114:117], v[154:157], v[182:185], v[114:117]
	v_mfma_f32_16x16x32_bf16 v[102:105], v[146:149], v[192:195], v[102:105]
	v_mfma_f32_16x16x32_bf16 v[98:101], v[154:157], v[192:195], v[98:101]
	v_mfma_f32_16x16x32_bf16 v[86:89], v[146:149], v[200:203], v[86:89]
	v_mfma_f32_16x16x32_bf16 v[82:85], v[154:157], v[200:203], v[82:85]
	v_mfma_f32_16x16x32_bf16 v[70:73], v[146:149], v[212:215], v[70:73]
	v_mfma_f32_16x16x32_bf16 v[66:69], v[154:157], v[212:215], v[66:69]
	v_mfma_f32_16x16x32_bf16 v[118:121], v[150:153], v[186:189], v[118:121]
	v_mfma_f32_16x16x32_bf16 v[114:117], v[158:161], v[186:189], v[114:117]
	v_mfma_f32_16x16x32_bf16 v[102:105], v[150:153], v[196:199], v[102:105]
	v_mfma_f32_16x16x32_bf16 v[98:101], v[158:161], v[196:199], v[98:101]
	v_mfma_f32_16x16x32_bf16 v[86:89], v[150:153], v[208:211], v[86:89]
	v_mfma_f32_16x16x32_bf16 v[82:85], v[158:161], v[208:211], v[82:85]
	v_mfma_f32_16x16x32_bf16 v[70:73], v[150:153], v[216:219], v[70:73]
	v_mfma_f32_16x16x32_bf16 v[66:69], v[158:161], v[216:219], v[66:69]
	s_setprio 0
	s_barrier
	s_add_i32 s6, s63, s52
	v_lshl_add_u64 v[220:221], s[10:11], 0, v[164:165]
	s_mov_b32 m0, s6
	ds_read_b128 v[182:185], v206 offset:16384
	ds_read_b128 v[186:189], v206 offset:17408
	ds_read_b128 v[192:195], v206 offset:18432
	ds_read_b128 v[196:199], v206 offset:19456
	ds_read_b128 v[200:203], v206 offset:20480
	ds_read_b128 v[208:211], v206 offset:21504
	ds_read_b128 v[212:215], v206 offset:22528
	ds_read_b128 v[216:219], v206 offset:23552
	global_load_lds_dwordx4 v[220:221], off
	s_add_i32 m0, s6, 0x2000
	s_add_u32 s6, s10, 0xb0000
	v_lshl_add_u64 v[222:223], s[10:11], 0, v[168:169]
	s_addc_u32 s7, s11, 0
	s_add_i32 s15, s64, s52
	global_load_lds_dwordx4 v[222:223], off
	v_lshl_add_u64 v[224:225], s[6:7], 0, v[164:165]
	s_mov_b32 m0, s15
	v_lshl_add_u64 v[226:227], s[40:41], 0, v[166:167]
	global_load_lds_dwordx4 v[224:225], off
	v_lshl_add_u64 v[224:225], s[6:7], 0, v[168:169]
	s_add_i32 m0, s15, 0x2000
	s_nop 0
	global_load_lds_dwordx4 v[224:225], off
	v_lshl_add_u64 v[224:225], s[40:41], 0, v[162:163]
	s_mov_b32 m0, s53
	s_nop 0
	global_load_lds_dwordx4 v[224:225], off
	s_mov_b32 m0, s54
	s_nop 0
	global_load_lds_dwordx4 v[226:227], off
	s_waitcnt vmcnt(8)
	s_waitcnt lgkmcnt(0)
	s_barrier
; #define PG8_STAGE(bufoff, gbase, voff) do { _Pragma("unroll") for (int _i = 0; _i < 2; ++_i) \
;         __builtin_amdgcn_global_load_lds((const unsigned*)((const char*)(gbase) + (voff)[_i]), (PG8_LAS unsigned*)(lds + (bufoff) + ldsw + _i * 8192), 16, 0, 0); } while (0)
; #define PG8_LDA(dst, b, h) do { _Pragma("unroll") for (int m = 0; m < 4; ++m) _Pragma("unroll") for (int k = 0; k < 2; ++k) dst[m][k] = *(const PG8_LAS bf16x8*)(lds + PG8_SA(b, h) + aoff + m * 2048 + k * 1024); } while (0)
; #define PG8_LDB(dst, b, h) do { _Pragma("unroll") for (int n = 0; n < 2; ++n) _Pragma("unroll") for (int k = 0; k < 2; ++k) dst[n][k] = *(const PG8_LAS bf16x8*)(lds + PG8_SB(b, h) + boff + n * 2048 + k * 1024); } while (0)
; #define PG8_MMA(ai, bj, At, Bt) do { __builtin_amdgcn_s_setprio(1); _Pragma("unroll") for (int m = 0; m < 4; ++m) _Pragma("unroll") for (int n = 0; n < 2; ++n) _Pragma("unroll") for (int k = 0; k < 2; ++k) \
;         acc[ai][bj][m][n] = __builtin_amdgcn_mfma_f32_16x16x32_bf16(Bt[n][k], At[m][k], acc[ai][bj][m][n], 0, 0, 0); __builtin_amdgcn_s_setprio(0); } while (0)
; #define PG8_WAIT_V(n) asm volatile("s_waitcnt vmcnt(" #n ")" ::: "memory")
; #define PG8_WAIT_L(n) asm volatile("s_waitcnt lgkmcnt(" #n ")" ::: "memory")
; #define PG8_BAR __builtin_amdgcn_s_barrier()
; #define PG8_SCHED __builtin_amdgcn_sched_barrier(0)
; template <class Epi, class Sched, bool ALIGN_EPI = false, bool SP2 = false>
; __device__ __forceinline__ void gemm_phase(PG8_LAS unsigned char* lds, const Gemm g, const Sched& S, const Epi& E, const int tid) {
;     ...
;             PG8_WAIT_V(8); PG8_WAIT_L(0); PG8_BAR; PG8_MMA(1, 0, At, B0); PG8_MMA(1, 1, At, B1); PG8_BAR; PG8_SCHED;
;             PG8_LDB(B0, 1, 0); PG8_LDB(B1, 1, 1); PG8_SCHED; PG8_LDA(At, 1, 0); PG8_STAGE(PG8_SA(0, 1), a2 + hstep, voffA);
;             PG8_WAIT_V(8); PG8_WAIT_L(0); PG8_BAR; PG8_MMA(0, 0, At, B0); PG8_MMA(0, 1, At, B1); PG8_BAR; PG8_SCHED;
	s_setprio 1
	v_mfma_f32_16x16x32_bf16 v[62:65], v[130:133], v[182:185], v[62:65]
	v_mfma_f32_16x16x32_bf16 v[58:61], v[138:141], v[182:185], v[58:61]
	v_mfma_f32_16x16x32_bf16 v[46:49], v[130:133], v[192:195], v[46:49]
	v_mfma_f32_16x16x32_bf16 v[42:45], v[138:141], v[192:195], v[42:45]
	v_mfma_f32_16x16x32_bf16 v[30:33], v[130:133], v[200:203], v[30:33]
	v_mfma_f32_16x16x32_bf16 v[26:29], v[138:141], v[200:203], v[26:29]
	v_mfma_f32_16x16x32_bf16 v[14:17], v[130:133], v[212:215], v[14:17]
	v_mfma_f32_16x16x32_bf16 v[10:13], v[138:141], v[212:215], v[10:13]
	v_mfma_f32_16x16x32_bf16 v[62:65], v[134:137], v[186:189], v[62:65]
	v_mfma_f32_16x16x32_bf16 v[58:61], v[142:145], v[186:189], v[58:61]
	v_mfma_f32_16x16x32_bf16 v[46:49], v[134:137], v[196:199], v[46:49]
	v_mfma_f32_16x16x32_bf16 v[42:45], v[142:145], v[196:199], v[42:45]
	v_mfma_f32_16x16x32_bf16 v[30:33], v[134:137], v[208:211], v[30:33]
	v_mfma_f32_16x16x32_bf16 v[26:29], v[142:145], v[208:211], v[26:29]
	v_mfma_f32_16x16x32_bf16 v[14:17], v[134:137], v[216:219], v[14:17]
	v_mfma_f32_16x16x32_bf16 v[10:13], v[142:145], v[216:219], v[10:13]
	s_setprio 0
	s_setprio 1
	v_mfma_f32_16x16x32_bf16 v[54:57], v[146:149], v[182:185], v[54:57]
	v_mfma_f32_16x16x32_bf16 v[50:53], v[154:157], v[182:185], v[50:53]
	v_mfma_f32_16x16x32_bf16 v[38:41], v[146:149], v[192:195], v[38:41]
	v_mfma_f32_16x16x32_bf16 v[34:37], v[154:157], v[192:195], v[34:37]
	v_mfma_f32_16x16x32_bf16 v[22:25], v[146:149], v[200:203], v[22:25]
	v_mfma_f32_16x16x32_bf16 v[18:21], v[154:157], v[200:203], v[18:21]
	v_mfma_f32_16x16x32_bf16 v[6:9], v[146:149], v[212:215], v[6:9]
	v_mfma_f32_16x16x32_bf16 v[2:5], v[154:157], v[212:215], v[2:5]
	v_mfma_f32_16x16x32_bf16 v[54:57], v[150:153], v[186:189], v[54:57]
	v_mfma_f32_16x16x32_bf16 v[50:53], v[158:161], v[186:189], v[50:53]
	v_mfma_f32_16x16x32_bf16 v[38:41], v[150:153], v[196:199], v[38:41]
	v_mfma_f32_16x16x32_bf16 v[34:37], v[158:161], v[196:199], v[34:37]
	v_mfma_f32_16x16x32_bf16 v[22:25], v[150:153], v[208:211], v[22:25]
	v_mfma_f32_16x16x32_bf16 v[18:21], v[158:161], v[208:211], v[18:21]
	v_mfma_f32_16x16x32_bf16 v[6:9], v[150:153], v[216:219], v[6:9]
	v_mfma_f32_16x16x32_bf16 v[2:5], v[158:161], v[216:219], v[2:5]
	s_setprio 0
	s_barrier
	s_add_i32 s15, 0, 0x18000
	s_add_i32 s18, 0, 0x1c000
	v_add_u32_e32 v142, s15, v191
	v_add_u32_e32 v158, s18, v191
	ds_read_b128 v[130:133], v142
	ds_read_b128 v[134:137], v142 offset:1024
	ds_read_b128 v[138:141], v142 offset:2048
	ds_read_b128 v[142:145], v142 offset:3072
	ds_read_b128 v[146:149], v158
	ds_read_b128 v[150:153], v158 offset:1024
	ds_read_b128 v[154:157], v158 offset:2048
	ds_read_b128 v[158:161], v158 offset:3072
	s_add_u32 s6, s40, 0xb0000
	s_addc_u32 s7, s41, 0
	s_mov_b32 m0, s55
	v_lshl_add_u64 v[228:229], s[6:7], 0, v[162:163]
	ds_read_b128 v[182:185], v206 offset:32768
	ds_read_b128 v[186:189], v206 offset:33792
	ds_read_b128 v[192:195], v206 offset:34816
	ds_read_b128 v[196:199], v206 offset:35840
	ds_read_b128 v[200:203], v206 offset:36864
	ds_read_b128 v[208:211], v206 offset:37888
	ds_read_b128 v[212:215], v206 offset:38912
	ds_read_b128 v[216:219], v206 offset:39936
	global_load_lds_dwordx4 v[228:229], off
	v_lshl_add_u64 v[228:229], s[6:7], 0, v[166:167]
	s_mov_b32 m0, s56
	s_nop 0
	global_load_lds_dwordx4 v[228:229], off
	s_waitcnt vmcnt(8)
	s_waitcnt lgkmcnt(0)
	s_barrier
	s_setprio 1
	v_mfma_f32_16x16x32_bf16 v[126:129], v[130:133], v[182:185], v[126:129]
	v_mfma_f32_16x16x32_bf16 v[122:125], v[138:141], v[182:185], v[122:125]
	v_mfma_f32_16x16x32_bf16 v[110:113], v[130:133], v[192:195], v[110:113]
	v_mfma_f32_16x16x32_bf16 v[106:109], v[138:141], v[192:195], v[106:109]
	v_mfma_f32_16x16x32_bf16 v[94:97], v[130:133], v[200:203], v[94:97]
	v_mfma_f32_16x16x32_bf16 v[90:93], v[138:141], v[200:203], v[90:93]
	v_mfma_f32_16x16x32_bf16 v[78:81], v[130:133], v[212:215], v[78:81]
	v_mfma_f32_16x16x32_bf16 v[74:77], v[138:141], v[212:215], v[74:77]
	v_mfma_f32_16x16x32_bf16 v[126:129], v[134:137], v[186:189], v[126:129]
	v_mfma_f32_16x16x32_bf16 v[122:125], v[142:145], v[186:189], v[122:125]
	v_mfma_f32_16x16x32_bf16 v[110:113], v[134:137], v[196:199], v[110:113]
	v_mfma_f32_16x16x32_bf16 v[106:109], v[142:145], v[196:199], v[106:109]
	v_mfma_f32_16x16x32_bf16 v[94:97], v[134:137], v[208:211], v[94:97]
	v_mfma_f32_16x16x32_bf16 v[90:93], v[142:145], v[208:211], v[90:93]
	v_mfma_f32_16x16x32_bf16 v[78:81], v[134:137], v[216:219], v[78:81]
	v_mfma_f32_16x16x32_bf16 v[74:77], v[142:145], v[216:219], v[74:77]
	s_setprio 0
	s_setprio 1
	v_mfma_f32_16x16x32_bf16 v[118:121], v[146:149], v[182:185], v[118:121]
	v_mfma_f32_16x16x32_bf16 v[114:117], v[154:157], v[182:185], v[114:117]
	v_mfma_f32_16x16x32_bf16 v[102:105], v[146:149], v[192:195], v[102:105]
	v_mfma_f32_16x16x32_bf16 v[98:101], v[154:157], v[192:195], v[98:101]
	v_mfma_f32_16x16x32_bf16 v[86:89], v[146:149], v[200:203], v[86:89]
	v_mfma_f32_16x16x32_bf16 v[82:85], v[154:157], v[200:203], v[82:85]
	v_mfma_f32_16x16x32_bf16 v[70:73], v[146:149], v[212:215], v[70:73]
	v_mfma_f32_16x16x32_bf16 v[66:69], v[154:157], v[212:215], v[66:69]
	v_mfma_f32_16x16x32_bf16 v[118:121], v[150:153], v[186:189], v[118:121]
	v_mfma_f32_16x16x32_bf16 v[114:117], v[158:161], v[186:189], v[114:117]
	v_mfma_f32_16x16x32_bf16 v[102:105], v[150:153], v[196:199], v[102:105]
	v_mfma_f32_16x16x32_bf16 v[98:101], v[158:161], v[196:199], v[98:101]
	v_mfma_f32_16x16x32_bf16 v[86:89], v[150:153], v[208:211], v[86:89]
	v_mfma_f32_16x16x32_bf16 v[82:85], v[158:161], v[208:211], v[82:85]
	v_mfma_f32_16x16x32_bf16 v[70:73], v[150:153], v[216:219], v[70:73]
	v_mfma_f32_16x16x32_bf16 v[66:69], v[158:161], v[216:219], v[66:69]
	s_setprio 0
	s_barrier
; #define PG8_STAGE(bufoff, gbase, voff) do { _Pragma("unroll") for (int _i = 0; _i < 2; ++_i) \
;         __builtin_amdgcn_global_load_lds((const unsigned*)((const char*)(gbase) + (voff)[_i]), (PG8_LAS unsigned*)(lds + (bufoff) + ldsw + _i * 8192), 16, 0, 0); } while (0)
; #define PG8_LDA(dst, b, h) do { _Pragma("unroll") for (int m = 0; m < 4; ++m) _Pragma("unroll") for (int k = 0; k < 2; ++k) dst[m][k] = *(const PG8_LAS bf16x8*)(lds + PG8_SA(b, h) + aoff + m * 2048 + k * 1024); } while (0)
; #define PG8_MMA(ai, bj, At, Bt) do { __builtin_amdgcn_s_setprio(1); _Pragma("unroll") for (int m = 0; m < 4; ++m) _Pragma("unroll") for (int n = 0; n < 2; ++n) _Pragma("unroll") for (int k = 0; k < 2; ++k) \
;         acc[ai][bj][m][n] = __builtin_amdgcn_mfma_f32_16x16x32_bf16(Bt[n][k], At[m][k], acc[ai][bj][m][n], 0, 0, 0); __builtin_amdgcn_s_setprio(0); } while (0)
; #define PG8_WAIT_V(n) asm volatile("s_waitcnt vmcnt(" #n ")" ::: "memory")
; #define PG8_WAIT_L(n) asm volatile("s_waitcnt lgkmcnt(" #n ")" ::: "memory")
; #define PG8_BAR __builtin_amdgcn_s_barrier()
; #define PG8_SCHED __builtin_amdgcn_sched_barrier(0)
; template <class Epi, class Sched, bool ALIGN_EPI = false, bool SP2 = false>
; __device__ __forceinline__ void gemm_phase(PG8_LAS unsigned char* lds, const Gemm g, const Sched& S, const Epi& E, const int tid) {
;     ...
;             PG8_LDA(At, 1, 1); PG8_STAGE(PG8_SB(1, 0), b3, voffB); PG8_STAGE(PG8_SB(1, 1), b3 + hstep, voffB); PG8_STAGE(PG8_SA(1, 0), a3, voffA);
;             PG8_WAIT_V(8); PG8_WAIT_L(0); PG8_BAR; PG8_MMA(1, 0, At, B0); PG8_MMA(1, 1, At, B1); PG8_BAR; PG8_SCHED;
;     ...
;         if constexpr (ALIGN_EPI) { if (wr == 0) PG8_BAR; }
	s_add_i32 s6, s15, s52
	v_lshl_add_u64 v[220:221], v[220:221], 0, s[34:35]
	s_mov_b32 m0, s6
	ds_read_b128 v[182:185], v206 offset:49152
	ds_read_b128 v[186:189], v206 offset:50176
	ds_read_b128 v[192:195], v206 offset:51200
	ds_read_b128 v[196:199], v206 offset:52224
	ds_read_b128 v[200:203], v206 offset:53248
	ds_read_b128 v[208:211], v206 offset:54272
	ds_read_b128 v[212:215], v206 offset:55296
	ds_read_b128 v[216:219], v206 offset:56320
	global_load_lds_dwordx4 v[220:221], off
	s_add_i32 m0, s6, 0x2000
	s_add_u32 s6, s10, 0xb0080
	v_lshl_add_u64 v[220:221], v[222:223], 0, s[34:35]
	s_addc_u32 s7, s11, 0
	s_add_i32 s10, s18, s52
	global_load_lds_dwordx4 v[220:221], off
	v_lshl_add_u64 v[220:221], s[6:7], 0, v[164:165]
	s_mov_b32 m0, s10
	s_nop 0
	global_load_lds_dwordx4 v[220:221], off
	v_lshl_add_u64 v[220:221], s[6:7], 0, v[168:169]
	s_add_i32 m0, s10, 0x2000
	s_nop 0
	global_load_lds_dwordx4 v[220:221], off
	v_lshl_add_u64 v[220:221], v[224:225], 0, s[34:35]
	s_mov_b32 m0, s58
	s_nop 0
	global_load_lds_dwordx4 v[220:221], off
	v_lshl_add_u64 v[220:221], v[226:227], 0, s[34:35]
	s_mov_b32 m0, s59
	s_nop 0
	global_load_lds_dwordx4 v[220:221], off
	s_waitcnt vmcnt(8)
	s_waitcnt lgkmcnt(0)
	s_barrier
	s_setprio 1
	v_mfma_f32_16x16x32_bf16 v[62:65], v[130:133], v[182:185], v[62:65]
	v_mfma_f32_16x16x32_bf16 v[58:61], v[138:141], v[182:185], v[58:61]
	v_mfma_f32_16x16x32_bf16 v[46:49], v[130:133], v[192:195], v[46:49]
	v_mfma_f32_16x16x32_bf16 v[42:45], v[138:141], v[192:195], v[42:45]
	v_mfma_f32_16x16x32_bf16 v[30:33], v[130:133], v[200:203], v[30:33]
	v_mfma_f32_16x16x32_bf16 v[26:29], v[138:141], v[200:203], v[26:29]
	v_mfma_f32_16x16x32_bf16 v[14:17], v[130:133], v[212:215], v[14:17]
	v_mfma_f32_16x16x32_bf16 v[10:13], v[138:141], v[212:215], v[10:13]
	v_mfma_f32_16x16x32_bf16 v[62:65], v[134:137], v[186:189], v[62:65]
	v_mfma_f32_16x16x32_bf16 v[58:61], v[142:145], v[186:189], v[58:61]
	v_mfma_f32_16x16x32_bf16 v[46:49], v[134:137], v[196:199], v[46:49]
	v_mfma_f32_16x16x32_bf16 v[42:45], v[142:145], v[196:199], v[42:45]
	v_mfma_f32_16x16x32_bf16 v[30:33], v[134:137], v[208:211], v[30:33]
	v_mfma_f32_16x16x32_bf16 v[26:29], v[142:145], v[208:211], v[26:29]
	v_mfma_f32_16x16x32_bf16 v[14:17], v[134:137], v[216:219], v[14:17]
	v_mfma_f32_16x16x32_bf16 v[10:13], v[142:145], v[216:219], v[10:13]
	s_setprio 0
	s_setprio 1
	v_mfma_f32_16x16x32_bf16 v[54:57], v[146:149], v[182:185], v[54:57]
	v_mfma_f32_16x16x32_bf16 v[50:53], v[154:157], v[182:185], v[50:53]
	v_mfma_f32_16x16x32_bf16 v[38:41], v[146:149], v[192:195], v[38:41]
	v_mfma_f32_16x16x32_bf16 v[34:37], v[154:157], v[192:195], v[34:37]
	v_mfma_f32_16x16x32_bf16 v[22:25], v[146:149], v[200:203], v[22:25]
	v_mfma_f32_16x16x32_bf16 v[18:21], v[154:157], v[200:203], v[18:21]
	v_mfma_f32_16x16x32_bf16 v[6:9], v[146:149], v[212:215], v[6:9]
	v_mfma_f32_16x16x32_bf16 v[2:5], v[154:157], v[212:215], v[2:5]
	v_mfma_f32_16x16x32_bf16 v[54:57], v[150:153], v[186:189], v[54:57]
	v_mfma_f32_16x16x32_bf16 v[50:53], v[158:161], v[186:189], v[50:53]
	v_mfma_f32_16x16x32_bf16 v[38:41], v[150:153], v[196:199], v[38:41]
	v_mfma_f32_16x16x32_bf16 v[34:37], v[158:161], v[196:199], v[34:37]
	v_mfma_f32_16x16x32_bf16 v[22:25], v[150:153], v[208:211], v[22:25]
	v_mfma_f32_16x16x32_bf16 v[18:21], v[158:161], v[208:211], v[18:21]
	v_mfma_f32_16x16x32_bf16 v[6:9], v[150:153], v[216:219], v[6:9]
	v_mfma_f32_16x16x32_bf16 v[2:5], v[158:161], v[216:219], v[2:5]
	s_setprio 0
	s_barrier
	s_add_i32 s74, s74, 2
	s_add_u32 s43, s43, 0x100
	s_addc_u32 s45, s45, 0
	s_cmp_gt_u32 s74, 41
	s_mov_b64 s[6:7], s[8:9]
	s_cbranch_scc0 .LBB0_5220
	s_and_b64 vcc, exec, s[36:37]
	s_cbranch_vccz .LBB0_5223
	s_barrier

; #define PG8_STAGE(bufoff, gbase, voff) do { _Pragma("unroll") for (int _i = 0; _i < 2; ++_i) \
;         __builtin_amdgcn_global_load_lds((const unsigned*)((const char*)(gbase) + (voff)[_i]), (PG8_LAS unsigned*)(lds + (bufoff) + ldsw + _i * 8192), 16, 0, 0); } while (0)
; #define PG8_LDA(dst, b, h) do { _Pragma("unroll") for (int m = 0; m < 4; ++m) _Pragma("unroll") for (int k = 0; k < 2; ++k) dst[m][k] = *(const PG8_LAS bf16x8*)(lds + PG8_SA(b, h) + aoff + m * 2048 + k * 1024); } while (0)
; #define PG8_LDB(dst, b, h) do { _Pragma("unroll") for (int n = 0; n < 2; ++n) _Pragma("unroll") for (int k = 0; k < 2; ++k) dst[n][k] = *(const PG8_LAS bf16x8*)(lds + PG8_SB(b, h) + boff + n * 2048 + k * 1024); } while (0)
; #define PG8_MMA(ai, bj, At, Bt) do { __builtin_amdgcn_s_setprio(1); _Pragma("unroll") for (int m = 0; m < 4; ++m) _Pragma("unroll") for (int n = 0; n < 2; ++n) _Pragma("unroll") for (int k = 0; k < 2; ++k) \
;         acc[ai][bj][m][n] = __builtin_amdgcn_mfma_f32_16x16x32_bf16(Bt[n][k], At[m][k], acc[ai][bj][m][n], 0, 0, 0); __builtin_amdgcn_s_setprio(0); } while (0)
; #define PG8_WAIT_V(n) asm volatile("s_waitcnt vmcnt(" #n ")" ::: "memory")
; #define PG8_BAR __builtin_amdgcn_s_barrier()
; template <class Epi, class Sched, bool ALIGN_EPI = false, bool SP2 = false>
; __device__ __forceinline__ void gemm_phase(PG8_LAS unsigned char* lds, const Gemm g, const Sched& S, const Epi& E, const int tid) {
;     ...
;         for (int t = 0; t < nt; t += 2) {
;             const bool last = (t == nt - 2);
;             const char* a1 = cA + (size_t)(t + 1) * kstep;
;             const char* a2 = last ? nA : cA + (size_t)(t + 2) * kstep; const char* b2 = last ? nB : cB + (size_t)(t + 2) * kstep;
;             const char* a3 = a2 + kstep; const char* b3 = b2 + kstep;
;             if (last && has_next) S.a_ready(nxt);
;             if constexpr (SP2) {
;             PG8_LDB(B0, 0, 0); PG8_LDB(B1, 0, 1); PG8_SCHED; PG8_LDA(At, 0, 0); PG8_STAGE(PG8_SA(1, 1), a1 + hstep, voffA);
;             PG8_WAIT_V(8); PG8_WAIT_L(0); PG8_BAR; PG8_MMA(0, 0, At, B0); PG8_MMA(0, 1, At, B1); PG8_BAR; PG8_SCHED;
;             PG8_LDA(At, 0, 1); PG8_STAGE(PG8_SB(0, 0), b2, voffB); PG8_STAGE(PG8_SB(0, 1), b2 + hstep, voffB); PG8_STAGE(PG8_SA(0, 0), a2, voffA);
;             PG8_WAIT_V(8); PG8_WAIT_L(0); PG8_BAR; PG8_MMA(1, 0, At, B0); PG8_MMA(1, 1, At, B1); PG8_BAR; PG8_SCHED;
.LBB0_5776:
	s_add_u32 s5, s54, 0x100
	s_addc_u32 s47, s55, 0
	s_add_u32 s54, s56, 0x40080
	s_addc_u32 s55, s57, 0
	s_mov_b32 s49, -2
	s_add_u32 s15, s54, 0xfffc0080
	s_addc_u32 s18, s55, -1
	s_cmp_eq_u32 s49, 12
	s_cselect_b32 s59, s1, s18
	s_cselect_b32 s58, s0, s15
	s_cselect_b32 s57, s51, s47
	s_cselect_b32 s56, s50, s5
	v_lshl_add_u64 v[168:169], s[54:55], 0, v[154:155]
	s_add_i32 m0, s64, 0xc000
	global_load_lds_dwordx4 v[168:169], off
	v_lshl_add_u64 v[168:169], s[54:55], 0, v[152:153]
	s_add_i32 m0, s64, 0xe000
	s_nop 0
	global_load_lds_dwordx4 v[168:169], off
	s_waitcnt vmcnt(8)
	s_waitcnt lgkmcnt(0)
	s_barrier
	s_setprio 1
	v_mfma_f32_16x16x32_bf16 v[126:129], v[130:133], v[196:199], 0
	v_mfma_f32_16x16x32_bf16 v[122:125], v[160:163], v[196:199], 0
	v_mfma_f32_16x16x32_bf16 v[110:113], v[130:133], v[204:207], 0
	v_mfma_f32_16x16x32_bf16 v[106:109], v[160:163], v[204:207], 0
	v_mfma_f32_16x16x32_bf16 v[94:97], v[130:133], v[212:215], 0
	v_mfma_f32_16x16x32_bf16 v[90:93], v[160:163], v[212:215], 0
	v_mfma_f32_16x16x32_bf16 v[78:81], v[130:133], v[220:223], 0
	v_mfma_f32_16x16x32_bf16 v[74:77], v[160:163], v[220:223], 0
	v_mfma_f32_16x16x32_bf16 v[126:129], v[134:137], v[200:203], v[126:129]
	v_mfma_f32_16x16x32_bf16 v[122:125], v[164:167], v[200:203], v[122:125]
	v_mfma_f32_16x16x32_bf16 v[110:113], v[134:137], v[208:211], v[110:113]
	v_mfma_f32_16x16x32_bf16 v[106:109], v[164:167], v[208:211], v[106:109]
	v_mfma_f32_16x16x32_bf16 v[94:97], v[134:137], v[216:219], v[94:97]
	v_mfma_f32_16x16x32_bf16 v[90:93], v[164:167], v[216:219], v[90:93]
	v_mfma_f32_16x16x32_bf16 v[78:81], v[134:137], v[224:227], v[78:81]
	v_mfma_f32_16x16x32_bf16 v[74:77], v[164:167], v[224:227], v[74:77]
	s_setprio 0
	s_setprio 1
	v_mfma_f32_16x16x32_bf16 v[118:121], v[176:179], v[196:199], 0
	v_mfma_f32_16x16x32_bf16 v[114:117], v[184:187], v[196:199], 0
	v_mfma_f32_16x16x32_bf16 v[102:105], v[176:179], v[204:207], 0
	v_mfma_f32_16x16x32_bf16 v[98:101], v[184:187], v[204:207], 0
	v_mfma_f32_16x16x32_bf16 v[86:89], v[176:179], v[212:215], 0
	v_mfma_f32_16x16x32_bf16 v[82:85], v[184:187], v[212:215], 0
	v_mfma_f32_16x16x32_bf16 v[70:73], v[176:179], v[220:223], 0
	v_mfma_f32_16x16x32_bf16 v[66:69], v[184:187], v[220:223], 0
	v_mfma_f32_16x16x32_bf16 v[118:121], v[180:183], v[200:203], v[118:121]
	v_mfma_f32_16x16x32_bf16 v[114:117], v[192:195], v[200:203], v[114:117]
	v_mfma_f32_16x16x32_bf16 v[102:105], v[180:183], v[208:211], v[102:105]
	v_mfma_f32_16x16x32_bf16 v[98:101], v[192:195], v[208:211], v[98:101]
	v_mfma_f32_16x16x32_bf16 v[86:89], v[180:183], v[216:219], v[86:89]
	v_mfma_f32_16x16x32_bf16 v[82:85], v[192:195], v[216:219], v[82:85]
	v_mfma_f32_16x16x32_bf16 v[70:73], v[180:183], v[224:227], v[70:73]
	v_mfma_f32_16x16x32_bf16 v[66:69], v[192:195], v[224:227], v[66:69]
	s_setprio 0
	s_barrier
	s_add_i32 s15, s83, s63
	v_lshl_add_u64 v[168:169], s[56:57], 0, v[140:141]
	s_mov_b32 m0, s15
	ds_read_b128 v[196:199], v173 offset:16384
	ds_read_b128 v[200:203], v173 offset:17408
	ds_read_b128 v[204:207], v173 offset:18432
	ds_read_b128 v[208:211], v173 offset:19456
	ds_read_b128 v[212:215], v173 offset:20480
	ds_read_b128 v[216:219], v173 offset:21504
	ds_read_b128 v[220:223], v173 offset:22528
	ds_read_b128 v[224:227], v173 offset:23552
	global_load_lds_dwordx4 v[168:169], off
	s_add_i32 m0, s15, 0x2000
	s_add_u32 s18, s56, 0x40000
	v_lshl_add_u64 v[188:189], s[56:57], 0, v[144:145]
	s_addc_u32 s19, s57, 0
	s_add_i32 s15, s84, s63
	global_load_lds_dwordx4 v[188:189], off
	v_lshl_add_u64 v[228:229], s[18:19], 0, v[140:141]
	s_mov_b32 m0, s15
	v_lshl_add_u64 v[230:231], s[58:59], 0, v[142:143]
	global_load_lds_dwordx4 v[228:229], off
	v_lshl_add_u64 v[228:229], s[18:19], 0, v[144:145]
	s_add_i32 m0, s15, 0x2000
	s_nop 0
	global_load_lds_dwordx4 v[228:229], off
	v_lshl_add_u64 v[228:229], s[58:59], 0, v[138:139]
	s_mov_b32 m0, s64
	s_nop 0
	global_load_lds_dwordx4 v[228:229], off
	s_mov_b32 m0, s65
	s_nop 0
	global_load_lds_dwordx4 v[230:231], off
	s_waitcnt vmcnt(8)
	s_waitcnt lgkmcnt(0)
	s_barrier
	s_setprio 1
	v_mfma_f32_16x16x32_bf16 v[62:65], v[130:133], v[196:199], 0
	v_mfma_f32_16x16x32_bf16 v[58:61], v[160:163], v[196:199], 0
	v_mfma_f32_16x16x32_bf16 v[46:49], v[130:133], v[204:207], 0
	v_mfma_f32_16x16x32_bf16 v[42:45], v[160:163], v[204:207], 0
	v_mfma_f32_16x16x32_bf16 v[30:33], v[130:133], v[212:215], 0
	v_mfma_f32_16x16x32_bf16 v[26:29], v[160:163], v[212:215], 0
	v_mfma_f32_16x16x32_bf16 v[14:17], v[130:133], v[220:223], 0
	v_mfma_f32_16x16x32_bf16 v[10:13], v[160:163], v[220:223], 0
	v_mfma_f32_16x16x32_bf16 v[62:65], v[134:137], v[200:203], v[62:65]
	v_mfma_f32_16x16x32_bf16 v[58:61], v[164:167], v[200:203], v[58:61]
	v_mfma_f32_16x16x32_bf16 v[46:49], v[134:137], v[208:211], v[46:49]
	v_mfma_f32_16x16x32_bf16 v[42:45], v[164:167], v[208:211], v[42:45]
	v_mfma_f32_16x16x32_bf16 v[30:33], v[134:137], v[216:219], v[30:33]
	v_mfma_f32_16x16x32_bf16 v[26:29], v[164:167], v[216:219], v[26:29]
	v_mfma_f32_16x16x32_bf16 v[14:17], v[134:137], v[224:227], v[14:17]
	v_mfma_f32_16x16x32_bf16 v[10:13], v[164:167], v[224:227], v[10:13]
	s_setprio 0
	s_setprio 1
	v_mfma_f32_16x16x32_bf16 v[54:57], v[176:179], v[196:199], 0
	v_mfma_f32_16x16x32_bf16 v[50:53], v[184:187], v[196:199], 0
	v_mfma_f32_16x16x32_bf16 v[38:41], v[176:179], v[204:207], 0
	v_mfma_f32_16x16x32_bf16 v[34:37], v[184:187], v[204:207], 0
	v_mfma_f32_16x16x32_bf16 v[22:25], v[176:179], v[212:215], 0
	v_mfma_f32_16x16x32_bf16 v[18:21], v[184:187], v[212:215], 0
	v_mfma_f32_16x16x32_bf16 v[6:9], v[176:179], v[220:223], 0
	v_mfma_f32_16x16x32_bf16 v[2:5], v[184:187], v[220:223], 0
	v_mfma_f32_16x16x32_bf16 v[54:57], v[180:183], v[200:203], v[54:57]
	v_mfma_f32_16x16x32_bf16 v[50:53], v[192:195], v[200:203], v[50:53]
	v_mfma_f32_16x16x32_bf16 v[38:41], v[180:183], v[208:211], v[38:41]
	v_mfma_f32_16x16x32_bf16 v[34:37], v[192:195], v[208:211], v[34:37]
	v_mfma_f32_16x16x32_bf16 v[22:25], v[180:183], v[216:219], v[22:25]
	v_mfma_f32_16x16x32_bf16 v[18:21], v[192:195], v[216:219], v[18:21]
	v_mfma_f32_16x16x32_bf16 v[6:9], v[180:183], v[224:227], v[6:9]
	v_mfma_f32_16x16x32_bf16 v[2:5], v[192:195], v[224:227], v[2:5]
	s_setprio 0
	s_barrier
; #define PG8_STAGE(bufoff, gbase, voff) do { _Pragma("unroll") for (int _i = 0; _i < 2; ++_i) \
;         __builtin_amdgcn_global_load_lds((const unsigned*)((const char*)(gbase) + (voff)[_i]), (PG8_LAS unsigned*)(lds + (bufoff) + ldsw + _i * 8192), 16, 0, 0); } while (0)
; #define PG8_LDA(dst, b, h) do { _Pragma("unroll") for (int m = 0; m < 4; ++m) _Pragma("unroll") for (int k = 0; k < 2; ++k) dst[m][k] = *(const PG8_LAS bf16x8*)(lds + PG8_SA(b, h) + aoff + m * 2048 + k * 1024); } while (0)
; #define PG8_LDB(dst, b, h) do { _Pragma("unroll") for (int n = 0; n < 2; ++n) _Pragma("unroll") for (int k = 0; k < 2; ++k) dst[n][k] = *(const PG8_LAS bf16x8*)(lds + PG8_SB(b, h) + boff + n * 2048 + k * 1024); } while (0)
; #define PG8_MMA(ai, bj, At, Bt) do { __builtin_amdgcn_s_setprio(1); _Pragma("unroll") for (int m = 0; m < 4; ++m) _Pragma("unroll") for (int n = 0; n < 2; ++n) _Pragma("unroll") for (int k = 0; k < 2; ++k) \
;         acc[ai][bj][m][n] = __builtin_amdgcn_mfma_f32_16x16x32_bf16(Bt[n][k], At[m][k], acc[ai][bj][m][n], 0, 0, 0); __builtin_amdgcn_s_setprio(0); } while (0)
; #define PG8_WAIT_V(n) asm volatile("s_waitcnt vmcnt(" #n ")" ::: "memory")
; #define PG8_WAIT_L(n) asm volatile("s_waitcnt lgkmcnt(" #n ")" ::: "memory")
; #define PG8_BAR __builtin_amdgcn_s_barrier()
; #define PG8_SCHED __builtin_amdgcn_sched_barrier(0)
; template <class Epi, class Sched, bool ALIGN_EPI = false, bool SP2 = false>
; __device__ __forceinline__ void gemm_phase(PG8_LAS unsigned char* lds, const Gemm g, const Sched& S, const Epi& E, const int tid) {
;     ...
;             PG8_LDB(B0, 1, 0); PG8_LDB(B1, 1, 1); PG8_SCHED; PG8_LDA(At, 1, 0); PG8_STAGE(PG8_SA(0, 1), a2 + hstep, voffA);
;             PG8_WAIT_V(8); PG8_WAIT_L(0); PG8_BAR; PG8_MMA(0, 0, At, B0); PG8_MMA(0, 1, At, B1); PG8_BAR; PG8_SCHED;
;             PG8_LDA(At, 1, 1); PG8_STAGE(PG8_SB(1, 0), b3, voffB); PG8_STAGE(PG8_SB(1, 1), b3 + hstep, voffB); PG8_STAGE(PG8_SA(1, 0), a3, voffA);
	s_add_i32 s15, 0, 0x18000
	s_add_i32 s60, 0, 0x1c000
	v_add_u32_e32 v164, s15, v170
	v_add_u32_e32 v175, s60, v170
	ds_read_b128 v[130:133], v164
	ds_read_b128 v[134:137], v164 offset:1024
	ds_read_b128 v[160:163], v164 offset:2048
	ds_read_b128 v[164:167], v164 offset:3072
	ds_read_b128 v[176:179], v175
	ds_read_b128 v[180:183], v175 offset:1024
	ds_read_b128 v[184:187], v175 offset:2048
	ds_read_b128 v[192:195], v175 offset:3072
	s_add_u32 s18, s58, 0x40000
	s_addc_u32 s19, s59, 0
	s_mov_b32 m0, s66
	v_lshl_add_u64 v[232:233], s[18:19], 0, v[138:139]
	ds_read_b128 v[196:199], v173 offset:32768
	ds_read_b128 v[200:203], v173 offset:33792
	ds_read_b128 v[204:207], v173 offset:34816
	ds_read_b128 v[208:211], v173 offset:35840
	ds_read_b128 v[212:215], v173 offset:36864
	ds_read_b128 v[216:219], v173 offset:37888
	ds_read_b128 v[220:223], v173 offset:38912
	ds_read_b128 v[224:227], v173 offset:39936
	global_load_lds_dwordx4 v[232:233], off
	v_lshl_add_u64 v[232:233], s[18:19], 0, v[142:143]
	s_mov_b32 m0, s67
	s_nop 0
	global_load_lds_dwordx4 v[232:233], off
	s_waitcnt vmcnt(8)
	s_waitcnt lgkmcnt(0)
	s_barrier
	s_setprio 1
	v_mfma_f32_16x16x32_bf16 v[126:129], v[130:133], v[196:199], v[126:129]
	v_mfma_f32_16x16x32_bf16 v[122:125], v[160:163], v[196:199], v[122:125]
	v_mfma_f32_16x16x32_bf16 v[110:113], v[130:133], v[204:207], v[110:113]
	v_mfma_f32_16x16x32_bf16 v[106:109], v[160:163], v[204:207], v[106:109]
	v_mfma_f32_16x16x32_bf16 v[94:97], v[130:133], v[212:215], v[94:97]
	v_mfma_f32_16x16x32_bf16 v[90:93], v[160:163], v[212:215], v[90:93]
	v_mfma_f32_16x16x32_bf16 v[78:81], v[130:133], v[220:223], v[78:81]
	v_mfma_f32_16x16x32_bf16 v[74:77], v[160:163], v[220:223], v[74:77]
	v_mfma_f32_16x16x32_bf16 v[126:129], v[134:137], v[200:203], v[126:129]
	v_mfma_f32_16x16x32_bf16 v[122:125], v[164:167], v[200:203], v[122:125]
	v_mfma_f32_16x16x32_bf16 v[110:113], v[134:137], v[208:211], v[110:113]
	v_mfma_f32_16x16x32_bf16 v[106:109], v[164:167], v[208:211], v[106:109]
	v_mfma_f32_16x16x32_bf16 v[94:97], v[134:137], v[216:219], v[94:97]
	v_mfma_f32_16x16x32_bf16 v[90:93], v[164:167], v[216:219], v[90:93]
	v_mfma_f32_16x16x32_bf16 v[78:81], v[134:137], v[224:227], v[78:81]
	v_mfma_f32_16x16x32_bf16 v[74:77], v[164:167], v[224:227], v[74:77]
	s_setprio 0
	s_setprio 1
	v_mfma_f32_16x16x32_bf16 v[118:121], v[176:179], v[196:199], v[118:121]
	v_mfma_f32_16x16x32_bf16 v[114:117], v[184:187], v[196:199], v[114:117]
	v_mfma_f32_16x16x32_bf16 v[102:105], v[176:179], v[204:207], v[102:105]
	v_mfma_f32_16x16x32_bf16 v[98:101], v[184:187], v[204:207], v[98:101]
	v_mfma_f32_16x16x32_bf16 v[86:89], v[176:179], v[212:215], v[86:89]
	v_mfma_f32_16x16x32_bf16 v[82:85], v[184:187], v[212:215], v[82:85]
	v_mfma_f32_16x16x32_bf16 v[70:73], v[176:179], v[220:223], v[70:73]
	v_mfma_f32_16x16x32_bf16 v[66:69], v[184:187], v[220:223], v[66:69]
	v_mfma_f32_16x16x32_bf16 v[118:121], v[180:183], v[200:203], v[118:121]
	v_mfma_f32_16x16x32_bf16 v[114:117], v[192:195], v[200:203], v[114:117]
	v_mfma_f32_16x16x32_bf16 v[102:105], v[180:183], v[208:211], v[102:105]
	v_mfma_f32_16x16x32_bf16 v[98:101], v[192:195], v[208:211], v[98:101]
	v_mfma_f32_16x16x32_bf16 v[86:89], v[180:183], v[216:219], v[86:89]
	v_mfma_f32_16x16x32_bf16 v[82:85], v[192:195], v[216:219], v[82:85]
	v_mfma_f32_16x16x32_bf16 v[70:73], v[180:183], v[224:227], v[70:73]
	v_mfma_f32_16x16x32_bf16 v[66:69], v[192:195], v[224:227], v[66:69]
	s_setprio 0
	s_barrier
	s_add_i32 s15, s15, s63
	v_lshl_add_u64 v[168:169], v[168:169], 0, s[42:43]
	s_mov_b32 m0, s15
	ds_read_b128 v[196:199], v173 offset:49152
	ds_read_b128 v[200:203], v173 offset:50176
	ds_read_b128 v[204:207], v173 offset:51200
	ds_read_b128 v[208:211], v173 offset:52224
	ds_read_b128 v[212:215], v173 offset:53248
	ds_read_b128 v[216:219], v173 offset:54272
	ds_read_b128 v[220:223], v173 offset:55296
	ds_read_b128 v[224:227], v173 offset:56320
	global_load_lds_dwordx4 v[168:169], off
	s_add_i32 m0, s15, 0x2000
	s_add_u32 s18, s56, 0x40080
	v_lshl_add_u64 v[168:169], v[188:189], 0, s[42:43]
	s_addc_u32 s19, s57, 0
	s_add_i32 s15, s60, s63
	global_load_lds_dwordx4 v[168:169], off
	v_lshl_add_u64 v[168:169], s[18:19], 0, v[140:141]
	s_mov_b32 m0, s15
	s_nop 0
	global_load_lds_dwordx4 v[168:169], off
	v_lshl_add_u64 v[168:169], s[18:19], 0, v[144:145]
	s_add_i32 m0, s15, 0x2000
	s_nop 0
	global_load_lds_dwordx4 v[168:169], off
	v_lshl_add_u64 v[168:169], v[228:229], 0, s[42:43]
	s_mov_b32 m0, s74
	s_nop 0
	global_load_lds_dwordx4 v[168:169], off
	v_lshl_add_u64 v[168:169], v[230:231], 0, s[42:43]
	s_mov_b32 m0, s75
	s_nop 0
	global_load_lds_dwordx4 v[168:169], off
	s_waitcnt vmcnt(8)
	s_waitcnt lgkmcnt(0)
	s_barrier
; #define PG8_STAGE(bufoff, gbase, voff) do { _Pragma("unroll") for (int _i = 0; _i < 2; ++_i) \
;         __builtin_amdgcn_global_load_lds((const unsigned*)((const char*)(gbase) + (voff)[_i]), (PG8_LAS unsigned*)(lds + (bufoff) + ldsw + _i * 8192), 16, 0, 0); } while (0)
; #define PG8_LDA(dst, b, h) do { _Pragma("unroll") for (int m = 0; m < 4; ++m) _Pragma("unroll") for (int k = 0; k < 2; ++k) dst[m][k] = *(const PG8_LAS bf16x8*)(lds + PG8_SA(b, h) + aoff + m * 2048 + k * 1024); } while (0)
; #define PG8_WAIT_V(n) asm volatile("s_waitcnt vmcnt(" #n ")" ::: "memory")
; #define PG8_WAIT_L(n) asm volatile("s_waitcnt lgkmcnt(" #n ")" ::: "memory")
; #define PG8_BAR __builtin_amdgcn_s_barrier()
; template <class Epi, class Sched, bool ALIGN_EPI = false, bool SP2 = false>
; __device__ __forceinline__ void gemm_phase(PG8_LAS unsigned char* lds, const Gemm g, const Sched& S, const Epi& E, const int tid) {
;     ...
;         for (int t = 0; t < nt; t += 2) {
;             const bool last = (t == nt - 2);
;             const char* a1 = cA + (size_t)(t + 1) * kstep;
;             const char* a2 = last ? nA : cA + (size_t)(t + 2) * kstep; const char* b2 = last ? nB : cB + (size_t)(t + 2) * kstep;
;             const char* a3 = a2 + kstep; const char* b3 = b2 + kstep;
;             if (last && has_next) S.a_ready(nxt);
;             if constexpr (SP2) {
;             PG8_LDB(B0, 0, 0); PG8_LDB(B1, 0, 1); PG8_SCHED; PG8_LDA(At, 0, 0); PG8_STAGE(PG8_SA(1, 1), a1 + hstep, voffA);
;             PG8_WAIT_V(8); PG8_WAIT_L(0); PG8_BAR; PG8_MMA(0, 0, At, B0); PG8_MMA(0, 1, At, B1); PG8_BAR; PG8_SCHED;
;             PG8_LDA(At, 0, 1); PG8_STAGE(PG8_SB(0, 0), b2, voffB); PG8_STAGE(PG8_SB(0, 1), b2 + hstep, voffB); PG8_STAGE(PG8_SA(0, 0), a2, voffA);
;             PG8_WAIT_V(8); PG8_WAIT_L(0); PG8_BAR; PG8_MMA(1, 0, At, B0); PG8_MMA(1, 1, At, B1); PG8_BAR; PG8_SCHED;
;             PG8_LDB(B0, 1, 0); PG8_LDB(B1, 1, 1); PG8_SCHED; PG8_LDA(At, 1, 0); PG8_STAGE(PG8_SA(0, 1), a2 + hstep, voffA);
;             PG8_WAIT_V(8); PG8_WAIT_L(0); PG8_BAR; PG8_MMA(0, 0, At, B0); PG8_MMA(0, 1, At, B1); PG8_BAR; PG8_SCHED;
;             PG8_LDA(At, 1, 1); PG8_STAGE(PG8_SB(1, 0), b3, voffB); PG8_STAGE(PG8_SB(1, 1), b3 + hstep, voffB); PG8_STAGE(PG8_SA(1, 0), a3, voffA);
;             PG8_WAIT_V(8); PG8_WAIT_L(0); PG8_BAR; PG8_MMA(1, 0, At, B0); PG8_MMA(1, 1, At, B1); PG8_BAR; PG8_SCHED;
	s_setprio 1
	v_mfma_f32_16x16x32_bf16 v[62:65], v[130:133], v[196:199], v[62:65]
	v_mfma_f32_16x16x32_bf16 v[58:61], v[160:163], v[196:199], v[58:61]
	v_mfma_f32_16x16x32_bf16 v[46:49], v[130:133], v[204:207], v[46:49]
	v_mfma_f32_16x16x32_bf16 v[42:45], v[160:163], v[204:207], v[42:45]
	v_mfma_f32_16x16x32_bf16 v[30:33], v[130:133], v[212:215], v[30:33]
	v_mfma_f32_16x16x32_bf16 v[26:29], v[160:163], v[212:215], v[26:29]
	v_mfma_f32_16x16x32_bf16 v[14:17], v[130:133], v[220:223], v[14:17]
	v_mfma_f32_16x16x32_bf16 v[10:13], v[160:163], v[220:223], v[10:13]
	v_mfma_f32_16x16x32_bf16 v[62:65], v[134:137], v[200:203], v[62:65]
	v_mfma_f32_16x16x32_bf16 v[58:61], v[164:167], v[200:203], v[58:61]
	v_mfma_f32_16x16x32_bf16 v[46:49], v[134:137], v[208:211], v[46:49]
	v_mfma_f32_16x16x32_bf16 v[42:45], v[164:167], v[208:211], v[42:45]
	v_mfma_f32_16x16x32_bf16 v[30:33], v[134:137], v[216:219], v[30:33]
	v_mfma_f32_16x16x32_bf16 v[26:29], v[164:167], v[216:219], v[26:29]
	v_mfma_f32_16x16x32_bf16 v[14:17], v[134:137], v[224:227], v[14:17]
	v_mfma_f32_16x16x32_bf16 v[10:13], v[164:167], v[224:227], v[10:13]
	s_setprio 0
	s_setprio 1
	v_mfma_f32_16x16x32_bf16 v[54:57], v[176:179], v[196:199], v[54:57]
	v_mfma_f32_16x16x32_bf16 v[50:53], v[184:187], v[196:199], v[50:53]
	v_mfma_f32_16x16x32_bf16 v[38:41], v[176:179], v[204:207], v[38:41]
	v_mfma_f32_16x16x32_bf16 v[34:37], v[184:187], v[204:207], v[34:37]
	v_mfma_f32_16x16x32_bf16 v[22:25], v[176:179], v[212:215], v[22:25]
	v_mfma_f32_16x16x32_bf16 v[18:21], v[184:187], v[212:215], v[18:21]
	v_mfma_f32_16x16x32_bf16 v[6:9], v[176:179], v[220:223], v[6:9]
	v_mfma_f32_16x16x32_bf16 v[2:5], v[184:187], v[220:223], v[2:5]
	v_mfma_f32_16x16x32_bf16 v[54:57], v[180:183], v[200:203], v[54:57]
	v_mfma_f32_16x16x32_bf16 v[50:53], v[192:195], v[200:203], v[50:53]
	v_mfma_f32_16x16x32_bf16 v[38:41], v[180:183], v[208:211], v[38:41]
	v_mfma_f32_16x16x32_bf16 v[34:37], v[192:195], v[208:211], v[34:37]
	v_mfma_f32_16x16x32_bf16 v[22:25], v[180:183], v[216:219], v[22:25]
	v_mfma_f32_16x16x32_bf16 v[18:21], v[192:195], v[216:219], v[18:21]
	v_mfma_f32_16x16x32_bf16 v[6:9], v[180:183], v[224:227], v[6:9]
	v_mfma_f32_16x16x32_bf16 v[2:5], v[192:195], v[224:227], v[2:5]
	s_setprio 0
	s_barrier
	s_add_i32 s49, s49, 2
	s_add_u32 s5, s5, 0x100
	s_addc_u32 s47, s47, 0
	s_add_u32 s54, s54, 0x100
	s_addc_u32 s55, s55, 0
.LBB0_5777:
	ds_read_b128 v[130:133], v171
	ds_read_b128 v[134:137], v171 offset:1024
	ds_read_b128 v[160:163], v171 offset:2048
	ds_read_b128 v[164:167], v171 offset:3072
	ds_read_b128 v[176:179], v172
	ds_read_b128 v[180:183], v172 offset:1024
	ds_read_b128 v[184:187], v172 offset:2048
	ds_read_b128 v[192:195], v172 offset:3072
	s_add_u32 s15, s54, 0xfffc0080
	s_addc_u32 s18, s55, -1
	s_cmp_eq_u32 s49, 12
	s_cselect_b32 s59, s1, s18
	s_cselect_b32 s58, s0, s15
	s_cselect_b32 s57, s51, s47
	s_cselect_b32 s56, s50, s5
	v_lshl_add_u64 v[168:169], s[54:55], 0, v[154:155]
	s_add_i32 m0, s64, 0xc000
	ds_read_b128 v[196:199], v173
	ds_read_b128 v[200:203], v173 offset:1024
	ds_read_b128 v[204:207], v173 offset:2048
	ds_read_b128 v[208:211], v173 offset:3072
	ds_read_b128 v[212:215], v173 offset:4096
	ds_read_b128 v[216:219], v173 offset:5120
	ds_read_b128 v[220:223], v173 offset:6144
	ds_read_b128 v[224:227], v173 offset:7168
	global_load_lds_dwordx4 v[168:169], off
	v_lshl_add_u64 v[168:169], s[54:55], 0, v[152:153]
	s_add_i32 m0, s64, 0xe000
	s_nop 0
	global_load_lds_dwordx4 v[168:169], off
	s_waitcnt vmcnt(8)
	s_waitcnt lgkmcnt(0)
	s_barrier
	s_setprio 1
	v_mfma_f32_16x16x32_bf16 v[126:129], v[130:133], v[196:199], v[126:129]
	v_mfma_f32_16x16x32_bf16 v[122:125], v[160:163], v[196:199], v[122:125]
	v_mfma_f32_16x16x32_bf16 v[110:113], v[130:133], v[204:207], v[110:113]
	v_mfma_f32_16x16x32_bf16 v[106:109], v[160:163], v[204:207], v[106:109]
	v_mfma_f32_16x16x32_bf16 v[94:97], v[130:133], v[212:215], v[94:97]
	v_mfma_f32_16x16x32_bf16 v[90:93], v[160:163], v[212:215], v[90:93]
	v_mfma_f32_16x16x32_bf16 v[78:81], v[130:133], v[220:223], v[78:81]
	v_mfma_f32_16x16x32_bf16 v[74:77], v[160:163], v[220:223], v[74:77]
	v_mfma_f32_16x16x32_bf16 v[126:129], v[134:137], v[200:203], v[126:129]
	v_mfma_f32_16x16x32_bf16 v[122:125], v[164:167], v[200:203], v[122:125]
	v_mfma_f32_16x16x32_bf16 v[110:113], v[134:137], v[208:211], v[110:113]
	v_mfma_f32_16x16x32_bf16 v[106:109], v[164:167], v[208:211], v[106:109]
	v_mfma_f32_16x16x32_bf16 v[94:97], v[134:137], v[216:219], v[94:97]
	v_mfma_f32_16x16x32_bf16 v[90:93], v[164:167], v[216:219], v[90:93]
	v_mfma_f32_16x16x32_bf16 v[78:81], v[134:137], v[224:227], v[78:81]
	v_mfma_f32_16x16x32_bf16 v[74:77], v[164:167], v[224:227], v[74:77]
	s_setprio 0
	s_setprio 1
	v_mfma_f32_16x16x32_bf16 v[118:121], v[176:179], v[196:199], v[118:121]
	v_mfma_f32_16x16x32_bf16 v[114:117], v[184:187], v[196:199], v[114:117]
	v_mfma_f32_16x16x32_bf16 v[102:105], v[176:179], v[204:207], v[102:105]
	v_mfma_f32_16x16x32_bf16 v[98:101], v[184:187], v[204:207], v[98:101]
	v_mfma_f32_16x16x32_bf16 v[86:89], v[176:179], v[212:215], v[86:89]
	v_mfma_f32_16x16x32_bf16 v[82:85], v[184:187], v[212:215], v[82:85]
	v_mfma_f32_16x16x32_bf16 v[70:73], v[176:179], v[220:223], v[70:73]
	v_mfma_f32_16x16x32_bf16 v[66:69], v[184:187], v[220:223], v[66:69]
	v_mfma_f32_16x16x32_bf16 v[118:121], v[180:183], v[200:203], v[118:121]
	v_mfma_f32_16x16x32_bf16 v[114:117], v[192:195], v[200:203], v[114:117]
	v_mfma_f32_16x16x32_bf16 v[102:105], v[180:183], v[208:211], v[102:105]
	v_mfma_f32_16x16x32_bf16 v[98:101], v[192:195], v[208:211], v[98:101]
	v_mfma_f32_16x16x32_bf16 v[86:89], v[180:183], v[216:219], v[86:89]
	v_mfma_f32_16x16x32_bf16 v[82:85], v[192:195], v[216:219], v[82:85]
	v_mfma_f32_16x16x32_bf16 v[70:73], v[180:183], v[224:227], v[70:73]
	v_mfma_f32_16x16x32_bf16 v[66:69], v[192:195], v[224:227], v[66:69]
	s_setprio 0
	s_barrier
; #define PG8_STAGE(bufoff, gbase, voff) do { _Pragma("unroll") for (int _i = 0; _i < 2; ++_i) \
;         __builtin_amdgcn_global_load_lds((const unsigned*)((const char*)(gbase) + (voff)[_i]), (PG8_LAS unsigned*)(lds + (bufoff) + ldsw + _i * 8192), 16, 0, 0); } while (0)
; #define PG8_LDA(dst, b, h) do { _Pragma("unroll") for (int m = 0; m < 4; ++m) _Pragma("unroll") for (int k = 0; k < 2; ++k) dst[m][k] = *(const PG8_LAS bf16x8*)(lds + PG8_SA(b, h) + aoff + m * 2048 + k * 1024); } while (0)
; #define PG8_LDB(dst, b, h) do { _Pragma("unroll") for (int n = 0; n < 2; ++n) _Pragma("unroll") for (int k = 0; k < 2; ++k) dst[n][k] = *(const PG8_LAS bf16x8*)(lds + PG8_SB(b, h) + boff + n * 2048 + k * 1024); } while (0)
; #define PG8_MMA(ai, bj, At, Bt) do { __builtin_amdgcn_s_setprio(1); _Pragma("unroll") for (int m = 0; m < 4; ++m) _Pragma("unroll") for (int n = 0; n < 2; ++n) _Pragma("unroll") for (int k = 0; k < 2; ++k) \
;         acc[ai][bj][m][n] = __builtin_amdgcn_mfma_f32_16x16x32_bf16(Bt[n][k], At[m][k], acc[ai][bj][m][n], 0, 0, 0); __builtin_amdgcn_s_setprio(0); } while (0)
; #define PG8_WAIT_V(n) asm volatile("s_waitcnt vmcnt(" #n ")" ::: "memory")
; #define PG8_WAIT_L(n) asm volatile("s_waitcnt lgkmcnt(" #n ")" ::: "memory")
; #define PG8_BAR __builtin_amdgcn_s_barrier()
; #define PG8_SCHED __builtin_amdgcn_sched_barrier(0)
; template <class Epi, class Sched, bool ALIGN_EPI = false, bool SP2 = false>
; __device__ __forceinline__ void gemm_phase(PG8_LAS unsigned char* lds, const Gemm g, const Sched& S, const Epi& E, const int tid) {
;     ...
;             PG8_LDA(At, 0, 1); PG8_STAGE(PG8_SB(0, 0), b2, voffB); PG8_STAGE(PG8_SB(0, 1), b2 + hstep, voffB); PG8_STAGE(PG8_SA(0, 0), a2, voffA);
;             PG8_WAIT_V(8); PG8_WAIT_L(0); PG8_BAR; PG8_MMA(1, 0, At, B0); PG8_MMA(1, 1, At, B1); PG8_BAR; PG8_SCHED;
;             PG8_LDB(B0, 1, 0); PG8_LDB(B1, 1, 1); PG8_SCHED; PG8_LDA(At, 1, 0); PG8_STAGE(PG8_SA(0, 1), a2 + hstep, voffA);
	s_add_i32 s15, s83, s63
	v_lshl_add_u64 v[168:169], s[56:57], 0, v[140:141]
	s_mov_b32 m0, s15
	ds_read_b128 v[196:199], v173 offset:16384
	ds_read_b128 v[200:203], v173 offset:17408
	ds_read_b128 v[204:207], v173 offset:18432
	ds_read_b128 v[208:211], v173 offset:19456
	ds_read_b128 v[212:215], v173 offset:20480
	ds_read_b128 v[216:219], v173 offset:21504
	ds_read_b128 v[220:223], v173 offset:22528
	ds_read_b128 v[224:227], v173 offset:23552
	global_load_lds_dwordx4 v[168:169], off
	s_add_i32 m0, s15, 0x2000
	s_add_u32 s18, s56, 0x40000
	v_lshl_add_u64 v[188:189], s[56:57], 0, v[144:145]
	s_addc_u32 s19, s57, 0
	s_add_i32 s15, s84, s63
	global_load_lds_dwordx4 v[188:189], off
	v_lshl_add_u64 v[228:229], s[18:19], 0, v[140:141]
	s_mov_b32 m0, s15
	v_lshl_add_u64 v[230:231], s[58:59], 0, v[142:143]
	global_load_lds_dwordx4 v[228:229], off
	v_lshl_add_u64 v[228:229], s[18:19], 0, v[144:145]
	s_add_i32 m0, s15, 0x2000
	s_nop 0
	global_load_lds_dwordx4 v[228:229], off
	v_lshl_add_u64 v[228:229], s[58:59], 0, v[138:139]
	s_mov_b32 m0, s64
	s_nop 0
	global_load_lds_dwordx4 v[228:229], off
	s_mov_b32 m0, s65
	s_nop 0
	global_load_lds_dwordx4 v[230:231], off
	s_waitcnt vmcnt(8)
	s_waitcnt lgkmcnt(0)
	s_barrier
	s_setprio 1
	v_mfma_f32_16x16x32_bf16 v[62:65], v[130:133], v[196:199], v[62:65]
	v_mfma_f32_16x16x32_bf16 v[58:61], v[160:163], v[196:199], v[58:61]
	v_mfma_f32_16x16x32_bf16 v[46:49], v[130:133], v[204:207], v[46:49]
	v_mfma_f32_16x16x32_bf16 v[42:45], v[160:163], v[204:207], v[42:45]
	v_mfma_f32_16x16x32_bf16 v[30:33], v[130:133], v[212:215], v[30:33]
	v_mfma_f32_16x16x32_bf16 v[26:29], v[160:163], v[212:215], v[26:29]
	v_mfma_f32_16x16x32_bf16 v[14:17], v[130:133], v[220:223], v[14:17]
	v_mfma_f32_16x16x32_bf16 v[10:13], v[160:163], v[220:223], v[10:13]
	v_mfma_f32_16x16x32_bf16 v[62:65], v[134:137], v[200:203], v[62:65]
	v_mfma_f32_16x16x32_bf16 v[58:61], v[164:167], v[200:203], v[58:61]
	v_mfma_f32_16x16x32_bf16 v[46:49], v[134:137], v[208:211], v[46:49]
	v_mfma_f32_16x16x32_bf16 v[42:45], v[164:167], v[208:211], v[42:45]
	v_mfma_f32_16x16x32_bf16 v[30:33], v[134:137], v[216:219], v[30:33]
	v_mfma_f32_16x16x32_bf16 v[26:29], v[164:167], v[216:219], v[26:29]
	v_mfma_f32_16x16x32_bf16 v[14:17], v[134:137], v[224:227], v[14:17]
	v_mfma_f32_16x16x32_bf16 v[10:13], v[164:167], v[224:227], v[10:13]
	s_setprio 0
	s_setprio 1
	v_mfma_f32_16x16x32_bf16 v[54:57], v[176:179], v[196:199], v[54:57]
	v_mfma_f32_16x16x32_bf16 v[50:53], v[184:187], v[196:199], v[50:53]
	v_mfma_f32_16x16x32_bf16 v[38:41], v[176:179], v[204:207], v[38:41]
	v_mfma_f32_16x16x32_bf16 v[34:37], v[184:187], v[204:207], v[34:37]
	v_mfma_f32_16x16x32_bf16 v[22:25], v[176:179], v[212:215], v[22:25]
	v_mfma_f32_16x16x32_bf16 v[18:21], v[184:187], v[212:215], v[18:21]
	v_mfma_f32_16x16x32_bf16 v[6:9], v[176:179], v[220:223], v[6:9]
	v_mfma_f32_16x16x32_bf16 v[2:5], v[184:187], v[220:223], v[2:5]
	v_mfma_f32_16x16x32_bf16 v[54:57], v[180:183], v[200:203], v[54:57]
	v_mfma_f32_16x16x32_bf16 v[50:53], v[192:195], v[200:203], v[50:53]
	v_mfma_f32_16x16x32_bf16 v[38:41], v[180:183], v[208:211], v[38:41]
	v_mfma_f32_16x16x32_bf16 v[34:37], v[192:195], v[208:211], v[34:37]
	v_mfma_f32_16x16x32_bf16 v[22:25], v[180:183], v[216:219], v[22:25]
	v_mfma_f32_16x16x32_bf16 v[18:21], v[192:195], v[216:219], v[18:21]
	v_mfma_f32_16x16x32_bf16 v[6:9], v[180:183], v[224:227], v[6:9]
	v_mfma_f32_16x16x32_bf16 v[2:5], v[192:195], v[224:227], v[2:5]
	s_setprio 0
	s_barrier
	s_add_i32 s15, 0, 0x18000
	s_add_i32 s60, 0, 0x1c000
	v_add_u32_e32 v164, s15, v170
	v_add_u32_e32 v175, s60, v170
	ds_read_b128 v[130:133], v164
	ds_read_b128 v[134:137], v164 offset:1024
	ds_read_b128 v[160:163], v164 offset:2048
	ds_read_b128 v[164:167], v164 offset:3072
	ds_read_b128 v[176:179], v175
	ds_read_b128 v[180:183], v175 offset:1024
	ds_read_b128 v[184:187], v175 offset:2048
	ds_read_b128 v[192:195], v175 offset:3072
	s_add_u32 s18, s58, 0x40000
	s_addc_u32 s19, s59, 0
	s_mov_b32 m0, s66
	v_lshl_add_u64 v[232:233], s[18:19], 0, v[138:139]
	ds_read_b128 v[196:199], v173 offset:32768
	ds_read_b128 v[200:203], v173 offset:33792
	ds_read_b128 v[204:207], v173 offset:34816
	ds_read_b128 v[208:211], v173 offset:35840
	ds_read_b128 v[212:215], v173 offset:36864
	ds_read_b128 v[216:219], v173 offset:37888
	ds_read_b128 v[220:223], v173 offset:38912
	ds_read_b128 v[224:227], v173 offset:39936
	global_load_lds_dwordx4 v[232:233], off
	v_lshl_add_u64 v[232:233], s[18:19], 0, v[142:143]
	s_mov_b32 m0, s67
	s_nop 0
	global_load_lds_dwordx4 v[232:233], off
	s_waitcnt vmcnt(8)
	s_waitcnt lgkmcnt(0)
	s_barrier
; #define PG8_STAGE(bufoff, gbase, voff) do { _Pragma("unroll") for (int _i = 0; _i < 2; ++_i) \
;         __builtin_amdgcn_global_load_lds((const unsigned*)((const char*)(gbase) + (voff)[_i]), (PG8_LAS unsigned*)(lds + (bufoff) + ldsw + _i * 8192), 16, 0, 0); } while (0)
; #define PG8_LDA(dst, b, h) do { _Pragma("unroll") for (int m = 0; m < 4; ++m) _Pragma("unroll") for (int k = 0; k < 2; ++k) dst[m][k] = *(const PG8_LAS bf16x8*)(lds + PG8_SA(b, h) + aoff + m * 2048 + k * 1024); } while (0)
; #define PG8_MMA(ai, bj, At, Bt) do { __builtin_amdgcn_s_setprio(1); _Pragma("unroll") for (int m = 0; m < 4; ++m) _Pragma("unroll") for (int n = 0; n < 2; ++n) _Pragma("unroll") for (int k = 0; k < 2; ++k) \
;         acc[ai][bj][m][n] = __builtin_amdgcn_mfma_f32_16x16x32_bf16(Bt[n][k], At[m][k], acc[ai][bj][m][n], 0, 0, 0); __builtin_amdgcn_s_setprio(0); } while (0)
; #define PG8_WAIT_V(n) asm volatile("s_waitcnt vmcnt(" #n ")" ::: "memory")
; #define PG8_WAIT_L(n) asm volatile("s_waitcnt lgkmcnt(" #n ")" ::: "memory")
; #define PG8_BAR __builtin_amdgcn_s_barrier()
; #define PG8_SCHED __builtin_amdgcn_sched_barrier(0)
; template <class Epi, class Sched, bool ALIGN_EPI = false, bool SP2 = false>
; __device__ __forceinline__ void gemm_phase(PG8_LAS unsigned char* lds, const Gemm g, const Sched& S, const Epi& E, const int tid) {
;     ...
;             PG8_WAIT_V(8); PG8_WAIT_L(0); PG8_BAR; PG8_MMA(0, 0, At, B0); PG8_MMA(0, 1, At, B1); PG8_BAR; PG8_SCHED;
;             PG8_LDA(At, 1, 1); PG8_STAGE(PG8_SB(1, 0), b3, voffB); PG8_STAGE(PG8_SB(1, 1), b3 + hstep, voffB); PG8_STAGE(PG8_SA(1, 0), a3, voffA);
;             PG8_WAIT_V(8); PG8_WAIT_L(0); PG8_BAR; PG8_MMA(1, 0, At, B0); PG8_MMA(1, 1, At, B1); PG8_BAR; PG8_SCHED;
;     ...
;         if constexpr (ALIGN_EPI) { if (wr == 0) PG8_BAR; }
	s_setprio 1
	v_mfma_f32_16x16x32_bf16 v[126:129], v[130:133], v[196:199], v[126:129]
	v_mfma_f32_16x16x32_bf16 v[122:125], v[160:163], v[196:199], v[122:125]
	v_mfma_f32_16x16x32_bf16 v[110:113], v[130:133], v[204:207], v[110:113]
	v_mfma_f32_16x16x32_bf16 v[106:109], v[160:163], v[204:207], v[106:109]
	v_mfma_f32_16x16x32_bf16 v[94:97], v[130:133], v[212:215], v[94:97]
	v_mfma_f32_16x16x32_bf16 v[90:93], v[160:163], v[212:215], v[90:93]
	v_mfma_f32_16x16x32_bf16 v[78:81], v[130:133], v[220:223], v[78:81]
	v_mfma_f32_16x16x32_bf16 v[74:77], v[160:163], v[220:223], v[74:77]
	v_mfma_f32_16x16x32_bf16 v[126:129], v[134:137], v[200:203], v[126:129]
	v_mfma_f32_16x16x32_bf16 v[122:125], v[164:167], v[200:203], v[122:125]
	v_mfma_f32_16x16x32_bf16 v[110:113], v[134:137], v[208:211], v[110:113]
	v_mfma_f32_16x16x32_bf16 v[106:109], v[164:167], v[208:211], v[106:109]
	v_mfma_f32_16x16x32_bf16 v[94:97], v[134:137], v[216:219], v[94:97]
	v_mfma_f32_16x16x32_bf16 v[90:93], v[164:167], v[216:219], v[90:93]
	v_mfma_f32_16x16x32_bf16 v[78:81], v[134:137], v[224:227], v[78:81]
	v_mfma_f32_16x16x32_bf16 v[74:77], v[164:167], v[224:227], v[74:77]
	s_setprio 0
	s_setprio 1
	v_mfma_f32_16x16x32_bf16 v[118:121], v[176:179], v[196:199], v[118:121]
	v_mfma_f32_16x16x32_bf16 v[114:117], v[184:187], v[196:199], v[114:117]
	v_mfma_f32_16x16x32_bf16 v[102:105], v[176:179], v[204:207], v[102:105]
	v_mfma_f32_16x16x32_bf16 v[98:101], v[184:187], v[204:207], v[98:101]
	v_mfma_f32_16x16x32_bf16 v[86:89], v[176:179], v[212:215], v[86:89]
	v_mfma_f32_16x16x32_bf16 v[82:85], v[184:187], v[212:215], v[82:85]
	v_mfma_f32_16x16x32_bf16 v[70:73], v[176:179], v[220:223], v[70:73]
	v_mfma_f32_16x16x32_bf16 v[66:69], v[184:187], v[220:223], v[66:69]
	v_mfma_f32_16x16x32_bf16 v[118:121], v[180:183], v[200:203], v[118:121]
	v_mfma_f32_16x16x32_bf16 v[114:117], v[192:195], v[200:203], v[114:117]
	v_mfma_f32_16x16x32_bf16 v[102:105], v[180:183], v[208:211], v[102:105]
	v_mfma_f32_16x16x32_bf16 v[98:101], v[192:195], v[208:211], v[98:101]
	v_mfma_f32_16x16x32_bf16 v[86:89], v[180:183], v[216:219], v[86:89]
	v_mfma_f32_16x16x32_bf16 v[82:85], v[192:195], v[216:219], v[82:85]
	v_mfma_f32_16x16x32_bf16 v[70:73], v[180:183], v[224:227], v[70:73]
	v_mfma_f32_16x16x32_bf16 v[66:69], v[192:195], v[224:227], v[66:69]
	s_setprio 0
	s_barrier
	s_add_i32 s15, s15, s63
	v_lshl_add_u64 v[168:169], v[168:169], 0, s[42:43]
	s_mov_b32 m0, s15
	ds_read_b128 v[196:199], v173 offset:49152
	ds_read_b128 v[200:203], v173 offset:50176
	ds_read_b128 v[204:207], v173 offset:51200
	ds_read_b128 v[208:211], v173 offset:52224
	ds_read_b128 v[212:215], v173 offset:53248
	ds_read_b128 v[216:219], v173 offset:54272
	ds_read_b128 v[220:223], v173 offset:55296
	ds_read_b128 v[224:227], v173 offset:56320
	global_load_lds_dwordx4 v[168:169], off
	s_add_i32 m0, s15, 0x2000
	s_add_u32 s18, s56, 0x40080
	v_lshl_add_u64 v[168:169], v[188:189], 0, s[42:43]
	s_addc_u32 s19, s57, 0
	s_add_i32 s15, s60, s63
	global_load_lds_dwordx4 v[168:169], off
	v_lshl_add_u64 v[168:169], s[18:19], 0, v[140:141]
	s_mov_b32 m0, s15
	s_nop 0
	global_load_lds_dwordx4 v[168:169], off
	v_lshl_add_u64 v[168:169], s[18:19], 0, v[144:145]
	s_add_i32 m0, s15, 0x2000
	s_nop 0
	global_load_lds_dwordx4 v[168:169], off
	v_lshl_add_u64 v[168:169], v[228:229], 0, s[42:43]
	s_mov_b32 m0, s74
	s_nop 0
	global_load_lds_dwordx4 v[168:169], off
	v_lshl_add_u64 v[168:169], v[230:231], 0, s[42:43]
	s_mov_b32 m0, s75
	s_nop 0
	global_load_lds_dwordx4 v[168:169], off
	s_waitcnt vmcnt(8)
	s_waitcnt lgkmcnt(0)
	s_barrier
	s_setprio 1
	v_mfma_f32_16x16x32_bf16 v[62:65], v[130:133], v[196:199], v[62:65]
	v_mfma_f32_16x16x32_bf16 v[58:61], v[160:163], v[196:199], v[58:61]
	v_mfma_f32_16x16x32_bf16 v[46:49], v[130:133], v[204:207], v[46:49]
	v_mfma_f32_16x16x32_bf16 v[42:45], v[160:163], v[204:207], v[42:45]
	v_mfma_f32_16x16x32_bf16 v[30:33], v[130:133], v[212:215], v[30:33]
	v_mfma_f32_16x16x32_bf16 v[26:29], v[160:163], v[212:215], v[26:29]
	v_mfma_f32_16x16x32_bf16 v[14:17], v[130:133], v[220:223], v[14:17]
	v_mfma_f32_16x16x32_bf16 v[10:13], v[160:163], v[220:223], v[10:13]
	v_mfma_f32_16x16x32_bf16 v[62:65], v[134:137], v[200:203], v[62:65]
	v_mfma_f32_16x16x32_bf16 v[58:61], v[164:167], v[200:203], v[58:61]
	v_mfma_f32_16x16x32_bf16 v[46:49], v[134:137], v[208:211], v[46:49]
	v_mfma_f32_16x16x32_bf16 v[42:45], v[164:167], v[208:211], v[42:45]
	v_mfma_f32_16x16x32_bf16 v[30:33], v[134:137], v[216:219], v[30:33]
	v_mfma_f32_16x16x32_bf16 v[26:29], v[164:167], v[216:219], v[26:29]
	v_mfma_f32_16x16x32_bf16 v[14:17], v[134:137], v[224:227], v[14:17]
	v_mfma_f32_16x16x32_bf16 v[10:13], v[164:167], v[224:227], v[10:13]
	s_setprio 0
	s_setprio 1
	v_mfma_f32_16x16x32_bf16 v[54:57], v[176:179], v[196:199], v[54:57]
	v_mfma_f32_16x16x32_bf16 v[50:53], v[184:187], v[196:199], v[50:53]
	v_mfma_f32_16x16x32_bf16 v[38:41], v[176:179], v[204:207], v[38:41]
	v_mfma_f32_16x16x32_bf16 v[34:37], v[184:187], v[204:207], v[34:37]
	v_mfma_f32_16x16x32_bf16 v[22:25], v[176:179], v[212:215], v[22:25]
	v_mfma_f32_16x16x32_bf16 v[18:21], v[184:187], v[212:215], v[18:21]
	v_mfma_f32_16x16x32_bf16 v[6:9], v[176:179], v[220:223], v[6:9]
	v_mfma_f32_16x16x32_bf16 v[2:5], v[184:187], v[220:223], v[2:5]
	v_mfma_f32_16x16x32_bf16 v[54:57], v[180:183], v[200:203], v[54:57]
	v_mfma_f32_16x16x32_bf16 v[50:53], v[192:195], v[200:203], v[50:53]
	v_mfma_f32_16x16x32_bf16 v[38:41], v[180:183], v[208:211], v[38:41]
	v_mfma_f32_16x16x32_bf16 v[34:37], v[192:195], v[208:211], v[34:37]
	v_mfma_f32_16x16x32_bf16 v[22:25], v[180:183], v[216:219], v[22:25]
	v_mfma_f32_16x16x32_bf16 v[18:21], v[192:195], v[216:219], v[18:21]
	v_mfma_f32_16x16x32_bf16 v[6:9], v[180:183], v[224:227], v[6:9]
	v_mfma_f32_16x16x32_bf16 v[2:5], v[192:195], v[224:227], v[2:5]
	s_setprio 0
	s_barrier
	s_add_i32 s49, s49, 2
	s_add_u32 s5, s5, 0x100
	s_addc_u32 s47, s47, 0
	s_add_u32 s54, s54, 0x100
	s_addc_u32 s55, s55, 0
	s_cmp_gt_u32 s49, 13
	s_cbranch_scc0 .LBB0_5777
	s_and_b64 vcc, exec, s[44:45]
	s_cbranch_vccz .LBB0_5780
	s_barrier
